# loopedge
# speedup vs baseline: 1.0135x; 1.0072x over previous
; #define STAGE(P, BASE, LD, br, kt) do { const char* _g = (const char*)((BASE) + (size_t)(br) * (LD) + (size_t)(kt) * 64); \
;     for (int _i = 0; _i < 2; ++_i) { int _b = tidx * 16 + _i * 8192; int _r, _c; stage_rc(_b, _r, _c); \
;       __builtin_amdgcn_global_load_lds((const unsigned*)(_g + (unsigned)((_r * (LD) + _c) * 2)), (unsigned*)((char*)(P) + _b), 16, 0, 0); } } while (0)
; #define LDA(dst, b, h) for (int m = 0; m < 4; ++m) for (int k = 0; k < 2; ++k) \
;     dst[m][k] = *reinterpret_cast<const bf16x8*>((char*)SA(b, h) + lds_byte(wr * 64 + m * 16 + fr, k * 32 + fq * 8))
; #define LDB(dst, b, h) for (int n = 0; n < 2; ++n) for (int k = 0; k < 2; ++k) \
;     dst[n][k] = *reinterpret_cast<const bf16x8*>((char*)SB(b, h) + lds_byte(wc * 32 + n * 16 + fr, k * 32 + fq * 8))
; #define MMA(ai, bj, At_, Bt_) do { __builtin_amdgcn_s_setprio(1); \
;     for (int k = 0; k < 2; ++k) for (int m = 0; m < 4; ++m) for (int n = 0; n < 2; ++n) \
;       acc[ai][bj][m][n] = __builtin_amdgcn_mfma_f32_16x16x32_bf16(At_[m][k], Bt_[n][k], acc[ai][bj][m][n], 0, 0, 0); \
;     __builtin_amdgcn_s_setprio(0); } while (0)
; #define WAIT_L(n) asm volatile("s_waitcnt lgkmcnt(" #n ")" ::: "memory")
; #define BAR __builtin_amdgcn_s_barrier()
; #define SCHED __builtin_amdgcn_sched_barrier(0)
; template <int EPI, int lda, int ldb, int N, int K>
; __device__ __forceinline__ void gemm_phase(const u16* __restrict__ A, const u16* __restrict__ Bt, const GemmEpi ep, int wv) {
;     ...
;     for (int t = 0; t < nt - 2; t += 2) {
;       LDB(B0, 0, 0); SCHED; LDA(At, 0, 0); STAGE(SA(1, 1), Ab, lda, brow + HALF, t + 1);
;       WAIT_L(8); BAR; WAIT_L(0); MMA(0, 0, At, B0); BAR; SCHED;
;       LDB(B1, 0, 1); STAGE(SB(0, 0), Bt, ldb, bcol, t + 2);
;       BAR; WAIT_L(0); MMA(0, 1, At, B1); BAR;
;       LDA(At, 0, 1); STAGE(SA(0, 0), Ab, lda, brow, t + 2);
;       BAR; WAIT_L(0); MMA(1, 0, At, B0); BAR; SCHED;
.LBB0_53:
	ds_read_b128 v[172:175], v161
	ds_read_b128 v[176:179], v161 offset:1024
	ds_read_b128 v[180:183], v161 offset:2048
	ds_read_b128 v[184:187], v161 offset:3072
	v_add_u32_e32 v169, 0xc000, v148
	v_lshl_add_u64 v[236:237], v[136:137], 0, s[42:43]
	v_readfirstlane_b32 s45, v169
	v_add_u32_e32 v170, 0xe000, v148
	v_lshl_add_u64 v[162:163], v[236:237], 0, s[14:15]
	s_mov_b32 m0, s45
	v_lshl_add_u64 v[238:239], v[134:135], 0, s[42:43]
	v_readfirstlane_b32 s45, v170
	ds_read_b128 v[164:167], v152
	ds_read_b128 v[188:191], v152 offset:1024
	ds_read_b128 v[192:195], v151
	ds_read_b128 v[196:199], v151 offset:1024
	ds_read_b128 v[200:203], v150
	ds_read_b128 v[204:207], v150 offset:1024
	ds_read_b128 v[208:211], v149
	ds_read_b128 v[212:215], v149 offset:1024
	global_load_lds_dwordx4 v[162:163], off
	v_lshl_add_u64 v[162:163], v[238:239], 0, s[14:15]
	s_mov_b32 m0, s45
	s_nop 0
	global_load_lds_dwordx4 v[162:163], off
	s_waitcnt lgkmcnt(8)
	s_barrier
	s_waitcnt lgkmcnt(0)
	s_waitcnt lgkmcnt(0)
	v_mfma_f32_16x16x32_bf16 v[124:127], v[172:175], v[164:167], v[124:127]
	v_mfma_f32_16x16x32_bf16 v[120:123], v[180:183], v[164:167], v[120:123]
	v_mfma_f32_16x16x32_bf16 v[116:119], v[172:175], v[192:195], v[116:119]
	v_mfma_f32_16x16x32_bf16 v[112:115], v[180:183], v[192:195], v[112:115]
	v_mfma_f32_16x16x32_bf16 v[108:111], v[172:175], v[200:203], v[108:111]
	v_mfma_f32_16x16x32_bf16 v[104:107], v[180:183], v[200:203], v[104:107]
	v_mfma_f32_16x16x32_bf16 v[100:103], v[172:175], v[208:211], v[100:103]
	v_mfma_f32_16x16x32_bf16 v[96:99], v[180:183], v[208:211], v[96:99]
	v_mfma_f32_16x16x32_bf16 v[124:127], v[176:179], v[188:191], v[124:127]
	v_mfma_f32_16x16x32_bf16 v[120:123], v[184:187], v[188:191], v[120:123]
	v_mfma_f32_16x16x32_bf16 v[116:119], v[176:179], v[196:199], v[116:119]
	v_mfma_f32_16x16x32_bf16 v[112:115], v[184:187], v[196:199], v[112:115]
	v_mfma_f32_16x16x32_bf16 v[108:111], v[176:179], v[204:207], v[108:111]
	v_mfma_f32_16x16x32_bf16 v[104:107], v[184:187], v[204:207], v[104:107]
	v_mfma_f32_16x16x32_bf16 v[100:103], v[176:179], v[212:215], v[100:103]
	v_mfma_f32_16x16x32_bf16 v[96:99], v[184:187], v[212:215], v[96:99]
	s_barrier
	v_add_u32_e32 v162, s54, v153
	v_lshl_add_u64 v[240:241], v[140:141], 0, s[42:43]
	v_readfirstlane_b32 s45, v162
	v_add_u32_e32 v163, 0x2000, v162
	v_lshl_add_u64 v[232:233], v[240:241], 0, s[16:17]
	s_mov_b32 m0, s45
	v_lshl_add_u64 v[242:243], v[138:139], 0, s[42:43]
	v_readfirstlane_b32 s45, v163
	ds_read_b128 v[216:219], v160
	ds_read_b128 v[220:223], v160 offset:1024
	ds_read_b128 v[224:227], v160 offset:2048
	ds_read_b128 v[228:231], v160 offset:3072
	global_load_lds_dwordx4 v[232:233], off
	v_lshl_add_u64 v[232:233], v[242:243], 0, s[16:17]
	s_mov_b32 m0, s45
	s_nop 0
	global_load_lds_dwordx4 v[232:233], off
	s_barrier
	s_waitcnt lgkmcnt(0)
	s_waitcnt lgkmcnt(0)
	v_mfma_f32_16x16x32_bf16 v[92:95], v[216:219], v[164:167], v[92:95]
	v_mfma_f32_16x16x32_bf16 v[88:91], v[224:227], v[164:167], v[88:91]
	v_mfma_f32_16x16x32_bf16 v[84:87], v[216:219], v[192:195], v[84:87]
	v_mfma_f32_16x16x32_bf16 v[80:83], v[224:227], v[192:195], v[80:83]
	v_mfma_f32_16x16x32_bf16 v[76:79], v[216:219], v[200:203], v[76:79]
	v_mfma_f32_16x16x32_bf16 v[72:75], v[224:227], v[200:203], v[72:75]
	v_mfma_f32_16x16x32_bf16 v[68:71], v[216:219], v[208:211], v[68:71]
	v_mfma_f32_16x16x32_bf16 v[64:67], v[224:227], v[208:211], v[64:67]
	v_mfma_f32_16x16x32_bf16 v[92:95], v[220:223], v[188:191], v[92:95]
	v_mfma_f32_16x16x32_bf16 v[88:91], v[228:231], v[188:191], v[88:91]
	v_mfma_f32_16x16x32_bf16 v[84:87], v[220:223], v[196:199], v[84:87]
	v_mfma_f32_16x16x32_bf16 v[80:83], v[228:231], v[196:199], v[80:83]
	v_mfma_f32_16x16x32_bf16 v[76:79], v[220:223], v[204:207], v[76:79]
	v_mfma_f32_16x16x32_bf16 v[72:75], v[228:231], v[204:207], v[72:75]
	v_mfma_f32_16x16x32_bf16 v[68:71], v[220:223], v[212:215], v[68:71]
	v_mfma_f32_16x16x32_bf16 v[64:67], v[228:231], v[212:215], v[64:67]
	s_barrier
	v_readfirstlane_b32 s45, v148
	v_lshl_add_u64 v[164:165], v[236:237], 0, s[18:19]
	s_mov_b32 m0, s45
	ds_read_b128 v[188:191], v152 offset:16384
	ds_read_b128 v[192:195], v152 offset:17408
	ds_read_b128 v[196:199], v151 offset:16384
	ds_read_b128 v[200:203], v151 offset:17408
	ds_read_b128 v[204:207], v150 offset:16384
	ds_read_b128 v[208:211], v150 offset:17408
	ds_read_b128 v[212:215], v149 offset:16384
	ds_read_b128 v[232:235], v149 offset:17408
	global_load_lds_dwordx4 v[164:165], off
	v_add_u32_e32 v164, 0x2000, v148
	v_lshl_add_u64 v[166:167], v[238:239], 0, s[18:19]
	v_readfirstlane_b32 s45, v164
	s_mov_b32 m0, s45
	s_nop 0
	global_load_lds_dwordx4 v[166:167], off
	s_barrier
	s_waitcnt lgkmcnt(0)
	s_waitcnt lgkmcnt(0)
	v_mfma_f32_16x16x32_bf16 v[60:63], v[172:175], v[188:191], v[60:63]
	v_mfma_f32_16x16x32_bf16 v[56:59], v[180:183], v[188:191], v[56:59]
	v_mfma_f32_16x16x32_bf16 v[52:55], v[172:175], v[196:199], v[52:55]
	v_mfma_f32_16x16x32_bf16 v[48:51], v[180:183], v[196:199], v[48:51]
	v_mfma_f32_16x16x32_bf16 v[44:47], v[172:175], v[204:207], v[44:47]
	v_mfma_f32_16x16x32_bf16 v[40:43], v[180:183], v[204:207], v[40:43]
	v_mfma_f32_16x16x32_bf16 v[36:39], v[172:175], v[212:215], v[36:39]
	v_mfma_f32_16x16x32_bf16 v[32:35], v[180:183], v[212:215], v[32:35]
	v_mfma_f32_16x16x32_bf16 v[60:63], v[176:179], v[192:195], v[60:63]
	v_mfma_f32_16x16x32_bf16 v[56:59], v[184:187], v[192:195], v[56:59]
	v_mfma_f32_16x16x32_bf16 v[52:55], v[176:179], v[200:203], v[52:55]
	v_mfma_f32_16x16x32_bf16 v[48:51], v[184:187], v[200:203], v[48:51]
	v_mfma_f32_16x16x32_bf16 v[44:47], v[176:179], v[208:211], v[44:47]
	v_mfma_f32_16x16x32_bf16 v[40:43], v[184:187], v[208:211], v[40:43]
	v_mfma_f32_16x16x32_bf16 v[36:39], v[176:179], v[232:235], v[36:39]
	v_mfma_f32_16x16x32_bf16 v[32:35], v[184:187], v[232:235], v[32:35]
	s_barrier
; #define STAGE(P, BASE, LD, br, kt) do { const char* _g = (const char*)((BASE) + (size_t)(br) * (LD) + (size_t)(kt) * 64); \
;     for (int _i = 0; _i < 2; ++_i) { int _b = tidx * 16 + _i * 8192; int _r, _c; stage_rc(_b, _r, _c); \
;       __builtin_amdgcn_global_load_lds((const unsigned*)(_g + (unsigned)((_r * (LD) + _c) * 2)), (unsigned*)((char*)(P) + _b), 16, 0, 0); } } while (0)
; #define LDA(dst, b, h) for (int m = 0; m < 4; ++m) for (int k = 0; k < 2; ++k) \
;     dst[m][k] = *reinterpret_cast<const bf16x8*>((char*)SA(b, h) + lds_byte(wr * 64 + m * 16 + fr, k * 32 + fq * 8))
; #define LDB(dst, b, h) for (int n = 0; n < 2; ++n) for (int k = 0; k < 2; ++k) \
;     dst[n][k] = *reinterpret_cast<const bf16x8*>((char*)SB(b, h) + lds_byte(wc * 32 + n * 16 + fr, k * 32 + fq * 8))
; #define MMA(ai, bj, At_, Bt_) do { __builtin_amdgcn_s_setprio(1); \
;     for (int k = 0; k < 2; ++k) for (int m = 0; m < 4; ++m) for (int n = 0; n < 2; ++n) \
;       acc[ai][bj][m][n] = __builtin_amdgcn_mfma_f32_16x16x32_bf16(At_[m][k], Bt_[n][k], acc[ai][bj][m][n], 0, 0, 0); \
;     __builtin_amdgcn_s_setprio(0); } while (0)
; #define WAIT_V(n) asm volatile("s_waitcnt vmcnt(" #n ")" ::: "memory")
; #define WAIT_L(n) asm volatile("s_waitcnt lgkmcnt(" #n ")" ::: "memory")
; #define BAR __builtin_amdgcn_s_barrier()
; #define SCHED __builtin_amdgcn_sched_barrier(0)
; template <int EPI, int lda, int ldb, int N, int K>
; __device__ __forceinline__ void gemm_phase(const u16* __restrict__ A, const u16* __restrict__ Bt, const GemmEpi ep, int wv) {
;     ...
;       STAGE(SB(0, 1), Bt, ldb, bcol + HALF, t + 2);
;       WAIT_V(6); BAR; MMA(1, 1, At, B1); BAR;
;       LDB(B0, 1, 0); SCHED; LDA(At, 1, 0); STAGE(SA(0, 1), Ab, lda, brow + HALF, t + 2);
;       WAIT_L(8); BAR; WAIT_L(0); MMA(0, 0, At, B0); BAR; SCHED;
;       LDB(B1, 1, 1); STAGE(SB(1, 0), Bt, ldb, bcol, t + 3);
;       BAR; WAIT_L(0); MMA(0, 1, At, B1); BAR;
;       LDA(At, 1, 1); STAGE(SA(1, 0), Ab, lda, brow, t + 3);
	v_add_u32_e32 v165, s55, v153
	v_lshl_add_u64 v[166:167], v[240:241], 0, s[20:21]
	v_readfirstlane_b32 s45, v165
	s_mov_b32 m0, s45
	v_lshl_add_u64 v[172:173], v[242:243], 0, s[20:21]
	global_load_lds_dwordx4 v[166:167], off
	v_add_u32_e32 v166, 0x2000, v165
	s_nop 0
	v_readfirstlane_b32 s45, v166
	s_mov_b32 m0, s45
	s_nop 0
	global_load_lds_dwordx4 v[172:173], off
	s_waitcnt vmcnt(6)
	s_barrier
	v_mfma_f32_16x16x32_bf16 v[28:31], v[216:219], v[188:191], v[28:31]
	v_mfma_f32_16x16x32_bf16 v[24:27], v[224:227], v[188:191], v[24:27]
	v_mfma_f32_16x16x32_bf16 v[20:23], v[216:219], v[196:199], v[20:23]
	v_mfma_f32_16x16x32_bf16 v[16:19], v[224:227], v[196:199], v[16:19]
	v_mfma_f32_16x16x32_bf16 v[12:15], v[216:219], v[204:207], v[12:15]
	v_mfma_f32_16x16x32_bf16 v[8:11], v[224:227], v[204:207], v[8:11]
	v_mfma_f32_16x16x32_bf16 v[4:7], v[216:219], v[212:215], v[4:7]
	v_mfma_f32_16x16x32_bf16 v[0:3], v[224:227], v[212:215], v[0:3]
	v_mfma_f32_16x16x32_bf16 v[28:31], v[220:223], v[192:195], v[28:31]
	v_mfma_f32_16x16x32_bf16 v[24:27], v[228:231], v[192:195], v[24:27]
	v_mfma_f32_16x16x32_bf16 v[20:23], v[220:223], v[200:203], v[20:23]
	v_mfma_f32_16x16x32_bf16 v[16:19], v[228:231], v[200:203], v[16:19]
	v_mfma_f32_16x16x32_bf16 v[12:15], v[220:223], v[208:211], v[12:15]
	v_mfma_f32_16x16x32_bf16 v[8:11], v[228:231], v[208:211], v[8:11]
	v_mfma_f32_16x16x32_bf16 v[4:7], v[220:223], v[232:235], v[4:7]
	v_mfma_f32_16x16x32_bf16 v[0:3], v[228:231], v[232:235], v[0:3]
	s_barrier
	ds_read_b128 v[172:175], v156
	ds_read_b128 v[176:179], v156 offset:1024
	ds_read_b128 v[180:183], v156 offset:2048
	ds_read_b128 v[184:187], v156 offset:3072
	v_add_u32_e32 v167, 0x4000, v148
	v_add_u32_e32 v168, 0x6000, v148
	v_readfirstlane_b32 s45, v167
	v_lshl_add_u64 v[220:221], v[236:237], 0, s[22:23]
	s_mov_b32 m0, s45
	v_readfirstlane_b32 s45, v168
	ds_read_b128 v[188:191], v152 offset:32768
	ds_read_b128 v[192:195], v152 offset:33792
	ds_read_b128 v[196:199], v151 offset:32768
	ds_read_b128 v[200:203], v151 offset:33792
	ds_read_b128 v[204:207], v150 offset:32768
	ds_read_b128 v[208:211], v150 offset:33792
	ds_read_b128 v[212:215], v149 offset:32768
	ds_read_b128 v[216:219], v149 offset:33792
	global_load_lds_dwordx4 v[220:221], off
	v_lshl_add_u64 v[220:221], v[238:239], 0, s[22:23]
	s_mov_b32 m0, s45
	s_nop 0
	global_load_lds_dwordx4 v[220:221], off
	s_waitcnt lgkmcnt(8)
	s_barrier
	s_waitcnt lgkmcnt(0)
	s_waitcnt lgkmcnt(0)
	v_mfma_f32_16x16x32_bf16 v[124:127], v[172:175], v[188:191], v[124:127]
	v_mfma_f32_16x16x32_bf16 v[120:123], v[180:183], v[188:191], v[120:123]
	v_mfma_f32_16x16x32_bf16 v[116:119], v[172:175], v[196:199], v[116:119]
	v_mfma_f32_16x16x32_bf16 v[112:115], v[180:183], v[196:199], v[112:115]
	v_mfma_f32_16x16x32_bf16 v[108:111], v[172:175], v[204:207], v[108:111]
	v_mfma_f32_16x16x32_bf16 v[104:107], v[180:183], v[204:207], v[104:107]
	v_mfma_f32_16x16x32_bf16 v[100:103], v[172:175], v[212:215], v[100:103]
	v_mfma_f32_16x16x32_bf16 v[96:99], v[180:183], v[212:215], v[96:99]
	v_mfma_f32_16x16x32_bf16 v[124:127], v[176:179], v[192:195], v[124:127]
	v_mfma_f32_16x16x32_bf16 v[120:123], v[184:187], v[192:195], v[120:123]
	v_mfma_f32_16x16x32_bf16 v[116:119], v[176:179], v[200:203], v[116:119]
	v_mfma_f32_16x16x32_bf16 v[112:115], v[184:187], v[200:203], v[112:115]
	v_mfma_f32_16x16x32_bf16 v[108:111], v[176:179], v[208:211], v[108:111]
	v_mfma_f32_16x16x32_bf16 v[104:107], v[184:187], v[208:211], v[104:107]
	v_mfma_f32_16x16x32_bf16 v[100:103], v[176:179], v[216:219], v[100:103]
	v_mfma_f32_16x16x32_bf16 v[96:99], v[184:187], v[216:219], v[96:99]
	s_barrier
	v_readfirstlane_b32 s45, v155
	v_add_u32_e32 v171, 0x2000, v155
	v_lshl_add_u64 v[244:245], v[240:241], 0, s[24:25]
	s_mov_b32 m0, s45
	v_readfirstlane_b32 s45, v171
	ds_read_b128 v[220:223], v154
	ds_read_b128 v[224:227], v154 offset:1024
	ds_read_b128 v[228:231], v154 offset:2048
	ds_read_b128 v[232:235], v154 offset:3072
	global_load_lds_dwordx4 v[244:245], off
	v_lshl_add_u64 v[244:245], v[242:243], 0, s[24:25]
	s_mov_b32 m0, s45
	s_nop 0
	global_load_lds_dwordx4 v[244:245], off
	s_barrier
	s_waitcnt lgkmcnt(0)
	s_waitcnt lgkmcnt(0)
	v_mfma_f32_16x16x32_bf16 v[92:95], v[220:223], v[188:191], v[92:95]
	v_mfma_f32_16x16x32_bf16 v[88:91], v[228:231], v[188:191], v[88:91]
	v_mfma_f32_16x16x32_bf16 v[84:87], v[220:223], v[196:199], v[84:87]
	v_mfma_f32_16x16x32_bf16 v[80:83], v[228:231], v[196:199], v[80:83]
	v_mfma_f32_16x16x32_bf16 v[76:79], v[220:223], v[204:207], v[76:79]
	v_mfma_f32_16x16x32_bf16 v[72:75], v[228:231], v[204:207], v[72:75]
	v_mfma_f32_16x16x32_bf16 v[68:71], v[220:223], v[212:215], v[68:71]
	v_mfma_f32_16x16x32_bf16 v[64:67], v[228:231], v[212:215], v[64:67]
	v_mfma_f32_16x16x32_bf16 v[92:95], v[224:227], v[192:195], v[92:95]
	v_mfma_f32_16x16x32_bf16 v[88:91], v[232:235], v[192:195], v[88:91]
	v_mfma_f32_16x16x32_bf16 v[84:87], v[224:227], v[200:203], v[84:87]
	v_mfma_f32_16x16x32_bf16 v[80:83], v[232:235], v[200:203], v[80:83]
	v_mfma_f32_16x16x32_bf16 v[76:79], v[224:227], v[208:211], v[76:79]
	v_mfma_f32_16x16x32_bf16 v[72:75], v[232:235], v[208:211], v[72:75]
	v_mfma_f32_16x16x32_bf16 v[68:71], v[224:227], v[216:219], v[68:71]
	v_mfma_f32_16x16x32_bf16 v[64:67], v[232:235], v[216:219], v[64:67]
	s_barrier
	v_readfirstlane_b32 s45, v157
	v_lshl_add_u64 v[236:237], v[236:237], 0, s[26:27]
	s_mov_b32 m0, s45
	v_readfirstlane_b32 s45, v158
	ds_read_b128 v[188:191], v152 offset:49152
	ds_read_b128 v[192:195], v152 offset:50176
	ds_read_b128 v[196:199], v151 offset:49152
	ds_read_b128 v[200:203], v151 offset:50176
	ds_read_b128 v[204:207], v150 offset:49152
	ds_read_b128 v[208:211], v150 offset:50176
	ds_read_b128 v[212:215], v149 offset:49152
	ds_read_b128 v[216:219], v149 offset:50176
	global_load_lds_dwordx4 v[236:237], off
	v_lshl_add_u64 v[236:237], v[238:239], 0, s[26:27]
	s_mov_b32 m0, s45
	s_nop 0
	global_load_lds_dwordx4 v[236:237], off
	s_barrier
; #define STAGE(P, BASE, LD, br, kt) do { const char* _g = (const char*)((BASE) + (size_t)(br) * (LD) + (size_t)(kt) * 64); \
;     for (int _i = 0; _i < 2; ++_i) { int _b = tidx * 16 + _i * 8192; int _r, _c; stage_rc(_b, _r, _c); \
;       __builtin_amdgcn_global_load_lds((const unsigned*)(_g + (unsigned)((_r * (LD) + _c) * 2)), (unsigned*)((char*)(P) + _b), 16, 0, 0); } } while (0)
; #define LDA(dst, b, h) for (int m = 0; m < 4; ++m) for (int k = 0; k < 2; ++k) \
;     dst[m][k] = *reinterpret_cast<const bf16x8*>((char*)SA(b, h) + lds_byte(wr * 64 + m * 16 + fr, k * 32 + fq * 8))
; #define LDB(dst, b, h) for (int n = 0; n < 2; ++n) for (int k = 0; k < 2; ++k) \
;     dst[n][k] = *reinterpret_cast<const bf16x8*>((char*)SB(b, h) + lds_byte(wc * 32 + n * 16 + fr, k * 32 + fq * 8))
; #define MMA(ai, bj, At_, Bt_) do { __builtin_amdgcn_s_setprio(1); \
;     for (int k = 0; k < 2; ++k) for (int m = 0; m < 4; ++m) for (int n = 0; n < 2; ++n) \
;       acc[ai][bj][m][n] = __builtin_amdgcn_mfma_f32_16x16x32_bf16(At_[m][k], Bt_[n][k], acc[ai][bj][m][n], 0, 0, 0); \
;     __builtin_amdgcn_s_setprio(0); } while (0)
; #define WAIT_V(n) asm volatile("s_waitcnt vmcnt(" #n ")" ::: "memory")
; #define WAIT_L(n) asm volatile("s_waitcnt lgkmcnt(" #n ")" ::: "memory")
; #define BAR __builtin_amdgcn_s_barrier()
; #define SCHED __builtin_amdgcn_sched_barrier(0)
; template <int EPI, int lda, int ldb, int N, int K>
; __device__ __forceinline__ void gemm_phase(const u16* __restrict__ A, const u16* __restrict__ Bt, const GemmEpi ep, int wv) {
;     ...
;       BAR; WAIT_L(0); MMA(1, 0, At, B0); BAR; SCHED;
;       STAGE(SB(1, 1), Bt, ldb, bcol + HALF, t + 3);
;       WAIT_V(6); BAR; MMA(1, 1, At, B1); BAR;
;     }
;     { LDB(B0, 0, 0); LDA(At, 0, 0); STAGE(SA(1, 1), Ab, lda, brow + HALF, nt - 1);
;       BAR; WAIT_L(0); MMA(0, 0, At, B0); BAR;
;       LDB(B1, 0, 1); BAR; WAIT_L(0); MMA(0, 1, At, B1); BAR;
	s_waitcnt lgkmcnt(0)
	s_waitcnt lgkmcnt(0)
	v_mfma_f32_16x16x32_bf16 v[60:63], v[172:175], v[188:191], v[60:63]
	v_mfma_f32_16x16x32_bf16 v[56:59], v[180:183], v[188:191], v[56:59]
	v_mfma_f32_16x16x32_bf16 v[52:55], v[172:175], v[196:199], v[52:55]
	v_mfma_f32_16x16x32_bf16 v[48:51], v[180:183], v[196:199], v[48:51]
	v_mfma_f32_16x16x32_bf16 v[44:47], v[172:175], v[204:207], v[44:47]
	v_mfma_f32_16x16x32_bf16 v[40:43], v[180:183], v[204:207], v[40:43]
	v_mfma_f32_16x16x32_bf16 v[36:39], v[172:175], v[212:215], v[36:39]
	v_mfma_f32_16x16x32_bf16 v[32:35], v[180:183], v[212:215], v[32:35]
	v_mfma_f32_16x16x32_bf16 v[60:63], v[176:179], v[192:195], v[60:63]
	v_mfma_f32_16x16x32_bf16 v[56:59], v[184:187], v[192:195], v[56:59]
	v_mfma_f32_16x16x32_bf16 v[52:55], v[176:179], v[200:203], v[52:55]
	v_mfma_f32_16x16x32_bf16 v[48:51], v[184:187], v[200:203], v[48:51]
	v_mfma_f32_16x16x32_bf16 v[44:47], v[176:179], v[208:211], v[44:47]
	v_mfma_f32_16x16x32_bf16 v[40:43], v[184:187], v[208:211], v[40:43]
	v_mfma_f32_16x16x32_bf16 v[36:39], v[176:179], v[216:219], v[36:39]
	v_mfma_f32_16x16x32_bf16 v[32:35], v[184:187], v[216:219], v[32:35]
	s_barrier
	v_readfirstlane_b32 s45, v159
	v_add_u32_e32 v171, 0x2000, v159
	v_lshl_add_u64 v[172:173], v[240:241], 0, s[34:35]
	s_mov_b32 m0, s45
	v_readfirstlane_b32 s45, v171
	global_load_lds_dwordx4 v[172:173], off
	v_lshl_add_u64 v[172:173], v[242:243], 0, s[34:35]
	s_mov_b32 m0, s45
	s_nop 0
	global_load_lds_dwordx4 v[172:173], off
	s_add_i32 s44, s44, 2
	s_add_u32 s42, s42, 0x100
	s_addc_u32 s43, s43, 0
	s_cmp_gt_u32 s44, 27
	s_waitcnt vmcnt(6)
	s_barrier
	v_mfma_f32_16x16x32_bf16 v[28:31], v[220:223], v[188:191], v[28:31]
	v_mfma_f32_16x16x32_bf16 v[24:27], v[228:231], v[188:191], v[24:27]
	v_mfma_f32_16x16x32_bf16 v[20:23], v[220:223], v[196:199], v[20:23]
	v_mfma_f32_16x16x32_bf16 v[16:19], v[228:231], v[196:199], v[16:19]
	v_mfma_f32_16x16x32_bf16 v[12:15], v[220:223], v[204:207], v[12:15]
	v_mfma_f32_16x16x32_bf16 v[8:11], v[228:231], v[204:207], v[8:11]
	v_mfma_f32_16x16x32_bf16 v[4:7], v[220:223], v[212:215], v[4:7]
	v_mfma_f32_16x16x32_bf16 v[0:3], v[228:231], v[212:215], v[0:3]
	v_mfma_f32_16x16x32_bf16 v[28:31], v[224:227], v[192:195], v[28:31]
	v_mfma_f32_16x16x32_bf16 v[24:27], v[232:235], v[192:195], v[24:27]
	v_mfma_f32_16x16x32_bf16 v[20:23], v[224:227], v[200:203], v[20:23]
	v_mfma_f32_16x16x32_bf16 v[16:19], v[232:235], v[200:203], v[16:19]
	v_mfma_f32_16x16x32_bf16 v[12:15], v[224:227], v[208:211], v[12:15]
	v_mfma_f32_16x16x32_bf16 v[8:11], v[232:235], v[208:211], v[8:11]
	v_mfma_f32_16x16x32_bf16 v[4:7], v[224:227], v[216:219], v[4:7]
	v_mfma_f32_16x16x32_bf16 v[0:3], v[232:235], v[216:219], v[0:3]
	s_barrier
	s_cbranch_scc0 .LBB0_53
	s_add_i32 s42, s38, 0x80
	s_mul_hi_i32 s43, s42, 0x1080
	s_mulk_i32 s42, 0x1080
	s_add_u32 s42, s51, s42
	s_addc_u32 s43, s52, s43
	v_lshl_add_u64 v[158:159], s[42:43], 0, v[128:129]
	v_readfirstlane_b32 s44, v169
	v_lshl_add_u64 v[158:159], v[158:159], 0, s[36:37]
	s_mov_b32 m0, s44
	ds_read_b128 v[134:137], v161
	ds_read_b128 v[138:141], v161 offset:1024
	ds_read_b128 v[172:175], v161 offset:2048
	ds_read_b128 v[176:179], v161 offset:3072
	ds_read_b128 v[180:183], v152
	ds_read_b128 v[184:187], v152 offset:1024
	ds_read_b128 v[188:191], v151
	ds_read_b128 v[192:195], v151 offset:1024
	ds_read_b128 v[196:199], v150
	ds_read_b128 v[200:203], v150 offset:1024
	ds_read_b128 v[204:207], v149
	ds_read_b128 v[208:211], v149 offset:1024
	global_load_lds_dwordx4 v[158:159], off
	v_lshl_add_u64 v[158:159], s[42:43], 0, v[132:133]
	v_readfirstlane_b32 s42, v170
	v_lshl_add_u64 v[158:159], v[158:159], 0, s[36:37]
	s_mov_b32 m0, s42
	s_nop 0
	global_load_lds_dwordx4 v[158:159], off
	s_barrier
	s_waitcnt lgkmcnt(0)
	s_waitcnt lgkmcnt(0)
	v_mfma_f32_16x16x32_bf16 v[124:127], v[134:137], v[180:183], v[124:127]
	v_mfma_f32_16x16x32_bf16 v[120:123], v[172:175], v[180:183], v[120:123]
	v_mfma_f32_16x16x32_bf16 v[116:119], v[134:137], v[188:191], v[116:119]
	v_mfma_f32_16x16x32_bf16 v[112:115], v[172:175], v[188:191], v[112:115]
	v_mfma_f32_16x16x32_bf16 v[108:111], v[134:137], v[196:199], v[108:111]
	v_mfma_f32_16x16x32_bf16 v[104:107], v[172:175], v[196:199], v[104:107]
	v_mfma_f32_16x16x32_bf16 v[100:103], v[134:137], v[204:207], v[100:103]
	v_mfma_f32_16x16x32_bf16 v[96:99], v[172:175], v[204:207], v[96:99]
	v_mfma_f32_16x16x32_bf16 v[124:127], v[138:141], v[184:187], v[124:127]
	v_mfma_f32_16x16x32_bf16 v[120:123], v[176:179], v[184:187], v[120:123]
	v_mfma_f32_16x16x32_bf16 v[116:119], v[138:141], v[192:195], v[116:119]
	v_mfma_f32_16x16x32_bf16 v[112:115], v[176:179], v[192:195], v[112:115]
	v_mfma_f32_16x16x32_bf16 v[108:111], v[138:141], v[200:203], v[108:111]
	v_mfma_f32_16x16x32_bf16 v[104:107], v[176:179], v[200:203], v[104:107]
	v_mfma_f32_16x16x32_bf16 v[100:103], v[138:141], v[208:211], v[100:103]
	v_mfma_f32_16x16x32_bf16 v[96:99], v[176:179], v[208:211], v[96:99]
	s_barrier
	ds_read_b128 v[212:215], v160
	ds_read_b128 v[216:219], v160 offset:1024
	ds_read_b128 v[220:223], v160 offset:2048
	ds_read_b128 v[158:161], v160 offset:3072
	s_barrier
; #define LDA(dst, b, h) for (int m = 0; m < 4; ++m) for (int k = 0; k < 2; ++k) \
;     dst[m][k] = *reinterpret_cast<const bf16x8*>((char*)SA(b, h) + lds_byte(wr * 64 + m * 16 + fr, k * 32 + fq * 8))
; #define LDB(dst, b, h) for (int n = 0; n < 2; ++n) for (int k = 0; k < 2; ++k) \
;     dst[n][k] = *reinterpret_cast<const bf16x8*>((char*)SB(b, h) + lds_byte(wc * 32 + n * 16 + fr, k * 32 + fq * 8))
; #define MMA(ai, bj, At_, Bt_) do { __builtin_amdgcn_s_setprio(1); \
;     for (int k = 0; k < 2; ++k) for (int m = 0; m < 4; ++m) for (int n = 0; n < 2; ++n) \
;       acc[ai][bj][m][n] = __builtin_amdgcn_mfma_f32_16x16x32_bf16(At_[m][k], Bt_[n][k], acc[ai][bj][m][n], 0, 0, 0); \
;     __builtin_amdgcn_s_setprio(0); } while (0)
; #define WAIT_V(n) asm volatile("s_waitcnt vmcnt(" #n ")" ::: "memory")
; #define WAIT_L(n) asm volatile("s_waitcnt lgkmcnt(" #n ")" ::: "memory")
; #define BAR __builtin_amdgcn_s_barrier()
; template <int EPI, int lda, int ldb, int N, int K>
; __device__ __forceinline__ void gemm_phase(const u16* __restrict__ A, const u16* __restrict__ Bt, const GemmEpi ep, int wv) {
;     ...
;       LDB(B1, 0, 1); BAR; WAIT_L(0); MMA(0, 1, At, B1); BAR;
;       LDA(At, 0, 1); WAIT_V(4); BAR; WAIT_L(0); MMA(1, 0, At, B0); MMA(1, 1, At, B1); BAR; }
;     { LDB(B0, 1, 0); LDA(At, 1, 0); WAIT_V(2); BAR; WAIT_L(0); MMA(0, 0, At, B0); BAR;
	s_waitcnt lgkmcnt(0)
	s_waitcnt lgkmcnt(0)
	v_mfma_f32_16x16x32_bf16 v[92:95], v[212:215], v[180:183], v[92:95]
	v_mfma_f32_16x16x32_bf16 v[88:91], v[220:223], v[180:183], v[88:91]
	v_mfma_f32_16x16x32_bf16 v[76:79], v[212:215], v[196:199], v[76:79]
	v_mfma_f32_16x16x32_bf16 v[72:75], v[220:223], v[196:199], v[72:75]
	v_mfma_f32_16x16x32_bf16 v[84:87], v[212:215], v[188:191], v[84:87]
	v_mfma_f32_16x16x32_bf16 v[80:83], v[220:223], v[188:191], v[80:83]
	v_mfma_f32_16x16x32_bf16 v[68:71], v[212:215], v[204:207], v[68:71]
	v_mfma_f32_16x16x32_bf16 v[64:67], v[220:223], v[204:207], v[64:67]
	v_mfma_f32_16x16x32_bf16 v[92:95], v[216:219], v[184:187], v[92:95]
	v_mfma_f32_16x16x32_bf16 v[88:91], v[158:161], v[184:187], v[88:91]
	v_mfma_f32_16x16x32_bf16 v[76:79], v[216:219], v[200:203], v[76:79]
	v_mfma_f32_16x16x32_bf16 v[72:75], v[158:161], v[200:203], v[72:75]
	v_mfma_f32_16x16x32_bf16 v[180:183], v[216:219], v[192:195], v[84:87]
	v_mfma_f32_16x16x32_bf16 v[184:187], v[158:161], v[192:195], v[80:83]
	v_mfma_f32_16x16x32_bf16 v[188:191], v[216:219], v[208:211], v[68:71]
	v_mfma_f32_16x16x32_bf16 v[192:195], v[158:161], v[208:211], v[64:67]
	s_barrier
	s_nop 0
	ds_read_b128 v[64:67], v152 offset:16384
	ds_read_b128 v[68:71], v152 offset:17408
	ds_read_b128 v[80:83], v151 offset:16384
	ds_read_b128 v[84:87], v151 offset:17408
	ds_read_b128 v[196:199], v150 offset:16384
	ds_read_b128 v[200:203], v150 offset:17408
	ds_read_b128 v[204:207], v149 offset:16384
	ds_read_b128 v[208:211], v149 offset:17408
	s_waitcnt vmcnt(4)
	s_barrier
	s_waitcnt lgkmcnt(0)
	s_waitcnt lgkmcnt(0)
	v_mfma_f32_16x16x32_bf16 v[60:63], v[134:137], v[64:67], v[60:63]
	v_mfma_f32_16x16x32_bf16 v[56:59], v[172:175], v[64:67], v[56:59]
	v_mfma_f32_16x16x32_bf16 v[52:55], v[134:137], v[80:83], v[52:55]
	v_mfma_f32_16x16x32_bf16 v[48:51], v[172:175], v[80:83], v[48:51]
	v_mfma_f32_16x16x32_bf16 v[44:47], v[134:137], v[196:199], v[44:47]
	v_mfma_f32_16x16x32_bf16 v[40:43], v[172:175], v[196:199], v[40:43]
	v_mfma_f32_16x16x32_bf16 v[36:39], v[134:137], v[204:207], v[36:39]
	v_mfma_f32_16x16x32_bf16 v[32:35], v[172:175], v[204:207], v[32:35]
	v_mfma_f32_16x16x32_bf16 v[60:63], v[138:141], v[68:71], v[60:63]
	v_mfma_f32_16x16x32_bf16 v[56:59], v[176:179], v[68:71], v[56:59]
	v_mfma_f32_16x16x32_bf16 v[52:55], v[138:141], v[84:87], v[52:55]
	v_mfma_f32_16x16x32_bf16 v[48:51], v[176:179], v[84:87], v[48:51]
	v_mfma_f32_16x16x32_bf16 v[44:47], v[138:141], v[200:203], v[44:47]
	v_mfma_f32_16x16x32_bf16 v[40:43], v[176:179], v[200:203], v[40:43]
	v_mfma_f32_16x16x32_bf16 v[36:39], v[138:141], v[208:211], v[36:39]
	v_mfma_f32_16x16x32_bf16 v[32:35], v[176:179], v[208:211], v[32:35]
	v_mfma_f32_16x16x32_bf16 v[28:31], v[212:215], v[64:67], v[28:31]
	v_mfma_f32_16x16x32_bf16 v[24:27], v[220:223], v[64:67], v[24:27]
	v_mfma_f32_16x16x32_bf16 v[12:15], v[212:215], v[196:199], v[12:15]
	v_mfma_f32_16x16x32_bf16 v[8:11], v[220:223], v[196:199], v[8:11]
	v_mfma_f32_16x16x32_bf16 v[20:23], v[212:215], v[80:83], v[20:23]
	v_mfma_f32_16x16x32_bf16 v[16:19], v[220:223], v[80:83], v[16:19]
	v_mfma_f32_16x16x32_bf16 v[4:7], v[212:215], v[204:207], v[4:7]
	v_mfma_f32_16x16x32_bf16 v[0:3], v[220:223], v[204:207], v[0:3]
	v_mfma_f32_16x16x32_bf16 v[28:31], v[216:219], v[68:71], v[28:31]
	v_mfma_f32_16x16x32_bf16 v[24:27], v[158:161], v[68:71], v[24:27]
	v_mfma_f32_16x16x32_bf16 v[12:15], v[216:219], v[200:203], v[12:15]
	v_mfma_f32_16x16x32_bf16 v[8:11], v[158:161], v[200:203], v[8:11]
	v_mfma_f32_16x16x32_bf16 v[134:137], v[216:219], v[84:87], v[20:23]
	v_mfma_f32_16x16x32_bf16 v[138:141], v[158:161], v[84:87], v[16:19]
	v_mfma_f32_16x16x32_bf16 v[170:173], v[216:219], v[208:211], v[4:7]
	v_mfma_f32_16x16x32_bf16 v[158:161], v[158:161], v[208:211], v[0:3]
	s_barrier
	s_nop 0
	ds_read_b128 v[0:3], v156
	ds_read_b128 v[4:7], v156 offset:1024
	ds_read_b128 v[16:19], v156 offset:2048
	ds_read_b128 v[174:177], v156 offset:3072
	ds_read_b128 v[20:23], v152 offset:32768
	ds_read_b128 v[196:199], v152 offset:33792
	ds_read_b128 v[200:203], v151 offset:32768
	ds_read_b128 v[204:207], v151 offset:33792
	ds_read_b128 v[208:211], v150 offset:32768
	ds_read_b128 v[212:215], v150 offset:33792
	ds_read_b128 v[216:219], v149 offset:32768
	ds_read_b128 v[220:223], v149 offset:33792
	s_waitcnt vmcnt(2)
	s_barrier
; #define LDA(dst, b, h) for (int m = 0; m < 4; ++m) for (int k = 0; k < 2; ++k) \
;     dst[m][k] = *reinterpret_cast<const bf16x8*>((char*)SA(b, h) + lds_byte(wr * 64 + m * 16 + fr, k * 32 + fq * 8))
; #define LDB(dst, b, h) for (int n = 0; n < 2; ++n) for (int k = 0; k < 2; ++k) \
;     dst[n][k] = *reinterpret_cast<const bf16x8*>((char*)SB(b, h) + lds_byte(wc * 32 + n * 16 + fr, k * 32 + fq * 8))
; #define MMA(ai, bj, At_, Bt_) do { __builtin_amdgcn_s_setprio(1); \
;     for (int k = 0; k < 2; ++k) for (int m = 0; m < 4; ++m) for (int n = 0; n < 2; ++n) \
;       acc[ai][bj][m][n] = __builtin_amdgcn_mfma_f32_16x16x32_bf16(At_[m][k], Bt_[n][k], acc[ai][bj][m][n], 0, 0, 0); \
;     __builtin_amdgcn_s_setprio(0); } while (0)
; #define WAIT_V(n) asm volatile("s_waitcnt vmcnt(" #n ")" ::: "memory")
; #define WAIT_L(n) asm volatile("s_waitcnt lgkmcnt(" #n ")" ::: "memory")
; #define BAR __builtin_amdgcn_s_barrier()
; template <int EPI, int lda, int ldb, int N, int K>
; __device__ __forceinline__ void gemm_phase(const u16* __restrict__ A, const u16* __restrict__ Bt, const GemmEpi ep, int wv) {
;     ...
;     { LDB(B0, 1, 0); LDA(At, 1, 0); WAIT_V(2); BAR; WAIT_L(0); MMA(0, 0, At, B0); BAR;
;       LDB(B1, 1, 1); WAIT_V(0); BAR; WAIT_L(0); MMA(0, 1, At, B1); BAR;
;       LDA(At, 1, 1); BAR; WAIT_L(0); MMA(1, 0, At, B0); MMA(1, 1, At, B1); BAR; }
;     if (wr == 0) BAR;
	s_waitcnt lgkmcnt(0)
	s_waitcnt lgkmcnt(0)
	v_mfma_f32_16x16x32_bf16 v[64:67], v[0:3], v[20:23], v[124:127]
	v_mfma_f32_16x16x32_bf16 v[68:71], v[16:19], v[20:23], v[120:123]
	v_mfma_f32_16x16x32_bf16 v[80:83], v[0:3], v[200:203], v[116:119]
	v_mfma_f32_16x16x32_bf16 v[84:87], v[16:19], v[200:203], v[112:115]
	v_mfma_f32_16x16x32_bf16 v[108:111], v[0:3], v[208:211], v[108:111]
	v_mfma_f32_16x16x32_bf16 v[104:107], v[16:19], v[208:211], v[104:107]
	v_mfma_f32_16x16x32_bf16 v[120:123], v[0:3], v[216:219], v[100:103]
	v_mfma_f32_16x16x32_bf16 v[124:127], v[16:19], v[216:219], v[96:99]
	v_mfma_f32_16x16x32_bf16 v[116:119], v[4:7], v[196:199], v[64:67]
	v_mfma_f32_16x16x32_bf16 v[112:115], v[174:177], v[196:199], v[68:71]
	v_mfma_f32_16x16x32_bf16 v[100:103], v[4:7], v[204:207], v[80:83]
	v_mfma_f32_16x16x32_bf16 v[96:99], v[174:177], v[204:207], v[84:87]
	v_mfma_f32_16x16x32_bf16 v[84:87], v[4:7], v[212:215], v[108:111]
	v_mfma_f32_16x16x32_bf16 v[80:83], v[174:177], v[212:215], v[104:107]
	v_mfma_f32_16x16x32_bf16 v[68:71], v[4:7], v[220:223], v[120:123]
	v_mfma_f32_16x16x32_bf16 v[64:67], v[174:177], v[220:223], v[124:127]
	s_barrier
	ds_read_b128 v[224:227], v154
	ds_read_b128 v[228:231], v154 offset:1024
	ds_read_b128 v[232:235], v154 offset:2048
	ds_read_b128 v[154:157], v154 offset:3072
	s_waitcnt vmcnt(0)
	s_barrier
	s_waitcnt lgkmcnt(0)
	s_waitcnt lgkmcnt(0)
	v_mfma_f32_16x16x32_bf16 v[92:95], v[224:227], v[20:23], v[92:95]
	v_mfma_f32_16x16x32_bf16 v[20:23], v[232:235], v[20:23], v[88:91]
	v_mfma_f32_16x16x32_bf16 v[88:91], v[224:227], v[200:203], v[180:183]
	v_mfma_f32_16x16x32_bf16 v[104:107], v[232:235], v[200:203], v[184:187]
	v_mfma_f32_16x16x32_bf16 v[76:79], v[224:227], v[208:211], v[76:79]
	v_mfma_f32_16x16x32_bf16 v[72:75], v[232:235], v[208:211], v[72:75]
	v_mfma_f32_16x16x32_bf16 v[178:181], v[224:227], v[216:219], v[188:191]
	v_mfma_f32_16x16x32_bf16 v[182:185], v[232:235], v[216:219], v[192:195]
	v_mfma_f32_16x16x32_bf16 v[124:127], v[228:231], v[196:199], v[92:95]
	v_mfma_f32_16x16x32_bf16 v[120:123], v[154:157], v[196:199], v[20:23]
	v_mfma_f32_16x16x32_bf16 v[108:111], v[228:231], v[204:207], v[88:91]
	v_mfma_f32_16x16x32_bf16 v[104:107], v[154:157], v[204:207], v[104:107]
	v_mfma_f32_16x16x32_bf16 v[92:95], v[228:231], v[212:215], v[76:79]
	v_mfma_f32_16x16x32_bf16 v[88:91], v[154:157], v[212:215], v[72:75]
	v_mfma_f32_16x16x32_bf16 v[76:79], v[228:231], v[220:223], v[178:181]
	v_mfma_f32_16x16x32_bf16 v[72:75], v[154:157], v[220:223], v[182:185]
	s_barrier
	ds_read_b128 v[178:181], v152 offset:49152
	ds_read_b128 v[182:185], v152 offset:50176
	ds_read_b128 v[186:189], v151 offset:49152
	ds_read_b128 v[190:193], v151 offset:50176
	ds_read_b128 v[194:197], v150 offset:49152
	ds_read_b128 v[150:153], v150 offset:50176
	ds_read_b128 v[198:201], v149 offset:49152
	ds_read_b128 v[202:205], v149 offset:50176
	s_barrier
	s_waitcnt lgkmcnt(0)
	s_waitcnt lgkmcnt(0)
	v_mfma_f32_16x16x32_bf16 v[20:23], v[0:3], v[178:181], v[60:63]
	v_mfma_f32_16x16x32_bf16 v[56:59], v[16:19], v[178:181], v[56:59]
	v_mfma_f32_16x16x32_bf16 v[60:63], v[0:3], v[186:189], v[52:55]
	v_mfma_f32_16x16x32_bf16 v[206:209], v[16:19], v[186:189], v[48:51]
	v_mfma_f32_16x16x32_bf16 v[44:47], v[0:3], v[194:197], v[44:47]
	v_mfma_f32_16x16x32_bf16 v[40:43], v[16:19], v[194:197], v[40:43]
	v_mfma_f32_16x16x32_bf16 v[0:3], v[0:3], v[198:201], v[36:39]
	v_mfma_f32_16x16x32_bf16 v[210:213], v[16:19], v[198:201], v[32:35]
	v_mfma_f32_16x16x32_bf16 v[52:55], v[4:7], v[182:185], v[20:23]
	v_mfma_f32_16x16x32_bf16 v[48:51], v[174:177], v[182:185], v[56:59]
	v_mfma_f32_16x16x32_bf16 v[36:39], v[4:7], v[190:193], v[60:63]
	v_mfma_f32_16x16x32_bf16 v[32:35], v[174:177], v[190:193], v[206:209]
	v_mfma_f32_16x16x32_bf16 v[20:23], v[4:7], v[150:153], v[44:47]
	v_mfma_f32_16x16x32_bf16 v[16:19], v[174:177], v[150:153], v[40:43]
	v_mfma_f32_16x16x32_bf16 v[4:7], v[4:7], v[202:205], v[0:3]
	v_mfma_f32_16x16x32_bf16 v[0:3], v[174:177], v[202:205], v[210:213]
	v_mfma_f32_16x16x32_bf16 v[28:31], v[224:227], v[178:181], v[28:31]
	v_mfma_f32_16x16x32_bf16 v[24:27], v[232:235], v[178:181], v[24:27]
	v_mfma_f32_16x16x32_bf16 v[40:43], v[224:227], v[186:189], v[134:137]
	v_mfma_f32_16x16x32_bf16 v[134:137], v[232:235], v[186:189], v[138:141]
	v_mfma_f32_16x16x32_bf16 v[12:15], v[224:227], v[194:197], v[12:15]
	v_mfma_f32_16x16x32_bf16 v[8:11], v[232:235], v[194:197], v[8:11]
	v_mfma_f32_16x16x32_bf16 v[138:141], v[224:227], v[198:201], v[170:173]
	v_mfma_f32_16x16x32_bf16 v[158:161], v[232:235], v[198:201], v[158:161]
	v_mfma_f32_16x16x32_bf16 v[60:63], v[228:231], v[182:185], v[28:31]
	v_mfma_f32_16x16x32_bf16 v[56:59], v[154:157], v[182:185], v[24:27]
	v_mfma_f32_16x16x32_bf16 v[44:47], v[228:231], v[190:193], v[40:43]
	v_mfma_f32_16x16x32_bf16 v[40:43], v[154:157], v[190:193], v[134:137]
	v_mfma_f32_16x16x32_bf16 v[28:31], v[228:231], v[150:153], v[12:15]
	v_mfma_f32_16x16x32_bf16 v[24:27], v[154:157], v[150:153], v[8:11]
	v_mfma_f32_16x16x32_bf16 v[12:15], v[228:231], v[202:205], v[138:141]
	v_mfma_f32_16x16x32_bf16 v[8:11], v[154:157], v[202:205], v[158:161]
	v_cmp_gt_u32_e32 vcc, s56, v130
	s_barrier
	s_and_saveexec_b64 s[42:43], vcc
	s_cbranch_execz .LBB0_56
	s_barrier

; #define STAGE(P, BASE, LD, br, kt) do { const char* _g = (const char*)((BASE) + (size_t)(br) * (LD) + (size_t)(kt) * 64); \
;     for (int _i = 0; _i < 2; ++_i) { int _b = tidx * 16 + _i * 8192; int _r, _c; stage_rc(_b, _r, _c); \
;       __builtin_amdgcn_global_load_lds((const unsigned*)(_g + (unsigned)((_r * (LD) + _c) * 2)), (unsigned*)((char*)(P) + _b), 16, 0, 0); } } while (0)
; #define LDA(dst, b, h) for (int m = 0; m < 4; ++m) for (int k = 0; k < 2; ++k) \
;     dst[m][k] = *reinterpret_cast<const bf16x8*>((char*)SA(b, h) + lds_byte(wr * 64 + m * 16 + fr, k * 32 + fq * 8))
; #define LDB(dst, b, h) for (int n = 0; n < 2; ++n) for (int k = 0; k < 2; ++k) \
;     dst[n][k] = *reinterpret_cast<const bf16x8*>((char*)SB(b, h) + lds_byte(wc * 32 + n * 16 + fr, k * 32 + fq * 8))
; #define MMA(ai, bj, At_, Bt_) do { __builtin_amdgcn_s_setprio(1); \
;     for (int k = 0; k < 2; ++k) for (int m = 0; m < 4; ++m) for (int n = 0; n < 2; ++n) \
;       acc[ai][bj][m][n] = __builtin_amdgcn_mfma_f32_16x16x32_bf16(At_[m][k], Bt_[n][k], acc[ai][bj][m][n], 0, 0, 0); \
;     __builtin_amdgcn_s_setprio(0); } while (0)
; #define WAIT_L(n) asm volatile("s_waitcnt lgkmcnt(" #n ")" ::: "memory")
; #define BAR __builtin_amdgcn_s_barrier()
; #define SCHED __builtin_amdgcn_sched_barrier(0)
; template <int EPI, int lda, int ldb, int N, int K>
; __device__ __forceinline__ void gemm_phase(const u16* __restrict__ A, const u16* __restrict__ Bt, const GemmEpi ep, int wv) {
;     ...
;     for (int t = 0; t < nt - 2; t += 2) {
;       LDB(B0, 0, 0); SCHED; LDA(At, 0, 0); STAGE(SA(1, 1), Ab, lda, brow + HALF, t + 1);
;       WAIT_L(8); BAR; WAIT_L(0); MMA(0, 0, At, B0); BAR; SCHED;
;       LDB(B1, 0, 1); STAGE(SB(0, 0), Bt, ldb, bcol, t + 2);
;       BAR; WAIT_L(0); MMA(0, 1, At, B1); BAR;
;       LDA(At, 0, 1); STAGE(SA(0, 0), Ab, lda, brow, t + 2);
;       BAR; WAIT_L(0); MMA(1, 0, At, B0); BAR; SCHED;
.LBB0_224:
	ds_read_b128 v[168:171], v164
	ds_read_b128 v[174:177], v164 offset:1024
	ds_read_b128 v[178:181], v164 offset:2048
	ds_read_b128 v[182:185], v164 offset:3072
	v_add_u32_e32 v172, 0xc000, v147
	v_lshl_add_u64 v[238:239], v[136:137], 0, s[44:45]
	v_readfirstlane_b32 s66, v172
	v_add_u32_e32 v173, 0xe000, v147
	v_lshl_add_u64 v[166:167], v[238:239], 0, s[18:19]
	s_mov_b32 m0, s66
	v_lshl_add_u64 v[240:241], v[134:135], 0, s[44:45]
	v_readfirstlane_b32 s66, v173
	ds_read_b128 v[186:189], v155
	ds_read_b128 v[190:193], v155 offset:1024
	ds_read_b128 v[194:197], v154
	ds_read_b128 v[198:201], v154 offset:1024
	ds_read_b128 v[202:205], v153
	ds_read_b128 v[206:209], v153 offset:1024
	ds_read_b128 v[210:213], v152
	ds_read_b128 v[214:217], v152 offset:1024
	global_load_lds_dwordx4 v[166:167], off
	v_lshl_add_u64 v[166:167], v[240:241], 0, s[18:19]
	s_mov_b32 m0, s66
	s_nop 0
	global_load_lds_dwordx4 v[166:167], off
	s_waitcnt lgkmcnt(8)
	s_barrier
	s_waitcnt lgkmcnt(0)
	s_waitcnt lgkmcnt(0)
	v_mfma_f32_16x16x32_bf16 v[124:127], v[168:171], v[186:189], v[124:127]
	v_mfma_f32_16x16x32_bf16 v[120:123], v[178:181], v[186:189], v[120:123]
	v_mfma_f32_16x16x32_bf16 v[116:119], v[168:171], v[194:197], v[116:119]
	v_mfma_f32_16x16x32_bf16 v[112:115], v[178:181], v[194:197], v[112:115]
	v_mfma_f32_16x16x32_bf16 v[108:111], v[168:171], v[202:205], v[108:111]
	v_mfma_f32_16x16x32_bf16 v[104:107], v[178:181], v[202:205], v[104:107]
	v_mfma_f32_16x16x32_bf16 v[100:103], v[168:171], v[210:213], v[100:103]
	v_mfma_f32_16x16x32_bf16 v[96:99], v[178:181], v[210:213], v[96:99]
	v_mfma_f32_16x16x32_bf16 v[124:127], v[174:177], v[190:193], v[124:127]
	v_mfma_f32_16x16x32_bf16 v[120:123], v[182:185], v[190:193], v[120:123]
	v_mfma_f32_16x16x32_bf16 v[116:119], v[174:177], v[198:201], v[116:119]
	v_mfma_f32_16x16x32_bf16 v[112:115], v[182:185], v[198:201], v[112:115]
	v_mfma_f32_16x16x32_bf16 v[108:111], v[174:177], v[206:209], v[108:111]
	v_mfma_f32_16x16x32_bf16 v[104:107], v[182:185], v[206:209], v[104:107]
	v_mfma_f32_16x16x32_bf16 v[100:103], v[174:177], v[214:217], v[100:103]
	v_mfma_f32_16x16x32_bf16 v[96:99], v[182:185], v[214:217], v[96:99]
	s_barrier
	v_add_u32_e32 v165, s55, v156
	v_lshl_add_u64 v[242:243], v[144:145], 0, s[44:45]
	v_readfirstlane_b32 s66, v165
	v_lshl_add_u64 v[166:167], v[242:243], 0, s[20:21]
	s_mov_b32 m0, s66
	ds_read_b128 v[218:221], v163
	ds_read_b128 v[222:225], v163 offset:1024
	ds_read_b128 v[226:229], v163 offset:2048
	ds_read_b128 v[230:233], v163 offset:3072
	global_load_lds_dwordx4 v[166:167], off
	v_add_u32_e32 v166, 0x2000, v165
	v_lshl_add_u64 v[244:245], v[142:143], 0, s[44:45]
	v_readfirstlane_b32 s66, v166
	v_lshl_add_u64 v[234:235], v[244:245], 0, s[20:21]
	s_mov_b32 m0, s66
	s_nop 0
	global_load_lds_dwordx4 v[234:235], off
	s_barrier
	s_waitcnt lgkmcnt(0)
	s_waitcnt lgkmcnt(0)
	v_mfma_f32_16x16x32_bf16 v[92:95], v[218:221], v[186:189], v[92:95]
	v_mfma_f32_16x16x32_bf16 v[88:91], v[226:229], v[186:189], v[88:91]
	v_mfma_f32_16x16x32_bf16 v[84:87], v[218:221], v[194:197], v[84:87]
	v_mfma_f32_16x16x32_bf16 v[80:83], v[226:229], v[194:197], v[80:83]
	v_mfma_f32_16x16x32_bf16 v[76:79], v[218:221], v[202:205], v[76:79]
	v_mfma_f32_16x16x32_bf16 v[72:75], v[226:229], v[202:205], v[72:75]
	v_mfma_f32_16x16x32_bf16 v[68:71], v[218:221], v[210:213], v[68:71]
	v_mfma_f32_16x16x32_bf16 v[64:67], v[226:229], v[210:213], v[64:67]
	v_mfma_f32_16x16x32_bf16 v[92:95], v[222:225], v[190:193], v[92:95]
	v_mfma_f32_16x16x32_bf16 v[88:91], v[230:233], v[190:193], v[88:91]
	v_mfma_f32_16x16x32_bf16 v[84:87], v[222:225], v[198:201], v[84:87]
	v_mfma_f32_16x16x32_bf16 v[80:83], v[230:233], v[198:201], v[80:83]
	v_mfma_f32_16x16x32_bf16 v[76:79], v[222:225], v[206:209], v[76:79]
	v_mfma_f32_16x16x32_bf16 v[72:75], v[230:233], v[206:209], v[72:75]
	v_mfma_f32_16x16x32_bf16 v[68:71], v[222:225], v[214:217], v[68:71]
	v_mfma_f32_16x16x32_bf16 v[64:67], v[230:233], v[214:217], v[64:67]
	s_barrier
	v_readfirstlane_b32 s66, v147
	v_add_u32_e32 v167, 0x2000, v147
	v_lshl_add_u64 v[234:235], v[238:239], 0, s[22:23]
	s_mov_b32 m0, s66
	v_readfirstlane_b32 s66, v167
	ds_read_b128 v[186:189], v155 offset:16384
	ds_read_b128 v[190:193], v155 offset:17408
	ds_read_b128 v[194:197], v154 offset:16384
	ds_read_b128 v[198:201], v154 offset:17408
	ds_read_b128 v[202:205], v153 offset:16384
	ds_read_b128 v[206:209], v153 offset:17408
	ds_read_b128 v[210:213], v152 offset:16384
	ds_read_b128 v[214:217], v152 offset:17408
	global_load_lds_dwordx4 v[234:235], off
	v_lshl_add_u64 v[234:235], v[240:241], 0, s[22:23]
	s_mov_b32 m0, s66
	s_nop 0
	global_load_lds_dwordx4 v[234:235], off
	s_barrier
	s_waitcnt lgkmcnt(0)
	s_waitcnt lgkmcnt(0)
	v_mfma_f32_16x16x32_bf16 v[60:63], v[168:171], v[186:189], v[60:63]
	v_mfma_f32_16x16x32_bf16 v[56:59], v[178:181], v[186:189], v[56:59]
	v_mfma_f32_16x16x32_bf16 v[52:55], v[168:171], v[194:197], v[52:55]
	v_mfma_f32_16x16x32_bf16 v[48:51], v[178:181], v[194:197], v[48:51]
	v_mfma_f32_16x16x32_bf16 v[44:47], v[168:171], v[202:205], v[44:47]
	v_mfma_f32_16x16x32_bf16 v[40:43], v[178:181], v[202:205], v[40:43]
	v_mfma_f32_16x16x32_bf16 v[36:39], v[168:171], v[210:213], v[36:39]
	v_mfma_f32_16x16x32_bf16 v[32:35], v[178:181], v[210:213], v[32:35]
	v_mfma_f32_16x16x32_bf16 v[60:63], v[174:177], v[190:193], v[60:63]
	v_mfma_f32_16x16x32_bf16 v[56:59], v[182:185], v[190:193], v[56:59]
	v_mfma_f32_16x16x32_bf16 v[52:55], v[174:177], v[198:201], v[52:55]
	v_mfma_f32_16x16x32_bf16 v[48:51], v[182:185], v[198:201], v[48:51]
	v_mfma_f32_16x16x32_bf16 v[44:47], v[174:177], v[206:209], v[44:47]
	v_mfma_f32_16x16x32_bf16 v[40:43], v[182:185], v[206:209], v[40:43]
	v_mfma_f32_16x16x32_bf16 v[36:39], v[174:177], v[214:217], v[36:39]
	v_mfma_f32_16x16x32_bf16 v[32:35], v[182:185], v[214:217], v[32:35]
	s_barrier
; #define STAGE(P, BASE, LD, br, kt) do { const char* _g = (const char*)((BASE) + (size_t)(br) * (LD) + (size_t)(kt) * 64); \
;     for (int _i = 0; _i < 2; ++_i) { int _b = tidx * 16 + _i * 8192; int _r, _c; stage_rc(_b, _r, _c); \
;       __builtin_amdgcn_global_load_lds((const unsigned*)(_g + (unsigned)((_r * (LD) + _c) * 2)), (unsigned*)((char*)(P) + _b), 16, 0, 0); } } while (0)
; #define LDA(dst, b, h) for (int m = 0; m < 4; ++m) for (int k = 0; k < 2; ++k) \
;     dst[m][k] = *reinterpret_cast<const bf16x8*>((char*)SA(b, h) + lds_byte(wr * 64 + m * 16 + fr, k * 32 + fq * 8))
; #define LDB(dst, b, h) for (int n = 0; n < 2; ++n) for (int k = 0; k < 2; ++k) \
;     dst[n][k] = *reinterpret_cast<const bf16x8*>((char*)SB(b, h) + lds_byte(wc * 32 + n * 16 + fr, k * 32 + fq * 8))
; #define MMA(ai, bj, At_, Bt_) do { __builtin_amdgcn_s_setprio(1); \
;     for (int k = 0; k < 2; ++k) for (int m = 0; m < 4; ++m) for (int n = 0; n < 2; ++n) \
;       acc[ai][bj][m][n] = __builtin_amdgcn_mfma_f32_16x16x32_bf16(At_[m][k], Bt_[n][k], acc[ai][bj][m][n], 0, 0, 0); \
;     __builtin_amdgcn_s_setprio(0); } while (0)
; #define WAIT_V(n) asm volatile("s_waitcnt vmcnt(" #n ")" ::: "memory")
; #define WAIT_L(n) asm volatile("s_waitcnt lgkmcnt(" #n ")" ::: "memory")
; #define BAR __builtin_amdgcn_s_barrier()
; #define SCHED __builtin_amdgcn_sched_barrier(0)
; template <int EPI, int lda, int ldb, int N, int K>
; __device__ __forceinline__ void gemm_phase(const u16* __restrict__ A, const u16* __restrict__ Bt, const GemmEpi ep, int wv) {
;     ...
;       STAGE(SB(0, 1), Bt, ldb, bcol + HALF, t + 2);
;       WAIT_V(6); BAR; MMA(1, 1, At, B1); BAR;
;       LDB(B0, 1, 0); SCHED; LDA(At, 1, 0); STAGE(SA(0, 1), Ab, lda, brow + HALF, t + 2);
;       WAIT_L(8); BAR; WAIT_L(0); MMA(0, 0, At, B0); BAR; SCHED;
;       LDB(B1, 1, 1); STAGE(SB(1, 0), Bt, ldb, bcol, t + 3);
;       BAR; WAIT_L(0); MMA(0, 1, At, B1); BAR;
;       LDA(At, 1, 1); STAGE(SA(1, 0), Ab, lda, brow, t + 3);
	v_add_u32_e32 v168, s56, v156
	v_lshl_add_u64 v[246:247], v[140:141], 0, s[44:45]
	v_readfirstlane_b32 s66, v168
	v_add_u32_e32 v169, 0x2000, v168
	v_lshl_add_u64 v[170:171], v[246:247], 0, s[24:25]
	s_mov_b32 m0, s66
	v_lshl_add_u64 v[248:249], v[138:139], 0, s[44:45]
	v_readfirstlane_b32 s66, v169
	global_load_lds_dwordx4 v[170:171], off
	v_lshl_add_u64 v[170:171], v[248:249], 0, s[24:25]
	s_mov_b32 m0, s66
	s_nop 0
	global_load_lds_dwordx4 v[170:171], off
	s_waitcnt vmcnt(6)
	s_barrier
	v_mfma_f32_16x16x32_bf16 v[28:31], v[218:221], v[186:189], v[28:31]
	v_mfma_f32_16x16x32_bf16 v[24:27], v[226:229], v[186:189], v[24:27]
	v_mfma_f32_16x16x32_bf16 v[20:23], v[218:221], v[194:197], v[20:23]
	v_mfma_f32_16x16x32_bf16 v[16:19], v[226:229], v[194:197], v[16:19]
	v_mfma_f32_16x16x32_bf16 v[12:15], v[218:221], v[202:205], v[12:15]
	v_mfma_f32_16x16x32_bf16 v[8:11], v[226:229], v[202:205], v[8:11]
	v_mfma_f32_16x16x32_bf16 v[4:7], v[218:221], v[210:213], v[4:7]
	v_mfma_f32_16x16x32_bf16 v[0:3], v[226:229], v[210:213], v[0:3]
	v_mfma_f32_16x16x32_bf16 v[28:31], v[222:225], v[190:193], v[28:31]
	v_mfma_f32_16x16x32_bf16 v[24:27], v[230:233], v[190:193], v[24:27]
	v_mfma_f32_16x16x32_bf16 v[20:23], v[222:225], v[198:201], v[20:23]
	v_mfma_f32_16x16x32_bf16 v[16:19], v[230:233], v[198:201], v[16:19]
	v_mfma_f32_16x16x32_bf16 v[12:15], v[222:225], v[206:209], v[12:15]
	v_mfma_f32_16x16x32_bf16 v[8:11], v[230:233], v[206:209], v[8:11]
	v_mfma_f32_16x16x32_bf16 v[4:7], v[222:225], v[214:217], v[4:7]
	v_mfma_f32_16x16x32_bf16 v[0:3], v[230:233], v[214:217], v[0:3]
	s_barrier
	ds_read_b128 v[174:177], v159
	ds_read_b128 v[178:181], v159 offset:1024
	ds_read_b128 v[182:185], v159 offset:2048
	ds_read_b128 v[186:189], v159 offset:3072
	v_add_u32_e32 v170, 0x4000, v147
	v_add_u32_e32 v171, 0x6000, v147
	v_readfirstlane_b32 s66, v170
	v_lshl_add_u64 v[222:223], v[238:239], 0, s[26:27]
	s_mov_b32 m0, s66
	v_readfirstlane_b32 s66, v171
	ds_read_b128 v[190:193], v155 offset:32768
	ds_read_b128 v[194:197], v155 offset:33792
	ds_read_b128 v[198:201], v154 offset:32768
	ds_read_b128 v[202:205], v154 offset:33792
	ds_read_b128 v[206:209], v153 offset:32768
	ds_read_b128 v[210:213], v153 offset:33792
	ds_read_b128 v[214:217], v152 offset:32768
	ds_read_b128 v[218:221], v152 offset:33792
	global_load_lds_dwordx4 v[222:223], off
	v_lshl_add_u64 v[222:223], v[240:241], 0, s[26:27]
	s_mov_b32 m0, s66
	s_nop 0
	global_load_lds_dwordx4 v[222:223], off
	s_waitcnt lgkmcnt(8)
	s_barrier
	s_waitcnt lgkmcnt(0)
	s_waitcnt lgkmcnt(0)
	v_mfma_f32_16x16x32_bf16 v[124:127], v[174:177], v[190:193], v[124:127]
	v_mfma_f32_16x16x32_bf16 v[120:123], v[182:185], v[190:193], v[120:123]
	v_mfma_f32_16x16x32_bf16 v[116:119], v[174:177], v[198:201], v[116:119]
	v_mfma_f32_16x16x32_bf16 v[112:115], v[182:185], v[198:201], v[112:115]
	v_mfma_f32_16x16x32_bf16 v[108:111], v[174:177], v[206:209], v[108:111]
	v_mfma_f32_16x16x32_bf16 v[104:107], v[182:185], v[206:209], v[104:107]
	v_mfma_f32_16x16x32_bf16 v[100:103], v[174:177], v[214:217], v[100:103]
	v_mfma_f32_16x16x32_bf16 v[96:99], v[182:185], v[214:217], v[96:99]
	v_mfma_f32_16x16x32_bf16 v[124:127], v[178:181], v[194:197], v[124:127]
	v_mfma_f32_16x16x32_bf16 v[120:123], v[186:189], v[194:197], v[120:123]
	v_mfma_f32_16x16x32_bf16 v[116:119], v[178:181], v[202:205], v[116:119]
	v_mfma_f32_16x16x32_bf16 v[112:115], v[186:189], v[202:205], v[112:115]
	v_mfma_f32_16x16x32_bf16 v[108:111], v[178:181], v[210:213], v[108:111]
	v_mfma_f32_16x16x32_bf16 v[104:107], v[186:189], v[210:213], v[104:107]
	v_mfma_f32_16x16x32_bf16 v[100:103], v[178:181], v[218:221], v[100:103]
	v_mfma_f32_16x16x32_bf16 v[96:99], v[186:189], v[218:221], v[96:99]
	s_barrier
	v_readfirstlane_b32 s66, v158
	v_lshl_add_u64 v[242:243], v[242:243], 0, s[36:37]
	s_mov_b32 m0, s66
	ds_read_b128 v[222:225], v157
	ds_read_b128 v[226:229], v157 offset:1024
	ds_read_b128 v[230:233], v157 offset:2048
	ds_read_b128 v[234:237], v157 offset:3072
	global_load_lds_dwordx4 v[242:243], off
	v_lshl_add_u64 v[242:243], v[244:245], 0, s[36:37]
	v_add_u32_e32 v244, 0x2000, v158
	s_nop 0
	v_readfirstlane_b32 s66, v244
	s_mov_b32 m0, s66
	s_nop 0
	global_load_lds_dwordx4 v[242:243], off
	s_barrier
	s_waitcnt lgkmcnt(0)
	s_waitcnt lgkmcnt(0)
	v_mfma_f32_16x16x32_bf16 v[92:95], v[222:225], v[190:193], v[92:95]
	v_mfma_f32_16x16x32_bf16 v[88:91], v[230:233], v[190:193], v[88:91]
	v_mfma_f32_16x16x32_bf16 v[84:87], v[222:225], v[198:201], v[84:87]
	v_mfma_f32_16x16x32_bf16 v[80:83], v[230:233], v[198:201], v[80:83]
	v_mfma_f32_16x16x32_bf16 v[76:79], v[222:225], v[206:209], v[76:79]
	v_mfma_f32_16x16x32_bf16 v[72:75], v[230:233], v[206:209], v[72:75]
	v_mfma_f32_16x16x32_bf16 v[68:71], v[222:225], v[214:217], v[68:71]
	v_mfma_f32_16x16x32_bf16 v[64:67], v[230:233], v[214:217], v[64:67]
	v_mfma_f32_16x16x32_bf16 v[92:95], v[226:229], v[194:197], v[92:95]
	v_mfma_f32_16x16x32_bf16 v[88:91], v[234:237], v[194:197], v[88:91]
	v_mfma_f32_16x16x32_bf16 v[84:87], v[226:229], v[202:205], v[84:87]
	v_mfma_f32_16x16x32_bf16 v[80:83], v[234:237], v[202:205], v[80:83]
	v_mfma_f32_16x16x32_bf16 v[76:79], v[226:229], v[210:213], v[76:79]
	v_mfma_f32_16x16x32_bf16 v[72:75], v[234:237], v[210:213], v[72:75]
	v_mfma_f32_16x16x32_bf16 v[68:71], v[226:229], v[218:221], v[68:71]
	v_mfma_f32_16x16x32_bf16 v[64:67], v[234:237], v[218:221], v[64:67]
	s_barrier
; #define STAGE(P, BASE, LD, br, kt) do { const char* _g = (const char*)((BASE) + (size_t)(br) * (LD) + (size_t)(kt) * 64); \
;     for (int _i = 0; _i < 2; ++_i) { int _b = tidx * 16 + _i * 8192; int _r, _c; stage_rc(_b, _r, _c); \
;       __builtin_amdgcn_global_load_lds((const unsigned*)(_g + (unsigned)((_r * (LD) + _c) * 2)), (unsigned*)((char*)(P) + _b), 16, 0, 0); } } while (0)
; #define LDA(dst, b, h) for (int m = 0; m < 4; ++m) for (int k = 0; k < 2; ++k) \
;     dst[m][k] = *reinterpret_cast<const bf16x8*>((char*)SA(b, h) + lds_byte(wr * 64 + m * 16 + fr, k * 32 + fq * 8))
; #define LDB(dst, b, h) for (int n = 0; n < 2; ++n) for (int k = 0; k < 2; ++k) \
;     dst[n][k] = *reinterpret_cast<const bf16x8*>((char*)SB(b, h) + lds_byte(wc * 32 + n * 16 + fr, k * 32 + fq * 8))
; #define MMA(ai, bj, At_, Bt_) do { __builtin_amdgcn_s_setprio(1); \
;     for (int k = 0; k < 2; ++k) for (int m = 0; m < 4; ++m) for (int n = 0; n < 2; ++n) \
;       acc[ai][bj][m][n] = __builtin_amdgcn_mfma_f32_16x16x32_bf16(At_[m][k], Bt_[n][k], acc[ai][bj][m][n], 0, 0, 0); \
;     __builtin_amdgcn_s_setprio(0); } while (0)
; #define WAIT_V(n) asm volatile("s_waitcnt vmcnt(" #n ")" ::: "memory")
; #define WAIT_L(n) asm volatile("s_waitcnt lgkmcnt(" #n ")" ::: "memory")
; #define BAR __builtin_amdgcn_s_barrier()
; #define SCHED __builtin_amdgcn_sched_barrier(0)
; template <int EPI, int lda, int ldb, int N, int K>
; __device__ __forceinline__ void gemm_phase(const u16* __restrict__ A, const u16* __restrict__ Bt, const GemmEpi ep, int wv) {
;     ...
;       BAR; WAIT_L(0); MMA(1, 0, At, B0); BAR; SCHED;
;       STAGE(SB(1, 1), Bt, ldb, bcol + HALF, t + 3);
;       WAIT_V(6); BAR; MMA(1, 1, At, B1); BAR;
;     }
;     { LDB(B0, 0, 0); LDA(At, 0, 0); STAGE(SA(1, 1), Ab, lda, brow + HALF, nt - 1);
;       BAR; WAIT_L(0); MMA(0, 0, At, B0); BAR;
;       LDB(B1, 0, 1); BAR; WAIT_L(0); MMA(0, 1, At, B1); BAR;
	v_readfirstlane_b32 s66, v160
	v_lshl_add_u64 v[238:239], v[238:239], 0, s[38:39]
	s_mov_b32 m0, s66
	v_readfirstlane_b32 s66, v161
	ds_read_b128 v[190:193], v155 offset:49152
	ds_read_b128 v[194:197], v155 offset:50176
	ds_read_b128 v[198:201], v154 offset:49152
	ds_read_b128 v[202:205], v154 offset:50176
	ds_read_b128 v[206:209], v153 offset:49152
	ds_read_b128 v[210:213], v153 offset:50176
	ds_read_b128 v[214:217], v152 offset:49152
	ds_read_b128 v[218:221], v152 offset:50176
	global_load_lds_dwordx4 v[238:239], off
	v_lshl_add_u64 v[238:239], v[240:241], 0, s[38:39]
	s_mov_b32 m0, s66
	s_nop 0
	global_load_lds_dwordx4 v[238:239], off
	s_barrier
	s_waitcnt lgkmcnt(0)
	s_waitcnt lgkmcnt(0)
	v_mfma_f32_16x16x32_bf16 v[60:63], v[174:177], v[190:193], v[60:63]
	v_mfma_f32_16x16x32_bf16 v[56:59], v[182:185], v[190:193], v[56:59]
	v_mfma_f32_16x16x32_bf16 v[52:55], v[174:177], v[198:201], v[52:55]
	v_mfma_f32_16x16x32_bf16 v[48:51], v[182:185], v[198:201], v[48:51]
	v_mfma_f32_16x16x32_bf16 v[44:47], v[174:177], v[206:209], v[44:47]
	v_mfma_f32_16x16x32_bf16 v[40:43], v[182:185], v[206:209], v[40:43]
	v_mfma_f32_16x16x32_bf16 v[36:39], v[174:177], v[214:217], v[36:39]
	v_mfma_f32_16x16x32_bf16 v[32:35], v[182:185], v[214:217], v[32:35]
	v_mfma_f32_16x16x32_bf16 v[60:63], v[178:181], v[194:197], v[60:63]
	v_mfma_f32_16x16x32_bf16 v[56:59], v[186:189], v[194:197], v[56:59]
	v_mfma_f32_16x16x32_bf16 v[52:55], v[178:181], v[202:205], v[52:55]
	v_mfma_f32_16x16x32_bf16 v[48:51], v[186:189], v[202:205], v[48:51]
	v_mfma_f32_16x16x32_bf16 v[44:47], v[178:181], v[210:213], v[44:47]
	v_mfma_f32_16x16x32_bf16 v[40:43], v[186:189], v[210:213], v[40:43]
	v_mfma_f32_16x16x32_bf16 v[36:39], v[178:181], v[218:221], v[36:39]
	v_mfma_f32_16x16x32_bf16 v[32:35], v[186:189], v[218:221], v[32:35]
	s_barrier
	v_readfirstlane_b32 s66, v162
	v_add_u32_e32 v176, 0x2000, v162
	v_lshl_add_u64 v[174:175], v[246:247], 0, s[42:43]
	s_mov_b32 m0, s66
	v_readfirstlane_b32 s66, v176
	global_load_lds_dwordx4 v[174:175], off
	v_lshl_add_u64 v[174:175], v[248:249], 0, s[42:43]
	s_mov_b32 m0, s66
	s_nop 0
	global_load_lds_dwordx4 v[174:175], off
	s_add_i32 s65, s65, 2
	s_add_u32 s44, s44, 0x100
	s_addc_u32 s45, s45, 0
	s_cmpk_gt_u32 s65, 0x51
	s_waitcnt vmcnt(6)
	s_barrier
	v_mfma_f32_16x16x32_bf16 v[28:31], v[222:225], v[190:193], v[28:31]
	v_mfma_f32_16x16x32_bf16 v[24:27], v[230:233], v[190:193], v[24:27]
	v_mfma_f32_16x16x32_bf16 v[20:23], v[222:225], v[198:201], v[20:23]
	v_mfma_f32_16x16x32_bf16 v[16:19], v[230:233], v[198:201], v[16:19]
	v_mfma_f32_16x16x32_bf16 v[12:15], v[222:225], v[206:209], v[12:15]
	v_mfma_f32_16x16x32_bf16 v[8:11], v[230:233], v[206:209], v[8:11]
	v_mfma_f32_16x16x32_bf16 v[4:7], v[222:225], v[214:217], v[4:7]
	v_mfma_f32_16x16x32_bf16 v[0:3], v[230:233], v[214:217], v[0:3]
	v_mfma_f32_16x16x32_bf16 v[28:31], v[226:229], v[194:197], v[28:31]
	v_mfma_f32_16x16x32_bf16 v[24:27], v[234:237], v[194:197], v[24:27]
	v_mfma_f32_16x16x32_bf16 v[20:23], v[226:229], v[202:205], v[20:23]
	v_mfma_f32_16x16x32_bf16 v[16:19], v[234:237], v[202:205], v[16:19]
	v_mfma_f32_16x16x32_bf16 v[12:15], v[226:229], v[210:213], v[12:15]
	v_mfma_f32_16x16x32_bf16 v[8:11], v[234:237], v[210:213], v[8:11]
	v_mfma_f32_16x16x32_bf16 v[4:7], v[226:229], v[218:221], v[4:7]
	v_mfma_f32_16x16x32_bf16 v[0:3], v[234:237], v[218:221], v[0:3]
	s_barrier
	s_cbranch_scc0 .LBB0_224
	s_add_i32 s44, s14, 0x80
	s_mul_hi_i32 s45, s44, 0x2b00
	s_mulk_i32 s44, 0x2b00
	s_add_u32 s44, s48, s44
	s_addc_u32 s45, s49, s45
	s_add_u32 s44, s44, 0x2a80
	s_addc_u32 s45, s45, 0
	v_readfirstlane_b32 s65, v172
	v_lshl_add_u64 v[160:161], s[44:45], 0, v[128:129]
	s_mov_b32 m0, s65
	ds_read_b128 v[134:137], v164
	ds_read_b128 v[138:141], v164 offset:1024
	ds_read_b128 v[142:145], v164 offset:2048
	ds_read_b128 v[174:177], v164 offset:3072
	ds_read_b128 v[178:181], v155
	ds_read_b128 v[182:185], v155 offset:1024
	ds_read_b128 v[186:189], v154
	ds_read_b128 v[190:193], v154 offset:1024
	ds_read_b128 v[194:197], v153
	ds_read_b128 v[198:201], v153 offset:1024
	ds_read_b128 v[202:205], v152
	ds_read_b128 v[206:209], v152 offset:1024
	global_load_lds_dwordx4 v[160:161], off
	v_lshl_add_u64 v[160:161], s[44:45], 0, v[132:133]
	v_readfirstlane_b32 s44, v173
	s_mov_b32 m0, s44
	s_nop 0
	global_load_lds_dwordx4 v[160:161], off
	s_barrier
	s_waitcnt lgkmcnt(0)
	s_waitcnt lgkmcnt(0)
	v_mfma_f32_16x16x32_bf16 v[124:127], v[134:137], v[178:181], v[124:127]
	v_mfma_f32_16x16x32_bf16 v[120:123], v[142:145], v[178:181], v[120:123]
	v_mfma_f32_16x16x32_bf16 v[116:119], v[134:137], v[186:189], v[116:119]
	v_mfma_f32_16x16x32_bf16 v[112:115], v[142:145], v[186:189], v[112:115]
	v_mfma_f32_16x16x32_bf16 v[108:111], v[134:137], v[194:197], v[108:111]
	v_mfma_f32_16x16x32_bf16 v[104:107], v[142:145], v[194:197], v[104:107]
	v_mfma_f32_16x16x32_bf16 v[100:103], v[134:137], v[202:205], v[100:103]
	v_mfma_f32_16x16x32_bf16 v[96:99], v[142:145], v[202:205], v[96:99]
	v_mfma_f32_16x16x32_bf16 v[124:127], v[138:141], v[182:185], v[124:127]
	v_mfma_f32_16x16x32_bf16 v[120:123], v[174:177], v[182:185], v[120:123]
	v_mfma_f32_16x16x32_bf16 v[116:119], v[138:141], v[190:193], v[116:119]
	v_mfma_f32_16x16x32_bf16 v[112:115], v[174:177], v[190:193], v[112:115]
	v_mfma_f32_16x16x32_bf16 v[108:111], v[138:141], v[198:201], v[108:111]
	v_mfma_f32_16x16x32_bf16 v[104:107], v[174:177], v[198:201], v[104:107]
	v_mfma_f32_16x16x32_bf16 v[100:103], v[138:141], v[206:209], v[100:103]
	v_mfma_f32_16x16x32_bf16 v[96:99], v[174:177], v[206:209], v[96:99]
	s_barrier
; #define LDA(dst, b, h) for (int m = 0; m < 4; ++m) for (int k = 0; k < 2; ++k) \
;     dst[m][k] = *reinterpret_cast<const bf16x8*>((char*)SA(b, h) + lds_byte(wr * 64 + m * 16 + fr, k * 32 + fq * 8))
; #define LDB(dst, b, h) for (int n = 0; n < 2; ++n) for (int k = 0; k < 2; ++k) \
;     dst[n][k] = *reinterpret_cast<const bf16x8*>((char*)SB(b, h) + lds_byte(wc * 32 + n * 16 + fr, k * 32 + fq * 8))
; #define MMA(ai, bj, At_, Bt_) do { __builtin_amdgcn_s_setprio(1); \
;     for (int k = 0; k < 2; ++k) for (int m = 0; m < 4; ++m) for (int n = 0; n < 2; ++n) \
;       acc[ai][bj][m][n] = __builtin_amdgcn_mfma_f32_16x16x32_bf16(At_[m][k], Bt_[n][k], acc[ai][bj][m][n], 0, 0, 0); \
;     __builtin_amdgcn_s_setprio(0); } while (0)
; #define WAIT_V(n) asm volatile("s_waitcnt vmcnt(" #n ")" ::: "memory")
; #define WAIT_L(n) asm volatile("s_waitcnt lgkmcnt(" #n ")" ::: "memory")
; #define BAR __builtin_amdgcn_s_barrier()
; template <int EPI, int lda, int ldb, int N, int K>
; __device__ __forceinline__ void gemm_phase(const u16* __restrict__ A, const u16* __restrict__ Bt, const GemmEpi ep, int wv) {
;     ...
;       LDB(B1, 0, 1); BAR; WAIT_L(0); MMA(0, 1, At, B1); BAR;
;       LDA(At, 0, 1); WAIT_V(4); BAR; WAIT_L(0); MMA(1, 0, At, B0); MMA(1, 1, At, B1); BAR; }
;     { LDB(B0, 1, 0); LDA(At, 1, 0); WAIT_V(2); BAR; WAIT_L(0); MMA(0, 0, At, B0); BAR;
	ds_read_b128 v[210:213], v163
	ds_read_b128 v[214:217], v163 offset:1024
	ds_read_b128 v[218:221], v163 offset:2048
	ds_read_b128 v[160:163], v163 offset:3072
	s_barrier
	s_waitcnt lgkmcnt(0)
	s_waitcnt lgkmcnt(0)
	v_mfma_f32_16x16x32_bf16 v[92:95], v[210:213], v[178:181], v[92:95]
	v_mfma_f32_16x16x32_bf16 v[88:91], v[218:221], v[178:181], v[88:91]
	v_mfma_f32_16x16x32_bf16 v[76:79], v[210:213], v[194:197], v[76:79]
	v_mfma_f32_16x16x32_bf16 v[72:75], v[218:221], v[194:197], v[72:75]
	v_mfma_f32_16x16x32_bf16 v[84:87], v[210:213], v[186:189], v[84:87]
	v_mfma_f32_16x16x32_bf16 v[80:83], v[218:221], v[186:189], v[80:83]
	v_mfma_f32_16x16x32_bf16 v[68:71], v[210:213], v[202:205], v[68:71]
	v_mfma_f32_16x16x32_bf16 v[64:67], v[218:221], v[202:205], v[64:67]
	v_mfma_f32_16x16x32_bf16 v[92:95], v[214:217], v[182:185], v[92:95]
	v_mfma_f32_16x16x32_bf16 v[88:91], v[160:163], v[182:185], v[88:91]
	v_mfma_f32_16x16x32_bf16 v[76:79], v[214:217], v[198:201], v[76:79]
	v_mfma_f32_16x16x32_bf16 v[72:75], v[160:163], v[198:201], v[72:75]
	v_mfma_f32_16x16x32_bf16 v[178:181], v[214:217], v[190:193], v[84:87]
	v_mfma_f32_16x16x32_bf16 v[182:185], v[160:163], v[190:193], v[80:83]
	v_mfma_f32_16x16x32_bf16 v[186:189], v[214:217], v[206:209], v[68:71]
	v_mfma_f32_16x16x32_bf16 v[190:193], v[160:163], v[206:209], v[64:67]
	s_barrier
	s_nop 0
	ds_read_b128 v[64:67], v155 offset:16384
	ds_read_b128 v[68:71], v155 offset:17408
	ds_read_b128 v[80:83], v154 offset:16384
	ds_read_b128 v[84:87], v154 offset:17408
	ds_read_b128 v[194:197], v153 offset:16384
	ds_read_b128 v[198:201], v153 offset:17408
	ds_read_b128 v[202:205], v152 offset:16384
	ds_read_b128 v[206:209], v152 offset:17408
	s_waitcnt vmcnt(4)
	s_barrier
	s_waitcnt lgkmcnt(0)
	s_waitcnt lgkmcnt(0)
	v_mfma_f32_16x16x32_bf16 v[60:63], v[134:137], v[64:67], v[60:63]
	v_mfma_f32_16x16x32_bf16 v[56:59], v[142:145], v[64:67], v[56:59]
	v_mfma_f32_16x16x32_bf16 v[52:55], v[134:137], v[80:83], v[52:55]
	v_mfma_f32_16x16x32_bf16 v[48:51], v[142:145], v[80:83], v[48:51]
	v_mfma_f32_16x16x32_bf16 v[44:47], v[134:137], v[194:197], v[44:47]
	v_mfma_f32_16x16x32_bf16 v[40:43], v[142:145], v[194:197], v[40:43]
	v_mfma_f32_16x16x32_bf16 v[36:39], v[134:137], v[202:205], v[36:39]
	v_mfma_f32_16x16x32_bf16 v[32:35], v[142:145], v[202:205], v[32:35]
	v_mfma_f32_16x16x32_bf16 v[60:63], v[138:141], v[68:71], v[60:63]
	v_mfma_f32_16x16x32_bf16 v[56:59], v[174:177], v[68:71], v[56:59]
	v_mfma_f32_16x16x32_bf16 v[52:55], v[138:141], v[84:87], v[52:55]
	v_mfma_f32_16x16x32_bf16 v[48:51], v[174:177], v[84:87], v[48:51]
	v_mfma_f32_16x16x32_bf16 v[44:47], v[138:141], v[198:201], v[44:47]
	v_mfma_f32_16x16x32_bf16 v[40:43], v[174:177], v[198:201], v[40:43]
	v_mfma_f32_16x16x32_bf16 v[36:39], v[138:141], v[206:209], v[36:39]
	v_mfma_f32_16x16x32_bf16 v[32:35], v[174:177], v[206:209], v[32:35]
	v_mfma_f32_16x16x32_bf16 v[28:31], v[210:213], v[64:67], v[28:31]
	v_mfma_f32_16x16x32_bf16 v[16:19], v[218:221], v[80:83], v[16:19]
	v_mfma_f32_16x16x32_bf16 v[12:15], v[210:213], v[194:197], v[12:15]
	v_mfma_f32_16x16x32_bf16 v[0:3], v[218:221], v[202:205], v[0:3]
	v_mfma_f32_16x16x32_bf16 v[24:27], v[218:221], v[64:67], v[24:27]
	v_mfma_f32_16x16x32_bf16 v[20:23], v[210:213], v[80:83], v[20:23]
	v_mfma_f32_16x16x32_bf16 v[8:11], v[218:221], v[194:197], v[8:11]
	v_mfma_f32_16x16x32_bf16 v[4:7], v[210:213], v[202:205], v[4:7]
	v_mfma_f32_16x16x32_bf16 v[28:31], v[214:217], v[68:71], v[28:31]
	v_mfma_f32_16x16x32_bf16 v[16:19], v[160:163], v[84:87], v[16:19]
	v_mfma_f32_16x16x32_bf16 v[12:15], v[214:217], v[198:201], v[12:15]
	v_mfma_f32_16x16x32_bf16 v[0:3], v[160:163], v[206:209], v[0:3]
	v_mfma_f32_16x16x32_bf16 v[134:137], v[160:163], v[68:71], v[24:27]
	v_mfma_f32_16x16x32_bf16 v[138:141], v[214:217], v[84:87], v[20:23]
	v_mfma_f32_16x16x32_bf16 v[142:145], v[160:163], v[198:201], v[8:11]
	v_mfma_f32_16x16x32_bf16 v[172:175], v[214:217], v[206:209], v[4:7]
	s_barrier
	s_nop 0
	ds_read_b128 v[4:7], v159
	ds_read_b128 v[8:11], v159 offset:1024
	ds_read_b128 v[20:23], v159 offset:2048
	ds_read_b128 v[158:161], v159 offset:3072
	ds_read_b128 v[24:27], v155 offset:32768
	ds_read_b128 v[194:197], v155 offset:33792
	ds_read_b128 v[198:201], v154 offset:32768
	ds_read_b128 v[202:205], v154 offset:33792
	ds_read_b128 v[206:209], v153 offset:32768
	ds_read_b128 v[210:213], v153 offset:33792
	ds_read_b128 v[214:217], v152 offset:32768
	ds_read_b128 v[218:221], v152 offset:33792
	s_waitcnt vmcnt(2)
	s_barrier
; #define LDA(dst, b, h) for (int m = 0; m < 4; ++m) for (int k = 0; k < 2; ++k) \
;     dst[m][k] = *reinterpret_cast<const bf16x8*>((char*)SA(b, h) + lds_byte(wr * 64 + m * 16 + fr, k * 32 + fq * 8))
; #define LDB(dst, b, h) for (int n = 0; n < 2; ++n) for (int k = 0; k < 2; ++k) \
;     dst[n][k] = *reinterpret_cast<const bf16x8*>((char*)SB(b, h) + lds_byte(wc * 32 + n * 16 + fr, k * 32 + fq * 8))
; #define MMA(ai, bj, At_, Bt_) do { __builtin_amdgcn_s_setprio(1); \
;     for (int k = 0; k < 2; ++k) for (int m = 0; m < 4; ++m) for (int n = 0; n < 2; ++n) \
;       acc[ai][bj][m][n] = __builtin_amdgcn_mfma_f32_16x16x32_bf16(At_[m][k], Bt_[n][k], acc[ai][bj][m][n], 0, 0, 0); \
;     __builtin_amdgcn_s_setprio(0); } while (0)
; #define WAIT_V(n) asm volatile("s_waitcnt vmcnt(" #n ")" ::: "memory")
; #define WAIT_L(n) asm volatile("s_waitcnt lgkmcnt(" #n ")" ::: "memory")
; #define BAR __builtin_amdgcn_s_barrier()
; template <int EPI, int lda, int ldb, int N, int K>
; __device__ __forceinline__ void gemm_phase(const u16* __restrict__ A, const u16* __restrict__ Bt, const GemmEpi ep, int wv) {
;     ...
;     { LDB(B0, 1, 0); LDA(At, 1, 0); WAIT_V(2); BAR; WAIT_L(0); MMA(0, 0, At, B0); BAR;
;       LDB(B1, 1, 1); WAIT_V(0); BAR; WAIT_L(0); MMA(0, 1, At, B1); BAR;
;       LDA(At, 1, 1); BAR; WAIT_L(0); MMA(1, 0, At, B0); MMA(1, 1, At, B1); BAR; }
;     if (wr == 0) BAR;
	s_waitcnt lgkmcnt(0)
	s_waitcnt lgkmcnt(0)
	v_mfma_f32_16x16x32_bf16 v[64:67], v[4:7], v[24:27], v[124:127]
	v_mfma_f32_16x16x32_bf16 v[68:71], v[20:23], v[24:27], v[120:123]
	v_mfma_f32_16x16x32_bf16 v[80:83], v[4:7], v[198:201], v[116:119]
	v_mfma_f32_16x16x32_bf16 v[84:87], v[20:23], v[198:201], v[112:115]
	v_mfma_f32_16x16x32_bf16 v[108:111], v[4:7], v[206:209], v[108:111]
	v_mfma_f32_16x16x32_bf16 v[104:107], v[20:23], v[206:209], v[104:107]
	v_mfma_f32_16x16x32_bf16 v[120:123], v[4:7], v[214:217], v[100:103]
	v_mfma_f32_16x16x32_bf16 v[124:127], v[20:23], v[214:217], v[96:99]
	v_mfma_f32_16x16x32_bf16 v[116:119], v[8:11], v[194:197], v[64:67]
	v_mfma_f32_16x16x32_bf16 v[112:115], v[158:161], v[194:197], v[68:71]
	v_mfma_f32_16x16x32_bf16 v[100:103], v[8:11], v[202:205], v[80:83]
	v_mfma_f32_16x16x32_bf16 v[96:99], v[158:161], v[202:205], v[84:87]
	v_mfma_f32_16x16x32_bf16 v[84:87], v[8:11], v[210:213], v[108:111]
	v_mfma_f32_16x16x32_bf16 v[80:83], v[158:161], v[210:213], v[104:107]
	v_mfma_f32_16x16x32_bf16 v[68:71], v[8:11], v[218:221], v[120:123]
	v_mfma_f32_16x16x32_bf16 v[64:67], v[158:161], v[218:221], v[124:127]
	s_barrier
	ds_read_b128 v[222:225], v157
	ds_read_b128 v[226:229], v157 offset:1024
	ds_read_b128 v[230:233], v157 offset:2048
	ds_read_b128 v[234:237], v157 offset:3072
	s_waitcnt vmcnt(0)
	s_barrier
	s_waitcnt lgkmcnt(0)
	s_waitcnt lgkmcnt(0)
	v_mfma_f32_16x16x32_bf16 v[92:95], v[222:225], v[24:27], v[92:95]
	v_mfma_f32_16x16x32_bf16 v[24:27], v[230:233], v[24:27], v[88:91]
	v_mfma_f32_16x16x32_bf16 v[88:91], v[222:225], v[198:201], v[178:181]
	v_mfma_f32_16x16x32_bf16 v[104:107], v[230:233], v[198:201], v[182:185]
	v_mfma_f32_16x16x32_bf16 v[76:79], v[222:225], v[206:209], v[76:79]
	v_mfma_f32_16x16x32_bf16 v[72:75], v[230:233], v[206:209], v[72:75]
	v_mfma_f32_16x16x32_bf16 v[176:179], v[222:225], v[214:217], v[186:189]
	v_mfma_f32_16x16x32_bf16 v[180:183], v[230:233], v[214:217], v[190:193]
	v_mfma_f32_16x16x32_bf16 v[124:127], v[226:229], v[194:197], v[92:95]
	v_mfma_f32_16x16x32_bf16 v[120:123], v[234:237], v[194:197], v[24:27]
	v_mfma_f32_16x16x32_bf16 v[108:111], v[226:229], v[202:205], v[88:91]
	v_mfma_f32_16x16x32_bf16 v[104:107], v[234:237], v[202:205], v[104:107]
	v_mfma_f32_16x16x32_bf16 v[92:95], v[226:229], v[210:213], v[76:79]
	v_mfma_f32_16x16x32_bf16 v[88:91], v[234:237], v[210:213], v[72:75]
	v_mfma_f32_16x16x32_bf16 v[76:79], v[226:229], v[218:221], v[176:179]
	v_mfma_f32_16x16x32_bf16 v[72:75], v[234:237], v[218:221], v[180:183]
	s_barrier
	ds_read_b128 v[176:179], v155 offset:49152
	ds_read_b128 v[180:183], v155 offset:50176
	ds_read_b128 v[184:187], v154 offset:49152
	ds_read_b128 v[154:157], v154 offset:50176
	ds_read_b128 v[188:191], v153 offset:49152
	ds_read_b128 v[192:195], v153 offset:50176
	ds_read_b128 v[196:199], v152 offset:49152
	ds_read_b128 v[200:203], v152 offset:50176
	s_barrier
	s_waitcnt lgkmcnt(0)
	s_waitcnt lgkmcnt(0)
	v_mfma_f32_16x16x32_bf16 v[24:27], v[4:7], v[176:179], v[60:63]
	v_mfma_f32_16x16x32_bf16 v[60:63], v[20:23], v[176:179], v[56:59]
	v_mfma_f32_16x16x32_bf16 v[204:207], v[4:7], v[184:187], v[52:55]
	v_mfma_f32_16x16x32_bf16 v[48:51], v[20:23], v[184:187], v[48:51]
	v_mfma_f32_16x16x32_bf16 v[44:47], v[4:7], v[188:191], v[44:47]
	v_mfma_f32_16x16x32_bf16 v[208:211], v[20:23], v[188:191], v[40:43]
	v_mfma_f32_16x16x32_bf16 v[4:7], v[4:7], v[196:199], v[36:39]
	v_mfma_f32_16x16x32_bf16 v[32:35], v[20:23], v[196:199], v[32:35]
	v_mfma_f32_16x16x32_bf16 v[56:59], v[8:11], v[180:183], v[24:27]
	v_mfma_f32_16x16x32_bf16 v[52:55], v[158:161], v[180:183], v[60:63]
	v_mfma_f32_16x16x32_bf16 v[40:43], v[8:11], v[154:157], v[204:207]
	v_mfma_f32_16x16x32_bf16 v[36:39], v[158:161], v[154:157], v[48:51]
	v_mfma_f32_16x16x32_bf16 v[24:27], v[8:11], v[192:195], v[44:47]
	v_mfma_f32_16x16x32_bf16 v[20:23], v[158:161], v[192:195], v[208:211]
	v_mfma_f32_16x16x32_bf16 v[8:11], v[8:11], v[200:203], v[4:7]
	v_mfma_f32_16x16x32_bf16 v[4:7], v[158:161], v[200:203], v[32:35]
	v_mfma_f32_16x16x32_bf16 v[28:31], v[222:225], v[176:179], v[28:31]
	v_mfma_f32_16x16x32_bf16 v[32:35], v[230:233], v[176:179], v[134:137]
	v_mfma_f32_16x16x32_bf16 v[44:47], v[222:225], v[184:187], v[138:141]
	v_mfma_f32_16x16x32_bf16 v[16:19], v[230:233], v[184:187], v[16:19]
	v_mfma_f32_16x16x32_bf16 v[12:15], v[222:225], v[188:191], v[12:15]
	v_mfma_f32_16x16x32_bf16 v[134:137], v[230:233], v[188:191], v[142:145]
	v_mfma_f32_16x16x32_bf16 v[138:141], v[222:225], v[196:199], v[172:175]
	v_mfma_f32_16x16x32_bf16 v[0:3], v[230:233], v[196:199], v[0:3]
	v_mfma_f32_16x16x32_bf16 v[60:63], v[226:229], v[180:183], v[28:31]
	v_mfma_f32_16x16x32_bf16 v[48:51], v[234:237], v[180:183], v[32:35]
	v_mfma_f32_16x16x32_bf16 v[44:47], v[226:229], v[154:157], v[44:47]
	v_mfma_f32_16x16x32_bf16 v[32:35], v[234:237], v[154:157], v[16:19]
	v_mfma_f32_16x16x32_bf16 v[28:31], v[226:229], v[192:195], v[12:15]
	v_mfma_f32_16x16x32_bf16 v[16:19], v[234:237], v[192:195], v[134:137]
	v_mfma_f32_16x16x32_bf16 v[12:15], v[226:229], v[200:203], v[138:141]
	v_mfma_f32_16x16x32_bf16 v[0:3], v[234:237], v[200:203], v[0:3]
	v_cmp_gt_u32_e32 vcc, s62, v130
	s_barrier
	s_and_saveexec_b64 s[44:45], vcc
	s_cbranch_execz .LBB0_227
	s_barrier

; #define STAGE(P, BASE, LD, br, kt) do { const char* _g = (const char*)((BASE) + (size_t)(br) * (LD) + (size_t)(kt) * 64); \
;     for (int _i = 0; _i < 2; ++_i) { int _b = tidx * 16 + _i * 8192; int _r, _c; stage_rc(_b, _r, _c); \
;       __builtin_amdgcn_global_load_lds((const unsigned*)(_g + (unsigned)((_r * (LD) + _c) * 2)), (unsigned*)((char*)(P) + _b), 16, 0, 0); } } while (0)
; #define LDA(dst, b, h) for (int m = 0; m < 4; ++m) for (int k = 0; k < 2; ++k) \
;     dst[m][k] = *reinterpret_cast<const bf16x8*>((char*)SA(b, h) + lds_byte(wr * 64 + m * 16 + fr, k * 32 + fq * 8))
; #define LDB(dst, b, h) for (int n = 0; n < 2; ++n) for (int k = 0; k < 2; ++k) \
;     dst[n][k] = *reinterpret_cast<const bf16x8*>((char*)SB(b, h) + lds_byte(wc * 32 + n * 16 + fr, k * 32 + fq * 8))
; #define MMA(ai, bj, At_, Bt_) do { __builtin_amdgcn_s_setprio(1); \
;     for (int k = 0; k < 2; ++k) for (int m = 0; m < 4; ++m) for (int n = 0; n < 2; ++n) \
;       acc[ai][bj][m][n] = __builtin_amdgcn_mfma_f32_16x16x32_bf16(At_[m][k], Bt_[n][k], acc[ai][bj][m][n], 0, 0, 0); \
;     __builtin_amdgcn_s_setprio(0); } while (0)
; #define WAIT_L(n) asm volatile("s_waitcnt lgkmcnt(" #n ")" ::: "memory")
; #define BAR __builtin_amdgcn_s_barrier()
; #define SCHED __builtin_amdgcn_sched_barrier(0)
; template <int EPI, int lda, int ldb, int N, int K>
; __device__ __forceinline__ void gemm_phase(const u16* __restrict__ A, const u16* __restrict__ Bt, const GemmEpi ep, int wv) {
;     ...
;     for (int t = 0; t < nt - 2; t += 2) {
;       LDB(B0, 0, 0); SCHED; LDA(At, 0, 0); STAGE(SA(1, 1), Ab, lda, brow + HALF, t + 1);
;       WAIT_L(8); BAR; WAIT_L(0); MMA(0, 0, At, B0); BAR; SCHED;
;       LDB(B1, 0, 1); STAGE(SB(0, 0), Bt, ldb, bcol, t + 2);
;       BAR; WAIT_L(0); MMA(0, 1, At, B1); BAR;
;       LDA(At, 0, 1); STAGE(SA(0, 0), Ab, lda, brow, t + 2);
;       BAR; WAIT_L(0); MMA(1, 0, At, B0); BAR; SCHED;
.LBB0_340:
	ds_read_b128 v[166:169], v162
	ds_read_b128 v[172:175], v162 offset:1024
	ds_read_b128 v[176:179], v162 offset:2048
	ds_read_b128 v[180:183], v162 offset:3072
	v_add_u32_e32 v170, 0xc000, v149
	v_lshl_add_u64 v[236:237], v[138:139], 0, s[48:49]
	v_readfirstlane_b32 s51, v170
	v_add_u32_e32 v171, 0xe000, v149
	v_lshl_add_u64 v[164:165], v[236:237], 0, s[18:19]
	s_mov_b32 m0, s51
	v_lshl_add_u64 v[238:239], v[140:141], 0, s[48:49]
	v_readfirstlane_b32 s51, v171
	ds_read_b128 v[184:187], v153
	ds_read_b128 v[188:191], v153 offset:1024
	ds_read_b128 v[192:195], v152
	ds_read_b128 v[196:199], v152 offset:1024
	ds_read_b128 v[200:203], v151
	ds_read_b128 v[204:207], v151 offset:1024
	ds_read_b128 v[208:211], v150
	ds_read_b128 v[212:215], v150 offset:1024
	global_load_lds_dwordx4 v[164:165], off
	v_lshl_add_u64 v[164:165], v[238:239], 0, s[18:19]
	s_mov_b32 m0, s51
	s_nop 0
	global_load_lds_dwordx4 v[164:165], off
	s_waitcnt lgkmcnt(8)
	s_barrier
	s_waitcnt lgkmcnt(0)
	s_waitcnt lgkmcnt(0)
	v_mfma_f32_16x16x32_bf16 v[124:127], v[184:187], v[166:169], v[124:127]
	v_mfma_f32_16x16x32_bf16 v[120:123], v[184:187], v[176:179], v[120:123]
	v_mfma_f32_16x16x32_bf16 v[116:119], v[192:195], v[166:169], v[116:119]
	v_mfma_f32_16x16x32_bf16 v[112:115], v[192:195], v[176:179], v[112:115]
	v_mfma_f32_16x16x32_bf16 v[108:111], v[200:203], v[166:169], v[108:111]
	v_mfma_f32_16x16x32_bf16 v[104:107], v[200:203], v[176:179], v[104:107]
	v_mfma_f32_16x16x32_bf16 v[100:103], v[208:211], v[166:169], v[100:103]
	v_mfma_f32_16x16x32_bf16 v[96:99], v[208:211], v[176:179], v[96:99]
	v_mfma_f32_16x16x32_bf16 v[124:127], v[188:191], v[172:175], v[124:127]
	v_mfma_f32_16x16x32_bf16 v[120:123], v[188:191], v[180:183], v[120:123]
	v_mfma_f32_16x16x32_bf16 v[116:119], v[196:199], v[172:175], v[116:119]
	v_mfma_f32_16x16x32_bf16 v[112:115], v[196:199], v[180:183], v[112:115]
	v_mfma_f32_16x16x32_bf16 v[108:111], v[204:207], v[172:175], v[108:111]
	v_mfma_f32_16x16x32_bf16 v[104:107], v[204:207], v[180:183], v[104:107]
	v_mfma_f32_16x16x32_bf16 v[100:103], v[212:215], v[172:175], v[100:103]
	v_mfma_f32_16x16x32_bf16 v[96:99], v[212:215], v[180:183], v[96:99]
	s_barrier
	v_add_u32_e32 v163, s62, v155
	v_lshl_add_u64 v[240:241], v[134:135], 0, s[48:49]
	v_readfirstlane_b32 s51, v163
	v_lshl_add_u64 v[164:165], v[240:241], 0, s[20:21]
	s_mov_b32 m0, s51
	ds_read_b128 v[216:219], v161
	ds_read_b128 v[220:223], v161 offset:1024
	ds_read_b128 v[224:227], v161 offset:2048
	ds_read_b128 v[228:231], v161 offset:3072
	global_load_lds_dwordx4 v[164:165], off
	v_add_u32_e32 v164, 0x2000, v163
	v_lshl_add_u64 v[242:243], v[136:137], 0, s[48:49]
	v_readfirstlane_b32 s51, v164
	v_lshl_add_u64 v[232:233], v[242:243], 0, s[20:21]
	s_mov_b32 m0, s51
	s_nop 0
	global_load_lds_dwordx4 v[232:233], off
	s_barrier
	s_waitcnt lgkmcnt(0)
	s_waitcnt lgkmcnt(0)
	v_mfma_f32_16x16x32_bf16 v[92:95], v[184:187], v[216:219], v[92:95]
	v_mfma_f32_16x16x32_bf16 v[88:91], v[184:187], v[224:227], v[88:91]
	v_mfma_f32_16x16x32_bf16 v[84:87], v[192:195], v[216:219], v[84:87]
	v_mfma_f32_16x16x32_bf16 v[80:83], v[192:195], v[224:227], v[80:83]
	v_mfma_f32_16x16x32_bf16 v[76:79], v[200:203], v[216:219], v[76:79]
	v_mfma_f32_16x16x32_bf16 v[72:75], v[200:203], v[224:227], v[72:75]
	v_mfma_f32_16x16x32_bf16 v[68:71], v[208:211], v[216:219], v[68:71]
	v_mfma_f32_16x16x32_bf16 v[64:67], v[208:211], v[224:227], v[64:67]
	v_mfma_f32_16x16x32_bf16 v[92:95], v[188:191], v[220:223], v[92:95]
	v_mfma_f32_16x16x32_bf16 v[88:91], v[188:191], v[228:231], v[88:91]
	v_mfma_f32_16x16x32_bf16 v[84:87], v[196:199], v[220:223], v[84:87]
	v_mfma_f32_16x16x32_bf16 v[80:83], v[196:199], v[228:231], v[80:83]
	v_mfma_f32_16x16x32_bf16 v[76:79], v[204:207], v[220:223], v[76:79]
	v_mfma_f32_16x16x32_bf16 v[72:75], v[204:207], v[228:231], v[72:75]
	v_mfma_f32_16x16x32_bf16 v[68:71], v[212:215], v[220:223], v[68:71]
	v_mfma_f32_16x16x32_bf16 v[64:67], v[212:215], v[228:231], v[64:67]
	s_barrier
	v_readfirstlane_b32 s51, v149
	v_add_u32_e32 v165, 0x2000, v149
	v_lshl_add_u64 v[232:233], v[236:237], 0, s[22:23]
	s_mov_b32 m0, s51
	v_readfirstlane_b32 s51, v165
	ds_read_b128 v[184:187], v153 offset:16384
	ds_read_b128 v[188:191], v153 offset:17408
	ds_read_b128 v[192:195], v152 offset:16384
	ds_read_b128 v[196:199], v152 offset:17408
	ds_read_b128 v[200:203], v151 offset:16384
	ds_read_b128 v[204:207], v151 offset:17408
	ds_read_b128 v[208:211], v150 offset:16384
	ds_read_b128 v[212:215], v150 offset:17408
	global_load_lds_dwordx4 v[232:233], off
	v_lshl_add_u64 v[232:233], v[238:239], 0, s[22:23]
	s_mov_b32 m0, s51
	s_nop 0
	global_load_lds_dwordx4 v[232:233], off
	s_barrier
	s_waitcnt lgkmcnt(0)
	s_waitcnt lgkmcnt(0)
	v_mfma_f32_16x16x32_bf16 v[60:63], v[184:187], v[166:169], v[60:63]
	v_mfma_f32_16x16x32_bf16 v[56:59], v[184:187], v[176:179], v[56:59]
	v_mfma_f32_16x16x32_bf16 v[52:55], v[192:195], v[166:169], v[52:55]
	v_mfma_f32_16x16x32_bf16 v[48:51], v[192:195], v[176:179], v[48:51]
	v_mfma_f32_16x16x32_bf16 v[44:47], v[200:203], v[166:169], v[44:47]
	v_mfma_f32_16x16x32_bf16 v[40:43], v[200:203], v[176:179], v[40:43]
	v_mfma_f32_16x16x32_bf16 v[36:39], v[208:211], v[166:169], v[36:39]
	v_mfma_f32_16x16x32_bf16 v[32:35], v[208:211], v[176:179], v[32:35]
	v_mfma_f32_16x16x32_bf16 v[60:63], v[188:191], v[172:175], v[60:63]
	v_mfma_f32_16x16x32_bf16 v[56:59], v[188:191], v[180:183], v[56:59]
	v_mfma_f32_16x16x32_bf16 v[52:55], v[196:199], v[172:175], v[52:55]
	v_mfma_f32_16x16x32_bf16 v[48:51], v[196:199], v[180:183], v[48:51]
	v_mfma_f32_16x16x32_bf16 v[44:47], v[204:207], v[172:175], v[44:47]
	v_mfma_f32_16x16x32_bf16 v[40:43], v[204:207], v[180:183], v[40:43]
	v_mfma_f32_16x16x32_bf16 v[36:39], v[212:215], v[172:175], v[36:39]
	v_mfma_f32_16x16x32_bf16 v[32:35], v[212:215], v[180:183], v[32:35]
	s_barrier
; #define STAGE(P, BASE, LD, br, kt) do { const char* _g = (const char*)((BASE) + (size_t)(br) * (LD) + (size_t)(kt) * 64); \
;     for (int _i = 0; _i < 2; ++_i) { int _b = tidx * 16 + _i * 8192; int _r, _c; stage_rc(_b, _r, _c); \
;       __builtin_amdgcn_global_load_lds((const unsigned*)(_g + (unsigned)((_r * (LD) + _c) * 2)), (unsigned*)((char*)(P) + _b), 16, 0, 0); } } while (0)
; #define LDA(dst, b, h) for (int m = 0; m < 4; ++m) for (int k = 0; k < 2; ++k) \
;     dst[m][k] = *reinterpret_cast<const bf16x8*>((char*)SA(b, h) + lds_byte(wr * 64 + m * 16 + fr, k * 32 + fq * 8))
; #define LDB(dst, b, h) for (int n = 0; n < 2; ++n) for (int k = 0; k < 2; ++k) \
;     dst[n][k] = *reinterpret_cast<const bf16x8*>((char*)SB(b, h) + lds_byte(wc * 32 + n * 16 + fr, k * 32 + fq * 8))
; #define MMA(ai, bj, At_, Bt_) do { __builtin_amdgcn_s_setprio(1); \
;     for (int k = 0; k < 2; ++k) for (int m = 0; m < 4; ++m) for (int n = 0; n < 2; ++n) \
;       acc[ai][bj][m][n] = __builtin_amdgcn_mfma_f32_16x16x32_bf16(At_[m][k], Bt_[n][k], acc[ai][bj][m][n], 0, 0, 0); \
;     __builtin_amdgcn_s_setprio(0); } while (0)
; #define WAIT_V(n) asm volatile("s_waitcnt vmcnt(" #n ")" ::: "memory")
; #define WAIT_L(n) asm volatile("s_waitcnt lgkmcnt(" #n ")" ::: "memory")
; #define BAR __builtin_amdgcn_s_barrier()
; #define SCHED __builtin_amdgcn_sched_barrier(0)
; template <int EPI, int lda, int ldb, int N, int K>
; __device__ __forceinline__ void gemm_phase(const u16* __restrict__ A, const u16* __restrict__ Bt, const GemmEpi ep, int wv) {
;     ...
;       STAGE(SB(0, 1), Bt, ldb, bcol + HALF, t + 2);
;       WAIT_V(6); BAR; MMA(1, 1, At, B1); BAR;
;       LDB(B0, 1, 0); SCHED; LDA(At, 1, 0); STAGE(SA(0, 1), Ab, lda, brow + HALF, t + 2);
;       WAIT_L(8); BAR; WAIT_L(0); MMA(0, 0, At, B0); BAR; SCHED;
;       LDB(B1, 1, 1); STAGE(SB(1, 0), Bt, ldb, bcol, t + 3);
;       BAR; WAIT_L(0); MMA(0, 1, At, B1); BAR;
;       LDA(At, 1, 1); STAGE(SA(1, 0), Ab, lda, brow, t + 3);
	v_add_u32_e32 v166, s63, v155
	v_add_u32_e32 v167, 0x2000, v166
	v_readfirstlane_b32 s51, v166
	v_lshl_add_u64 v[168:169], v[240:241], 0, s[24:25]
	s_mov_b32 m0, s51
	v_readfirstlane_b32 s51, v167
	global_load_lds_dwordx4 v[168:169], off
	v_lshl_add_u64 v[168:169], v[242:243], 0, s[24:25]
	s_mov_b32 m0, s51
	s_nop 0
	global_load_lds_dwordx4 v[168:169], off
	s_waitcnt vmcnt(6)
	s_barrier
	v_mfma_f32_16x16x32_bf16 v[28:31], v[184:187], v[216:219], v[28:31]
	v_mfma_f32_16x16x32_bf16 v[24:27], v[184:187], v[224:227], v[24:27]
	v_mfma_f32_16x16x32_bf16 v[20:23], v[192:195], v[216:219], v[20:23]
	v_mfma_f32_16x16x32_bf16 v[16:19], v[192:195], v[224:227], v[16:19]
	v_mfma_f32_16x16x32_bf16 v[12:15], v[200:203], v[216:219], v[12:15]
	v_mfma_f32_16x16x32_bf16 v[8:11], v[200:203], v[224:227], v[8:11]
	v_mfma_f32_16x16x32_bf16 v[4:7], v[208:211], v[216:219], v[4:7]
	v_mfma_f32_16x16x32_bf16 v[0:3], v[208:211], v[224:227], v[0:3]
	v_mfma_f32_16x16x32_bf16 v[28:31], v[188:191], v[220:223], v[28:31]
	v_mfma_f32_16x16x32_bf16 v[24:27], v[188:191], v[228:231], v[24:27]
	v_mfma_f32_16x16x32_bf16 v[20:23], v[196:199], v[220:223], v[20:23]
	v_mfma_f32_16x16x32_bf16 v[16:19], v[196:199], v[228:231], v[16:19]
	v_mfma_f32_16x16x32_bf16 v[12:15], v[204:207], v[220:223], v[12:15]
	v_mfma_f32_16x16x32_bf16 v[8:11], v[204:207], v[228:231], v[8:11]
	v_mfma_f32_16x16x32_bf16 v[4:7], v[212:215], v[220:223], v[4:7]
	v_mfma_f32_16x16x32_bf16 v[0:3], v[212:215], v[228:231], v[0:3]
	s_barrier
	ds_read_b128 v[172:175], v156
	ds_read_b128 v[176:179], v156 offset:1024
	ds_read_b128 v[180:183], v156 offset:2048
	ds_read_b128 v[184:187], v156 offset:3072
	v_add_u32_e32 v168, 0x4000, v149
	v_add_u32_e32 v169, 0x6000, v149
	v_readfirstlane_b32 s51, v168
	v_lshl_add_u64 v[220:221], v[236:237], 0, s[26:27]
	s_mov_b32 m0, s51
	v_readfirstlane_b32 s51, v169
	ds_read_b128 v[188:191], v153 offset:32768
	ds_read_b128 v[192:195], v153 offset:33792
	ds_read_b128 v[196:199], v152 offset:32768
	ds_read_b128 v[200:203], v152 offset:33792
	ds_read_b128 v[204:207], v151 offset:32768
	ds_read_b128 v[208:211], v151 offset:33792
	ds_read_b128 v[212:215], v150 offset:32768
	ds_read_b128 v[216:219], v150 offset:33792
	global_load_lds_dwordx4 v[220:221], off
	v_lshl_add_u64 v[220:221], v[238:239], 0, s[26:27]
	s_mov_b32 m0, s51
	s_nop 0
	global_load_lds_dwordx4 v[220:221], off
	s_waitcnt lgkmcnt(8)
	s_barrier
	s_waitcnt lgkmcnt(0)
	s_waitcnt lgkmcnt(0)
	v_mfma_f32_16x16x32_bf16 v[124:127], v[188:191], v[172:175], v[124:127]
	v_mfma_f32_16x16x32_bf16 v[120:123], v[188:191], v[180:183], v[120:123]
	v_mfma_f32_16x16x32_bf16 v[116:119], v[196:199], v[172:175], v[116:119]
	v_mfma_f32_16x16x32_bf16 v[112:115], v[196:199], v[180:183], v[112:115]
	v_mfma_f32_16x16x32_bf16 v[108:111], v[204:207], v[172:175], v[108:111]
	v_mfma_f32_16x16x32_bf16 v[104:107], v[204:207], v[180:183], v[104:107]
	v_mfma_f32_16x16x32_bf16 v[100:103], v[212:215], v[172:175], v[100:103]
	v_mfma_f32_16x16x32_bf16 v[96:99], v[212:215], v[180:183], v[96:99]
	v_mfma_f32_16x16x32_bf16 v[124:127], v[192:195], v[176:179], v[124:127]
	v_mfma_f32_16x16x32_bf16 v[120:123], v[192:195], v[184:187], v[120:123]
	v_mfma_f32_16x16x32_bf16 v[116:119], v[200:203], v[176:179], v[116:119]
	v_mfma_f32_16x16x32_bf16 v[112:115], v[200:203], v[184:187], v[112:115]
	v_mfma_f32_16x16x32_bf16 v[108:111], v[208:211], v[176:179], v[108:111]
	v_mfma_f32_16x16x32_bf16 v[104:107], v[208:211], v[184:187], v[104:107]
	v_mfma_f32_16x16x32_bf16 v[100:103], v[216:219], v[176:179], v[100:103]
	v_mfma_f32_16x16x32_bf16 v[96:99], v[216:219], v[184:187], v[96:99]
	s_barrier
	v_readfirstlane_b32 s51, v157
	v_add_u32_e32 v246, 0x2000, v157
	v_lshl_add_u64 v[244:245], v[240:241], 0, s[36:37]
	s_mov_b32 m0, s51
	v_readfirstlane_b32 s51, v246
	ds_read_b128 v[220:223], v154
	ds_read_b128 v[224:227], v154 offset:1024
	ds_read_b128 v[228:231], v154 offset:2048
	ds_read_b128 v[232:235], v154 offset:3072
	global_load_lds_dwordx4 v[244:245], off
	v_lshl_add_u64 v[244:245], v[242:243], 0, s[36:37]
	s_mov_b32 m0, s51
	s_nop 0
	global_load_lds_dwordx4 v[244:245], off
	s_barrier
	s_waitcnt lgkmcnt(0)
	s_waitcnt lgkmcnt(0)
	v_mfma_f32_16x16x32_bf16 v[92:95], v[188:191], v[220:223], v[92:95]
	v_mfma_f32_16x16x32_bf16 v[88:91], v[188:191], v[228:231], v[88:91]
	v_mfma_f32_16x16x32_bf16 v[84:87], v[196:199], v[220:223], v[84:87]
	v_mfma_f32_16x16x32_bf16 v[80:83], v[196:199], v[228:231], v[80:83]
	v_mfma_f32_16x16x32_bf16 v[76:79], v[204:207], v[220:223], v[76:79]
	v_mfma_f32_16x16x32_bf16 v[72:75], v[204:207], v[228:231], v[72:75]
	v_mfma_f32_16x16x32_bf16 v[68:71], v[212:215], v[220:223], v[68:71]
	v_mfma_f32_16x16x32_bf16 v[64:67], v[212:215], v[228:231], v[64:67]
	v_mfma_f32_16x16x32_bf16 v[92:95], v[192:195], v[224:227], v[92:95]
	v_mfma_f32_16x16x32_bf16 v[88:91], v[192:195], v[232:235], v[88:91]
	v_mfma_f32_16x16x32_bf16 v[84:87], v[200:203], v[224:227], v[84:87]
	v_mfma_f32_16x16x32_bf16 v[80:83], v[200:203], v[232:235], v[80:83]
	v_mfma_f32_16x16x32_bf16 v[76:79], v[208:211], v[224:227], v[76:79]
	v_mfma_f32_16x16x32_bf16 v[72:75], v[208:211], v[232:235], v[72:75]
	v_mfma_f32_16x16x32_bf16 v[68:71], v[216:219], v[224:227], v[68:71]
	v_mfma_f32_16x16x32_bf16 v[64:67], v[216:219], v[232:235], v[64:67]
	s_barrier
	v_readfirstlane_b32 s51, v158
	v_lshl_add_u64 v[236:237], v[236:237], 0, s[38:39]
	s_mov_b32 m0, s51
	v_readfirstlane_b32 s51, v159
	ds_read_b128 v[188:191], v153 offset:49152
	ds_read_b128 v[192:195], v153 offset:50176
	ds_read_b128 v[196:199], v152 offset:49152
	ds_read_b128 v[200:203], v152 offset:50176
	ds_read_b128 v[204:207], v151 offset:49152
	ds_read_b128 v[208:211], v151 offset:50176
	ds_read_b128 v[212:215], v150 offset:49152
	ds_read_b128 v[216:219], v150 offset:50176
	global_load_lds_dwordx4 v[236:237], off
	v_lshl_add_u64 v[236:237], v[238:239], 0, s[38:39]
	s_mov_b32 m0, s51
	s_nop 0
	global_load_lds_dwordx4 v[236:237], off
	s_barrier
; #define STAGE(P, BASE, LD, br, kt) do { const char* _g = (const char*)((BASE) + (size_t)(br) * (LD) + (size_t)(kt) * 64); \
;     for (int _i = 0; _i < 2; ++_i) { int _b = tidx * 16 + _i * 8192; int _r, _c; stage_rc(_b, _r, _c); \
;       __builtin_amdgcn_global_load_lds((const unsigned*)(_g + (unsigned)((_r * (LD) + _c) * 2)), (unsigned*)((char*)(P) + _b), 16, 0, 0); } } while (0)
; #define LDA(dst, b, h) for (int m = 0; m < 4; ++m) for (int k = 0; k < 2; ++k) \
;     dst[m][k] = *reinterpret_cast<const bf16x8*>((char*)SA(b, h) + lds_byte(wr * 64 + m * 16 + fr, k * 32 + fq * 8))
; #define LDB(dst, b, h) for (int n = 0; n < 2; ++n) for (int k = 0; k < 2; ++k) \
;     dst[n][k] = *reinterpret_cast<const bf16x8*>((char*)SB(b, h) + lds_byte(wc * 32 + n * 16 + fr, k * 32 + fq * 8))
; #define MMA(ai, bj, At_, Bt_) do { __builtin_amdgcn_s_setprio(1); \
;     for (int k = 0; k < 2; ++k) for (int m = 0; m < 4; ++m) for (int n = 0; n < 2; ++n) \
;       acc[ai][bj][m][n] = __builtin_amdgcn_mfma_f32_16x16x32_bf16(At_[m][k], Bt_[n][k], acc[ai][bj][m][n], 0, 0, 0); \
;     __builtin_amdgcn_s_setprio(0); } while (0)
; #define WAIT_V(n) asm volatile("s_waitcnt vmcnt(" #n ")" ::: "memory")
; #define WAIT_L(n) asm volatile("s_waitcnt lgkmcnt(" #n ")" ::: "memory")
; #define BAR __builtin_amdgcn_s_barrier()
; #define SCHED __builtin_amdgcn_sched_barrier(0)
; template <int EPI, int lda, int ldb, int N, int K>
; __device__ __forceinline__ void gemm_phase(const u16* __restrict__ A, const u16* __restrict__ Bt, const GemmEpi ep, int wv) {
;     ...
;       BAR; WAIT_L(0); MMA(1, 0, At, B0); BAR; SCHED;
;       STAGE(SB(1, 1), Bt, ldb, bcol + HALF, t + 3);
;       WAIT_V(6); BAR; MMA(1, 1, At, B1); BAR;
;     }
;     { LDB(B0, 0, 0); LDA(At, 0, 0); STAGE(SA(1, 1), Ab, lda, brow + HALF, nt - 1);
;       BAR; WAIT_L(0); MMA(0, 0, At, B0); BAR;
;       LDB(B1, 0, 1); BAR; WAIT_L(0); MMA(0, 1, At, B1); BAR;
	s_waitcnt lgkmcnt(0)
	s_waitcnt lgkmcnt(0)
	v_mfma_f32_16x16x32_bf16 v[60:63], v[188:191], v[172:175], v[60:63]
	v_mfma_f32_16x16x32_bf16 v[56:59], v[188:191], v[180:183], v[56:59]
	v_mfma_f32_16x16x32_bf16 v[52:55], v[196:199], v[172:175], v[52:55]
	v_mfma_f32_16x16x32_bf16 v[48:51], v[196:199], v[180:183], v[48:51]
	v_mfma_f32_16x16x32_bf16 v[44:47], v[204:207], v[172:175], v[44:47]
	v_mfma_f32_16x16x32_bf16 v[40:43], v[204:207], v[180:183], v[40:43]
	v_mfma_f32_16x16x32_bf16 v[36:39], v[212:215], v[172:175], v[36:39]
	v_mfma_f32_16x16x32_bf16 v[32:35], v[212:215], v[180:183], v[32:35]
	v_mfma_f32_16x16x32_bf16 v[60:63], v[192:195], v[176:179], v[60:63]
	v_mfma_f32_16x16x32_bf16 v[56:59], v[192:195], v[184:187], v[56:59]
	v_mfma_f32_16x16x32_bf16 v[52:55], v[200:203], v[176:179], v[52:55]
	v_mfma_f32_16x16x32_bf16 v[48:51], v[200:203], v[184:187], v[48:51]
	v_mfma_f32_16x16x32_bf16 v[44:47], v[208:211], v[176:179], v[44:47]
	v_mfma_f32_16x16x32_bf16 v[40:43], v[208:211], v[184:187], v[40:43]
	v_mfma_f32_16x16x32_bf16 v[36:39], v[216:219], v[176:179], v[36:39]
	v_mfma_f32_16x16x32_bf16 v[32:35], v[216:219], v[184:187], v[32:35]
	s_barrier
	v_readfirstlane_b32 s51, v160
	v_add_u32_e32 v174, 0x2000, v160
	v_lshl_add_u64 v[172:173], v[240:241], 0, s[42:43]
	s_mov_b32 m0, s51
	v_readfirstlane_b32 s51, v174
	global_load_lds_dwordx4 v[172:173], off
	v_lshl_add_u64 v[172:173], v[242:243], 0, s[42:43]
	s_mov_b32 m0, s51
	s_nop 0
	global_load_lds_dwordx4 v[172:173], off
	s_add_i32 s50, s50, 2
	s_add_u32 s48, s48, 0x100
	s_addc_u32 s49, s49, 0
	s_cmp_gt_u32 s50, 27
	s_waitcnt vmcnt(6)
	s_barrier
	v_mfma_f32_16x16x32_bf16 v[28:31], v[188:191], v[220:223], v[28:31]
	v_mfma_f32_16x16x32_bf16 v[24:27], v[188:191], v[228:231], v[24:27]
	v_mfma_f32_16x16x32_bf16 v[20:23], v[196:199], v[220:223], v[20:23]
	v_mfma_f32_16x16x32_bf16 v[16:19], v[196:199], v[228:231], v[16:19]
	v_mfma_f32_16x16x32_bf16 v[12:15], v[204:207], v[220:223], v[12:15]
	v_mfma_f32_16x16x32_bf16 v[8:11], v[204:207], v[228:231], v[8:11]
	v_mfma_f32_16x16x32_bf16 v[4:7], v[212:215], v[220:223], v[4:7]
	v_mfma_f32_16x16x32_bf16 v[0:3], v[212:215], v[228:231], v[0:3]
	v_mfma_f32_16x16x32_bf16 v[28:31], v[192:195], v[224:227], v[28:31]
	v_mfma_f32_16x16x32_bf16 v[24:27], v[192:195], v[232:235], v[24:27]
	v_mfma_f32_16x16x32_bf16 v[20:23], v[200:203], v[224:227], v[20:23]
	v_mfma_f32_16x16x32_bf16 v[16:19], v[200:203], v[232:235], v[16:19]
	v_mfma_f32_16x16x32_bf16 v[12:15], v[208:211], v[224:227], v[12:15]
	v_mfma_f32_16x16x32_bf16 v[8:11], v[208:211], v[232:235], v[8:11]
	v_mfma_f32_16x16x32_bf16 v[4:7], v[216:219], v[224:227], v[4:7]
	v_mfma_f32_16x16x32_bf16 v[0:3], v[216:219], v[232:235], v[0:3]
	s_barrier
	s_cbranch_scc0 .LBB0_340
	s_add_i32 s48, s46, 0x80
	s_mul_hi_i32 s49, s48, 0x1080
	s_mulk_i32 s48, 0x1080
	s_add_u32 s48, s31, s48
	s_addc_u32 s49, s56, s49
	v_lshl_add_u64 v[158:159], s[48:49], 0, v[128:129]
	v_readfirstlane_b32 s50, v170
	v_lshl_add_u64 v[158:159], v[158:159], 0, s[44:45]
	s_mov_b32 m0, s50
	ds_read_b128 v[134:137], v162
	ds_read_b128 v[138:141], v162 offset:1024
	ds_read_b128 v[172:175], v162 offset:2048
	ds_read_b128 v[176:179], v162 offset:3072
	ds_read_b128 v[180:183], v153
	ds_read_b128 v[184:187], v153 offset:1024
	ds_read_b128 v[188:191], v152
	ds_read_b128 v[192:195], v152 offset:1024
	ds_read_b128 v[196:199], v151
	ds_read_b128 v[200:203], v151 offset:1024
	ds_read_b128 v[204:207], v150
	ds_read_b128 v[208:211], v150 offset:1024
	global_load_lds_dwordx4 v[158:159], off
	v_lshl_add_u64 v[158:159], s[48:49], 0, v[132:133]
	v_readfirstlane_b32 s48, v171
	v_lshl_add_u64 v[158:159], v[158:159], 0, s[44:45]
	s_mov_b32 m0, s48
	s_nop 0
	global_load_lds_dwordx4 v[158:159], off
	s_barrier
	s_waitcnt lgkmcnt(0)
	s_waitcnt lgkmcnt(0)
	v_mfma_f32_16x16x32_bf16 v[124:127], v[180:183], v[134:137], v[124:127]
	v_mfma_f32_16x16x32_bf16 v[120:123], v[180:183], v[172:175], v[120:123]
	v_mfma_f32_16x16x32_bf16 v[116:119], v[188:191], v[134:137], v[116:119]
	v_mfma_f32_16x16x32_bf16 v[112:115], v[188:191], v[172:175], v[112:115]
	v_mfma_f32_16x16x32_bf16 v[108:111], v[196:199], v[134:137], v[108:111]
	v_mfma_f32_16x16x32_bf16 v[104:107], v[196:199], v[172:175], v[104:107]
	v_mfma_f32_16x16x32_bf16 v[100:103], v[204:207], v[134:137], v[100:103]
	v_mfma_f32_16x16x32_bf16 v[96:99], v[204:207], v[172:175], v[96:99]
	v_mfma_f32_16x16x32_bf16 v[124:127], v[184:187], v[138:141], v[124:127]
	v_mfma_f32_16x16x32_bf16 v[120:123], v[184:187], v[176:179], v[120:123]
	v_mfma_f32_16x16x32_bf16 v[116:119], v[192:195], v[138:141], v[116:119]
	v_mfma_f32_16x16x32_bf16 v[112:115], v[192:195], v[176:179], v[112:115]
	v_mfma_f32_16x16x32_bf16 v[108:111], v[200:203], v[138:141], v[108:111]
	v_mfma_f32_16x16x32_bf16 v[104:107], v[200:203], v[176:179], v[104:107]
	v_mfma_f32_16x16x32_bf16 v[100:103], v[208:211], v[138:141], v[100:103]
	v_mfma_f32_16x16x32_bf16 v[96:99], v[208:211], v[176:179], v[96:99]
	s_barrier
	ds_read_b128 v[212:215], v161
	ds_read_b128 v[216:219], v161 offset:1024
	ds_read_b128 v[220:223], v161 offset:2048
	ds_read_b128 v[158:161], v161 offset:3072
	s_barrier
; #define LDA(dst, b, h) for (int m = 0; m < 4; ++m) for (int k = 0; k < 2; ++k) \
;     dst[m][k] = *reinterpret_cast<const bf16x8*>((char*)SA(b, h) + lds_byte(wr * 64 + m * 16 + fr, k * 32 + fq * 8))
; #define LDB(dst, b, h) for (int n = 0; n < 2; ++n) for (int k = 0; k < 2; ++k) \
;     dst[n][k] = *reinterpret_cast<const bf16x8*>((char*)SB(b, h) + lds_byte(wc * 32 + n * 16 + fr, k * 32 + fq * 8))
; #define MMA(ai, bj, At_, Bt_) do { __builtin_amdgcn_s_setprio(1); \
;     for (int k = 0; k < 2; ++k) for (int m = 0; m < 4; ++m) for (int n = 0; n < 2; ++n) \
;       acc[ai][bj][m][n] = __builtin_amdgcn_mfma_f32_16x16x32_bf16(At_[m][k], Bt_[n][k], acc[ai][bj][m][n], 0, 0, 0); \
;     __builtin_amdgcn_s_setprio(0); } while (0)
; #define WAIT_V(n) asm volatile("s_waitcnt vmcnt(" #n ")" ::: "memory")
; #define WAIT_L(n) asm volatile("s_waitcnt lgkmcnt(" #n ")" ::: "memory")
; #define BAR __builtin_amdgcn_s_barrier()
; template <int EPI, int lda, int ldb, int N, int K>
; __device__ __forceinline__ void gemm_phase(const u16* __restrict__ A, const u16* __restrict__ Bt, const GemmEpi ep, int wv) {
;     ...
;       LDB(B1, 0, 1); BAR; WAIT_L(0); MMA(0, 1, At, B1); BAR;
;       LDA(At, 0, 1); WAIT_V(4); BAR; WAIT_L(0); MMA(1, 0, At, B0); MMA(1, 1, At, B1); BAR; }
;     { LDB(B0, 1, 0); LDA(At, 1, 0); WAIT_V(2); BAR; WAIT_L(0); MMA(0, 0, At, B0); BAR;
	s_waitcnt lgkmcnt(0)
	s_waitcnt lgkmcnt(0)
	v_mfma_f32_16x16x32_bf16 v[92:95], v[180:183], v[212:215], v[92:95]
	v_mfma_f32_16x16x32_bf16 v[88:91], v[180:183], v[220:223], v[88:91]
	v_mfma_f32_16x16x32_bf16 v[76:79], v[196:199], v[212:215], v[76:79]
	v_mfma_f32_16x16x32_bf16 v[72:75], v[196:199], v[220:223], v[72:75]
	v_mfma_f32_16x16x32_bf16 v[68:71], v[204:207], v[212:215], v[68:71]
	v_mfma_f32_16x16x32_bf16 v[64:67], v[204:207], v[220:223], v[64:67]
	v_mfma_f32_16x16x32_bf16 v[84:87], v[188:191], v[212:215], v[84:87]
	v_mfma_f32_16x16x32_bf16 v[80:83], v[188:191], v[220:223], v[80:83]
	v_mfma_f32_16x16x32_bf16 v[92:95], v[184:187], v[216:219], v[92:95]
	v_mfma_f32_16x16x32_bf16 v[88:91], v[184:187], v[158:161], v[88:91]
	v_mfma_f32_16x16x32_bf16 v[76:79], v[200:203], v[216:219], v[76:79]
	v_mfma_f32_16x16x32_bf16 v[72:75], v[200:203], v[158:161], v[72:75]
	v_mfma_f32_16x16x32_bf16 v[68:71], v[208:211], v[216:219], v[68:71]
	v_mfma_f32_16x16x32_bf16 v[64:67], v[208:211], v[158:161], v[64:67]
	v_mfma_f32_16x16x32_bf16 v[180:183], v[192:195], v[216:219], v[84:87]
	v_mfma_f32_16x16x32_bf16 v[184:187], v[192:195], v[158:161], v[80:83]
	s_barrier
	s_nop 0
	ds_read_b128 v[80:83], v153 offset:16384
	ds_read_b128 v[84:87], v153 offset:17408
	ds_read_b128 v[188:191], v152 offset:16384
	ds_read_b128 v[192:195], v152 offset:17408
	ds_read_b128 v[196:199], v151 offset:16384
	ds_read_b128 v[200:203], v151 offset:17408
	ds_read_b128 v[204:207], v150 offset:16384
	ds_read_b128 v[208:211], v150 offset:17408
	s_waitcnt vmcnt(4)
	s_barrier
	s_waitcnt lgkmcnt(0)
	s_waitcnt lgkmcnt(0)
	v_mfma_f32_16x16x32_bf16 v[60:63], v[80:83], v[134:137], v[60:63]
	v_mfma_f32_16x16x32_bf16 v[44:47], v[196:199], v[134:137], v[44:47]
	v_mfma_f32_16x16x32_bf16 v[40:43], v[196:199], v[172:175], v[40:43]
	v_mfma_f32_16x16x32_bf16 v[36:39], v[204:207], v[134:137], v[36:39]
	v_mfma_f32_16x16x32_bf16 v[32:35], v[204:207], v[172:175], v[32:35]
	v_mfma_f32_16x16x32_bf16 v[56:59], v[80:83], v[172:175], v[56:59]
	v_mfma_f32_16x16x32_bf16 v[52:55], v[188:191], v[134:137], v[52:55]
	v_mfma_f32_16x16x32_bf16 v[48:51], v[188:191], v[172:175], v[48:51]
	v_mfma_f32_16x16x32_bf16 v[60:63], v[84:87], v[138:141], v[60:63]
	v_mfma_f32_16x16x32_bf16 v[44:47], v[200:203], v[138:141], v[44:47]
	v_mfma_f32_16x16x32_bf16 v[40:43], v[200:203], v[176:179], v[40:43]
	v_mfma_f32_16x16x32_bf16 v[36:39], v[208:211], v[138:141], v[36:39]
	v_mfma_f32_16x16x32_bf16 v[32:35], v[208:211], v[176:179], v[32:35]
	v_mfma_f32_16x16x32_bf16 v[134:137], v[84:87], v[176:179], v[56:59]
	v_mfma_f32_16x16x32_bf16 v[170:173], v[192:195], v[138:141], v[52:55]
	v_mfma_f32_16x16x32_bf16 v[224:227], v[192:195], v[176:179], v[48:51]
	v_mfma_f32_16x16x32_bf16 v[28:31], v[80:83], v[212:215], v[28:31]
	v_mfma_f32_16x16x32_bf16 v[20:23], v[188:191], v[212:215], v[20:23]
	v_mfma_f32_16x16x32_bf16 v[12:15], v[196:199], v[212:215], v[12:15]
	v_mfma_f32_16x16x32_bf16 v[4:7], v[204:207], v[212:215], v[4:7]
	v_mfma_f32_16x16x32_bf16 v[24:27], v[80:83], v[220:223], v[24:27]
	v_mfma_f32_16x16x32_bf16 v[16:19], v[188:191], v[220:223], v[16:19]
	v_mfma_f32_16x16x32_bf16 v[8:11], v[196:199], v[220:223], v[8:11]
	v_mfma_f32_16x16x32_bf16 v[0:3], v[204:207], v[220:223], v[0:3]
	v_mfma_f32_16x16x32_bf16 v[28:31], v[84:87], v[216:219], v[28:31]
	v_mfma_f32_16x16x32_bf16 v[20:23], v[192:195], v[216:219], v[20:23]
	v_mfma_f32_16x16x32_bf16 v[12:15], v[200:203], v[216:219], v[12:15]
	v_mfma_f32_16x16x32_bf16 v[4:7], v[208:211], v[216:219], v[4:7]
	v_mfma_f32_16x16x32_bf16 v[138:141], v[84:87], v[158:161], v[24:27]
	v_mfma_f32_16x16x32_bf16 v[174:177], v[192:195], v[158:161], v[16:19]
	v_mfma_f32_16x16x32_bf16 v[188:191], v[200:203], v[158:161], v[8:11]
	v_mfma_f32_16x16x32_bf16 v[158:161], v[208:211], v[158:161], v[0:3]
	s_barrier
	s_nop 0
	ds_read_b128 v[0:3], v156
	ds_read_b128 v[8:11], v156 offset:1024
	ds_read_b128 v[16:19], v156 offset:2048
	ds_read_b128 v[192:195], v156 offset:3072
	ds_read_b128 v[24:27], v153 offset:32768
	ds_read_b128 v[56:59], v153 offset:33792
	ds_read_b128 v[196:199], v152 offset:32768
	ds_read_b128 v[200:203], v152 offset:33792
	ds_read_b128 v[204:207], v151 offset:32768
	ds_read_b128 v[208:211], v151 offset:33792
	ds_read_b128 v[212:215], v150 offset:32768
	ds_read_b128 v[216:219], v150 offset:33792
	s_waitcnt vmcnt(2)
	s_barrier
; #define LDA(dst, b, h) for (int m = 0; m < 4; ++m) for (int k = 0; k < 2; ++k) \
;     dst[m][k] = *reinterpret_cast<const bf16x8*>((char*)SA(b, h) + lds_byte(wr * 64 + m * 16 + fr, k * 32 + fq * 8))
; #define LDB(dst, b, h) for (int n = 0; n < 2; ++n) for (int k = 0; k < 2; ++k) \
;     dst[n][k] = *reinterpret_cast<const bf16x8*>((char*)SB(b, h) + lds_byte(wc * 32 + n * 16 + fr, k * 32 + fq * 8))
; #define MMA(ai, bj, At_, Bt_) do { __builtin_amdgcn_s_setprio(1); \
;     for (int k = 0; k < 2; ++k) for (int m = 0; m < 4; ++m) for (int n = 0; n < 2; ++n) \
;       acc[ai][bj][m][n] = __builtin_amdgcn_mfma_f32_16x16x32_bf16(At_[m][k], Bt_[n][k], acc[ai][bj][m][n], 0, 0, 0); \
;     __builtin_amdgcn_s_setprio(0); } while (0)
; #define WAIT_V(n) asm volatile("s_waitcnt vmcnt(" #n ")" ::: "memory")
; #define WAIT_L(n) asm volatile("s_waitcnt lgkmcnt(" #n ")" ::: "memory")
; #define BAR __builtin_amdgcn_s_barrier()
; template <int EPI, int lda, int ldb, int N, int K>
; __device__ __forceinline__ void gemm_phase(const u16* __restrict__ A, const u16* __restrict__ Bt, const GemmEpi ep, int wv) {
;     ...
;     { LDB(B0, 1, 0); LDA(At, 1, 0); WAIT_V(2); BAR; WAIT_L(0); MMA(0, 0, At, B0); BAR;
;       LDB(B1, 1, 1); WAIT_V(0); BAR; WAIT_L(0); MMA(0, 1, At, B1); BAR;
;       LDA(At, 1, 1); BAR; WAIT_L(0); MMA(1, 0, At, B0); MMA(1, 1, At, B1); BAR; }
;     if (wr == 0) BAR;
	s_waitcnt lgkmcnt(0)
	s_waitcnt lgkmcnt(0)
	v_mfma_f32_16x16x32_bf16 v[48:51], v[24:27], v[0:3], v[124:127]
	v_mfma_f32_16x16x32_bf16 v[52:55], v[24:27], v[16:19], v[120:123]
	v_mfma_f32_16x16x32_bf16 v[80:83], v[196:199], v[0:3], v[116:119]
	v_mfma_f32_16x16x32_bf16 v[84:87], v[196:199], v[16:19], v[112:115]
	v_mfma_f32_16x16x32_bf16 v[108:111], v[204:207], v[0:3], v[108:111]
	v_mfma_f32_16x16x32_bf16 v[104:107], v[204:207], v[16:19], v[104:107]
	v_mfma_f32_16x16x32_bf16 v[112:115], v[212:215], v[0:3], v[100:103]
	v_mfma_f32_16x16x32_bf16 v[120:123], v[212:215], v[16:19], v[96:99]
	v_mfma_f32_16x16x32_bf16 v[124:127], v[56:59], v[8:11], v[48:51]
	v_mfma_f32_16x16x32_bf16 v[116:119], v[56:59], v[192:195], v[52:55]
	v_mfma_f32_16x16x32_bf16 v[100:103], v[200:203], v[8:11], v[80:83]
	v_mfma_f32_16x16x32_bf16 v[96:99], v[200:203], v[192:195], v[84:87]
	v_mfma_f32_16x16x32_bf16 v[84:87], v[208:211], v[8:11], v[108:111]
	v_mfma_f32_16x16x32_bf16 v[80:83], v[208:211], v[192:195], v[104:107]
	v_mfma_f32_16x16x32_bf16 v[52:55], v[216:219], v[8:11], v[112:115]
	v_mfma_f32_16x16x32_bf16 v[48:51], v[216:219], v[192:195], v[120:123]
	s_barrier
	ds_read_b128 v[220:223], v154
	ds_read_b128 v[228:231], v154 offset:1024
	ds_read_b128 v[232:235], v154 offset:2048
	ds_read_b128 v[154:157], v154 offset:3072
	s_waitcnt vmcnt(0)
	s_barrier
	s_waitcnt lgkmcnt(0)
	s_waitcnt lgkmcnt(0)
	v_mfma_f32_16x16x32_bf16 v[92:95], v[24:27], v[220:223], v[92:95]
	v_mfma_f32_16x16x32_bf16 v[24:27], v[24:27], v[232:235], v[88:91]
	v_mfma_f32_16x16x32_bf16 v[88:91], v[196:199], v[220:223], v[180:183]
	v_mfma_f32_16x16x32_bf16 v[104:107], v[196:199], v[232:235], v[184:187]
	v_mfma_f32_16x16x32_bf16 v[76:79], v[204:207], v[220:223], v[76:79]
	v_mfma_f32_16x16x32_bf16 v[72:75], v[204:207], v[232:235], v[72:75]
	v_mfma_f32_16x16x32_bf16 v[68:71], v[212:215], v[220:223], v[68:71]
	v_mfma_f32_16x16x32_bf16 v[64:67], v[212:215], v[232:235], v[64:67]
	v_mfma_f32_16x16x32_bf16 v[120:123], v[56:59], v[228:231], v[92:95]
	v_mfma_f32_16x16x32_bf16 v[112:115], v[56:59], v[154:157], v[24:27]
	v_mfma_f32_16x16x32_bf16 v[108:111], v[200:203], v[228:231], v[88:91]
	v_mfma_f32_16x16x32_bf16 v[104:107], v[200:203], v[154:157], v[104:107]
	v_mfma_f32_16x16x32_bf16 v[92:95], v[208:211], v[228:231], v[76:79]
	v_mfma_f32_16x16x32_bf16 v[88:91], v[208:211], v[154:157], v[72:75]
	v_mfma_f32_16x16x32_bf16 v[68:71], v[216:219], v[228:231], v[68:71]
	v_mfma_f32_16x16x32_bf16 v[56:59], v[216:219], v[154:157], v[64:67]
	s_barrier
	s_nop 0
	ds_read_b128 v[64:67], v153 offset:49152
	ds_read_b128 v[178:181], v153 offset:50176
	ds_read_b128 v[76:79], v152 offset:49152
	ds_read_b128 v[182:185], v152 offset:50176
	ds_read_b128 v[196:199], v151 offset:49152
	ds_read_b128 v[200:203], v151 offset:50176
	ds_read_b128 v[204:207], v150 offset:49152
	ds_read_b128 v[150:153], v150 offset:50176
	s_barrier
	s_waitcnt lgkmcnt(0)
	s_waitcnt lgkmcnt(0)
	v_mfma_f32_16x16x32_bf16 v[24:27], v[64:67], v[0:3], v[60:63]
	v_mfma_f32_16x16x32_bf16 v[60:63], v[64:67], v[16:19], v[134:137]
	v_mfma_f32_16x16x32_bf16 v[134:137], v[76:79], v[0:3], v[170:173]
	v_mfma_f32_16x16x32_bf16 v[170:173], v[76:79], v[16:19], v[224:227]
	v_mfma_f32_16x16x32_bf16 v[44:47], v[196:199], v[0:3], v[44:47]
	v_mfma_f32_16x16x32_bf16 v[208:211], v[196:199], v[16:19], v[40:43]
	v_mfma_f32_16x16x32_bf16 v[0:3], v[204:207], v[0:3], v[36:39]
	v_mfma_f32_16x16x32_bf16 v[36:39], v[204:207], v[16:19], v[32:35]
	v_mfma_f32_16x16x32_bf16 v[72:75], v[178:181], v[8:11], v[24:27]
	v_mfma_f32_16x16x32_bf16 v[60:63], v[178:181], v[192:195], v[60:63]
	v_mfma_f32_16x16x32_bf16 v[40:43], v[182:185], v[8:11], v[134:137]
	v_mfma_f32_16x16x32_bf16 v[32:35], v[182:185], v[192:195], v[170:173]
	v_mfma_f32_16x16x32_bf16 v[24:27], v[200:203], v[8:11], v[44:47]
	v_mfma_f32_16x16x32_bf16 v[16:19], v[200:203], v[192:195], v[208:211]
	v_mfma_f32_16x16x32_bf16 v[8:11], v[150:153], v[8:11], v[0:3]
	v_mfma_f32_16x16x32_bf16 v[0:3], v[150:153], v[192:195], v[36:39]
	v_mfma_f32_16x16x32_bf16 v[28:31], v[64:67], v[220:223], v[28:31]
	v_mfma_f32_16x16x32_bf16 v[36:39], v[64:67], v[232:235], v[138:141]
	v_mfma_f32_16x16x32_bf16 v[20:23], v[76:79], v[220:223], v[20:23]
	v_mfma_f32_16x16x32_bf16 v[134:137], v[76:79], v[232:235], v[174:177]
	v_mfma_f32_16x16x32_bf16 v[12:15], v[196:199], v[220:223], v[12:15]
	v_mfma_f32_16x16x32_bf16 v[138:141], v[196:199], v[232:235], v[188:191]
	v_mfma_f32_16x16x32_bf16 v[4:7], v[204:207], v[220:223], v[4:7]
	v_mfma_f32_16x16x32_bf16 v[158:161], v[204:207], v[232:235], v[158:161]
	v_mfma_f32_16x16x32_bf16 v[76:79], v[178:181], v[228:231], v[28:31]
	v_mfma_f32_16x16x32_bf16 v[64:67], v[178:181], v[154:157], v[36:39]
	v_mfma_f32_16x16x32_bf16 v[44:47], v[182:185], v[228:231], v[20:23]
	v_mfma_f32_16x16x32_bf16 v[36:39], v[182:185], v[154:157], v[134:137]
	v_mfma_f32_16x16x32_bf16 v[28:31], v[200:203], v[228:231], v[12:15]
	v_mfma_f32_16x16x32_bf16 v[20:23], v[200:203], v[154:157], v[138:141]
	v_mfma_f32_16x16x32_bf16 v[12:15], v[150:153], v[228:231], v[4:7]
	v_mfma_f32_16x16x32_bf16 v[4:7], v[150:153], v[154:157], v[158:161]
	v_cmp_gt_u32_e32 vcc, s64, v130
	s_barrier
	s_and_saveexec_b64 s[48:49], vcc
	s_cbranch_execz .LBB0_343
	s_barrier

; #define STAGE(P, BASE, LD, br, kt) do { const char* _g = (const char*)((BASE) + (size_t)(br) * (LD) + (size_t)(kt) * 64); \
;     for (int _i = 0; _i < 2; ++_i) { int _b = tidx * 16 + _i * 8192; int _r, _c; stage_rc(_b, _r, _c); \
;       __builtin_amdgcn_global_load_lds((const unsigned*)(_g + (unsigned)((_r * (LD) + _c) * 2)), (unsigned*)((char*)(P) + _b), 16, 0, 0); } } while (0)
; #define LDA(dst, b, h) for (int m = 0; m < 4; ++m) for (int k = 0; k < 2; ++k) \
;     dst[m][k] = *reinterpret_cast<const bf16x8*>((char*)SA(b, h) + lds_byte(wr * 64 + m * 16 + fr, k * 32 + fq * 8))
; #define LDB(dst, b, h) for (int n = 0; n < 2; ++n) for (int k = 0; k < 2; ++k) \
;     dst[n][k] = *reinterpret_cast<const bf16x8*>((char*)SB(b, h) + lds_byte(wc * 32 + n * 16 + fr, k * 32 + fq * 8))
; #define MMA(ai, bj, At_, Bt_) do { __builtin_amdgcn_s_setprio(1); \
;     for (int k = 0; k < 2; ++k) for (int m = 0; m < 4; ++m) for (int n = 0; n < 2; ++n) \
;       acc[ai][bj][m][n] = __builtin_amdgcn_mfma_f32_16x16x32_bf16(At_[m][k], Bt_[n][k], acc[ai][bj][m][n], 0, 0, 0); \
;     __builtin_amdgcn_s_setprio(0); } while (0)
; #define WAIT_L(n) asm volatile("s_waitcnt lgkmcnt(" #n ")" ::: "memory")
; #define BAR __builtin_amdgcn_s_barrier()
; #define SCHED __builtin_amdgcn_sched_barrier(0)
; template <int EPI, int lda, int ldb, int N, int K>
; __device__ __forceinline__ void gemm_phase(const u16* __restrict__ A, const u16* __restrict__ Bt, const GemmEpi ep, int wv) {
;     ...
;     for (int t = 0; t < nt - 2; t += 2) {
;       LDB(B0, 0, 0); SCHED; LDA(At, 0, 0); STAGE(SA(1, 1), Ab, lda, brow + HALF, t + 1);
;       WAIT_L(8); BAR; WAIT_L(0); MMA(0, 0, At, B0); BAR; SCHED;
;       LDB(B1, 0, 1); STAGE(SB(0, 0), Bt, ldb, bcol, t + 2);
;       BAR; WAIT_L(0); MMA(0, 1, At, B1); BAR;
;       LDA(At, 0, 1); STAGE(SA(0, 0), Ab, lda, brow, t + 2);
;       BAR; WAIT_L(0); MMA(1, 0, At, B0); BAR; SCHED;
.LBB0_654:
	ds_read_b128 v[164:167], v160
	ds_read_b128 v[170:173], v160 offset:1024
	ds_read_b128 v[174:177], v160 offset:2048
	ds_read_b128 v[178:181], v160 offset:3072
	v_add_u32_e32 v168, 0xc000, v143
	v_lshl_add_u64 v[234:235], v[138:139], 0, s[52:53]
	v_readfirstlane_b32 s55, v168
	v_add_u32_e32 v169, 0xe000, v143
	v_lshl_add_u64 v[162:163], v[234:235], 0, s[20:21]
	s_mov_b32 m0, s55
	v_lshl_add_u64 v[236:237], v[140:141], 0, s[52:53]
	v_readfirstlane_b32 s55, v169
	ds_read_b128 v[182:185], v151
	ds_read_b128 v[186:189], v151 offset:1024
	ds_read_b128 v[190:193], v150
	ds_read_b128 v[194:197], v150 offset:1024
	ds_read_b128 v[198:201], v149
	ds_read_b128 v[202:205], v149 offset:1024
	ds_read_b128 v[206:209], v148
	ds_read_b128 v[210:213], v148 offset:1024
	global_load_lds_dwordx4 v[162:163], off
	v_lshl_add_u64 v[162:163], v[236:237], 0, s[20:21]
	s_mov_b32 m0, s55
	s_nop 0
	global_load_lds_dwordx4 v[162:163], off
	s_waitcnt lgkmcnt(8)
	s_barrier
	s_waitcnt lgkmcnt(0)
	s_waitcnt lgkmcnt(0)
	v_mfma_f32_16x16x32_bf16 v[124:127], v[164:167], v[182:185], v[124:127]
	v_mfma_f32_16x16x32_bf16 v[120:123], v[174:177], v[182:185], v[120:123]
	v_mfma_f32_16x16x32_bf16 v[116:119], v[164:167], v[190:193], v[116:119]
	v_mfma_f32_16x16x32_bf16 v[112:115], v[174:177], v[190:193], v[112:115]
	v_mfma_f32_16x16x32_bf16 v[108:111], v[164:167], v[198:201], v[108:111]
	v_mfma_f32_16x16x32_bf16 v[104:107], v[174:177], v[198:201], v[104:107]
	v_mfma_f32_16x16x32_bf16 v[100:103], v[164:167], v[206:209], v[100:103]
	v_mfma_f32_16x16x32_bf16 v[96:99], v[174:177], v[206:209], v[96:99]
	v_mfma_f32_16x16x32_bf16 v[124:127], v[170:173], v[186:189], v[124:127]
	v_mfma_f32_16x16x32_bf16 v[120:123], v[178:181], v[186:189], v[120:123]
	v_mfma_f32_16x16x32_bf16 v[116:119], v[170:173], v[194:197], v[116:119]
	v_mfma_f32_16x16x32_bf16 v[112:115], v[178:181], v[194:197], v[112:115]
	v_mfma_f32_16x16x32_bf16 v[108:111], v[170:173], v[202:205], v[108:111]
	v_mfma_f32_16x16x32_bf16 v[104:107], v[178:181], v[202:205], v[104:107]
	v_mfma_f32_16x16x32_bf16 v[100:103], v[170:173], v[210:213], v[100:103]
	v_mfma_f32_16x16x32_bf16 v[96:99], v[178:181], v[210:213], v[96:99]
	s_barrier
	v_add_u32_e32 v161, s65, v153
	v_lshl_add_u64 v[238:239], v[134:135], 0, s[52:53]
	v_readfirstlane_b32 s55, v161
	v_lshl_add_u64 v[162:163], v[238:239], 0, s[22:23]
	s_mov_b32 m0, s55
	ds_read_b128 v[214:217], v159
	ds_read_b128 v[218:221], v159 offset:1024
	ds_read_b128 v[222:225], v159 offset:2048
	ds_read_b128 v[226:229], v159 offset:3072
	global_load_lds_dwordx4 v[162:163], off
	v_add_u32_e32 v162, 0x2000, v161
	v_lshl_add_u64 v[240:241], v[136:137], 0, s[52:53]
	v_readfirstlane_b32 s55, v162
	v_lshl_add_u64 v[230:231], v[240:241], 0, s[22:23]
	s_mov_b32 m0, s55
	s_nop 0
	global_load_lds_dwordx4 v[230:231], off
	s_barrier
	s_waitcnt lgkmcnt(0)
	s_waitcnt lgkmcnt(0)
	v_mfma_f32_16x16x32_bf16 v[92:95], v[214:217], v[182:185], v[92:95]
	v_mfma_f32_16x16x32_bf16 v[88:91], v[222:225], v[182:185], v[88:91]
	v_mfma_f32_16x16x32_bf16 v[84:87], v[214:217], v[190:193], v[84:87]
	v_mfma_f32_16x16x32_bf16 v[80:83], v[222:225], v[190:193], v[80:83]
	v_mfma_f32_16x16x32_bf16 v[76:79], v[214:217], v[198:201], v[76:79]
	v_mfma_f32_16x16x32_bf16 v[72:75], v[222:225], v[198:201], v[72:75]
	v_mfma_f32_16x16x32_bf16 v[68:71], v[214:217], v[206:209], v[68:71]
	v_mfma_f32_16x16x32_bf16 v[64:67], v[222:225], v[206:209], v[64:67]
	v_mfma_f32_16x16x32_bf16 v[92:95], v[218:221], v[186:189], v[92:95]
	v_mfma_f32_16x16x32_bf16 v[88:91], v[226:229], v[186:189], v[88:91]
	v_mfma_f32_16x16x32_bf16 v[84:87], v[218:221], v[194:197], v[84:87]
	v_mfma_f32_16x16x32_bf16 v[80:83], v[226:229], v[194:197], v[80:83]
	v_mfma_f32_16x16x32_bf16 v[76:79], v[218:221], v[202:205], v[76:79]
	v_mfma_f32_16x16x32_bf16 v[72:75], v[226:229], v[202:205], v[72:75]
	v_mfma_f32_16x16x32_bf16 v[68:71], v[218:221], v[210:213], v[68:71]
	v_mfma_f32_16x16x32_bf16 v[64:67], v[226:229], v[210:213], v[64:67]
	s_barrier
	v_readfirstlane_b32 s55, v143
	v_add_u32_e32 v163, 0x2000, v143
	v_lshl_add_u64 v[230:231], v[234:235], 0, s[24:25]
	s_mov_b32 m0, s55
	v_readfirstlane_b32 s55, v163
	ds_read_b128 v[182:185], v151 offset:16384
	ds_read_b128 v[186:189], v151 offset:17408
	ds_read_b128 v[190:193], v150 offset:16384
	ds_read_b128 v[194:197], v150 offset:17408
	ds_read_b128 v[198:201], v149 offset:16384
	ds_read_b128 v[202:205], v149 offset:17408
	ds_read_b128 v[206:209], v148 offset:16384
	ds_read_b128 v[210:213], v148 offset:17408
	global_load_lds_dwordx4 v[230:231], off
	v_lshl_add_u64 v[230:231], v[236:237], 0, s[24:25]
	s_mov_b32 m0, s55
	s_nop 0
	global_load_lds_dwordx4 v[230:231], off
	s_barrier
	s_waitcnt lgkmcnt(0)
	s_waitcnt lgkmcnt(0)
	v_mfma_f32_16x16x32_bf16 v[60:63], v[164:167], v[182:185], v[60:63]
	v_mfma_f32_16x16x32_bf16 v[56:59], v[174:177], v[182:185], v[56:59]
	v_mfma_f32_16x16x32_bf16 v[52:55], v[164:167], v[190:193], v[52:55]
	v_mfma_f32_16x16x32_bf16 v[48:51], v[174:177], v[190:193], v[48:51]
	v_mfma_f32_16x16x32_bf16 v[44:47], v[164:167], v[198:201], v[44:47]
	v_mfma_f32_16x16x32_bf16 v[40:43], v[174:177], v[198:201], v[40:43]
	v_mfma_f32_16x16x32_bf16 v[36:39], v[164:167], v[206:209], v[36:39]
	v_mfma_f32_16x16x32_bf16 v[32:35], v[174:177], v[206:209], v[32:35]
	v_mfma_f32_16x16x32_bf16 v[60:63], v[170:173], v[186:189], v[60:63]
	v_mfma_f32_16x16x32_bf16 v[56:59], v[178:181], v[186:189], v[56:59]
	v_mfma_f32_16x16x32_bf16 v[52:55], v[170:173], v[194:197], v[52:55]
	v_mfma_f32_16x16x32_bf16 v[48:51], v[178:181], v[194:197], v[48:51]
	v_mfma_f32_16x16x32_bf16 v[44:47], v[170:173], v[202:205], v[44:47]
	v_mfma_f32_16x16x32_bf16 v[40:43], v[178:181], v[202:205], v[40:43]
	v_mfma_f32_16x16x32_bf16 v[36:39], v[170:173], v[210:213], v[36:39]
	v_mfma_f32_16x16x32_bf16 v[32:35], v[178:181], v[210:213], v[32:35]
	s_barrier
; #define STAGE(P, BASE, LD, br, kt) do { const char* _g = (const char*)((BASE) + (size_t)(br) * (LD) + (size_t)(kt) * 64); \
;     for (int _i = 0; _i < 2; ++_i) { int _b = tidx * 16 + _i * 8192; int _r, _c; stage_rc(_b, _r, _c); \
;       __builtin_amdgcn_global_load_lds((const unsigned*)(_g + (unsigned)((_r * (LD) + _c) * 2)), (unsigned*)((char*)(P) + _b), 16, 0, 0); } } while (0)
; #define LDA(dst, b, h) for (int m = 0; m < 4; ++m) for (int k = 0; k < 2; ++k) \
;     dst[m][k] = *reinterpret_cast<const bf16x8*>((char*)SA(b, h) + lds_byte(wr * 64 + m * 16 + fr, k * 32 + fq * 8))
; #define LDB(dst, b, h) for (int n = 0; n < 2; ++n) for (int k = 0; k < 2; ++k) \
;     dst[n][k] = *reinterpret_cast<const bf16x8*>((char*)SB(b, h) + lds_byte(wc * 32 + n * 16 + fr, k * 32 + fq * 8))
; #define MMA(ai, bj, At_, Bt_) do { __builtin_amdgcn_s_setprio(1); \
;     for (int k = 0; k < 2; ++k) for (int m = 0; m < 4; ++m) for (int n = 0; n < 2; ++n) \
;       acc[ai][bj][m][n] = __builtin_amdgcn_mfma_f32_16x16x32_bf16(At_[m][k], Bt_[n][k], acc[ai][bj][m][n], 0, 0, 0); \
;     __builtin_amdgcn_s_setprio(0); } while (0)
; #define WAIT_V(n) asm volatile("s_waitcnt vmcnt(" #n ")" ::: "memory")
; #define WAIT_L(n) asm volatile("s_waitcnt lgkmcnt(" #n ")" ::: "memory")
; #define BAR __builtin_amdgcn_s_barrier()
; #define SCHED __builtin_amdgcn_sched_barrier(0)
; template <int EPI, int lda, int ldb, int N, int K>
; __device__ __forceinline__ void gemm_phase(const u16* __restrict__ A, const u16* __restrict__ Bt, const GemmEpi ep, int wv) {
;     ...
;       STAGE(SB(0, 1), Bt, ldb, bcol + HALF, t + 2);
;       WAIT_V(6); BAR; MMA(1, 1, At, B1); BAR;
;       LDB(B0, 1, 0); SCHED; LDA(At, 1, 0); STAGE(SA(0, 1), Ab, lda, brow + HALF, t + 2);
;       WAIT_L(8); BAR; WAIT_L(0); MMA(0, 0, At, B0); BAR; SCHED;
;       LDB(B1, 1, 1); STAGE(SB(1, 0), Bt, ldb, bcol, t + 3);
;       BAR; WAIT_L(0); MMA(0, 1, At, B1); BAR;
;       LDA(At, 1, 1); STAGE(SA(1, 0), Ab, lda, brow, t + 3);
	v_add_u32_e32 v164, s66, v153
	v_add_u32_e32 v165, 0x2000, v164
	v_readfirstlane_b32 s55, v164
	v_lshl_add_u64 v[166:167], v[238:239], 0, s[26:27]
	s_mov_b32 m0, s55
	v_readfirstlane_b32 s55, v165
	global_load_lds_dwordx4 v[166:167], off
	v_lshl_add_u64 v[166:167], v[240:241], 0, s[26:27]
	s_mov_b32 m0, s55
	s_nop 0
	global_load_lds_dwordx4 v[166:167], off
	s_waitcnt vmcnt(6)
	s_barrier
	v_mfma_f32_16x16x32_bf16 v[28:31], v[214:217], v[182:185], v[28:31]
	v_mfma_f32_16x16x32_bf16 v[24:27], v[222:225], v[182:185], v[24:27]
	v_mfma_f32_16x16x32_bf16 v[20:23], v[214:217], v[190:193], v[20:23]
	v_mfma_f32_16x16x32_bf16 v[16:19], v[222:225], v[190:193], v[16:19]
	v_mfma_f32_16x16x32_bf16 v[12:15], v[214:217], v[198:201], v[12:15]
	v_mfma_f32_16x16x32_bf16 v[8:11], v[222:225], v[198:201], v[8:11]
	v_mfma_f32_16x16x32_bf16 v[4:7], v[214:217], v[206:209], v[4:7]
	v_mfma_f32_16x16x32_bf16 v[0:3], v[222:225], v[206:209], v[0:3]
	v_mfma_f32_16x16x32_bf16 v[28:31], v[218:221], v[186:189], v[28:31]
	v_mfma_f32_16x16x32_bf16 v[24:27], v[226:229], v[186:189], v[24:27]
	v_mfma_f32_16x16x32_bf16 v[20:23], v[218:221], v[194:197], v[20:23]
	v_mfma_f32_16x16x32_bf16 v[16:19], v[226:229], v[194:197], v[16:19]
	v_mfma_f32_16x16x32_bf16 v[12:15], v[218:221], v[202:205], v[12:15]
	v_mfma_f32_16x16x32_bf16 v[8:11], v[226:229], v[202:205], v[8:11]
	v_mfma_f32_16x16x32_bf16 v[4:7], v[218:221], v[210:213], v[4:7]
	v_mfma_f32_16x16x32_bf16 v[0:3], v[226:229], v[210:213], v[0:3]
	s_barrier
	ds_read_b128 v[170:173], v154
	ds_read_b128 v[174:177], v154 offset:1024
	ds_read_b128 v[178:181], v154 offset:2048
	ds_read_b128 v[182:185], v154 offset:3072
	v_add_u32_e32 v166, 0x4000, v143
	v_add_u32_e32 v167, 0x6000, v143
	v_readfirstlane_b32 s55, v166
	v_lshl_add_u64 v[218:219], v[234:235], 0, s[42:43]
	s_mov_b32 m0, s55
	v_readfirstlane_b32 s55, v167
	ds_read_b128 v[186:189], v151 offset:32768
	ds_read_b128 v[190:193], v151 offset:33792
	ds_read_b128 v[194:197], v150 offset:32768
	ds_read_b128 v[198:201], v150 offset:33792
	ds_read_b128 v[202:205], v149 offset:32768
	ds_read_b128 v[206:209], v149 offset:33792
	ds_read_b128 v[210:213], v148 offset:32768
	ds_read_b128 v[214:217], v148 offset:33792
	global_load_lds_dwordx4 v[218:219], off
	v_lshl_add_u64 v[218:219], v[236:237], 0, s[42:43]
	s_mov_b32 m0, s55
	s_nop 0
	global_load_lds_dwordx4 v[218:219], off
	s_waitcnt lgkmcnt(8)
	s_barrier
	s_waitcnt lgkmcnt(0)
	s_waitcnt lgkmcnt(0)
	v_mfma_f32_16x16x32_bf16 v[124:127], v[170:173], v[186:189], v[124:127]
	v_mfma_f32_16x16x32_bf16 v[120:123], v[178:181], v[186:189], v[120:123]
	v_mfma_f32_16x16x32_bf16 v[116:119], v[170:173], v[194:197], v[116:119]
	v_mfma_f32_16x16x32_bf16 v[112:115], v[178:181], v[194:197], v[112:115]
	v_mfma_f32_16x16x32_bf16 v[108:111], v[170:173], v[202:205], v[108:111]
	v_mfma_f32_16x16x32_bf16 v[104:107], v[178:181], v[202:205], v[104:107]
	v_mfma_f32_16x16x32_bf16 v[100:103], v[170:173], v[210:213], v[100:103]
	v_mfma_f32_16x16x32_bf16 v[96:99], v[178:181], v[210:213], v[96:99]
	v_mfma_f32_16x16x32_bf16 v[124:127], v[174:177], v[190:193], v[124:127]
	v_mfma_f32_16x16x32_bf16 v[120:123], v[182:185], v[190:193], v[120:123]
	v_mfma_f32_16x16x32_bf16 v[116:119], v[174:177], v[198:201], v[116:119]
	v_mfma_f32_16x16x32_bf16 v[112:115], v[182:185], v[198:201], v[112:115]
	v_mfma_f32_16x16x32_bf16 v[108:111], v[174:177], v[206:209], v[108:111]
	v_mfma_f32_16x16x32_bf16 v[104:107], v[182:185], v[206:209], v[104:107]
	v_mfma_f32_16x16x32_bf16 v[100:103], v[174:177], v[214:217], v[100:103]
	v_mfma_f32_16x16x32_bf16 v[96:99], v[182:185], v[214:217], v[96:99]
	s_barrier
	v_readfirstlane_b32 s55, v155
	v_add_u32_e32 v244, 0x2000, v155
	v_lshl_add_u64 v[242:243], v[238:239], 0, s[44:45]
	s_mov_b32 m0, s55
	v_readfirstlane_b32 s55, v244
	ds_read_b128 v[218:221], v152
	ds_read_b128 v[222:225], v152 offset:1024
	ds_read_b128 v[226:229], v152 offset:2048
	ds_read_b128 v[230:233], v152 offset:3072
	global_load_lds_dwordx4 v[242:243], off
	v_lshl_add_u64 v[242:243], v[240:241], 0, s[44:45]
	s_mov_b32 m0, s55
	s_nop 0
	global_load_lds_dwordx4 v[242:243], off
	s_barrier
	s_waitcnt lgkmcnt(0)
	s_waitcnt lgkmcnt(0)
	v_mfma_f32_16x16x32_bf16 v[92:95], v[218:221], v[186:189], v[92:95]
	v_mfma_f32_16x16x32_bf16 v[88:91], v[226:229], v[186:189], v[88:91]
	v_mfma_f32_16x16x32_bf16 v[84:87], v[218:221], v[194:197], v[84:87]
	v_mfma_f32_16x16x32_bf16 v[80:83], v[226:229], v[194:197], v[80:83]
	v_mfma_f32_16x16x32_bf16 v[76:79], v[218:221], v[202:205], v[76:79]
	v_mfma_f32_16x16x32_bf16 v[72:75], v[226:229], v[202:205], v[72:75]
	v_mfma_f32_16x16x32_bf16 v[68:71], v[218:221], v[210:213], v[68:71]
	v_mfma_f32_16x16x32_bf16 v[64:67], v[226:229], v[210:213], v[64:67]
	v_mfma_f32_16x16x32_bf16 v[92:95], v[222:225], v[190:193], v[92:95]
	v_mfma_f32_16x16x32_bf16 v[88:91], v[230:233], v[190:193], v[88:91]
	v_mfma_f32_16x16x32_bf16 v[84:87], v[222:225], v[198:201], v[84:87]
	v_mfma_f32_16x16x32_bf16 v[80:83], v[230:233], v[198:201], v[80:83]
	v_mfma_f32_16x16x32_bf16 v[76:79], v[222:225], v[206:209], v[76:79]
	v_mfma_f32_16x16x32_bf16 v[72:75], v[230:233], v[206:209], v[72:75]
	v_mfma_f32_16x16x32_bf16 v[68:71], v[222:225], v[214:217], v[68:71]
	v_mfma_f32_16x16x32_bf16 v[64:67], v[230:233], v[214:217], v[64:67]
	s_barrier
	v_readfirstlane_b32 s55, v156
	v_lshl_add_u64 v[234:235], v[234:235], 0, s[46:47]
	s_mov_b32 m0, s55
	v_readfirstlane_b32 s55, v157
	ds_read_b128 v[186:189], v151 offset:49152
	ds_read_b128 v[190:193], v151 offset:50176
	ds_read_b128 v[194:197], v150 offset:49152
	ds_read_b128 v[198:201], v150 offset:50176
	ds_read_b128 v[202:205], v149 offset:49152
	ds_read_b128 v[206:209], v149 offset:50176
	ds_read_b128 v[210:213], v148 offset:49152
	ds_read_b128 v[214:217], v148 offset:50176
	global_load_lds_dwordx4 v[234:235], off
	v_lshl_add_u64 v[234:235], v[236:237], 0, s[46:47]
	s_mov_b32 m0, s55
	s_nop 0
	global_load_lds_dwordx4 v[234:235], off
	s_barrier
; #define STAGE(P, BASE, LD, br, kt) do { const char* _g = (const char*)((BASE) + (size_t)(br) * (LD) + (size_t)(kt) * 64); \
;     for (int _i = 0; _i < 2; ++_i) { int _b = tidx * 16 + _i * 8192; int _r, _c; stage_rc(_b, _r, _c); \
;       __builtin_amdgcn_global_load_lds((const unsigned*)(_g + (unsigned)((_r * (LD) + _c) * 2)), (unsigned*)((char*)(P) + _b), 16, 0, 0); } } while (0)
; #define LDA(dst, b, h) for (int m = 0; m < 4; ++m) for (int k = 0; k < 2; ++k) \
;     dst[m][k] = *reinterpret_cast<const bf16x8*>((char*)SA(b, h) + lds_byte(wr * 64 + m * 16 + fr, k * 32 + fq * 8))
; #define LDB(dst, b, h) for (int n = 0; n < 2; ++n) for (int k = 0; k < 2; ++k) \
;     dst[n][k] = *reinterpret_cast<const bf16x8*>((char*)SB(b, h) + lds_byte(wc * 32 + n * 16 + fr, k * 32 + fq * 8))
; #define MMA(ai, bj, At_, Bt_) do { __builtin_amdgcn_s_setprio(1); \
;     for (int k = 0; k < 2; ++k) for (int m = 0; m < 4; ++m) for (int n = 0; n < 2; ++n) \
;       acc[ai][bj][m][n] = __builtin_amdgcn_mfma_f32_16x16x32_bf16(At_[m][k], Bt_[n][k], acc[ai][bj][m][n], 0, 0, 0); \
;     __builtin_amdgcn_s_setprio(0); } while (0)
; #define WAIT_V(n) asm volatile("s_waitcnt vmcnt(" #n ")" ::: "memory")
; #define WAIT_L(n) asm volatile("s_waitcnt lgkmcnt(" #n ")" ::: "memory")
; #define BAR __builtin_amdgcn_s_barrier()
; #define SCHED __builtin_amdgcn_sched_barrier(0)
; template <int EPI, int lda, int ldb, int N, int K>
; __device__ __forceinline__ void gemm_phase(const u16* __restrict__ A, const u16* __restrict__ Bt, const GemmEpi ep, int wv) {
;     ...
;       BAR; WAIT_L(0); MMA(1, 0, At, B0); BAR; SCHED;
;       STAGE(SB(1, 1), Bt, ldb, bcol + HALF, t + 3);
;       WAIT_V(6); BAR; MMA(1, 1, At, B1); BAR;
;     }
;     { LDB(B0, 0, 0); LDA(At, 0, 0); STAGE(SA(1, 1), Ab, lda, brow + HALF, nt - 1);
;       BAR; WAIT_L(0); MMA(0, 0, At, B0); BAR;
;       LDB(B1, 0, 1); BAR; WAIT_L(0); MMA(0, 1, At, B1); BAR;
	s_waitcnt lgkmcnt(0)
	s_waitcnt lgkmcnt(0)
	v_mfma_f32_16x16x32_bf16 v[60:63], v[170:173], v[186:189], v[60:63]
	v_mfma_f32_16x16x32_bf16 v[56:59], v[178:181], v[186:189], v[56:59]
	v_mfma_f32_16x16x32_bf16 v[52:55], v[170:173], v[194:197], v[52:55]
	v_mfma_f32_16x16x32_bf16 v[48:51], v[178:181], v[194:197], v[48:51]
	v_mfma_f32_16x16x32_bf16 v[44:47], v[170:173], v[202:205], v[44:47]
	v_mfma_f32_16x16x32_bf16 v[40:43], v[178:181], v[202:205], v[40:43]
	v_mfma_f32_16x16x32_bf16 v[36:39], v[170:173], v[210:213], v[36:39]
	v_mfma_f32_16x16x32_bf16 v[32:35], v[178:181], v[210:213], v[32:35]
	v_mfma_f32_16x16x32_bf16 v[60:63], v[174:177], v[190:193], v[60:63]
	v_mfma_f32_16x16x32_bf16 v[56:59], v[182:185], v[190:193], v[56:59]
	v_mfma_f32_16x16x32_bf16 v[52:55], v[174:177], v[198:201], v[52:55]
	v_mfma_f32_16x16x32_bf16 v[48:51], v[182:185], v[198:201], v[48:51]
	v_mfma_f32_16x16x32_bf16 v[44:47], v[174:177], v[206:209], v[44:47]
	v_mfma_f32_16x16x32_bf16 v[40:43], v[182:185], v[206:209], v[40:43]
	v_mfma_f32_16x16x32_bf16 v[36:39], v[174:177], v[214:217], v[36:39]
	v_mfma_f32_16x16x32_bf16 v[32:35], v[182:185], v[214:217], v[32:35]
	s_barrier
	v_readfirstlane_b32 s55, v158
	v_add_u32_e32 v172, 0x2000, v158
	v_lshl_add_u64 v[170:171], v[238:239], 0, s[48:49]
	s_mov_b32 m0, s55
	v_readfirstlane_b32 s55, v172
	global_load_lds_dwordx4 v[170:171], off
	v_lshl_add_u64 v[170:171], v[240:241], 0, s[48:49]
	s_mov_b32 m0, s55
	s_nop 0
	global_load_lds_dwordx4 v[170:171], off
	s_add_i32 s54, s54, 2
	s_add_u32 s52, s52, 0x100
	s_addc_u32 s53, s53, 0
	s_cmp_gt_u32 s54, 27
	s_waitcnt vmcnt(6)
	s_barrier
	v_mfma_f32_16x16x32_bf16 v[28:31], v[218:221], v[186:189], v[28:31]
	v_mfma_f32_16x16x32_bf16 v[24:27], v[226:229], v[186:189], v[24:27]
	v_mfma_f32_16x16x32_bf16 v[20:23], v[218:221], v[194:197], v[20:23]
	v_mfma_f32_16x16x32_bf16 v[16:19], v[226:229], v[194:197], v[16:19]
	v_mfma_f32_16x16x32_bf16 v[12:15], v[218:221], v[202:205], v[12:15]
	v_mfma_f32_16x16x32_bf16 v[8:11], v[226:229], v[202:205], v[8:11]
	v_mfma_f32_16x16x32_bf16 v[4:7], v[218:221], v[210:213], v[4:7]
	v_mfma_f32_16x16x32_bf16 v[0:3], v[226:229], v[210:213], v[0:3]
	v_mfma_f32_16x16x32_bf16 v[28:31], v[222:225], v[190:193], v[28:31]
	v_mfma_f32_16x16x32_bf16 v[24:27], v[230:233], v[190:193], v[24:27]
	v_mfma_f32_16x16x32_bf16 v[20:23], v[222:225], v[198:201], v[20:23]
	v_mfma_f32_16x16x32_bf16 v[16:19], v[230:233], v[198:201], v[16:19]
	v_mfma_f32_16x16x32_bf16 v[12:15], v[222:225], v[206:209], v[12:15]
	v_mfma_f32_16x16x32_bf16 v[8:11], v[230:233], v[206:209], v[8:11]
	v_mfma_f32_16x16x32_bf16 v[4:7], v[222:225], v[214:217], v[4:7]
	v_mfma_f32_16x16x32_bf16 v[0:3], v[230:233], v[214:217], v[0:3]
	s_barrier
	s_cbranch_scc0 .LBB0_654
	s_lshl_b64 s[52:53], s[16:17], 12
	s_add_u32 s52, s14, s52
	s_addc_u32 s53, s15, s53
	s_add_u32 s52, s52, 0x80000
	s_addc_u32 s53, s53, 0
	v_lshl_add_u64 v[156:157], s[52:53], 0, v[128:129]
	v_readfirstlane_b32 s54, v168
	v_lshl_add_u64 v[156:157], v[156:157], 0, s[50:51]
	s_mov_b32 m0, s54
	ds_read_b128 v[134:137], v160
	ds_read_b128 v[138:141], v160 offset:1024
	ds_read_b128 v[170:173], v160 offset:2048
	ds_read_b128 v[174:177], v160 offset:3072
	ds_read_b128 v[178:181], v151
	ds_read_b128 v[182:185], v151 offset:1024
	ds_read_b128 v[186:189], v150
	ds_read_b128 v[190:193], v150 offset:1024
	ds_read_b128 v[194:197], v149
	ds_read_b128 v[198:201], v149 offset:1024
	ds_read_b128 v[202:205], v148
	ds_read_b128 v[206:209], v148 offset:1024
	global_load_lds_dwordx4 v[156:157], off
	v_lshl_add_u64 v[156:157], s[52:53], 0, v[132:133]
	v_readfirstlane_b32 s52, v169
	v_lshl_add_u64 v[156:157], v[156:157], 0, s[50:51]
	s_mov_b32 m0, s52
	s_nop 0
	global_load_lds_dwordx4 v[156:157], off
	s_barrier
	s_waitcnt lgkmcnt(0)
	s_waitcnt lgkmcnt(0)
	v_mfma_f32_16x16x32_bf16 v[124:127], v[134:137], v[178:181], v[124:127]
	v_mfma_f32_16x16x32_bf16 v[120:123], v[170:173], v[178:181], v[120:123]
	v_mfma_f32_16x16x32_bf16 v[116:119], v[134:137], v[186:189], v[116:119]
	v_mfma_f32_16x16x32_bf16 v[112:115], v[170:173], v[186:189], v[112:115]
	v_mfma_f32_16x16x32_bf16 v[108:111], v[134:137], v[194:197], v[108:111]
	v_mfma_f32_16x16x32_bf16 v[104:107], v[170:173], v[194:197], v[104:107]
	v_mfma_f32_16x16x32_bf16 v[100:103], v[134:137], v[202:205], v[100:103]
	v_mfma_f32_16x16x32_bf16 v[96:99], v[170:173], v[202:205], v[96:99]
	v_mfma_f32_16x16x32_bf16 v[124:127], v[138:141], v[182:185], v[124:127]
	v_mfma_f32_16x16x32_bf16 v[120:123], v[174:177], v[182:185], v[120:123]
	v_mfma_f32_16x16x32_bf16 v[116:119], v[138:141], v[190:193], v[116:119]
	v_mfma_f32_16x16x32_bf16 v[112:115], v[174:177], v[190:193], v[112:115]
	v_mfma_f32_16x16x32_bf16 v[108:111], v[138:141], v[198:201], v[108:111]
	v_mfma_f32_16x16x32_bf16 v[104:107], v[174:177], v[198:201], v[104:107]
	v_mfma_f32_16x16x32_bf16 v[100:103], v[138:141], v[206:209], v[100:103]
	v_mfma_f32_16x16x32_bf16 v[96:99], v[174:177], v[206:209], v[96:99]
	s_barrier
	ds_read_b128 v[210:213], v159
	ds_read_b128 v[214:217], v159 offset:1024
	ds_read_b128 v[218:221], v159 offset:2048
	ds_read_b128 v[156:159], v159 offset:3072
	s_barrier
; #define LDA(dst, b, h) for (int m = 0; m < 4; ++m) for (int k = 0; k < 2; ++k) \
;     dst[m][k] = *reinterpret_cast<const bf16x8*>((char*)SA(b, h) + lds_byte(wr * 64 + m * 16 + fr, k * 32 + fq * 8))
; #define LDB(dst, b, h) for (int n = 0; n < 2; ++n) for (int k = 0; k < 2; ++k) \
;     dst[n][k] = *reinterpret_cast<const bf16x8*>((char*)SB(b, h) + lds_byte(wc * 32 + n * 16 + fr, k * 32 + fq * 8))
; #define MMA(ai, bj, At_, Bt_) do { __builtin_amdgcn_s_setprio(1); \
;     for (int k = 0; k < 2; ++k) for (int m = 0; m < 4; ++m) for (int n = 0; n < 2; ++n) \
;       acc[ai][bj][m][n] = __builtin_amdgcn_mfma_f32_16x16x32_bf16(At_[m][k], Bt_[n][k], acc[ai][bj][m][n], 0, 0, 0); \
;     __builtin_amdgcn_s_setprio(0); } while (0)
; #define WAIT_V(n) asm volatile("s_waitcnt vmcnt(" #n ")" ::: "memory")
; #define WAIT_L(n) asm volatile("s_waitcnt lgkmcnt(" #n ")" ::: "memory")
; #define BAR __builtin_amdgcn_s_barrier()
; template <int EPI, int lda, int ldb, int N, int K>
; __device__ __forceinline__ void gemm_phase(const u16* __restrict__ A, const u16* __restrict__ Bt, const GemmEpi ep, int wv) {
;     ...
;       LDB(B1, 0, 1); BAR; WAIT_L(0); MMA(0, 1, At, B1); BAR;
;       LDA(At, 0, 1); WAIT_V(4); BAR; WAIT_L(0); MMA(1, 0, At, B0); MMA(1, 1, At, B1); BAR; }
;     { LDB(B0, 1, 0); LDA(At, 1, 0); WAIT_V(2); BAR; WAIT_L(0); MMA(0, 0, At, B0); BAR;
	s_waitcnt lgkmcnt(0)
	s_waitcnt lgkmcnt(0)
	v_mfma_f32_16x16x32_bf16 v[92:95], v[210:213], v[178:181], v[92:95]
	v_mfma_f32_16x16x32_bf16 v[88:91], v[218:221], v[178:181], v[88:91]
	v_mfma_f32_16x16x32_bf16 v[76:79], v[210:213], v[194:197], v[76:79]
	v_mfma_f32_16x16x32_bf16 v[72:75], v[218:221], v[194:197], v[72:75]
	v_mfma_f32_16x16x32_bf16 v[84:87], v[210:213], v[186:189], v[84:87]
	v_mfma_f32_16x16x32_bf16 v[80:83], v[218:221], v[186:189], v[80:83]
	v_mfma_f32_16x16x32_bf16 v[68:71], v[210:213], v[202:205], v[68:71]
	v_mfma_f32_16x16x32_bf16 v[64:67], v[218:221], v[202:205], v[64:67]
	v_mfma_f32_16x16x32_bf16 v[92:95], v[214:217], v[182:185], v[92:95]
	v_mfma_f32_16x16x32_bf16 v[88:91], v[156:159], v[182:185], v[88:91]
	v_mfma_f32_16x16x32_bf16 v[76:79], v[214:217], v[198:201], v[76:79]
	v_mfma_f32_16x16x32_bf16 v[72:75], v[156:159], v[198:201], v[72:75]
	v_mfma_f32_16x16x32_bf16 v[178:181], v[214:217], v[190:193], v[84:87]
	v_mfma_f32_16x16x32_bf16 v[182:185], v[156:159], v[190:193], v[80:83]
	v_mfma_f32_16x16x32_bf16 v[186:189], v[214:217], v[206:209], v[68:71]
	v_mfma_f32_16x16x32_bf16 v[190:193], v[156:159], v[206:209], v[64:67]
	s_barrier
	s_nop 0
	ds_read_b128 v[64:67], v151 offset:16384
	ds_read_b128 v[68:71], v151 offset:17408
	ds_read_b128 v[80:83], v150 offset:16384
	ds_read_b128 v[84:87], v150 offset:17408
	ds_read_b128 v[194:197], v149 offset:16384
	ds_read_b128 v[198:201], v149 offset:17408
	ds_read_b128 v[202:205], v148 offset:16384
	ds_read_b128 v[206:209], v148 offset:17408
	s_waitcnt vmcnt(4)
	s_barrier
	s_waitcnt lgkmcnt(0)
	s_waitcnt lgkmcnt(0)
	v_mfma_f32_16x16x32_bf16 v[60:63], v[134:137], v[64:67], v[60:63]
	v_mfma_f32_16x16x32_bf16 v[56:59], v[170:173], v[64:67], v[56:59]
	v_mfma_f32_16x16x32_bf16 v[52:55], v[134:137], v[80:83], v[52:55]
	v_mfma_f32_16x16x32_bf16 v[48:51], v[170:173], v[80:83], v[48:51]
	v_mfma_f32_16x16x32_bf16 v[44:47], v[134:137], v[194:197], v[44:47]
	v_mfma_f32_16x16x32_bf16 v[40:43], v[170:173], v[194:197], v[40:43]
	v_mfma_f32_16x16x32_bf16 v[36:39], v[134:137], v[202:205], v[36:39]
	v_mfma_f32_16x16x32_bf16 v[32:35], v[170:173], v[202:205], v[32:35]
	v_mfma_f32_16x16x32_bf16 v[60:63], v[138:141], v[68:71], v[60:63]
	v_mfma_f32_16x16x32_bf16 v[56:59], v[174:177], v[68:71], v[56:59]
	v_mfma_f32_16x16x32_bf16 v[52:55], v[138:141], v[84:87], v[52:55]
	v_mfma_f32_16x16x32_bf16 v[48:51], v[174:177], v[84:87], v[48:51]
	v_mfma_f32_16x16x32_bf16 v[44:47], v[138:141], v[198:201], v[44:47]
	v_mfma_f32_16x16x32_bf16 v[40:43], v[174:177], v[198:201], v[40:43]
	v_mfma_f32_16x16x32_bf16 v[36:39], v[138:141], v[206:209], v[36:39]
	v_mfma_f32_16x16x32_bf16 v[32:35], v[174:177], v[206:209], v[32:35]
	v_mfma_f32_16x16x32_bf16 v[28:31], v[210:213], v[64:67], v[28:31]
	v_mfma_f32_16x16x32_bf16 v[20:23], v[210:213], v[80:83], v[20:23]
	v_mfma_f32_16x16x32_bf16 v[12:15], v[210:213], v[194:197], v[12:15]
	v_mfma_f32_16x16x32_bf16 v[4:7], v[210:213], v[202:205], v[4:7]
	v_mfma_f32_16x16x32_bf16 v[24:27], v[218:221], v[64:67], v[24:27]
	v_mfma_f32_16x16x32_bf16 v[16:19], v[218:221], v[80:83], v[16:19]
	v_mfma_f32_16x16x32_bf16 v[8:11], v[218:221], v[194:197], v[8:11]
	v_mfma_f32_16x16x32_bf16 v[0:3], v[218:221], v[202:205], v[0:3]
	v_mfma_f32_16x16x32_bf16 v[28:31], v[214:217], v[68:71], v[28:31]
	v_mfma_f32_16x16x32_bf16 v[20:23], v[214:217], v[84:87], v[20:23]
	v_mfma_f32_16x16x32_bf16 v[12:15], v[214:217], v[198:201], v[12:15]
	v_mfma_f32_16x16x32_bf16 v[4:7], v[214:217], v[206:209], v[4:7]
	v_mfma_f32_16x16x32_bf16 v[134:137], v[156:159], v[68:71], v[24:27]
	v_mfma_f32_16x16x32_bf16 v[138:141], v[156:159], v[84:87], v[16:19]
	v_mfma_f32_16x16x32_bf16 v[168:171], v[156:159], v[198:201], v[8:11]
	v_mfma_f32_16x16x32_bf16 v[156:159], v[156:159], v[206:209], v[0:3]
	s_barrier
	s_nop 0
	ds_read_b128 v[0:3], v154
	ds_read_b128 v[8:11], v154 offset:1024
	ds_read_b128 v[16:19], v154 offset:2048
	ds_read_b128 v[172:175], v154 offset:3072
	ds_read_b128 v[24:27], v151 offset:32768
	ds_read_b128 v[194:197], v151 offset:33792
	ds_read_b128 v[198:201], v150 offset:32768
	ds_read_b128 v[202:205], v150 offset:33792
	ds_read_b128 v[206:209], v149 offset:32768
	ds_read_b128 v[210:213], v149 offset:33792
	ds_read_b128 v[214:217], v148 offset:32768
	ds_read_b128 v[218:221], v148 offset:33792
	s_waitcnt vmcnt(2)
	s_barrier
; #define LDA(dst, b, h) for (int m = 0; m < 4; ++m) for (int k = 0; k < 2; ++k) \
;     dst[m][k] = *reinterpret_cast<const bf16x8*>((char*)SA(b, h) + lds_byte(wr * 64 + m * 16 + fr, k * 32 + fq * 8))
; #define LDB(dst, b, h) for (int n = 0; n < 2; ++n) for (int k = 0; k < 2; ++k) \
;     dst[n][k] = *reinterpret_cast<const bf16x8*>((char*)SB(b, h) + lds_byte(wc * 32 + n * 16 + fr, k * 32 + fq * 8))
; #define MMA(ai, bj, At_, Bt_) do { __builtin_amdgcn_s_setprio(1); \
;     for (int k = 0; k < 2; ++k) for (int m = 0; m < 4; ++m) for (int n = 0; n < 2; ++n) \
;       acc[ai][bj][m][n] = __builtin_amdgcn_mfma_f32_16x16x32_bf16(At_[m][k], Bt_[n][k], acc[ai][bj][m][n], 0, 0, 0); \
;     __builtin_amdgcn_s_setprio(0); } while (0)
; #define WAIT_V(n) asm volatile("s_waitcnt vmcnt(" #n ")" ::: "memory")
; #define WAIT_L(n) asm volatile("s_waitcnt lgkmcnt(" #n ")" ::: "memory")
; #define BAR __builtin_amdgcn_s_barrier()
; template <int EPI, int lda, int ldb, int N, int K>
; __device__ __forceinline__ void gemm_phase(const u16* __restrict__ A, const u16* __restrict__ Bt, const GemmEpi ep, int wv) {
;     ...
;     { LDB(B0, 1, 0); LDA(At, 1, 0); WAIT_V(2); BAR; WAIT_L(0); MMA(0, 0, At, B0); BAR;
;       LDB(B1, 1, 1); WAIT_V(0); BAR; WAIT_L(0); MMA(0, 1, At, B1); BAR;
;       LDA(At, 1, 1); BAR; WAIT_L(0); MMA(1, 0, At, B0); MMA(1, 1, At, B1); BAR; }
;     if (wr == 0) BAR;
	s_waitcnt lgkmcnt(0)
	s_waitcnt lgkmcnt(0)
	v_mfma_f32_16x16x32_bf16 v[64:67], v[0:3], v[24:27], v[124:127]
	v_mfma_f32_16x16x32_bf16 v[68:71], v[16:19], v[24:27], v[120:123]
	v_mfma_f32_16x16x32_bf16 v[80:83], v[0:3], v[198:201], v[116:119]
	v_mfma_f32_16x16x32_bf16 v[84:87], v[16:19], v[198:201], v[112:115]
	v_mfma_f32_16x16x32_bf16 v[108:111], v[0:3], v[206:209], v[108:111]
	v_mfma_f32_16x16x32_bf16 v[104:107], v[16:19], v[206:209], v[104:107]
	v_mfma_f32_16x16x32_bf16 v[120:123], v[0:3], v[214:217], v[100:103]
	v_mfma_f32_16x16x32_bf16 v[124:127], v[16:19], v[214:217], v[96:99]
	v_mfma_f32_16x16x32_bf16 v[116:119], v[8:11], v[194:197], v[64:67]
	v_mfma_f32_16x16x32_bf16 v[112:115], v[172:175], v[194:197], v[68:71]
	v_mfma_f32_16x16x32_bf16 v[100:103], v[8:11], v[202:205], v[80:83]
	v_mfma_f32_16x16x32_bf16 v[96:99], v[172:175], v[202:205], v[84:87]
	v_mfma_f32_16x16x32_bf16 v[84:87], v[8:11], v[210:213], v[108:111]
	v_mfma_f32_16x16x32_bf16 v[80:83], v[172:175], v[210:213], v[104:107]
	v_mfma_f32_16x16x32_bf16 v[68:71], v[8:11], v[218:221], v[120:123]
	v_mfma_f32_16x16x32_bf16 v[64:67], v[172:175], v[218:221], v[124:127]
	s_barrier
	ds_read_b128 v[222:225], v152
	ds_read_b128 v[226:229], v152 offset:1024
	ds_read_b128 v[230:233], v152 offset:2048
	ds_read_b128 v[152:155], v152 offset:3072
	s_waitcnt vmcnt(0)
	s_barrier
	s_waitcnt lgkmcnt(0)
	s_waitcnt lgkmcnt(0)
	v_mfma_f32_16x16x32_bf16 v[92:95], v[222:225], v[24:27], v[92:95]
	v_mfma_f32_16x16x32_bf16 v[24:27], v[230:233], v[24:27], v[88:91]
	v_mfma_f32_16x16x32_bf16 v[88:91], v[222:225], v[198:201], v[178:181]
	v_mfma_f32_16x16x32_bf16 v[104:107], v[230:233], v[198:201], v[182:185]
	v_mfma_f32_16x16x32_bf16 v[76:79], v[222:225], v[206:209], v[76:79]
	v_mfma_f32_16x16x32_bf16 v[72:75], v[230:233], v[206:209], v[72:75]
	v_mfma_f32_16x16x32_bf16 v[176:179], v[222:225], v[214:217], v[186:189]
	v_mfma_f32_16x16x32_bf16 v[180:183], v[230:233], v[214:217], v[190:193]
	v_mfma_f32_16x16x32_bf16 v[124:127], v[226:229], v[194:197], v[92:95]
	v_mfma_f32_16x16x32_bf16 v[120:123], v[152:155], v[194:197], v[24:27]
	v_mfma_f32_16x16x32_bf16 v[108:111], v[226:229], v[202:205], v[88:91]
	v_mfma_f32_16x16x32_bf16 v[104:107], v[152:155], v[202:205], v[104:107]
	v_mfma_f32_16x16x32_bf16 v[92:95], v[226:229], v[210:213], v[76:79]
	v_mfma_f32_16x16x32_bf16 v[88:91], v[152:155], v[210:213], v[72:75]
	v_mfma_f32_16x16x32_bf16 v[76:79], v[226:229], v[218:221], v[176:179]
	v_mfma_f32_16x16x32_bf16 v[72:75], v[152:155], v[218:221], v[180:183]
	s_barrier
	ds_read_b128 v[176:179], v151 offset:49152
	ds_read_b128 v[180:183], v151 offset:50176
	ds_read_b128 v[184:187], v150 offset:49152
	ds_read_b128 v[188:191], v150 offset:50176
	ds_read_b128 v[192:195], v149 offset:49152
	ds_read_b128 v[196:199], v149 offset:50176
	ds_read_b128 v[200:203], v148 offset:49152
	ds_read_b128 v[148:151], v148 offset:50176
	s_barrier
	s_waitcnt lgkmcnt(0)
	s_waitcnt lgkmcnt(0)
	v_mfma_f32_16x16x32_bf16 v[24:27], v[0:3], v[176:179], v[60:63]
	v_mfma_f32_16x16x32_bf16 v[60:63], v[16:19], v[176:179], v[56:59]
	v_mfma_f32_16x16x32_bf16 v[52:55], v[0:3], v[184:187], v[52:55]
	v_mfma_f32_16x16x32_bf16 v[204:207], v[16:19], v[184:187], v[48:51]
	v_mfma_f32_16x16x32_bf16 v[44:47], v[0:3], v[192:195], v[44:47]
	v_mfma_f32_16x16x32_bf16 v[208:211], v[16:19], v[192:195], v[40:43]
	v_mfma_f32_16x16x32_bf16 v[0:3], v[0:3], v[200:203], v[36:39]
	v_mfma_f32_16x16x32_bf16 v[36:39], v[16:19], v[200:203], v[32:35]
	v_mfma_f32_16x16x32_bf16 v[56:59], v[8:11], v[180:183], v[24:27]
	v_mfma_f32_16x16x32_bf16 v[48:51], v[172:175], v[180:183], v[60:63]
	v_mfma_f32_16x16x32_bf16 v[40:43], v[8:11], v[188:191], v[52:55]
	v_mfma_f32_16x16x32_bf16 v[32:35], v[172:175], v[188:191], v[204:207]
	v_mfma_f32_16x16x32_bf16 v[24:27], v[8:11], v[196:199], v[44:47]
	v_mfma_f32_16x16x32_bf16 v[16:19], v[172:175], v[196:199], v[208:211]
	v_mfma_f32_16x16x32_bf16 v[8:11], v[8:11], v[148:151], v[0:3]
	v_mfma_f32_16x16x32_bf16 v[0:3], v[172:175], v[148:151], v[36:39]
	v_mfma_f32_16x16x32_bf16 v[28:31], v[222:225], v[176:179], v[28:31]
	v_mfma_f32_16x16x32_bf16 v[36:39], v[230:233], v[176:179], v[134:137]
	v_mfma_f32_16x16x32_bf16 v[20:23], v[222:225], v[184:187], v[20:23]
	v_mfma_f32_16x16x32_bf16 v[134:137], v[230:233], v[184:187], v[138:141]
	v_mfma_f32_16x16x32_bf16 v[12:15], v[222:225], v[192:195], v[12:15]
	v_mfma_f32_16x16x32_bf16 v[138:141], v[230:233], v[192:195], v[168:171]
	v_mfma_f32_16x16x32_bf16 v[4:7], v[222:225], v[200:203], v[4:7]
	v_mfma_f32_16x16x32_bf16 v[156:159], v[230:233], v[200:203], v[156:159]
	v_mfma_f32_16x16x32_bf16 v[60:63], v[226:229], v[180:183], v[28:31]
	v_mfma_f32_16x16x32_bf16 v[52:55], v[152:155], v[180:183], v[36:39]
	v_mfma_f32_16x16x32_bf16 v[44:47], v[226:229], v[188:191], v[20:23]
	v_mfma_f32_16x16x32_bf16 v[36:39], v[152:155], v[188:191], v[134:137]
	v_mfma_f32_16x16x32_bf16 v[28:31], v[226:229], v[196:199], v[12:15]
	v_mfma_f32_16x16x32_bf16 v[20:23], v[152:155], v[196:199], v[138:141]
	v_mfma_f32_16x16x32_bf16 v[12:15], v[226:229], v[148:151], v[4:7]
	v_mfma_f32_16x16x32_bf16 v[4:7], v[152:155], v[148:151], v[156:159]
	v_cmp_gt_u32_e32 vcc, s70, v130
	s_barrier
	s_and_saveexec_b64 s[52:53], vcc
	s_cbranch_execz .LBB0_657
	s_barrier

; #define STAGE(P, BASE, LD, br, kt) do { const char* _g = (const char*)((BASE) + (size_t)(br) * (LD) + (size_t)(kt) * 64); \
;     for (int _i = 0; _i < 2; ++_i) { int _b = tidx * 16 + _i * 8192; int _r, _c; stage_rc(_b, _r, _c); \
;       __builtin_amdgcn_global_load_lds((const unsigned*)(_g + (unsigned)((_r * (LD) + _c) * 2)), (unsigned*)((char*)(P) + _b), 16, 0, 0); } } while (0)
; #define LDA(dst, b, h) for (int m = 0; m < 4; ++m) for (int k = 0; k < 2; ++k) \
;     dst[m][k] = *reinterpret_cast<const bf16x8*>((char*)SA(b, h) + lds_byte(wr * 64 + m * 16 + fr, k * 32 + fq * 8))
; #define LDB(dst, b, h) for (int n = 0; n < 2; ++n) for (int k = 0; k < 2; ++k) \
;     dst[n][k] = *reinterpret_cast<const bf16x8*>((char*)SB(b, h) + lds_byte(wc * 32 + n * 16 + fr, k * 32 + fq * 8))
; #define MMA(ai, bj, At_, Bt_) do { __builtin_amdgcn_s_setprio(1); \
;     for (int k = 0; k < 2; ++k) for (int m = 0; m < 4; ++m) for (int n = 0; n < 2; ++n) \
;       acc[ai][bj][m][n] = __builtin_amdgcn_mfma_f32_16x16x32_bf16(At_[m][k], Bt_[n][k], acc[ai][bj][m][n], 0, 0, 0); \
;     __builtin_amdgcn_s_setprio(0); } while (0)
; #define WAIT_L(n) asm volatile("s_waitcnt lgkmcnt(" #n ")" ::: "memory")
; #define BAR __builtin_amdgcn_s_barrier()
; #define SCHED __builtin_amdgcn_sched_barrier(0)
; template <int EPI, int lda, int ldb, int N, int K>
; __device__ __forceinline__ void gemm_phase(const u16* __restrict__ A, const u16* __restrict__ Bt, const GemmEpi ep, int wv) {
;     ...
;     for (int t = 0; t < nt - 2; t += 2) {
;       LDB(B0, 0, 0); SCHED; LDA(At, 0, 0); STAGE(SA(1, 1), Ab, lda, brow + HALF, t + 1);
;       WAIT_L(8); BAR; WAIT_L(0); MMA(0, 0, At, B0); BAR; SCHED;
;       LDB(B1, 0, 1); STAGE(SB(0, 0), Bt, ldb, bcol, t + 2);
;       BAR; WAIT_L(0); MMA(0, 1, At, B1); BAR;
;       LDA(At, 0, 1); STAGE(SA(0, 0), Ab, lda, brow, t + 2);
;       BAR; WAIT_L(0); MMA(1, 0, At, B0); BAR; SCHED;
.LBB0_770:
	ds_read_b128 v[172:175], v161
	ds_read_b128 v[176:179], v161 offset:1024
	ds_read_b128 v[180:183], v161 offset:2048
	ds_read_b128 v[184:187], v161 offset:3072
	v_add_u32_e32 v169, 0xc000, v148
	v_lshl_add_u64 v[236:237], v[136:137], 0, s[50:51]
	v_readfirstlane_b32 s53, v169
	v_add_u32_e32 v170, 0xe000, v148
	v_lshl_add_u64 v[162:163], v[236:237], 0, s[18:19]
	s_mov_b32 m0, s53
	v_lshl_add_u64 v[238:239], v[134:135], 0, s[50:51]
	v_readfirstlane_b32 s53, v170
	ds_read_b128 v[164:167], v152
	ds_read_b128 v[188:191], v152 offset:1024
	ds_read_b128 v[192:195], v151
	ds_read_b128 v[196:199], v151 offset:1024
	ds_read_b128 v[200:203], v150
	ds_read_b128 v[204:207], v150 offset:1024
	ds_read_b128 v[208:211], v149
	ds_read_b128 v[212:215], v149 offset:1024
	global_load_lds_dwordx4 v[162:163], off
	v_lshl_add_u64 v[162:163], v[238:239], 0, s[18:19]
	s_mov_b32 m0, s53
	s_nop 0
	global_load_lds_dwordx4 v[162:163], off
	s_waitcnt lgkmcnt(8)
	s_barrier
	s_waitcnt lgkmcnt(0)
	s_waitcnt lgkmcnt(0)
	v_mfma_f32_16x16x32_bf16 v[124:127], v[172:175], v[164:167], v[124:127]
	v_mfma_f32_16x16x32_bf16 v[120:123], v[180:183], v[164:167], v[120:123]
	v_mfma_f32_16x16x32_bf16 v[116:119], v[172:175], v[192:195], v[116:119]
	v_mfma_f32_16x16x32_bf16 v[112:115], v[180:183], v[192:195], v[112:115]
	v_mfma_f32_16x16x32_bf16 v[108:111], v[172:175], v[200:203], v[108:111]
	v_mfma_f32_16x16x32_bf16 v[104:107], v[180:183], v[200:203], v[104:107]
	v_mfma_f32_16x16x32_bf16 v[100:103], v[172:175], v[208:211], v[100:103]
	v_mfma_f32_16x16x32_bf16 v[96:99], v[180:183], v[208:211], v[96:99]
	v_mfma_f32_16x16x32_bf16 v[124:127], v[176:179], v[188:191], v[124:127]
	v_mfma_f32_16x16x32_bf16 v[120:123], v[184:187], v[188:191], v[120:123]
	v_mfma_f32_16x16x32_bf16 v[116:119], v[176:179], v[196:199], v[116:119]
	v_mfma_f32_16x16x32_bf16 v[112:115], v[184:187], v[196:199], v[112:115]
	v_mfma_f32_16x16x32_bf16 v[108:111], v[176:179], v[204:207], v[108:111]
	v_mfma_f32_16x16x32_bf16 v[104:107], v[184:187], v[204:207], v[104:107]
	v_mfma_f32_16x16x32_bf16 v[100:103], v[176:179], v[212:215], v[100:103]
	v_mfma_f32_16x16x32_bf16 v[96:99], v[184:187], v[212:215], v[96:99]
	s_barrier
	v_add_u32_e32 v162, s64, v153
	v_lshl_add_u64 v[240:241], v[140:141], 0, s[50:51]
	v_readfirstlane_b32 s53, v162
	v_add_u32_e32 v163, 0x2000, v162
	v_lshl_add_u64 v[232:233], v[240:241], 0, s[20:21]
	s_mov_b32 m0, s53
	v_lshl_add_u64 v[242:243], v[138:139], 0, s[50:51]
	v_readfirstlane_b32 s53, v163
	ds_read_b128 v[216:219], v160
	ds_read_b128 v[220:223], v160 offset:1024
	ds_read_b128 v[224:227], v160 offset:2048
	ds_read_b128 v[228:231], v160 offset:3072
	global_load_lds_dwordx4 v[232:233], off
	v_lshl_add_u64 v[232:233], v[242:243], 0, s[20:21]
	s_mov_b32 m0, s53
	s_nop 0
	global_load_lds_dwordx4 v[232:233], off
	s_barrier
	s_waitcnt lgkmcnt(0)
	s_waitcnt lgkmcnt(0)
	v_mfma_f32_16x16x32_bf16 v[92:95], v[216:219], v[164:167], v[92:95]
	v_mfma_f32_16x16x32_bf16 v[88:91], v[224:227], v[164:167], v[88:91]
	v_mfma_f32_16x16x32_bf16 v[84:87], v[216:219], v[192:195], v[84:87]
	v_mfma_f32_16x16x32_bf16 v[80:83], v[224:227], v[192:195], v[80:83]
	v_mfma_f32_16x16x32_bf16 v[76:79], v[216:219], v[200:203], v[76:79]
	v_mfma_f32_16x16x32_bf16 v[72:75], v[224:227], v[200:203], v[72:75]
	v_mfma_f32_16x16x32_bf16 v[68:71], v[216:219], v[208:211], v[68:71]
	v_mfma_f32_16x16x32_bf16 v[64:67], v[224:227], v[208:211], v[64:67]
	v_mfma_f32_16x16x32_bf16 v[92:95], v[220:223], v[188:191], v[92:95]
	v_mfma_f32_16x16x32_bf16 v[88:91], v[228:231], v[188:191], v[88:91]
	v_mfma_f32_16x16x32_bf16 v[84:87], v[220:223], v[196:199], v[84:87]
	v_mfma_f32_16x16x32_bf16 v[80:83], v[228:231], v[196:199], v[80:83]
	v_mfma_f32_16x16x32_bf16 v[76:79], v[220:223], v[204:207], v[76:79]
	v_mfma_f32_16x16x32_bf16 v[72:75], v[228:231], v[204:207], v[72:75]
	v_mfma_f32_16x16x32_bf16 v[68:71], v[220:223], v[212:215], v[68:71]
	v_mfma_f32_16x16x32_bf16 v[64:67], v[228:231], v[212:215], v[64:67]
	s_barrier
	v_readfirstlane_b32 s53, v148
	v_lshl_add_u64 v[164:165], v[236:237], 0, s[22:23]
	s_mov_b32 m0, s53
	ds_read_b128 v[188:191], v152 offset:16384
	ds_read_b128 v[192:195], v152 offset:17408
	ds_read_b128 v[196:199], v151 offset:16384
	ds_read_b128 v[200:203], v151 offset:17408
	ds_read_b128 v[204:207], v150 offset:16384
	ds_read_b128 v[208:211], v150 offset:17408
	ds_read_b128 v[212:215], v149 offset:16384
	ds_read_b128 v[232:235], v149 offset:17408
	global_load_lds_dwordx4 v[164:165], off
	v_add_u32_e32 v164, 0x2000, v148
	v_lshl_add_u64 v[166:167], v[238:239], 0, s[22:23]
	v_readfirstlane_b32 s53, v164
	s_mov_b32 m0, s53
	s_nop 0
	global_load_lds_dwordx4 v[166:167], off
	s_barrier
	s_waitcnt lgkmcnt(0)
	s_waitcnt lgkmcnt(0)
	v_mfma_f32_16x16x32_bf16 v[60:63], v[172:175], v[188:191], v[60:63]
	v_mfma_f32_16x16x32_bf16 v[56:59], v[180:183], v[188:191], v[56:59]
	v_mfma_f32_16x16x32_bf16 v[52:55], v[172:175], v[196:199], v[52:55]
	v_mfma_f32_16x16x32_bf16 v[48:51], v[180:183], v[196:199], v[48:51]
	v_mfma_f32_16x16x32_bf16 v[44:47], v[172:175], v[204:207], v[44:47]
	v_mfma_f32_16x16x32_bf16 v[40:43], v[180:183], v[204:207], v[40:43]
	v_mfma_f32_16x16x32_bf16 v[36:39], v[172:175], v[212:215], v[36:39]
	v_mfma_f32_16x16x32_bf16 v[32:35], v[180:183], v[212:215], v[32:35]
	v_mfma_f32_16x16x32_bf16 v[60:63], v[176:179], v[192:195], v[60:63]
	v_mfma_f32_16x16x32_bf16 v[56:59], v[184:187], v[192:195], v[56:59]
	v_mfma_f32_16x16x32_bf16 v[52:55], v[176:179], v[200:203], v[52:55]
	v_mfma_f32_16x16x32_bf16 v[48:51], v[184:187], v[200:203], v[48:51]
	v_mfma_f32_16x16x32_bf16 v[44:47], v[176:179], v[208:211], v[44:47]
	v_mfma_f32_16x16x32_bf16 v[40:43], v[184:187], v[208:211], v[40:43]
	v_mfma_f32_16x16x32_bf16 v[36:39], v[176:179], v[232:235], v[36:39]
	v_mfma_f32_16x16x32_bf16 v[32:35], v[184:187], v[232:235], v[32:35]
	s_barrier
; #define STAGE(P, BASE, LD, br, kt) do { const char* _g = (const char*)((BASE) + (size_t)(br) * (LD) + (size_t)(kt) * 64); \
;     for (int _i = 0; _i < 2; ++_i) { int _b = tidx * 16 + _i * 8192; int _r, _c; stage_rc(_b, _r, _c); \
;       __builtin_amdgcn_global_load_lds((const unsigned*)(_g + (unsigned)((_r * (LD) + _c) * 2)), (unsigned*)((char*)(P) + _b), 16, 0, 0); } } while (0)
; #define LDA(dst, b, h) for (int m = 0; m < 4; ++m) for (int k = 0; k < 2; ++k) \
;     dst[m][k] = *reinterpret_cast<const bf16x8*>((char*)SA(b, h) + lds_byte(wr * 64 + m * 16 + fr, k * 32 + fq * 8))
; #define LDB(dst, b, h) for (int n = 0; n < 2; ++n) for (int k = 0; k < 2; ++k) \
;     dst[n][k] = *reinterpret_cast<const bf16x8*>((char*)SB(b, h) + lds_byte(wc * 32 + n * 16 + fr, k * 32 + fq * 8))
; #define MMA(ai, bj, At_, Bt_) do { __builtin_amdgcn_s_setprio(1); \
;     for (int k = 0; k < 2; ++k) for (int m = 0; m < 4; ++m) for (int n = 0; n < 2; ++n) \
;       acc[ai][bj][m][n] = __builtin_amdgcn_mfma_f32_16x16x32_bf16(At_[m][k], Bt_[n][k], acc[ai][bj][m][n], 0, 0, 0); \
;     __builtin_amdgcn_s_setprio(0); } while (0)
; #define WAIT_V(n) asm volatile("s_waitcnt vmcnt(" #n ")" ::: "memory")
; #define WAIT_L(n) asm volatile("s_waitcnt lgkmcnt(" #n ")" ::: "memory")
; #define BAR __builtin_amdgcn_s_barrier()
; #define SCHED __builtin_amdgcn_sched_barrier(0)
; template <int EPI, int lda, int ldb, int N, int K>
; __device__ __forceinline__ void gemm_phase(const u16* __restrict__ A, const u16* __restrict__ Bt, const GemmEpi ep, int wv) {
;     ...
;       STAGE(SB(0, 1), Bt, ldb, bcol + HALF, t + 2);
;       WAIT_V(6); BAR; MMA(1, 1, At, B1); BAR;
;       LDB(B0, 1, 0); SCHED; LDA(At, 1, 0); STAGE(SA(0, 1), Ab, lda, brow + HALF, t + 2);
;       WAIT_L(8); BAR; WAIT_L(0); MMA(0, 0, At, B0); BAR; SCHED;
;       LDB(B1, 1, 1); STAGE(SB(1, 0), Bt, ldb, bcol, t + 3);
;       BAR; WAIT_L(0); MMA(0, 1, At, B1); BAR;
;       LDA(At, 1, 1); STAGE(SA(1, 0), Ab, lda, brow, t + 3);
	v_add_u32_e32 v165, s65, v153
	v_lshl_add_u64 v[166:167], v[240:241], 0, s[24:25]
	v_readfirstlane_b32 s53, v165
	s_mov_b32 m0, s53
	v_lshl_add_u64 v[172:173], v[242:243], 0, s[24:25]
	global_load_lds_dwordx4 v[166:167], off
	v_add_u32_e32 v166, 0x2000, v165
	s_nop 0
	v_readfirstlane_b32 s53, v166
	s_mov_b32 m0, s53
	s_nop 0
	global_load_lds_dwordx4 v[172:173], off
	s_waitcnt vmcnt(6)
	s_barrier
	v_mfma_f32_16x16x32_bf16 v[28:31], v[216:219], v[188:191], v[28:31]
	v_mfma_f32_16x16x32_bf16 v[24:27], v[224:227], v[188:191], v[24:27]
	v_mfma_f32_16x16x32_bf16 v[20:23], v[216:219], v[196:199], v[20:23]
	v_mfma_f32_16x16x32_bf16 v[16:19], v[224:227], v[196:199], v[16:19]
	v_mfma_f32_16x16x32_bf16 v[12:15], v[216:219], v[204:207], v[12:15]
	v_mfma_f32_16x16x32_bf16 v[8:11], v[224:227], v[204:207], v[8:11]
	v_mfma_f32_16x16x32_bf16 v[4:7], v[216:219], v[212:215], v[4:7]
	v_mfma_f32_16x16x32_bf16 v[0:3], v[224:227], v[212:215], v[0:3]
	v_mfma_f32_16x16x32_bf16 v[28:31], v[220:223], v[192:195], v[28:31]
	v_mfma_f32_16x16x32_bf16 v[24:27], v[228:231], v[192:195], v[24:27]
	v_mfma_f32_16x16x32_bf16 v[20:23], v[220:223], v[200:203], v[20:23]
	v_mfma_f32_16x16x32_bf16 v[16:19], v[228:231], v[200:203], v[16:19]
	v_mfma_f32_16x16x32_bf16 v[12:15], v[220:223], v[208:211], v[12:15]
	v_mfma_f32_16x16x32_bf16 v[8:11], v[228:231], v[208:211], v[8:11]
	v_mfma_f32_16x16x32_bf16 v[4:7], v[220:223], v[232:235], v[4:7]
	v_mfma_f32_16x16x32_bf16 v[0:3], v[228:231], v[232:235], v[0:3]
	s_barrier
	ds_read_b128 v[172:175], v156
	ds_read_b128 v[176:179], v156 offset:1024
	ds_read_b128 v[180:183], v156 offset:2048
	ds_read_b128 v[184:187], v156 offset:3072
	v_add_u32_e32 v167, 0x4000, v148
	v_add_u32_e32 v168, 0x6000, v148
	v_readfirstlane_b32 s53, v167
	v_lshl_add_u64 v[220:221], v[236:237], 0, s[26:27]
	s_mov_b32 m0, s53
	v_readfirstlane_b32 s53, v168
	ds_read_b128 v[188:191], v152 offset:32768
	ds_read_b128 v[192:195], v152 offset:33792
	ds_read_b128 v[196:199], v151 offset:32768
	ds_read_b128 v[200:203], v151 offset:33792
	ds_read_b128 v[204:207], v150 offset:32768
	ds_read_b128 v[208:211], v150 offset:33792
	ds_read_b128 v[212:215], v149 offset:32768
	ds_read_b128 v[216:219], v149 offset:33792
	global_load_lds_dwordx4 v[220:221], off
	v_lshl_add_u64 v[220:221], v[238:239], 0, s[26:27]
	s_mov_b32 m0, s53
	s_nop 0
	global_load_lds_dwordx4 v[220:221], off
	s_waitcnt lgkmcnt(8)
	s_barrier
	s_waitcnt lgkmcnt(0)
	s_waitcnt lgkmcnt(0)
	v_mfma_f32_16x16x32_bf16 v[124:127], v[172:175], v[188:191], v[124:127]
	v_mfma_f32_16x16x32_bf16 v[120:123], v[180:183], v[188:191], v[120:123]
	v_mfma_f32_16x16x32_bf16 v[116:119], v[172:175], v[196:199], v[116:119]
	v_mfma_f32_16x16x32_bf16 v[112:115], v[180:183], v[196:199], v[112:115]
	v_mfma_f32_16x16x32_bf16 v[108:111], v[172:175], v[204:207], v[108:111]
	v_mfma_f32_16x16x32_bf16 v[104:107], v[180:183], v[204:207], v[104:107]
	v_mfma_f32_16x16x32_bf16 v[100:103], v[172:175], v[212:215], v[100:103]
	v_mfma_f32_16x16x32_bf16 v[96:99], v[180:183], v[212:215], v[96:99]
	v_mfma_f32_16x16x32_bf16 v[124:127], v[176:179], v[192:195], v[124:127]
	v_mfma_f32_16x16x32_bf16 v[120:123], v[184:187], v[192:195], v[120:123]
	v_mfma_f32_16x16x32_bf16 v[116:119], v[176:179], v[200:203], v[116:119]
	v_mfma_f32_16x16x32_bf16 v[112:115], v[184:187], v[200:203], v[112:115]
	v_mfma_f32_16x16x32_bf16 v[108:111], v[176:179], v[208:211], v[108:111]
	v_mfma_f32_16x16x32_bf16 v[104:107], v[184:187], v[208:211], v[104:107]
	v_mfma_f32_16x16x32_bf16 v[100:103], v[176:179], v[216:219], v[100:103]
	v_mfma_f32_16x16x32_bf16 v[96:99], v[184:187], v[216:219], v[96:99]
	s_barrier
	v_readfirstlane_b32 s53, v155
	v_add_u32_e32 v171, 0x2000, v155
	v_lshl_add_u64 v[244:245], v[240:241], 0, s[40:41]
	s_mov_b32 m0, s53
	v_readfirstlane_b32 s53, v171
	ds_read_b128 v[220:223], v154
	ds_read_b128 v[224:227], v154 offset:1024
	ds_read_b128 v[228:231], v154 offset:2048
	ds_read_b128 v[232:235], v154 offset:3072
	global_load_lds_dwordx4 v[244:245], off
	v_lshl_add_u64 v[244:245], v[242:243], 0, s[40:41]
	s_mov_b32 m0, s53
	s_nop 0
	global_load_lds_dwordx4 v[244:245], off
	s_barrier
	s_waitcnt lgkmcnt(0)
	s_waitcnt lgkmcnt(0)
	v_mfma_f32_16x16x32_bf16 v[92:95], v[220:223], v[188:191], v[92:95]
	v_mfma_f32_16x16x32_bf16 v[88:91], v[228:231], v[188:191], v[88:91]
	v_mfma_f32_16x16x32_bf16 v[84:87], v[220:223], v[196:199], v[84:87]
	v_mfma_f32_16x16x32_bf16 v[80:83], v[228:231], v[196:199], v[80:83]
	v_mfma_f32_16x16x32_bf16 v[76:79], v[220:223], v[204:207], v[76:79]
	v_mfma_f32_16x16x32_bf16 v[72:75], v[228:231], v[204:207], v[72:75]
	v_mfma_f32_16x16x32_bf16 v[68:71], v[220:223], v[212:215], v[68:71]
	v_mfma_f32_16x16x32_bf16 v[64:67], v[228:231], v[212:215], v[64:67]
	v_mfma_f32_16x16x32_bf16 v[92:95], v[224:227], v[192:195], v[92:95]
	v_mfma_f32_16x16x32_bf16 v[88:91], v[232:235], v[192:195], v[88:91]
	v_mfma_f32_16x16x32_bf16 v[84:87], v[224:227], v[200:203], v[84:87]
	v_mfma_f32_16x16x32_bf16 v[80:83], v[232:235], v[200:203], v[80:83]
	v_mfma_f32_16x16x32_bf16 v[76:79], v[224:227], v[208:211], v[76:79]
	v_mfma_f32_16x16x32_bf16 v[72:75], v[232:235], v[208:211], v[72:75]
	v_mfma_f32_16x16x32_bf16 v[68:71], v[224:227], v[216:219], v[68:71]
	v_mfma_f32_16x16x32_bf16 v[64:67], v[232:235], v[216:219], v[64:67]
	s_barrier
	v_readfirstlane_b32 s53, v157
	v_lshl_add_u64 v[236:237], v[236:237], 0, s[42:43]
	s_mov_b32 m0, s53
	v_readfirstlane_b32 s53, v158
	ds_read_b128 v[188:191], v152 offset:49152
	ds_read_b128 v[192:195], v152 offset:50176
	ds_read_b128 v[196:199], v151 offset:49152
	ds_read_b128 v[200:203], v151 offset:50176
	ds_read_b128 v[204:207], v150 offset:49152
	ds_read_b128 v[208:211], v150 offset:50176
	ds_read_b128 v[212:215], v149 offset:49152
	ds_read_b128 v[216:219], v149 offset:50176
	global_load_lds_dwordx4 v[236:237], off
	v_lshl_add_u64 v[236:237], v[238:239], 0, s[42:43]
	s_mov_b32 m0, s53
	s_nop 0
	global_load_lds_dwordx4 v[236:237], off
	s_barrier
; #define STAGE(P, BASE, LD, br, kt) do { const char* _g = (const char*)((BASE) + (size_t)(br) * (LD) + (size_t)(kt) * 64); \
;     for (int _i = 0; _i < 2; ++_i) { int _b = tidx * 16 + _i * 8192; int _r, _c; stage_rc(_b, _r, _c); \
;       __builtin_amdgcn_global_load_lds((const unsigned*)(_g + (unsigned)((_r * (LD) + _c) * 2)), (unsigned*)((char*)(P) + _b), 16, 0, 0); } } while (0)
; #define LDA(dst, b, h) for (int m = 0; m < 4; ++m) for (int k = 0; k < 2; ++k) \
;     dst[m][k] = *reinterpret_cast<const bf16x8*>((char*)SA(b, h) + lds_byte(wr * 64 + m * 16 + fr, k * 32 + fq * 8))
; #define LDB(dst, b, h) for (int n = 0; n < 2; ++n) for (int k = 0; k < 2; ++k) \
;     dst[n][k] = *reinterpret_cast<const bf16x8*>((char*)SB(b, h) + lds_byte(wc * 32 + n * 16 + fr, k * 32 + fq * 8))
; #define MMA(ai, bj, At_, Bt_) do { __builtin_amdgcn_s_setprio(1); \
;     for (int k = 0; k < 2; ++k) for (int m = 0; m < 4; ++m) for (int n = 0; n < 2; ++n) \
;       acc[ai][bj][m][n] = __builtin_amdgcn_mfma_f32_16x16x32_bf16(At_[m][k], Bt_[n][k], acc[ai][bj][m][n], 0, 0, 0); \
;     __builtin_amdgcn_s_setprio(0); } while (0)
; #define WAIT_V(n) asm volatile("s_waitcnt vmcnt(" #n ")" ::: "memory")
; #define WAIT_L(n) asm volatile("s_waitcnt lgkmcnt(" #n ")" ::: "memory")
; #define BAR __builtin_amdgcn_s_barrier()
; #define SCHED __builtin_amdgcn_sched_barrier(0)
; template <int EPI, int lda, int ldb, int N, int K>
; __device__ __forceinline__ void gemm_phase(const u16* __restrict__ A, const u16* __restrict__ Bt, const GemmEpi ep, int wv) {
;     ...
;       BAR; WAIT_L(0); MMA(1, 0, At, B0); BAR; SCHED;
;       STAGE(SB(1, 1), Bt, ldb, bcol + HALF, t + 3);
;       WAIT_V(6); BAR; MMA(1, 1, At, B1); BAR;
;     }
;     { LDB(B0, 0, 0); LDA(At, 0, 0); STAGE(SA(1, 1), Ab, lda, brow + HALF, nt - 1);
;       BAR; WAIT_L(0); MMA(0, 0, At, B0); BAR;
;       LDB(B1, 0, 1); BAR; WAIT_L(0); MMA(0, 1, At, B1); BAR;
	s_waitcnt lgkmcnt(0)
	s_waitcnt lgkmcnt(0)
	v_mfma_f32_16x16x32_bf16 v[60:63], v[172:175], v[188:191], v[60:63]
	v_mfma_f32_16x16x32_bf16 v[56:59], v[180:183], v[188:191], v[56:59]
	v_mfma_f32_16x16x32_bf16 v[52:55], v[172:175], v[196:199], v[52:55]
	v_mfma_f32_16x16x32_bf16 v[48:51], v[180:183], v[196:199], v[48:51]
	v_mfma_f32_16x16x32_bf16 v[44:47], v[172:175], v[204:207], v[44:47]
	v_mfma_f32_16x16x32_bf16 v[40:43], v[180:183], v[204:207], v[40:43]
	v_mfma_f32_16x16x32_bf16 v[36:39], v[172:175], v[212:215], v[36:39]
	v_mfma_f32_16x16x32_bf16 v[32:35], v[180:183], v[212:215], v[32:35]
	v_mfma_f32_16x16x32_bf16 v[60:63], v[176:179], v[192:195], v[60:63]
	v_mfma_f32_16x16x32_bf16 v[56:59], v[184:187], v[192:195], v[56:59]
	v_mfma_f32_16x16x32_bf16 v[52:55], v[176:179], v[200:203], v[52:55]
	v_mfma_f32_16x16x32_bf16 v[48:51], v[184:187], v[200:203], v[48:51]
	v_mfma_f32_16x16x32_bf16 v[44:47], v[176:179], v[208:211], v[44:47]
	v_mfma_f32_16x16x32_bf16 v[40:43], v[184:187], v[208:211], v[40:43]
	v_mfma_f32_16x16x32_bf16 v[36:39], v[176:179], v[216:219], v[36:39]
	v_mfma_f32_16x16x32_bf16 v[32:35], v[184:187], v[216:219], v[32:35]
	s_barrier
	v_readfirstlane_b32 s53, v159
	v_add_u32_e32 v171, 0x2000, v159
	v_lshl_add_u64 v[172:173], v[240:241], 0, s[44:45]
	s_mov_b32 m0, s53
	v_readfirstlane_b32 s53, v171
	global_load_lds_dwordx4 v[172:173], off
	v_lshl_add_u64 v[172:173], v[242:243], 0, s[44:45]
	s_mov_b32 m0, s53
	s_nop 0
	global_load_lds_dwordx4 v[172:173], off
	s_add_i32 s52, s52, 2
	s_add_u32 s50, s50, 0x100
	s_addc_u32 s51, s51, 0
	s_cmp_gt_u32 s52, 27
	s_waitcnt vmcnt(6)
	s_barrier
	v_mfma_f32_16x16x32_bf16 v[28:31], v[220:223], v[188:191], v[28:31]
	v_mfma_f32_16x16x32_bf16 v[24:27], v[228:231], v[188:191], v[24:27]
	v_mfma_f32_16x16x32_bf16 v[20:23], v[220:223], v[196:199], v[20:23]
	v_mfma_f32_16x16x32_bf16 v[16:19], v[228:231], v[196:199], v[16:19]
	v_mfma_f32_16x16x32_bf16 v[12:15], v[220:223], v[204:207], v[12:15]
	v_mfma_f32_16x16x32_bf16 v[8:11], v[228:231], v[204:207], v[8:11]
	v_mfma_f32_16x16x32_bf16 v[4:7], v[220:223], v[212:215], v[4:7]
	v_mfma_f32_16x16x32_bf16 v[0:3], v[228:231], v[212:215], v[0:3]
	v_mfma_f32_16x16x32_bf16 v[28:31], v[224:227], v[192:195], v[28:31]
	v_mfma_f32_16x16x32_bf16 v[24:27], v[232:235], v[192:195], v[24:27]
	v_mfma_f32_16x16x32_bf16 v[20:23], v[224:227], v[200:203], v[20:23]
	v_mfma_f32_16x16x32_bf16 v[16:19], v[232:235], v[200:203], v[16:19]
	v_mfma_f32_16x16x32_bf16 v[12:15], v[224:227], v[208:211], v[12:15]
	v_mfma_f32_16x16x32_bf16 v[8:11], v[232:235], v[208:211], v[8:11]
	v_mfma_f32_16x16x32_bf16 v[4:7], v[224:227], v[216:219], v[4:7]
	v_mfma_f32_16x16x32_bf16 v[0:3], v[232:235], v[216:219], v[0:3]
	s_barrier
	s_cbranch_scc0 .LBB0_770
	s_add_i32 s50, s48, 0x80
	s_mul_hi_i32 s51, s50, 0x1080
	s_mulk_i32 s50, 0x1080
	s_add_u32 s50, s61, s50
	s_addc_u32 s51, s62, s51
	v_lshl_add_u64 v[158:159], s[50:51], 0, v[128:129]
	v_readfirstlane_b32 s52, v169
	v_lshl_add_u64 v[158:159], v[158:159], 0, s[46:47]
	s_mov_b32 m0, s52
	ds_read_b128 v[134:137], v161
	ds_read_b128 v[138:141], v161 offset:1024
	ds_read_b128 v[172:175], v161 offset:2048
	ds_read_b128 v[176:179], v161 offset:3072
	ds_read_b128 v[180:183], v152
	ds_read_b128 v[184:187], v152 offset:1024
	ds_read_b128 v[188:191], v151
	ds_read_b128 v[192:195], v151 offset:1024
	ds_read_b128 v[196:199], v150
	ds_read_b128 v[200:203], v150 offset:1024
	ds_read_b128 v[204:207], v149
	ds_read_b128 v[208:211], v149 offset:1024
	global_load_lds_dwordx4 v[158:159], off
	v_lshl_add_u64 v[158:159], s[50:51], 0, v[132:133]
	v_readfirstlane_b32 s50, v170
	v_lshl_add_u64 v[158:159], v[158:159], 0, s[46:47]
	s_mov_b32 m0, s50
	s_nop 0
	global_load_lds_dwordx4 v[158:159], off
	s_barrier
	s_waitcnt lgkmcnt(0)
	s_waitcnt lgkmcnt(0)
	v_mfma_f32_16x16x32_bf16 v[124:127], v[134:137], v[180:183], v[124:127]
	v_mfma_f32_16x16x32_bf16 v[120:123], v[172:175], v[180:183], v[120:123]
	v_mfma_f32_16x16x32_bf16 v[116:119], v[134:137], v[188:191], v[116:119]
	v_mfma_f32_16x16x32_bf16 v[112:115], v[172:175], v[188:191], v[112:115]
	v_mfma_f32_16x16x32_bf16 v[108:111], v[134:137], v[196:199], v[108:111]
	v_mfma_f32_16x16x32_bf16 v[104:107], v[172:175], v[196:199], v[104:107]
	v_mfma_f32_16x16x32_bf16 v[100:103], v[134:137], v[204:207], v[100:103]
	v_mfma_f32_16x16x32_bf16 v[96:99], v[172:175], v[204:207], v[96:99]
	v_mfma_f32_16x16x32_bf16 v[124:127], v[138:141], v[184:187], v[124:127]
	v_mfma_f32_16x16x32_bf16 v[120:123], v[176:179], v[184:187], v[120:123]
	v_mfma_f32_16x16x32_bf16 v[116:119], v[138:141], v[192:195], v[116:119]
	v_mfma_f32_16x16x32_bf16 v[112:115], v[176:179], v[192:195], v[112:115]
	v_mfma_f32_16x16x32_bf16 v[108:111], v[138:141], v[200:203], v[108:111]
	v_mfma_f32_16x16x32_bf16 v[104:107], v[176:179], v[200:203], v[104:107]
	v_mfma_f32_16x16x32_bf16 v[100:103], v[138:141], v[208:211], v[100:103]
	v_mfma_f32_16x16x32_bf16 v[96:99], v[176:179], v[208:211], v[96:99]
	s_barrier
	ds_read_b128 v[212:215], v160
	ds_read_b128 v[216:219], v160 offset:1024
	ds_read_b128 v[220:223], v160 offset:2048
	ds_read_b128 v[158:161], v160 offset:3072
	s_barrier
; #define LDA(dst, b, h) for (int m = 0; m < 4; ++m) for (int k = 0; k < 2; ++k) \
;     dst[m][k] = *reinterpret_cast<const bf16x8*>((char*)SA(b, h) + lds_byte(wr * 64 + m * 16 + fr, k * 32 + fq * 8))
; #define LDB(dst, b, h) for (int n = 0; n < 2; ++n) for (int k = 0; k < 2; ++k) \
;     dst[n][k] = *reinterpret_cast<const bf16x8*>((char*)SB(b, h) + lds_byte(wc * 32 + n * 16 + fr, k * 32 + fq * 8))
; #define MMA(ai, bj, At_, Bt_) do { __builtin_amdgcn_s_setprio(1); \
;     for (int k = 0; k < 2; ++k) for (int m = 0; m < 4; ++m) for (int n = 0; n < 2; ++n) \
;       acc[ai][bj][m][n] = __builtin_amdgcn_mfma_f32_16x16x32_bf16(At_[m][k], Bt_[n][k], acc[ai][bj][m][n], 0, 0, 0); \
;     __builtin_amdgcn_s_setprio(0); } while (0)
; #define WAIT_V(n) asm volatile("s_waitcnt vmcnt(" #n ")" ::: "memory")
; #define WAIT_L(n) asm volatile("s_waitcnt lgkmcnt(" #n ")" ::: "memory")
; #define BAR __builtin_amdgcn_s_barrier()
; template <int EPI, int lda, int ldb, int N, int K>
; __device__ __forceinline__ void gemm_phase(const u16* __restrict__ A, const u16* __restrict__ Bt, const GemmEpi ep, int wv) {
;     ...
;       LDB(B1, 0, 1); BAR; WAIT_L(0); MMA(0, 1, At, B1); BAR;
;       LDA(At, 0, 1); WAIT_V(4); BAR; WAIT_L(0); MMA(1, 0, At, B0); MMA(1, 1, At, B1); BAR; }
;     { LDB(B0, 1, 0); LDA(At, 1, 0); WAIT_V(2); BAR; WAIT_L(0); MMA(0, 0, At, B0); BAR;
	s_waitcnt lgkmcnt(0)
	s_waitcnt lgkmcnt(0)
	v_mfma_f32_16x16x32_bf16 v[92:95], v[212:215], v[180:183], v[92:95]
	v_mfma_f32_16x16x32_bf16 v[88:91], v[220:223], v[180:183], v[88:91]
	v_mfma_f32_16x16x32_bf16 v[76:79], v[212:215], v[196:199], v[76:79]
	v_mfma_f32_16x16x32_bf16 v[72:75], v[220:223], v[196:199], v[72:75]
	v_mfma_f32_16x16x32_bf16 v[84:87], v[212:215], v[188:191], v[84:87]
	v_mfma_f32_16x16x32_bf16 v[80:83], v[220:223], v[188:191], v[80:83]
	v_mfma_f32_16x16x32_bf16 v[68:71], v[212:215], v[204:207], v[68:71]
	v_mfma_f32_16x16x32_bf16 v[64:67], v[220:223], v[204:207], v[64:67]
	v_mfma_f32_16x16x32_bf16 v[92:95], v[216:219], v[184:187], v[92:95]
	v_mfma_f32_16x16x32_bf16 v[88:91], v[158:161], v[184:187], v[88:91]
	v_mfma_f32_16x16x32_bf16 v[76:79], v[216:219], v[200:203], v[76:79]
	v_mfma_f32_16x16x32_bf16 v[72:75], v[158:161], v[200:203], v[72:75]
	v_mfma_f32_16x16x32_bf16 v[180:183], v[216:219], v[192:195], v[84:87]
	v_mfma_f32_16x16x32_bf16 v[184:187], v[158:161], v[192:195], v[80:83]
	v_mfma_f32_16x16x32_bf16 v[188:191], v[216:219], v[208:211], v[68:71]
	v_mfma_f32_16x16x32_bf16 v[192:195], v[158:161], v[208:211], v[64:67]
	s_barrier
	s_nop 0
	ds_read_b128 v[64:67], v152 offset:16384
	ds_read_b128 v[68:71], v152 offset:17408
	ds_read_b128 v[80:83], v151 offset:16384
	ds_read_b128 v[84:87], v151 offset:17408
	ds_read_b128 v[196:199], v150 offset:16384
	ds_read_b128 v[200:203], v150 offset:17408
	ds_read_b128 v[204:207], v149 offset:16384
	ds_read_b128 v[208:211], v149 offset:17408
	s_waitcnt vmcnt(4)
	s_barrier
	s_waitcnt lgkmcnt(0)
	s_waitcnt lgkmcnt(0)
	v_mfma_f32_16x16x32_bf16 v[60:63], v[134:137], v[64:67], v[60:63]
	v_mfma_f32_16x16x32_bf16 v[56:59], v[172:175], v[64:67], v[56:59]
	v_mfma_f32_16x16x32_bf16 v[52:55], v[134:137], v[80:83], v[52:55]
	v_mfma_f32_16x16x32_bf16 v[48:51], v[172:175], v[80:83], v[48:51]
	v_mfma_f32_16x16x32_bf16 v[44:47], v[134:137], v[196:199], v[44:47]
	v_mfma_f32_16x16x32_bf16 v[40:43], v[172:175], v[196:199], v[40:43]
	v_mfma_f32_16x16x32_bf16 v[36:39], v[134:137], v[204:207], v[36:39]
	v_mfma_f32_16x16x32_bf16 v[32:35], v[172:175], v[204:207], v[32:35]
	v_mfma_f32_16x16x32_bf16 v[60:63], v[138:141], v[68:71], v[60:63]
	v_mfma_f32_16x16x32_bf16 v[56:59], v[176:179], v[68:71], v[56:59]
	v_mfma_f32_16x16x32_bf16 v[52:55], v[138:141], v[84:87], v[52:55]
	v_mfma_f32_16x16x32_bf16 v[48:51], v[176:179], v[84:87], v[48:51]
	v_mfma_f32_16x16x32_bf16 v[44:47], v[138:141], v[200:203], v[44:47]
	v_mfma_f32_16x16x32_bf16 v[40:43], v[176:179], v[200:203], v[40:43]
	v_mfma_f32_16x16x32_bf16 v[36:39], v[138:141], v[208:211], v[36:39]
	v_mfma_f32_16x16x32_bf16 v[32:35], v[176:179], v[208:211], v[32:35]
	v_mfma_f32_16x16x32_bf16 v[28:31], v[212:215], v[64:67], v[28:31]
	v_mfma_f32_16x16x32_bf16 v[24:27], v[220:223], v[64:67], v[24:27]
	v_mfma_f32_16x16x32_bf16 v[12:15], v[212:215], v[196:199], v[12:15]
	v_mfma_f32_16x16x32_bf16 v[8:11], v[220:223], v[196:199], v[8:11]
	v_mfma_f32_16x16x32_bf16 v[20:23], v[212:215], v[80:83], v[20:23]
	v_mfma_f32_16x16x32_bf16 v[16:19], v[220:223], v[80:83], v[16:19]
	v_mfma_f32_16x16x32_bf16 v[4:7], v[212:215], v[204:207], v[4:7]
	v_mfma_f32_16x16x32_bf16 v[0:3], v[220:223], v[204:207], v[0:3]
	v_mfma_f32_16x16x32_bf16 v[28:31], v[216:219], v[68:71], v[28:31]
	v_mfma_f32_16x16x32_bf16 v[24:27], v[158:161], v[68:71], v[24:27]
	v_mfma_f32_16x16x32_bf16 v[12:15], v[216:219], v[200:203], v[12:15]
	v_mfma_f32_16x16x32_bf16 v[8:11], v[158:161], v[200:203], v[8:11]
	v_mfma_f32_16x16x32_bf16 v[134:137], v[216:219], v[84:87], v[20:23]
	v_mfma_f32_16x16x32_bf16 v[138:141], v[158:161], v[84:87], v[16:19]
	v_mfma_f32_16x16x32_bf16 v[170:173], v[216:219], v[208:211], v[4:7]
	v_mfma_f32_16x16x32_bf16 v[158:161], v[158:161], v[208:211], v[0:3]
	s_barrier
	s_nop 0
	ds_read_b128 v[0:3], v156
	ds_read_b128 v[4:7], v156 offset:1024
	ds_read_b128 v[16:19], v156 offset:2048
	ds_read_b128 v[174:177], v156 offset:3072
	ds_read_b128 v[20:23], v152 offset:32768
	ds_read_b128 v[196:199], v152 offset:33792
	ds_read_b128 v[200:203], v151 offset:32768
	ds_read_b128 v[204:207], v151 offset:33792
	ds_read_b128 v[208:211], v150 offset:32768
	ds_read_b128 v[212:215], v150 offset:33792
	ds_read_b128 v[216:219], v149 offset:32768
	ds_read_b128 v[220:223], v149 offset:33792
	s_waitcnt vmcnt(2)
	s_barrier
; #define LDA(dst, b, h) for (int m = 0; m < 4; ++m) for (int k = 0; k < 2; ++k) \
;     dst[m][k] = *reinterpret_cast<const bf16x8*>((char*)SA(b, h) + lds_byte(wr * 64 + m * 16 + fr, k * 32 + fq * 8))
; #define LDB(dst, b, h) for (int n = 0; n < 2; ++n) for (int k = 0; k < 2; ++k) \
;     dst[n][k] = *reinterpret_cast<const bf16x8*>((char*)SB(b, h) + lds_byte(wc * 32 + n * 16 + fr, k * 32 + fq * 8))
; #define MMA(ai, bj, At_, Bt_) do { __builtin_amdgcn_s_setprio(1); \
;     for (int k = 0; k < 2; ++k) for (int m = 0; m < 4; ++m) for (int n = 0; n < 2; ++n) \
;       acc[ai][bj][m][n] = __builtin_amdgcn_mfma_f32_16x16x32_bf16(At_[m][k], Bt_[n][k], acc[ai][bj][m][n], 0, 0, 0); \
;     __builtin_amdgcn_s_setprio(0); } while (0)
; #define WAIT_V(n) asm volatile("s_waitcnt vmcnt(" #n ")" ::: "memory")
; #define WAIT_L(n) asm volatile("s_waitcnt lgkmcnt(" #n ")" ::: "memory")
; #define BAR __builtin_amdgcn_s_barrier()
; template <int EPI, int lda, int ldb, int N, int K>
; __device__ __forceinline__ void gemm_phase(const u16* __restrict__ A, const u16* __restrict__ Bt, const GemmEpi ep, int wv) {
;     ...
;     { LDB(B0, 1, 0); LDA(At, 1, 0); WAIT_V(2); BAR; WAIT_L(0); MMA(0, 0, At, B0); BAR;
;       LDB(B1, 1, 1); WAIT_V(0); BAR; WAIT_L(0); MMA(0, 1, At, B1); BAR;
;       LDA(At, 1, 1); BAR; WAIT_L(0); MMA(1, 0, At, B0); MMA(1, 1, At, B1); BAR; }
;     if (wr == 0) BAR;
	s_waitcnt lgkmcnt(0)
	s_waitcnt lgkmcnt(0)
	v_mfma_f32_16x16x32_bf16 v[64:67], v[0:3], v[20:23], v[124:127]
	v_mfma_f32_16x16x32_bf16 v[68:71], v[16:19], v[20:23], v[120:123]
	v_mfma_f32_16x16x32_bf16 v[80:83], v[0:3], v[200:203], v[116:119]
	v_mfma_f32_16x16x32_bf16 v[84:87], v[16:19], v[200:203], v[112:115]
	v_mfma_f32_16x16x32_bf16 v[108:111], v[0:3], v[208:211], v[108:111]
	v_mfma_f32_16x16x32_bf16 v[104:107], v[16:19], v[208:211], v[104:107]
	v_mfma_f32_16x16x32_bf16 v[120:123], v[0:3], v[216:219], v[100:103]
	v_mfma_f32_16x16x32_bf16 v[124:127], v[16:19], v[216:219], v[96:99]
	v_mfma_f32_16x16x32_bf16 v[116:119], v[4:7], v[196:199], v[64:67]
	v_mfma_f32_16x16x32_bf16 v[112:115], v[174:177], v[196:199], v[68:71]
	v_mfma_f32_16x16x32_bf16 v[100:103], v[4:7], v[204:207], v[80:83]
	v_mfma_f32_16x16x32_bf16 v[96:99], v[174:177], v[204:207], v[84:87]
	v_mfma_f32_16x16x32_bf16 v[84:87], v[4:7], v[212:215], v[108:111]
	v_mfma_f32_16x16x32_bf16 v[80:83], v[174:177], v[212:215], v[104:107]
	v_mfma_f32_16x16x32_bf16 v[68:71], v[4:7], v[220:223], v[120:123]
	v_mfma_f32_16x16x32_bf16 v[64:67], v[174:177], v[220:223], v[124:127]
	s_barrier
	ds_read_b128 v[224:227], v154
	ds_read_b128 v[228:231], v154 offset:1024
	ds_read_b128 v[232:235], v154 offset:2048
	ds_read_b128 v[154:157], v154 offset:3072
	s_waitcnt vmcnt(0)
	s_barrier
	s_waitcnt lgkmcnt(0)
	s_waitcnt lgkmcnt(0)
	v_mfma_f32_16x16x32_bf16 v[92:95], v[224:227], v[20:23], v[92:95]
	v_mfma_f32_16x16x32_bf16 v[20:23], v[232:235], v[20:23], v[88:91]
	v_mfma_f32_16x16x32_bf16 v[88:91], v[224:227], v[200:203], v[180:183]
	v_mfma_f32_16x16x32_bf16 v[104:107], v[232:235], v[200:203], v[184:187]
	v_mfma_f32_16x16x32_bf16 v[76:79], v[224:227], v[208:211], v[76:79]
	v_mfma_f32_16x16x32_bf16 v[72:75], v[232:235], v[208:211], v[72:75]
	v_mfma_f32_16x16x32_bf16 v[178:181], v[224:227], v[216:219], v[188:191]
	v_mfma_f32_16x16x32_bf16 v[182:185], v[232:235], v[216:219], v[192:195]
	v_mfma_f32_16x16x32_bf16 v[124:127], v[228:231], v[196:199], v[92:95]
	v_mfma_f32_16x16x32_bf16 v[120:123], v[154:157], v[196:199], v[20:23]
	v_mfma_f32_16x16x32_bf16 v[108:111], v[228:231], v[204:207], v[88:91]
	v_mfma_f32_16x16x32_bf16 v[104:107], v[154:157], v[204:207], v[104:107]
	v_mfma_f32_16x16x32_bf16 v[92:95], v[228:231], v[212:215], v[76:79]
	v_mfma_f32_16x16x32_bf16 v[88:91], v[154:157], v[212:215], v[72:75]
	v_mfma_f32_16x16x32_bf16 v[76:79], v[228:231], v[220:223], v[178:181]
	v_mfma_f32_16x16x32_bf16 v[72:75], v[154:157], v[220:223], v[182:185]
	s_barrier
	ds_read_b128 v[178:181], v152 offset:49152
	ds_read_b128 v[182:185], v152 offset:50176
	ds_read_b128 v[186:189], v151 offset:49152
	ds_read_b128 v[190:193], v151 offset:50176
	ds_read_b128 v[194:197], v150 offset:49152
	ds_read_b128 v[150:153], v150 offset:50176
	ds_read_b128 v[198:201], v149 offset:49152
	ds_read_b128 v[202:205], v149 offset:50176
	s_barrier
	s_waitcnt lgkmcnt(0)
	s_waitcnt lgkmcnt(0)
	v_mfma_f32_16x16x32_bf16 v[20:23], v[0:3], v[178:181], v[60:63]
	v_mfma_f32_16x16x32_bf16 v[56:59], v[16:19], v[178:181], v[56:59]
	v_mfma_f32_16x16x32_bf16 v[60:63], v[0:3], v[186:189], v[52:55]
	v_mfma_f32_16x16x32_bf16 v[206:209], v[16:19], v[186:189], v[48:51]
	v_mfma_f32_16x16x32_bf16 v[44:47], v[0:3], v[194:197], v[44:47]
	v_mfma_f32_16x16x32_bf16 v[40:43], v[16:19], v[194:197], v[40:43]
	v_mfma_f32_16x16x32_bf16 v[0:3], v[0:3], v[198:201], v[36:39]
	v_mfma_f32_16x16x32_bf16 v[210:213], v[16:19], v[198:201], v[32:35]
	v_mfma_f32_16x16x32_bf16 v[52:55], v[4:7], v[182:185], v[20:23]
	v_mfma_f32_16x16x32_bf16 v[48:51], v[174:177], v[182:185], v[56:59]
	v_mfma_f32_16x16x32_bf16 v[36:39], v[4:7], v[190:193], v[60:63]
	v_mfma_f32_16x16x32_bf16 v[32:35], v[174:177], v[190:193], v[206:209]
	v_mfma_f32_16x16x32_bf16 v[20:23], v[4:7], v[150:153], v[44:47]
	v_mfma_f32_16x16x32_bf16 v[16:19], v[174:177], v[150:153], v[40:43]
	v_mfma_f32_16x16x32_bf16 v[4:7], v[4:7], v[202:205], v[0:3]
	v_mfma_f32_16x16x32_bf16 v[0:3], v[174:177], v[202:205], v[210:213]
	v_mfma_f32_16x16x32_bf16 v[28:31], v[224:227], v[178:181], v[28:31]
	v_mfma_f32_16x16x32_bf16 v[24:27], v[232:235], v[178:181], v[24:27]
	v_mfma_f32_16x16x32_bf16 v[40:43], v[224:227], v[186:189], v[134:137]
	v_mfma_f32_16x16x32_bf16 v[134:137], v[232:235], v[186:189], v[138:141]
	v_mfma_f32_16x16x32_bf16 v[12:15], v[224:227], v[194:197], v[12:15]
	v_mfma_f32_16x16x32_bf16 v[8:11], v[232:235], v[194:197], v[8:11]
	v_mfma_f32_16x16x32_bf16 v[138:141], v[224:227], v[198:201], v[170:173]
	v_mfma_f32_16x16x32_bf16 v[158:161], v[232:235], v[198:201], v[158:161]
	v_mfma_f32_16x16x32_bf16 v[60:63], v[228:231], v[182:185], v[28:31]
	v_mfma_f32_16x16x32_bf16 v[56:59], v[154:157], v[182:185], v[24:27]
	v_mfma_f32_16x16x32_bf16 v[44:47], v[228:231], v[190:193], v[40:43]
	v_mfma_f32_16x16x32_bf16 v[40:43], v[154:157], v[190:193], v[134:137]
	v_mfma_f32_16x16x32_bf16 v[28:31], v[228:231], v[150:153], v[12:15]
	v_mfma_f32_16x16x32_bf16 v[24:27], v[154:157], v[150:153], v[8:11]
	v_mfma_f32_16x16x32_bf16 v[12:15], v[228:231], v[202:205], v[138:141]
	v_mfma_f32_16x16x32_bf16 v[8:11], v[154:157], v[202:205], v[158:161]
	v_cmp_gt_u32_e32 vcc, s66, v130
	s_barrier
	s_and_saveexec_b64 s[50:51], vcc
	s_cbranch_execz .LBB0_773
	s_barrier

; #define STAGE(P, BASE, LD, br, kt) do { const char* _g = (const char*)((BASE) + (size_t)(br) * (LD) + (size_t)(kt) * 64); \
;     for (int _i = 0; _i < 2; ++_i) { int _b = tidx * 16 + _i * 8192; int _r, _c; stage_rc(_b, _r, _c); \
;       __builtin_amdgcn_global_load_lds((const unsigned*)(_g + (unsigned)((_r * (LD) + _c) * 2)), (unsigned*)((char*)(P) + _b), 16, 0, 0); } } while (0)
; #define LDA(dst, b, h) for (int m = 0; m < 4; ++m) for (int k = 0; k < 2; ++k) \
;     dst[m][k] = *reinterpret_cast<const bf16x8*>((char*)SA(b, h) + lds_byte(wr * 64 + m * 16 + fr, k * 32 + fq * 8))
; #define LDB(dst, b, h) for (int n = 0; n < 2; ++n) for (int k = 0; k < 2; ++k) \
;     dst[n][k] = *reinterpret_cast<const bf16x8*>((char*)SB(b, h) + lds_byte(wc * 32 + n * 16 + fr, k * 32 + fq * 8))
; #define MMA(ai, bj, At_, Bt_) do { __builtin_amdgcn_s_setprio(1); \
;     for (int k = 0; k < 2; ++k) for (int m = 0; m < 4; ++m) for (int n = 0; n < 2; ++n) \
;       acc[ai][bj][m][n] = __builtin_amdgcn_mfma_f32_16x16x32_bf16(At_[m][k], Bt_[n][k], acc[ai][bj][m][n], 0, 0, 0); \
;     __builtin_amdgcn_s_setprio(0); } while (0)
; #define WAIT_L(n) asm volatile("s_waitcnt lgkmcnt(" #n ")" ::: "memory")
; #define BAR __builtin_amdgcn_s_barrier()
; #define SCHED __builtin_amdgcn_sched_barrier(0)
; template <int EPI, int lda, int ldb, int N, int K>
; __device__ __forceinline__ void gemm_phase(const u16* __restrict__ A, const u16* __restrict__ Bt, const GemmEpi ep, int wv) {
;     ...
;     for (int t = 0; t < nt - 2; t += 2) {
;       LDB(B0, 0, 0); SCHED; LDA(At, 0, 0); STAGE(SA(1, 1), Ab, lda, brow + HALF, t + 1);
;       WAIT_L(8); BAR; WAIT_L(0); MMA(0, 0, At, B0); BAR; SCHED;
;       LDB(B1, 0, 1); STAGE(SB(0, 0), Bt, ldb, bcol, t + 2);
;       BAR; WAIT_L(0); MMA(0, 1, At, B1); BAR;
;       LDA(At, 0, 1); STAGE(SA(0, 0), Ab, lda, brow, t + 2);
;       BAR; WAIT_L(0); MMA(1, 0, At, B0); BAR; SCHED;
.LBB0_838:
	ds_read_b128 v[168:171], v164
	ds_read_b128 v[174:177], v164 offset:1024
	ds_read_b128 v[178:181], v164 offset:2048
	ds_read_b128 v[182:185], v164 offset:3072
	v_add_u32_e32 v172, 0xc000, v147
	v_lshl_add_u64 v[238:239], v[136:137], 0, s[50:51]
	v_readfirstlane_b32 s73, v172
	v_add_u32_e32 v173, 0xe000, v147
	v_lshl_add_u64 v[166:167], v[238:239], 0, s[22:23]
	s_mov_b32 m0, s73
	v_lshl_add_u64 v[240:241], v[134:135], 0, s[50:51]
	v_readfirstlane_b32 s73, v173
	ds_read_b128 v[186:189], v155
	ds_read_b128 v[190:193], v155 offset:1024
	ds_read_b128 v[194:197], v154
	ds_read_b128 v[198:201], v154 offset:1024
	ds_read_b128 v[202:205], v153
	ds_read_b128 v[206:209], v153 offset:1024
	ds_read_b128 v[210:213], v152
	ds_read_b128 v[214:217], v152 offset:1024
	global_load_lds_dwordx4 v[166:167], off
	v_lshl_add_u64 v[166:167], v[240:241], 0, s[22:23]
	s_mov_b32 m0, s73
	s_nop 0
	global_load_lds_dwordx4 v[166:167], off
	s_waitcnt lgkmcnt(8)
	s_barrier
	s_waitcnt lgkmcnt(0)
	s_waitcnt lgkmcnt(0)
	v_mfma_f32_16x16x32_bf16 v[124:127], v[168:171], v[186:189], v[124:127]
	v_mfma_f32_16x16x32_bf16 v[120:123], v[178:181], v[186:189], v[120:123]
	v_mfma_f32_16x16x32_bf16 v[116:119], v[168:171], v[194:197], v[116:119]
	v_mfma_f32_16x16x32_bf16 v[112:115], v[178:181], v[194:197], v[112:115]
	v_mfma_f32_16x16x32_bf16 v[108:111], v[168:171], v[202:205], v[108:111]
	v_mfma_f32_16x16x32_bf16 v[104:107], v[178:181], v[202:205], v[104:107]
	v_mfma_f32_16x16x32_bf16 v[100:103], v[168:171], v[210:213], v[100:103]
	v_mfma_f32_16x16x32_bf16 v[96:99], v[178:181], v[210:213], v[96:99]
	v_mfma_f32_16x16x32_bf16 v[124:127], v[174:177], v[190:193], v[124:127]
	v_mfma_f32_16x16x32_bf16 v[120:123], v[182:185], v[190:193], v[120:123]
	v_mfma_f32_16x16x32_bf16 v[116:119], v[174:177], v[198:201], v[116:119]
	v_mfma_f32_16x16x32_bf16 v[112:115], v[182:185], v[198:201], v[112:115]
	v_mfma_f32_16x16x32_bf16 v[108:111], v[174:177], v[206:209], v[108:111]
	v_mfma_f32_16x16x32_bf16 v[104:107], v[182:185], v[206:209], v[104:107]
	v_mfma_f32_16x16x32_bf16 v[100:103], v[174:177], v[214:217], v[100:103]
	v_mfma_f32_16x16x32_bf16 v[96:99], v[182:185], v[214:217], v[96:99]
	s_barrier
	v_add_u32_e32 v165, s63, v156
	v_lshl_add_u64 v[242:243], v[144:145], 0, s[50:51]
	v_readfirstlane_b32 s73, v165
	v_lshl_add_u64 v[166:167], v[242:243], 0, s[24:25]
	s_mov_b32 m0, s73
	ds_read_b128 v[218:221], v163
	ds_read_b128 v[222:225], v163 offset:1024
	ds_read_b128 v[226:229], v163 offset:2048
	ds_read_b128 v[230:233], v163 offset:3072
	global_load_lds_dwordx4 v[166:167], off
	v_add_u32_e32 v166, 0x2000, v165
	v_lshl_add_u64 v[244:245], v[142:143], 0, s[50:51]
	v_readfirstlane_b32 s73, v166
	v_lshl_add_u64 v[234:235], v[244:245], 0, s[24:25]
	s_mov_b32 m0, s73
	s_nop 0
	global_load_lds_dwordx4 v[234:235], off
	s_barrier
	s_waitcnt lgkmcnt(0)
	s_waitcnt lgkmcnt(0)
	v_mfma_f32_16x16x32_bf16 v[92:95], v[218:221], v[186:189], v[92:95]
	v_mfma_f32_16x16x32_bf16 v[88:91], v[226:229], v[186:189], v[88:91]
	v_mfma_f32_16x16x32_bf16 v[84:87], v[218:221], v[194:197], v[84:87]
	v_mfma_f32_16x16x32_bf16 v[80:83], v[226:229], v[194:197], v[80:83]
	v_mfma_f32_16x16x32_bf16 v[76:79], v[218:221], v[202:205], v[76:79]
	v_mfma_f32_16x16x32_bf16 v[72:75], v[226:229], v[202:205], v[72:75]
	v_mfma_f32_16x16x32_bf16 v[68:71], v[218:221], v[210:213], v[68:71]
	v_mfma_f32_16x16x32_bf16 v[64:67], v[226:229], v[210:213], v[64:67]
	v_mfma_f32_16x16x32_bf16 v[92:95], v[222:225], v[190:193], v[92:95]
	v_mfma_f32_16x16x32_bf16 v[88:91], v[230:233], v[190:193], v[88:91]
	v_mfma_f32_16x16x32_bf16 v[84:87], v[222:225], v[198:201], v[84:87]
	v_mfma_f32_16x16x32_bf16 v[80:83], v[230:233], v[198:201], v[80:83]
	v_mfma_f32_16x16x32_bf16 v[76:79], v[222:225], v[206:209], v[76:79]
	v_mfma_f32_16x16x32_bf16 v[72:75], v[230:233], v[206:209], v[72:75]
	v_mfma_f32_16x16x32_bf16 v[68:71], v[222:225], v[214:217], v[68:71]
	v_mfma_f32_16x16x32_bf16 v[64:67], v[230:233], v[214:217], v[64:67]
	s_barrier
	v_readfirstlane_b32 s73, v147
	v_add_u32_e32 v167, 0x2000, v147
	v_lshl_add_u64 v[234:235], v[238:239], 0, s[26:27]
	s_mov_b32 m0, s73
	v_readfirstlane_b32 s73, v167
	ds_read_b128 v[186:189], v155 offset:16384
	ds_read_b128 v[190:193], v155 offset:17408
	ds_read_b128 v[194:197], v154 offset:16384
	ds_read_b128 v[198:201], v154 offset:17408
	ds_read_b128 v[202:205], v153 offset:16384
	ds_read_b128 v[206:209], v153 offset:17408
	ds_read_b128 v[210:213], v152 offset:16384
	ds_read_b128 v[214:217], v152 offset:17408
	global_load_lds_dwordx4 v[234:235], off
	v_lshl_add_u64 v[234:235], v[240:241], 0, s[26:27]
	s_mov_b32 m0, s73
	s_nop 0
	global_load_lds_dwordx4 v[234:235], off
	s_barrier
	s_waitcnt lgkmcnt(0)
	s_waitcnt lgkmcnt(0)
	v_mfma_f32_16x16x32_bf16 v[60:63], v[168:171], v[186:189], v[60:63]
	v_mfma_f32_16x16x32_bf16 v[56:59], v[178:181], v[186:189], v[56:59]
	v_mfma_f32_16x16x32_bf16 v[52:55], v[168:171], v[194:197], v[52:55]
	v_mfma_f32_16x16x32_bf16 v[48:51], v[178:181], v[194:197], v[48:51]
	v_mfma_f32_16x16x32_bf16 v[44:47], v[168:171], v[202:205], v[44:47]
	v_mfma_f32_16x16x32_bf16 v[40:43], v[178:181], v[202:205], v[40:43]
	v_mfma_f32_16x16x32_bf16 v[36:39], v[168:171], v[210:213], v[36:39]
	v_mfma_f32_16x16x32_bf16 v[32:35], v[178:181], v[210:213], v[32:35]
	v_mfma_f32_16x16x32_bf16 v[60:63], v[174:177], v[190:193], v[60:63]
	v_mfma_f32_16x16x32_bf16 v[56:59], v[182:185], v[190:193], v[56:59]
	v_mfma_f32_16x16x32_bf16 v[52:55], v[174:177], v[198:201], v[52:55]
	v_mfma_f32_16x16x32_bf16 v[48:51], v[182:185], v[198:201], v[48:51]
	v_mfma_f32_16x16x32_bf16 v[44:47], v[174:177], v[206:209], v[44:47]
	v_mfma_f32_16x16x32_bf16 v[40:43], v[182:185], v[206:209], v[40:43]
	v_mfma_f32_16x16x32_bf16 v[36:39], v[174:177], v[214:217], v[36:39]
	v_mfma_f32_16x16x32_bf16 v[32:35], v[182:185], v[214:217], v[32:35]
	s_barrier
; #define STAGE(P, BASE, LD, br, kt) do { const char* _g = (const char*)((BASE) + (size_t)(br) * (LD) + (size_t)(kt) * 64); \
;     for (int _i = 0; _i < 2; ++_i) { int _b = tidx * 16 + _i * 8192; int _r, _c; stage_rc(_b, _r, _c); \
;       __builtin_amdgcn_global_load_lds((const unsigned*)(_g + (unsigned)((_r * (LD) + _c) * 2)), (unsigned*)((char*)(P) + _b), 16, 0, 0); } } while (0)
; #define LDA(dst, b, h) for (int m = 0; m < 4; ++m) for (int k = 0; k < 2; ++k) \
;     dst[m][k] = *reinterpret_cast<const bf16x8*>((char*)SA(b, h) + lds_byte(wr * 64 + m * 16 + fr, k * 32 + fq * 8))
; #define LDB(dst, b, h) for (int n = 0; n < 2; ++n) for (int k = 0; k < 2; ++k) \
;     dst[n][k] = *reinterpret_cast<const bf16x8*>((char*)SB(b, h) + lds_byte(wc * 32 + n * 16 + fr, k * 32 + fq * 8))
; #define MMA(ai, bj, At_, Bt_) do { __builtin_amdgcn_s_setprio(1); \
;     for (int k = 0; k < 2; ++k) for (int m = 0; m < 4; ++m) for (int n = 0; n < 2; ++n) \
;       acc[ai][bj][m][n] = __builtin_amdgcn_mfma_f32_16x16x32_bf16(At_[m][k], Bt_[n][k], acc[ai][bj][m][n], 0, 0, 0); \
;     __builtin_amdgcn_s_setprio(0); } while (0)
; #define WAIT_V(n) asm volatile("s_waitcnt vmcnt(" #n ")" ::: "memory")
; #define WAIT_L(n) asm volatile("s_waitcnt lgkmcnt(" #n ")" ::: "memory")
; #define BAR __builtin_amdgcn_s_barrier()
; #define SCHED __builtin_amdgcn_sched_barrier(0)
; template <int EPI, int lda, int ldb, int N, int K>
; __device__ __forceinline__ void gemm_phase(const u16* __restrict__ A, const u16* __restrict__ Bt, const GemmEpi ep, int wv) {
;     ...
;       STAGE(SB(0, 1), Bt, ldb, bcol + HALF, t + 2);
;       WAIT_V(6); BAR; MMA(1, 1, At, B1); BAR;
;       LDB(B0, 1, 0); SCHED; LDA(At, 1, 0); STAGE(SA(0, 1), Ab, lda, brow + HALF, t + 2);
;       WAIT_L(8); BAR; WAIT_L(0); MMA(0, 0, At, B0); BAR; SCHED;
;       LDB(B1, 1, 1); STAGE(SB(1, 0), Bt, ldb, bcol, t + 3);
;       BAR; WAIT_L(0); MMA(0, 1, At, B1); BAR;
;       LDA(At, 1, 1); STAGE(SA(1, 0), Ab, lda, brow, t + 3);
	v_add_u32_e32 v168, s64, v156
	v_lshl_add_u64 v[246:247], v[140:141], 0, s[50:51]
	v_readfirstlane_b32 s73, v168
	v_add_u32_e32 v169, 0x2000, v168
	v_lshl_add_u64 v[170:171], v[246:247], 0, s[40:41]
	s_mov_b32 m0, s73
	v_lshl_add_u64 v[248:249], v[138:139], 0, s[50:51]
	v_readfirstlane_b32 s73, v169
	global_load_lds_dwordx4 v[170:171], off
	v_lshl_add_u64 v[170:171], v[248:249], 0, s[40:41]
	s_mov_b32 m0, s73
	s_nop 0
	global_load_lds_dwordx4 v[170:171], off
	s_waitcnt vmcnt(6)
	s_barrier
	v_mfma_f32_16x16x32_bf16 v[28:31], v[218:221], v[186:189], v[28:31]
	v_mfma_f32_16x16x32_bf16 v[24:27], v[226:229], v[186:189], v[24:27]
	v_mfma_f32_16x16x32_bf16 v[20:23], v[218:221], v[194:197], v[20:23]
	v_mfma_f32_16x16x32_bf16 v[16:19], v[226:229], v[194:197], v[16:19]
	v_mfma_f32_16x16x32_bf16 v[12:15], v[218:221], v[202:205], v[12:15]
	v_mfma_f32_16x16x32_bf16 v[8:11], v[226:229], v[202:205], v[8:11]
	v_mfma_f32_16x16x32_bf16 v[4:7], v[218:221], v[210:213], v[4:7]
	v_mfma_f32_16x16x32_bf16 v[0:3], v[226:229], v[210:213], v[0:3]
	v_mfma_f32_16x16x32_bf16 v[28:31], v[222:225], v[190:193], v[28:31]
	v_mfma_f32_16x16x32_bf16 v[24:27], v[230:233], v[190:193], v[24:27]
	v_mfma_f32_16x16x32_bf16 v[20:23], v[222:225], v[198:201], v[20:23]
	v_mfma_f32_16x16x32_bf16 v[16:19], v[230:233], v[198:201], v[16:19]
	v_mfma_f32_16x16x32_bf16 v[12:15], v[222:225], v[206:209], v[12:15]
	v_mfma_f32_16x16x32_bf16 v[8:11], v[230:233], v[206:209], v[8:11]
	v_mfma_f32_16x16x32_bf16 v[4:7], v[222:225], v[214:217], v[4:7]
	v_mfma_f32_16x16x32_bf16 v[0:3], v[230:233], v[214:217], v[0:3]
	s_barrier
	ds_read_b128 v[174:177], v159
	ds_read_b128 v[178:181], v159 offset:1024
	ds_read_b128 v[182:185], v159 offset:2048
	ds_read_b128 v[186:189], v159 offset:3072
	v_add_u32_e32 v170, 0x4000, v147
	v_add_u32_e32 v171, 0x6000, v147
	v_readfirstlane_b32 s73, v170
	v_lshl_add_u64 v[222:223], v[238:239], 0, s[42:43]
	s_mov_b32 m0, s73
	v_readfirstlane_b32 s73, v171
	ds_read_b128 v[190:193], v155 offset:32768
	ds_read_b128 v[194:197], v155 offset:33792
	ds_read_b128 v[198:201], v154 offset:32768
	ds_read_b128 v[202:205], v154 offset:33792
	ds_read_b128 v[206:209], v153 offset:32768
	ds_read_b128 v[210:213], v153 offset:33792
	ds_read_b128 v[214:217], v152 offset:32768
	ds_read_b128 v[218:221], v152 offset:33792
	global_load_lds_dwordx4 v[222:223], off
	v_lshl_add_u64 v[222:223], v[240:241], 0, s[42:43]
	s_mov_b32 m0, s73
	s_nop 0
	global_load_lds_dwordx4 v[222:223], off
	s_waitcnt lgkmcnt(8)
	s_barrier
	s_waitcnt lgkmcnt(0)
	s_waitcnt lgkmcnt(0)
	v_mfma_f32_16x16x32_bf16 v[124:127], v[174:177], v[190:193], v[124:127]
	v_mfma_f32_16x16x32_bf16 v[120:123], v[182:185], v[190:193], v[120:123]
	v_mfma_f32_16x16x32_bf16 v[116:119], v[174:177], v[198:201], v[116:119]
	v_mfma_f32_16x16x32_bf16 v[112:115], v[182:185], v[198:201], v[112:115]
	v_mfma_f32_16x16x32_bf16 v[108:111], v[174:177], v[206:209], v[108:111]
	v_mfma_f32_16x16x32_bf16 v[104:107], v[182:185], v[206:209], v[104:107]
	v_mfma_f32_16x16x32_bf16 v[100:103], v[174:177], v[214:217], v[100:103]
	v_mfma_f32_16x16x32_bf16 v[96:99], v[182:185], v[214:217], v[96:99]
	v_mfma_f32_16x16x32_bf16 v[124:127], v[178:181], v[194:197], v[124:127]
	v_mfma_f32_16x16x32_bf16 v[120:123], v[186:189], v[194:197], v[120:123]
	v_mfma_f32_16x16x32_bf16 v[116:119], v[178:181], v[202:205], v[116:119]
	v_mfma_f32_16x16x32_bf16 v[112:115], v[186:189], v[202:205], v[112:115]
	v_mfma_f32_16x16x32_bf16 v[108:111], v[178:181], v[210:213], v[108:111]
	v_mfma_f32_16x16x32_bf16 v[104:107], v[186:189], v[210:213], v[104:107]
	v_mfma_f32_16x16x32_bf16 v[100:103], v[178:181], v[218:221], v[100:103]
	v_mfma_f32_16x16x32_bf16 v[96:99], v[186:189], v[218:221], v[96:99]
	s_barrier
	v_readfirstlane_b32 s73, v158
	v_lshl_add_u64 v[242:243], v[242:243], 0, s[44:45]
	s_mov_b32 m0, s73
	ds_read_b128 v[222:225], v157
	ds_read_b128 v[226:229], v157 offset:1024
	ds_read_b128 v[230:233], v157 offset:2048
	ds_read_b128 v[234:237], v157 offset:3072
	global_load_lds_dwordx4 v[242:243], off
	v_lshl_add_u64 v[242:243], v[244:245], 0, s[44:45]
	v_add_u32_e32 v244, 0x2000, v158
	s_nop 0
	v_readfirstlane_b32 s73, v244
	s_mov_b32 m0, s73
	s_nop 0
	global_load_lds_dwordx4 v[242:243], off
	s_barrier
	s_waitcnt lgkmcnt(0)
	s_waitcnt lgkmcnt(0)
	v_mfma_f32_16x16x32_bf16 v[92:95], v[222:225], v[190:193], v[92:95]
	v_mfma_f32_16x16x32_bf16 v[88:91], v[230:233], v[190:193], v[88:91]
	v_mfma_f32_16x16x32_bf16 v[84:87], v[222:225], v[198:201], v[84:87]
	v_mfma_f32_16x16x32_bf16 v[80:83], v[230:233], v[198:201], v[80:83]
	v_mfma_f32_16x16x32_bf16 v[76:79], v[222:225], v[206:209], v[76:79]
	v_mfma_f32_16x16x32_bf16 v[72:75], v[230:233], v[206:209], v[72:75]
	v_mfma_f32_16x16x32_bf16 v[68:71], v[222:225], v[214:217], v[68:71]
	v_mfma_f32_16x16x32_bf16 v[64:67], v[230:233], v[214:217], v[64:67]
	v_mfma_f32_16x16x32_bf16 v[92:95], v[226:229], v[194:197], v[92:95]
	v_mfma_f32_16x16x32_bf16 v[88:91], v[234:237], v[194:197], v[88:91]
	v_mfma_f32_16x16x32_bf16 v[84:87], v[226:229], v[202:205], v[84:87]
	v_mfma_f32_16x16x32_bf16 v[80:83], v[234:237], v[202:205], v[80:83]
	v_mfma_f32_16x16x32_bf16 v[76:79], v[226:229], v[210:213], v[76:79]
	v_mfma_f32_16x16x32_bf16 v[72:75], v[234:237], v[210:213], v[72:75]
	v_mfma_f32_16x16x32_bf16 v[68:71], v[226:229], v[218:221], v[68:71]
	v_mfma_f32_16x16x32_bf16 v[64:67], v[234:237], v[218:221], v[64:67]
	s_barrier
; #define STAGE(P, BASE, LD, br, kt) do { const char* _g = (const char*)((BASE) + (size_t)(br) * (LD) + (size_t)(kt) * 64); \
;     for (int _i = 0; _i < 2; ++_i) { int _b = tidx * 16 + _i * 8192; int _r, _c; stage_rc(_b, _r, _c); \
;       __builtin_amdgcn_global_load_lds((const unsigned*)(_g + (unsigned)((_r * (LD) + _c) * 2)), (unsigned*)((char*)(P) + _b), 16, 0, 0); } } while (0)
; #define LDA(dst, b, h) for (int m = 0; m < 4; ++m) for (int k = 0; k < 2; ++k) \
;     dst[m][k] = *reinterpret_cast<const bf16x8*>((char*)SA(b, h) + lds_byte(wr * 64 + m * 16 + fr, k * 32 + fq * 8))
; #define LDB(dst, b, h) for (int n = 0; n < 2; ++n) for (int k = 0; k < 2; ++k) \
;     dst[n][k] = *reinterpret_cast<const bf16x8*>((char*)SB(b, h) + lds_byte(wc * 32 + n * 16 + fr, k * 32 + fq * 8))
; #define MMA(ai, bj, At_, Bt_) do { __builtin_amdgcn_s_setprio(1); \
;     for (int k = 0; k < 2; ++k) for (int m = 0; m < 4; ++m) for (int n = 0; n < 2; ++n) \
;       acc[ai][bj][m][n] = __builtin_amdgcn_mfma_f32_16x16x32_bf16(At_[m][k], Bt_[n][k], acc[ai][bj][m][n], 0, 0, 0); \
;     __builtin_amdgcn_s_setprio(0); } while (0)
; #define WAIT_V(n) asm volatile("s_waitcnt vmcnt(" #n ")" ::: "memory")
; #define WAIT_L(n) asm volatile("s_waitcnt lgkmcnt(" #n ")" ::: "memory")
; #define BAR __builtin_amdgcn_s_barrier()
; #define SCHED __builtin_amdgcn_sched_barrier(0)
; template <int EPI, int lda, int ldb, int N, int K>
; __device__ __forceinline__ void gemm_phase(const u16* __restrict__ A, const u16* __restrict__ Bt, const GemmEpi ep, int wv) {
;     ...
;       BAR; WAIT_L(0); MMA(1, 0, At, B0); BAR; SCHED;
;       STAGE(SB(1, 1), Bt, ldb, bcol + HALF, t + 3);
;       WAIT_V(6); BAR; MMA(1, 1, At, B1); BAR;
;     }
;     { LDB(B0, 0, 0); LDA(At, 0, 0); STAGE(SA(1, 1), Ab, lda, brow + HALF, nt - 1);
;       BAR; WAIT_L(0); MMA(0, 0, At, B0); BAR;
;       LDB(B1, 0, 1); BAR; WAIT_L(0); MMA(0, 1, At, B1); BAR;
	v_readfirstlane_b32 s73, v160
	v_lshl_add_u64 v[238:239], v[238:239], 0, s[46:47]
	s_mov_b32 m0, s73
	v_readfirstlane_b32 s73, v161
	ds_read_b128 v[190:193], v155 offset:49152
	ds_read_b128 v[194:197], v155 offset:50176
	ds_read_b128 v[198:201], v154 offset:49152
	ds_read_b128 v[202:205], v154 offset:50176
	ds_read_b128 v[206:209], v153 offset:49152
	ds_read_b128 v[210:213], v153 offset:50176
	ds_read_b128 v[214:217], v152 offset:49152
	ds_read_b128 v[218:221], v152 offset:50176
	global_load_lds_dwordx4 v[238:239], off
	v_lshl_add_u64 v[238:239], v[240:241], 0, s[46:47]
	s_mov_b32 m0, s73
	s_nop 0
	global_load_lds_dwordx4 v[238:239], off
	s_barrier
	s_waitcnt lgkmcnt(0)
	s_waitcnt lgkmcnt(0)
	v_mfma_f32_16x16x32_bf16 v[60:63], v[174:177], v[190:193], v[60:63]
	v_mfma_f32_16x16x32_bf16 v[56:59], v[182:185], v[190:193], v[56:59]
	v_mfma_f32_16x16x32_bf16 v[52:55], v[174:177], v[198:201], v[52:55]
	v_mfma_f32_16x16x32_bf16 v[48:51], v[182:185], v[198:201], v[48:51]
	v_mfma_f32_16x16x32_bf16 v[44:47], v[174:177], v[206:209], v[44:47]
	v_mfma_f32_16x16x32_bf16 v[40:43], v[182:185], v[206:209], v[40:43]
	v_mfma_f32_16x16x32_bf16 v[36:39], v[174:177], v[214:217], v[36:39]
	v_mfma_f32_16x16x32_bf16 v[32:35], v[182:185], v[214:217], v[32:35]
	v_mfma_f32_16x16x32_bf16 v[60:63], v[178:181], v[194:197], v[60:63]
	v_mfma_f32_16x16x32_bf16 v[56:59], v[186:189], v[194:197], v[56:59]
	v_mfma_f32_16x16x32_bf16 v[52:55], v[178:181], v[202:205], v[52:55]
	v_mfma_f32_16x16x32_bf16 v[48:51], v[186:189], v[202:205], v[48:51]
	v_mfma_f32_16x16x32_bf16 v[44:47], v[178:181], v[210:213], v[44:47]
	v_mfma_f32_16x16x32_bf16 v[40:43], v[186:189], v[210:213], v[40:43]
	v_mfma_f32_16x16x32_bf16 v[36:39], v[178:181], v[218:221], v[36:39]
	v_mfma_f32_16x16x32_bf16 v[32:35], v[186:189], v[218:221], v[32:35]
	s_barrier
	v_readfirstlane_b32 s73, v162
	v_add_u32_e32 v176, 0x2000, v162
	v_lshl_add_u64 v[174:175], v[246:247], 0, s[48:49]
	s_mov_b32 m0, s73
	v_readfirstlane_b32 s73, v176
	global_load_lds_dwordx4 v[174:175], off
	v_lshl_add_u64 v[174:175], v[248:249], 0, s[48:49]
	s_mov_b32 m0, s73
	s_nop 0
	global_load_lds_dwordx4 v[174:175], off
	s_add_i32 s72, s72, 2
	s_add_u32 s50, s50, 0x100
	s_addc_u32 s51, s51, 0
	s_cmpk_gt_u32 s72, 0x51
	s_waitcnt vmcnt(6)
	s_barrier
	v_mfma_f32_16x16x32_bf16 v[28:31], v[222:225], v[190:193], v[28:31]
	v_mfma_f32_16x16x32_bf16 v[24:27], v[230:233], v[190:193], v[24:27]
	v_mfma_f32_16x16x32_bf16 v[20:23], v[222:225], v[198:201], v[20:23]
	v_mfma_f32_16x16x32_bf16 v[16:19], v[230:233], v[198:201], v[16:19]
	v_mfma_f32_16x16x32_bf16 v[12:15], v[222:225], v[206:209], v[12:15]
	v_mfma_f32_16x16x32_bf16 v[8:11], v[230:233], v[206:209], v[8:11]
	v_mfma_f32_16x16x32_bf16 v[4:7], v[222:225], v[214:217], v[4:7]
	v_mfma_f32_16x16x32_bf16 v[0:3], v[230:233], v[214:217], v[0:3]
	v_mfma_f32_16x16x32_bf16 v[28:31], v[226:229], v[194:197], v[28:31]
	v_mfma_f32_16x16x32_bf16 v[24:27], v[234:237], v[194:197], v[24:27]
	v_mfma_f32_16x16x32_bf16 v[20:23], v[226:229], v[202:205], v[20:23]
	v_mfma_f32_16x16x32_bf16 v[16:19], v[234:237], v[202:205], v[16:19]
	v_mfma_f32_16x16x32_bf16 v[12:15], v[226:229], v[210:213], v[12:15]
	v_mfma_f32_16x16x32_bf16 v[8:11], v[234:237], v[210:213], v[8:11]
	v_mfma_f32_16x16x32_bf16 v[4:7], v[226:229], v[218:221], v[4:7]
	v_mfma_f32_16x16x32_bf16 v[0:3], v[234:237], v[218:221], v[0:3]
	s_barrier
	s_cbranch_scc0 .LBB0_838
	s_add_i32 s50, s18, 0x80
	s_mul_hi_i32 s51, s50, 0x2b00
	s_mulk_i32 s50, 0x2b00
	s_add_u32 s50, s56, s50
	s_addc_u32 s51, s57, s51
	s_add_u32 s50, s50, 0x2a80
	s_addc_u32 s51, s51, 0
	v_readfirstlane_b32 s72, v172
	v_lshl_add_u64 v[160:161], s[50:51], 0, v[128:129]
	s_mov_b32 m0, s72
	ds_read_b128 v[134:137], v164
	ds_read_b128 v[138:141], v164 offset:1024
	ds_read_b128 v[142:145], v164 offset:2048
	ds_read_b128 v[174:177], v164 offset:3072
	ds_read_b128 v[178:181], v155
	ds_read_b128 v[182:185], v155 offset:1024
	ds_read_b128 v[186:189], v154
	ds_read_b128 v[190:193], v154 offset:1024
	ds_read_b128 v[194:197], v153
	ds_read_b128 v[198:201], v153 offset:1024
	ds_read_b128 v[202:205], v152
	ds_read_b128 v[206:209], v152 offset:1024
	global_load_lds_dwordx4 v[160:161], off
	v_lshl_add_u64 v[160:161], s[50:51], 0, v[132:133]
	v_readfirstlane_b32 s50, v173
	s_mov_b32 m0, s50
	s_nop 0
	global_load_lds_dwordx4 v[160:161], off
	s_barrier
	s_waitcnt lgkmcnt(0)
	s_waitcnt lgkmcnt(0)
	v_mfma_f32_16x16x32_bf16 v[124:127], v[134:137], v[178:181], v[124:127]
	v_mfma_f32_16x16x32_bf16 v[120:123], v[142:145], v[178:181], v[120:123]
	v_mfma_f32_16x16x32_bf16 v[116:119], v[134:137], v[186:189], v[116:119]
	v_mfma_f32_16x16x32_bf16 v[112:115], v[142:145], v[186:189], v[112:115]
	v_mfma_f32_16x16x32_bf16 v[108:111], v[134:137], v[194:197], v[108:111]
	v_mfma_f32_16x16x32_bf16 v[104:107], v[142:145], v[194:197], v[104:107]
	v_mfma_f32_16x16x32_bf16 v[100:103], v[134:137], v[202:205], v[100:103]
	v_mfma_f32_16x16x32_bf16 v[96:99], v[142:145], v[202:205], v[96:99]
	v_mfma_f32_16x16x32_bf16 v[124:127], v[138:141], v[182:185], v[124:127]
	v_mfma_f32_16x16x32_bf16 v[120:123], v[174:177], v[182:185], v[120:123]
	v_mfma_f32_16x16x32_bf16 v[116:119], v[138:141], v[190:193], v[116:119]
	v_mfma_f32_16x16x32_bf16 v[112:115], v[174:177], v[190:193], v[112:115]
	v_mfma_f32_16x16x32_bf16 v[108:111], v[138:141], v[198:201], v[108:111]
	v_mfma_f32_16x16x32_bf16 v[104:107], v[174:177], v[198:201], v[104:107]
	v_mfma_f32_16x16x32_bf16 v[100:103], v[138:141], v[206:209], v[100:103]
	v_mfma_f32_16x16x32_bf16 v[96:99], v[174:177], v[206:209], v[96:99]
	s_barrier
; #define LDA(dst, b, h) for (int m = 0; m < 4; ++m) for (int k = 0; k < 2; ++k) \
;     dst[m][k] = *reinterpret_cast<const bf16x8*>((char*)SA(b, h) + lds_byte(wr * 64 + m * 16 + fr, k * 32 + fq * 8))
; #define LDB(dst, b, h) for (int n = 0; n < 2; ++n) for (int k = 0; k < 2; ++k) \
;     dst[n][k] = *reinterpret_cast<const bf16x8*>((char*)SB(b, h) + lds_byte(wc * 32 + n * 16 + fr, k * 32 + fq * 8))
; #define MMA(ai, bj, At_, Bt_) do { __builtin_amdgcn_s_setprio(1); \
;     for (int k = 0; k < 2; ++k) for (int m = 0; m < 4; ++m) for (int n = 0; n < 2; ++n) \
;       acc[ai][bj][m][n] = __builtin_amdgcn_mfma_f32_16x16x32_bf16(At_[m][k], Bt_[n][k], acc[ai][bj][m][n], 0, 0, 0); \
;     __builtin_amdgcn_s_setprio(0); } while (0)
; #define WAIT_V(n) asm volatile("s_waitcnt vmcnt(" #n ")" ::: "memory")
; #define WAIT_L(n) asm volatile("s_waitcnt lgkmcnt(" #n ")" ::: "memory")
; #define BAR __builtin_amdgcn_s_barrier()
; template <int EPI, int lda, int ldb, int N, int K>
; __device__ __forceinline__ void gemm_phase(const u16* __restrict__ A, const u16* __restrict__ Bt, const GemmEpi ep, int wv) {
;     ...
;       LDB(B1, 0, 1); BAR; WAIT_L(0); MMA(0, 1, At, B1); BAR;
;       LDA(At, 0, 1); WAIT_V(4); BAR; WAIT_L(0); MMA(1, 0, At, B0); MMA(1, 1, At, B1); BAR; }
;     { LDB(B0, 1, 0); LDA(At, 1, 0); WAIT_V(2); BAR; WAIT_L(0); MMA(0, 0, At, B0); BAR;
	ds_read_b128 v[210:213], v163
	ds_read_b128 v[214:217], v163 offset:1024
	ds_read_b128 v[218:221], v163 offset:2048
	ds_read_b128 v[160:163], v163 offset:3072
	s_barrier
	s_waitcnt lgkmcnt(0)
	s_waitcnt lgkmcnt(0)
	v_mfma_f32_16x16x32_bf16 v[92:95], v[210:213], v[178:181], v[92:95]
	v_mfma_f32_16x16x32_bf16 v[88:91], v[218:221], v[178:181], v[88:91]
	v_mfma_f32_16x16x32_bf16 v[76:79], v[210:213], v[194:197], v[76:79]
	v_mfma_f32_16x16x32_bf16 v[72:75], v[218:221], v[194:197], v[72:75]
	v_mfma_f32_16x16x32_bf16 v[84:87], v[210:213], v[186:189], v[84:87]
	v_mfma_f32_16x16x32_bf16 v[80:83], v[218:221], v[186:189], v[80:83]
	v_mfma_f32_16x16x32_bf16 v[68:71], v[210:213], v[202:205], v[68:71]
	v_mfma_f32_16x16x32_bf16 v[64:67], v[218:221], v[202:205], v[64:67]
	v_mfma_f32_16x16x32_bf16 v[92:95], v[214:217], v[182:185], v[92:95]
	v_mfma_f32_16x16x32_bf16 v[88:91], v[160:163], v[182:185], v[88:91]
	v_mfma_f32_16x16x32_bf16 v[76:79], v[214:217], v[198:201], v[76:79]
	v_mfma_f32_16x16x32_bf16 v[72:75], v[160:163], v[198:201], v[72:75]
	v_mfma_f32_16x16x32_bf16 v[178:181], v[214:217], v[190:193], v[84:87]
	v_mfma_f32_16x16x32_bf16 v[182:185], v[160:163], v[190:193], v[80:83]
	v_mfma_f32_16x16x32_bf16 v[186:189], v[214:217], v[206:209], v[68:71]
	v_mfma_f32_16x16x32_bf16 v[190:193], v[160:163], v[206:209], v[64:67]
	s_barrier
	s_nop 0
	ds_read_b128 v[64:67], v155 offset:16384
	ds_read_b128 v[68:71], v155 offset:17408
	ds_read_b128 v[80:83], v154 offset:16384
	ds_read_b128 v[84:87], v154 offset:17408
	ds_read_b128 v[194:197], v153 offset:16384
	ds_read_b128 v[198:201], v153 offset:17408
	ds_read_b128 v[202:205], v152 offset:16384
	ds_read_b128 v[206:209], v152 offset:17408
	s_waitcnt vmcnt(4)
	s_barrier
	s_waitcnt lgkmcnt(0)
	s_waitcnt lgkmcnt(0)
	v_mfma_f32_16x16x32_bf16 v[60:63], v[134:137], v[64:67], v[60:63]
	v_mfma_f32_16x16x32_bf16 v[56:59], v[142:145], v[64:67], v[56:59]
	v_mfma_f32_16x16x32_bf16 v[52:55], v[134:137], v[80:83], v[52:55]
	v_mfma_f32_16x16x32_bf16 v[48:51], v[142:145], v[80:83], v[48:51]
	v_mfma_f32_16x16x32_bf16 v[44:47], v[134:137], v[194:197], v[44:47]
	v_mfma_f32_16x16x32_bf16 v[40:43], v[142:145], v[194:197], v[40:43]
	v_mfma_f32_16x16x32_bf16 v[36:39], v[134:137], v[202:205], v[36:39]
	v_mfma_f32_16x16x32_bf16 v[32:35], v[142:145], v[202:205], v[32:35]
	v_mfma_f32_16x16x32_bf16 v[60:63], v[138:141], v[68:71], v[60:63]
	v_mfma_f32_16x16x32_bf16 v[56:59], v[174:177], v[68:71], v[56:59]
	v_mfma_f32_16x16x32_bf16 v[52:55], v[138:141], v[84:87], v[52:55]
	v_mfma_f32_16x16x32_bf16 v[48:51], v[174:177], v[84:87], v[48:51]
	v_mfma_f32_16x16x32_bf16 v[44:47], v[138:141], v[198:201], v[44:47]
	v_mfma_f32_16x16x32_bf16 v[40:43], v[174:177], v[198:201], v[40:43]
	v_mfma_f32_16x16x32_bf16 v[36:39], v[138:141], v[206:209], v[36:39]
	v_mfma_f32_16x16x32_bf16 v[32:35], v[174:177], v[206:209], v[32:35]
	v_mfma_f32_16x16x32_bf16 v[28:31], v[210:213], v[64:67], v[28:31]
	v_mfma_f32_16x16x32_bf16 v[16:19], v[218:221], v[80:83], v[16:19]
	v_mfma_f32_16x16x32_bf16 v[12:15], v[210:213], v[194:197], v[12:15]
	v_mfma_f32_16x16x32_bf16 v[0:3], v[218:221], v[202:205], v[0:3]
	v_mfma_f32_16x16x32_bf16 v[24:27], v[218:221], v[64:67], v[24:27]
	v_mfma_f32_16x16x32_bf16 v[20:23], v[210:213], v[80:83], v[20:23]
	v_mfma_f32_16x16x32_bf16 v[8:11], v[218:221], v[194:197], v[8:11]
	v_mfma_f32_16x16x32_bf16 v[4:7], v[210:213], v[202:205], v[4:7]
	v_mfma_f32_16x16x32_bf16 v[28:31], v[214:217], v[68:71], v[28:31]
	v_mfma_f32_16x16x32_bf16 v[16:19], v[160:163], v[84:87], v[16:19]
	v_mfma_f32_16x16x32_bf16 v[12:15], v[214:217], v[198:201], v[12:15]
	v_mfma_f32_16x16x32_bf16 v[0:3], v[160:163], v[206:209], v[0:3]
	v_mfma_f32_16x16x32_bf16 v[134:137], v[160:163], v[68:71], v[24:27]
	v_mfma_f32_16x16x32_bf16 v[138:141], v[214:217], v[84:87], v[20:23]
	v_mfma_f32_16x16x32_bf16 v[142:145], v[160:163], v[198:201], v[8:11]
	v_mfma_f32_16x16x32_bf16 v[172:175], v[214:217], v[206:209], v[4:7]
	s_barrier
	s_nop 0
	ds_read_b128 v[4:7], v159
	ds_read_b128 v[8:11], v159 offset:1024
	ds_read_b128 v[20:23], v159 offset:2048
	ds_read_b128 v[158:161], v159 offset:3072
	ds_read_b128 v[24:27], v155 offset:32768
	ds_read_b128 v[194:197], v155 offset:33792
	ds_read_b128 v[198:201], v154 offset:32768
	ds_read_b128 v[202:205], v154 offset:33792
	ds_read_b128 v[206:209], v153 offset:32768
	ds_read_b128 v[210:213], v153 offset:33792
	ds_read_b128 v[214:217], v152 offset:32768
	ds_read_b128 v[218:221], v152 offset:33792
	s_waitcnt vmcnt(2)
	s_barrier
; #define LDA(dst, b, h) for (int m = 0; m < 4; ++m) for (int k = 0; k < 2; ++k) \
;     dst[m][k] = *reinterpret_cast<const bf16x8*>((char*)SA(b, h) + lds_byte(wr * 64 + m * 16 + fr, k * 32 + fq * 8))
; #define LDB(dst, b, h) for (int n = 0; n < 2; ++n) for (int k = 0; k < 2; ++k) \
;     dst[n][k] = *reinterpret_cast<const bf16x8*>((char*)SB(b, h) + lds_byte(wc * 32 + n * 16 + fr, k * 32 + fq * 8))
; #define MMA(ai, bj, At_, Bt_) do { __builtin_amdgcn_s_setprio(1); \
;     for (int k = 0; k < 2; ++k) for (int m = 0; m < 4; ++m) for (int n = 0; n < 2; ++n) \
;       acc[ai][bj][m][n] = __builtin_amdgcn_mfma_f32_16x16x32_bf16(At_[m][k], Bt_[n][k], acc[ai][bj][m][n], 0, 0, 0); \
;     __builtin_amdgcn_s_setprio(0); } while (0)
; #define WAIT_V(n) asm volatile("s_waitcnt vmcnt(" #n ")" ::: "memory")
; #define WAIT_L(n) asm volatile("s_waitcnt lgkmcnt(" #n ")" ::: "memory")
; #define BAR __builtin_amdgcn_s_barrier()
; template <int EPI, int lda, int ldb, int N, int K>
; __device__ __forceinline__ void gemm_phase(const u16* __restrict__ A, const u16* __restrict__ Bt, const GemmEpi ep, int wv) {
;     ...
;     { LDB(B0, 1, 0); LDA(At, 1, 0); WAIT_V(2); BAR; WAIT_L(0); MMA(0, 0, At, B0); BAR;
;       LDB(B1, 1, 1); WAIT_V(0); BAR; WAIT_L(0); MMA(0, 1, At, B1); BAR;
;       LDA(At, 1, 1); BAR; WAIT_L(0); MMA(1, 0, At, B0); MMA(1, 1, At, B1); BAR; }
;     if (wr == 0) BAR;
	s_waitcnt lgkmcnt(0)
	s_waitcnt lgkmcnt(0)
	v_mfma_f32_16x16x32_bf16 v[64:67], v[4:7], v[24:27], v[124:127]
	v_mfma_f32_16x16x32_bf16 v[68:71], v[20:23], v[24:27], v[120:123]
	v_mfma_f32_16x16x32_bf16 v[80:83], v[4:7], v[198:201], v[116:119]
	v_mfma_f32_16x16x32_bf16 v[84:87], v[20:23], v[198:201], v[112:115]
	v_mfma_f32_16x16x32_bf16 v[108:111], v[4:7], v[206:209], v[108:111]
	v_mfma_f32_16x16x32_bf16 v[104:107], v[20:23], v[206:209], v[104:107]
	v_mfma_f32_16x16x32_bf16 v[120:123], v[4:7], v[214:217], v[100:103]
	v_mfma_f32_16x16x32_bf16 v[124:127], v[20:23], v[214:217], v[96:99]
	v_mfma_f32_16x16x32_bf16 v[116:119], v[8:11], v[194:197], v[64:67]
	v_mfma_f32_16x16x32_bf16 v[112:115], v[158:161], v[194:197], v[68:71]
	v_mfma_f32_16x16x32_bf16 v[100:103], v[8:11], v[202:205], v[80:83]
	v_mfma_f32_16x16x32_bf16 v[96:99], v[158:161], v[202:205], v[84:87]
	v_mfma_f32_16x16x32_bf16 v[84:87], v[8:11], v[210:213], v[108:111]
	v_mfma_f32_16x16x32_bf16 v[80:83], v[158:161], v[210:213], v[104:107]
	v_mfma_f32_16x16x32_bf16 v[68:71], v[8:11], v[218:221], v[120:123]
	v_mfma_f32_16x16x32_bf16 v[64:67], v[158:161], v[218:221], v[124:127]
	s_barrier
	ds_read_b128 v[222:225], v157
	ds_read_b128 v[226:229], v157 offset:1024
	ds_read_b128 v[230:233], v157 offset:2048
	ds_read_b128 v[234:237], v157 offset:3072
	s_waitcnt vmcnt(0)
	s_barrier
	s_waitcnt lgkmcnt(0)
	s_waitcnt lgkmcnt(0)
	v_mfma_f32_16x16x32_bf16 v[92:95], v[222:225], v[24:27], v[92:95]
	v_mfma_f32_16x16x32_bf16 v[24:27], v[230:233], v[24:27], v[88:91]
	v_mfma_f32_16x16x32_bf16 v[88:91], v[222:225], v[198:201], v[178:181]
	v_mfma_f32_16x16x32_bf16 v[104:107], v[230:233], v[198:201], v[182:185]
	v_mfma_f32_16x16x32_bf16 v[76:79], v[222:225], v[206:209], v[76:79]
	v_mfma_f32_16x16x32_bf16 v[72:75], v[230:233], v[206:209], v[72:75]
	v_mfma_f32_16x16x32_bf16 v[176:179], v[222:225], v[214:217], v[186:189]
	v_mfma_f32_16x16x32_bf16 v[180:183], v[230:233], v[214:217], v[190:193]
	v_mfma_f32_16x16x32_bf16 v[124:127], v[226:229], v[194:197], v[92:95]
	v_mfma_f32_16x16x32_bf16 v[120:123], v[234:237], v[194:197], v[24:27]
	v_mfma_f32_16x16x32_bf16 v[108:111], v[226:229], v[202:205], v[88:91]
	v_mfma_f32_16x16x32_bf16 v[104:107], v[234:237], v[202:205], v[104:107]
	v_mfma_f32_16x16x32_bf16 v[92:95], v[226:229], v[210:213], v[76:79]
	v_mfma_f32_16x16x32_bf16 v[88:91], v[234:237], v[210:213], v[72:75]
	v_mfma_f32_16x16x32_bf16 v[76:79], v[226:229], v[218:221], v[176:179]
	v_mfma_f32_16x16x32_bf16 v[72:75], v[234:237], v[218:221], v[180:183]
	s_barrier
	ds_read_b128 v[176:179], v155 offset:49152
	ds_read_b128 v[180:183], v155 offset:50176
	ds_read_b128 v[184:187], v154 offset:49152
	ds_read_b128 v[154:157], v154 offset:50176
	ds_read_b128 v[188:191], v153 offset:49152
	ds_read_b128 v[192:195], v153 offset:50176
	ds_read_b128 v[196:199], v152 offset:49152
	ds_read_b128 v[200:203], v152 offset:50176
	s_barrier
	s_waitcnt lgkmcnt(0)
	s_waitcnt lgkmcnt(0)
	v_mfma_f32_16x16x32_bf16 v[24:27], v[4:7], v[176:179], v[60:63]
	v_mfma_f32_16x16x32_bf16 v[60:63], v[20:23], v[176:179], v[56:59]
	v_mfma_f32_16x16x32_bf16 v[204:207], v[4:7], v[184:187], v[52:55]
	v_mfma_f32_16x16x32_bf16 v[48:51], v[20:23], v[184:187], v[48:51]
	v_mfma_f32_16x16x32_bf16 v[44:47], v[4:7], v[188:191], v[44:47]
	v_mfma_f32_16x16x32_bf16 v[208:211], v[20:23], v[188:191], v[40:43]
	v_mfma_f32_16x16x32_bf16 v[4:7], v[4:7], v[196:199], v[36:39]
	v_mfma_f32_16x16x32_bf16 v[32:35], v[20:23], v[196:199], v[32:35]
	v_mfma_f32_16x16x32_bf16 v[56:59], v[8:11], v[180:183], v[24:27]
	v_mfma_f32_16x16x32_bf16 v[52:55], v[158:161], v[180:183], v[60:63]
	v_mfma_f32_16x16x32_bf16 v[40:43], v[8:11], v[154:157], v[204:207]
	v_mfma_f32_16x16x32_bf16 v[36:39], v[158:161], v[154:157], v[48:51]
	v_mfma_f32_16x16x32_bf16 v[24:27], v[8:11], v[192:195], v[44:47]
	v_mfma_f32_16x16x32_bf16 v[20:23], v[158:161], v[192:195], v[208:211]
	v_mfma_f32_16x16x32_bf16 v[8:11], v[8:11], v[200:203], v[4:7]
	v_mfma_f32_16x16x32_bf16 v[4:7], v[158:161], v[200:203], v[32:35]
	v_mfma_f32_16x16x32_bf16 v[28:31], v[222:225], v[176:179], v[28:31]
	v_mfma_f32_16x16x32_bf16 v[32:35], v[230:233], v[176:179], v[134:137]
	v_mfma_f32_16x16x32_bf16 v[44:47], v[222:225], v[184:187], v[138:141]
	v_mfma_f32_16x16x32_bf16 v[16:19], v[230:233], v[184:187], v[16:19]
	v_mfma_f32_16x16x32_bf16 v[12:15], v[222:225], v[188:191], v[12:15]
	v_mfma_f32_16x16x32_bf16 v[134:137], v[230:233], v[188:191], v[142:145]
	v_mfma_f32_16x16x32_bf16 v[138:141], v[222:225], v[196:199], v[172:175]
	v_mfma_f32_16x16x32_bf16 v[0:3], v[230:233], v[196:199], v[0:3]
	v_mfma_f32_16x16x32_bf16 v[60:63], v[226:229], v[180:183], v[28:31]
	v_mfma_f32_16x16x32_bf16 v[48:51], v[234:237], v[180:183], v[32:35]
	v_mfma_f32_16x16x32_bf16 v[44:47], v[226:229], v[154:157], v[44:47]
	v_mfma_f32_16x16x32_bf16 v[32:35], v[234:237], v[154:157], v[16:19]
	v_mfma_f32_16x16x32_bf16 v[28:31], v[226:229], v[192:195], v[12:15]
	v_mfma_f32_16x16x32_bf16 v[16:19], v[234:237], v[192:195], v[134:137]
	v_mfma_f32_16x16x32_bf16 v[12:15], v[226:229], v[200:203], v[138:141]
	v_mfma_f32_16x16x32_bf16 v[0:3], v[234:237], v[200:203], v[0:3]
	v_cmp_gt_u32_e32 vcc, s69, v130
	s_barrier
	s_and_saveexec_b64 s[50:51], vcc
	s_cbranch_execz .LBB0_841
	s_barrier

; #define STAGE(P, BASE, LD, br, kt) do { const char* _g = (const char*)((BASE) + (size_t)(br) * (LD) + (size_t)(kt) * 64); \
;     for (int _i = 0; _i < 2; ++_i) { int _b = tidx * 16 + _i * 8192; int _r, _c; stage_rc(_b, _r, _c); \
;       __builtin_amdgcn_global_load_lds((const unsigned*)(_g + (unsigned)((_r * (LD) + _c) * 2)), (unsigned*)((char*)(P) + _b), 16, 0, 0); } } while (0)
; #define LDA(dst, b, h) for (int m = 0; m < 4; ++m) for (int k = 0; k < 2; ++k) \
;     dst[m][k] = *reinterpret_cast<const bf16x8*>((char*)SA(b, h) + lds_byte(wr * 64 + m * 16 + fr, k * 32 + fq * 8))
; #define LDB(dst, b, h) for (int n = 0; n < 2; ++n) for (int k = 0; k < 2; ++k) \
;     dst[n][k] = *reinterpret_cast<const bf16x8*>((char*)SB(b, h) + lds_byte(wc * 32 + n * 16 + fr, k * 32 + fq * 8))
; #define MMA(ai, bj, At_, Bt_) do { __builtin_amdgcn_s_setprio(1); \
;     for (int k = 0; k < 2; ++k) for (int m = 0; m < 4; ++m) for (int n = 0; n < 2; ++n) \
;       acc[ai][bj][m][n] = __builtin_amdgcn_mfma_f32_16x16x32_bf16(At_[m][k], Bt_[n][k], acc[ai][bj][m][n], 0, 0, 0); \
;     __builtin_amdgcn_s_setprio(0); } while (0)
; #define WAIT_L(n) asm volatile("s_waitcnt lgkmcnt(" #n ")" ::: "memory")
; #define BAR __builtin_amdgcn_s_barrier()
; #define SCHED __builtin_amdgcn_sched_barrier(0)
; template <int EPI, int lda, int ldb, int N, int K>
; __device__ __forceinline__ void gemm_phase(const u16* __restrict__ A, const u16* __restrict__ Bt, const GemmEpi ep, int wv) {
;     ...
;     for (int t = 0; t < nt - 2; t += 2) {
;       LDB(B0, 0, 0); SCHED; LDA(At, 0, 0); STAGE(SA(1, 1), Ab, lda, brow + HALF, t + 1);
;       WAIT_L(8); BAR; WAIT_L(0); MMA(0, 0, At, B0); BAR; SCHED;
;       LDB(B1, 0, 1); STAGE(SB(0, 0), Bt, ldb, bcol, t + 2);
;       BAR; WAIT_L(0); MMA(0, 1, At, B1); BAR;
;       LDA(At, 0, 1); STAGE(SA(0, 0), Ab, lda, brow, t + 2);
;       BAR; WAIT_L(0); MMA(1, 0, At, B0); BAR; SCHED;
.LBB0_1147:
	ds_read_b128 v[172:175], v161
	ds_read_b128 v[176:179], v161 offset:1024
	ds_read_b128 v[180:183], v161 offset:2048
	ds_read_b128 v[184:187], v161 offset:3072
	v_add_u32_e32 v169, 0xc000, v148
	v_lshl_add_u64 v[236:237], v[138:139], 0, s[60:61]
	v_readfirstlane_b32 s63, v169
	v_add_u32_e32 v170, 0xe000, v148
	v_lshl_add_u64 v[162:163], v[236:237], 0, s[22:23]
	s_mov_b32 m0, s63
	v_lshl_add_u64 v[238:239], v[140:141], 0, s[60:61]
	v_readfirstlane_b32 s63, v170
	ds_read_b128 v[164:167], v152
	ds_read_b128 v[188:191], v152 offset:1024
	ds_read_b128 v[192:195], v151
	ds_read_b128 v[196:199], v151 offset:1024
	ds_read_b128 v[200:203], v150
	ds_read_b128 v[204:207], v150 offset:1024
	ds_read_b128 v[208:211], v149
	ds_read_b128 v[212:215], v149 offset:1024
	global_load_lds_dwordx4 v[162:163], off
	v_lshl_add_u64 v[162:163], v[238:239], 0, s[22:23]
	s_mov_b32 m0, s63
	s_nop 0
	global_load_lds_dwordx4 v[162:163], off
	s_waitcnt lgkmcnt(8)
	s_barrier
	s_waitcnt lgkmcnt(0)
	s_waitcnt lgkmcnt(0)
	v_mfma_f32_16x16x32_bf16 v[124:127], v[164:167], v[172:175], v[124:127]
	v_mfma_f32_16x16x32_bf16 v[120:123], v[164:167], v[180:183], v[120:123]
	v_mfma_f32_16x16x32_bf16 v[116:119], v[192:195], v[172:175], v[116:119]
	v_mfma_f32_16x16x32_bf16 v[112:115], v[192:195], v[180:183], v[112:115]
	v_mfma_f32_16x16x32_bf16 v[108:111], v[200:203], v[172:175], v[108:111]
	v_mfma_f32_16x16x32_bf16 v[104:107], v[200:203], v[180:183], v[104:107]
	v_mfma_f32_16x16x32_bf16 v[100:103], v[208:211], v[172:175], v[100:103]
	v_mfma_f32_16x16x32_bf16 v[96:99], v[208:211], v[180:183], v[96:99]
	v_mfma_f32_16x16x32_bf16 v[124:127], v[188:191], v[176:179], v[124:127]
	v_mfma_f32_16x16x32_bf16 v[120:123], v[188:191], v[184:187], v[120:123]
	v_mfma_f32_16x16x32_bf16 v[116:119], v[196:199], v[176:179], v[116:119]
	v_mfma_f32_16x16x32_bf16 v[112:115], v[196:199], v[184:187], v[112:115]
	v_mfma_f32_16x16x32_bf16 v[108:111], v[204:207], v[176:179], v[108:111]
	v_mfma_f32_16x16x32_bf16 v[104:107], v[204:207], v[184:187], v[104:107]
	v_mfma_f32_16x16x32_bf16 v[100:103], v[212:215], v[176:179], v[100:103]
	v_mfma_f32_16x16x32_bf16 v[96:99], v[212:215], v[184:187], v[96:99]
	s_barrier
	v_add_u32_e32 v162, s75, v154
	v_lshl_add_u64 v[240:241], v[134:135], 0, s[60:61]
	v_readfirstlane_b32 s63, v162
	v_add_u32_e32 v163, 0x2000, v162
	v_lshl_add_u64 v[232:233], v[240:241], 0, s[24:25]
	s_mov_b32 m0, s63
	v_lshl_add_u64 v[242:243], v[136:137], 0, s[60:61]
	v_readfirstlane_b32 s63, v163
	ds_read_b128 v[216:219], v160
	ds_read_b128 v[220:223], v160 offset:1024
	ds_read_b128 v[224:227], v160 offset:2048
	ds_read_b128 v[228:231], v160 offset:3072
	global_load_lds_dwordx4 v[232:233], off
	v_lshl_add_u64 v[232:233], v[242:243], 0, s[24:25]
	s_mov_b32 m0, s63
	s_nop 0
	global_load_lds_dwordx4 v[232:233], off
	s_barrier
	s_waitcnt lgkmcnt(0)
	s_waitcnt lgkmcnt(0)
	v_mfma_f32_16x16x32_bf16 v[92:95], v[164:167], v[216:219], v[92:95]
	v_mfma_f32_16x16x32_bf16 v[88:91], v[164:167], v[224:227], v[88:91]
	v_mfma_f32_16x16x32_bf16 v[84:87], v[192:195], v[216:219], v[84:87]
	v_mfma_f32_16x16x32_bf16 v[80:83], v[192:195], v[224:227], v[80:83]
	v_mfma_f32_16x16x32_bf16 v[76:79], v[200:203], v[216:219], v[76:79]
	v_mfma_f32_16x16x32_bf16 v[72:75], v[200:203], v[224:227], v[72:75]
	v_mfma_f32_16x16x32_bf16 v[68:71], v[208:211], v[216:219], v[68:71]
	v_mfma_f32_16x16x32_bf16 v[64:67], v[208:211], v[224:227], v[64:67]
	v_mfma_f32_16x16x32_bf16 v[92:95], v[188:191], v[220:223], v[92:95]
	v_mfma_f32_16x16x32_bf16 v[88:91], v[188:191], v[228:231], v[88:91]
	v_mfma_f32_16x16x32_bf16 v[84:87], v[196:199], v[220:223], v[84:87]
	v_mfma_f32_16x16x32_bf16 v[80:83], v[196:199], v[228:231], v[80:83]
	v_mfma_f32_16x16x32_bf16 v[76:79], v[204:207], v[220:223], v[76:79]
	v_mfma_f32_16x16x32_bf16 v[72:75], v[204:207], v[228:231], v[72:75]
	v_mfma_f32_16x16x32_bf16 v[68:71], v[212:215], v[220:223], v[68:71]
	v_mfma_f32_16x16x32_bf16 v[64:67], v[212:215], v[228:231], v[64:67]
	s_barrier
	v_readfirstlane_b32 s63, v148
	v_lshl_add_u64 v[164:165], v[236:237], 0, s[26:27]
	s_mov_b32 m0, s63
	ds_read_b128 v[188:191], v152 offset:16384
	ds_read_b128 v[192:195], v152 offset:17408
	ds_read_b128 v[196:199], v151 offset:16384
	ds_read_b128 v[200:203], v151 offset:17408
	ds_read_b128 v[204:207], v150 offset:16384
	ds_read_b128 v[208:211], v150 offset:17408
	ds_read_b128 v[212:215], v149 offset:16384
	ds_read_b128 v[232:235], v149 offset:17408
	global_load_lds_dwordx4 v[164:165], off
	v_add_u32_e32 v164, 0x2000, v148
	v_lshl_add_u64 v[166:167], v[238:239], 0, s[26:27]
	v_readfirstlane_b32 s63, v164
	s_mov_b32 m0, s63
	s_nop 0
	global_load_lds_dwordx4 v[166:167], off
	s_barrier
	s_waitcnt lgkmcnt(0)
	s_waitcnt lgkmcnt(0)
	v_mfma_f32_16x16x32_bf16 v[60:63], v[188:191], v[172:175], v[60:63]
	v_mfma_f32_16x16x32_bf16 v[56:59], v[188:191], v[180:183], v[56:59]
	v_mfma_f32_16x16x32_bf16 v[52:55], v[196:199], v[172:175], v[52:55]
	v_mfma_f32_16x16x32_bf16 v[48:51], v[196:199], v[180:183], v[48:51]
	v_mfma_f32_16x16x32_bf16 v[44:47], v[204:207], v[172:175], v[44:47]
	v_mfma_f32_16x16x32_bf16 v[40:43], v[204:207], v[180:183], v[40:43]
	v_mfma_f32_16x16x32_bf16 v[36:39], v[212:215], v[172:175], v[36:39]
	v_mfma_f32_16x16x32_bf16 v[32:35], v[212:215], v[180:183], v[32:35]
	v_mfma_f32_16x16x32_bf16 v[60:63], v[192:195], v[176:179], v[60:63]
	v_mfma_f32_16x16x32_bf16 v[56:59], v[192:195], v[184:187], v[56:59]
	v_mfma_f32_16x16x32_bf16 v[52:55], v[200:203], v[176:179], v[52:55]
	v_mfma_f32_16x16x32_bf16 v[48:51], v[200:203], v[184:187], v[48:51]
	v_mfma_f32_16x16x32_bf16 v[44:47], v[208:211], v[176:179], v[44:47]
	v_mfma_f32_16x16x32_bf16 v[40:43], v[208:211], v[184:187], v[40:43]
	v_mfma_f32_16x16x32_bf16 v[36:39], v[232:235], v[176:179], v[36:39]
	v_mfma_f32_16x16x32_bf16 v[32:35], v[232:235], v[184:187], v[32:35]
	s_barrier
; #define STAGE(P, BASE, LD, br, kt) do { const char* _g = (const char*)((BASE) + (size_t)(br) * (LD) + (size_t)(kt) * 64); \
;     for (int _i = 0; _i < 2; ++_i) { int _b = tidx * 16 + _i * 8192; int _r, _c; stage_rc(_b, _r, _c); \
;       __builtin_amdgcn_global_load_lds((const unsigned*)(_g + (unsigned)((_r * (LD) + _c) * 2)), (unsigned*)((char*)(P) + _b), 16, 0, 0); } } while (0)
; #define LDA(dst, b, h) for (int m = 0; m < 4; ++m) for (int k = 0; k < 2; ++k) \
;     dst[m][k] = *reinterpret_cast<const bf16x8*>((char*)SA(b, h) + lds_byte(wr * 64 + m * 16 + fr, k * 32 + fq * 8))
; #define LDB(dst, b, h) for (int n = 0; n < 2; ++n) for (int k = 0; k < 2; ++k) \
;     dst[n][k] = *reinterpret_cast<const bf16x8*>((char*)SB(b, h) + lds_byte(wc * 32 + n * 16 + fr, k * 32 + fq * 8))
; #define MMA(ai, bj, At_, Bt_) do { __builtin_amdgcn_s_setprio(1); \
;     for (int k = 0; k < 2; ++k) for (int m = 0; m < 4; ++m) for (int n = 0; n < 2; ++n) \
;       acc[ai][bj][m][n] = __builtin_amdgcn_mfma_f32_16x16x32_bf16(At_[m][k], Bt_[n][k], acc[ai][bj][m][n], 0, 0, 0); \
;     __builtin_amdgcn_s_setprio(0); } while (0)
; #define WAIT_V(n) asm volatile("s_waitcnt vmcnt(" #n ")" ::: "memory")
; #define WAIT_L(n) asm volatile("s_waitcnt lgkmcnt(" #n ")" ::: "memory")
; #define BAR __builtin_amdgcn_s_barrier()
; #define SCHED __builtin_amdgcn_sched_barrier(0)
; template <int EPI, int lda, int ldb, int N, int K>
; __device__ __forceinline__ void gemm_phase(const u16* __restrict__ A, const u16* __restrict__ Bt, const GemmEpi ep, int wv) {
;     ...
;       STAGE(SB(0, 1), Bt, ldb, bcol + HALF, t + 2);
;       WAIT_V(6); BAR; MMA(1, 1, At, B1); BAR;
;       LDB(B0, 1, 0); SCHED; LDA(At, 1, 0); STAGE(SA(0, 1), Ab, lda, brow + HALF, t + 2);
;       WAIT_L(8); BAR; WAIT_L(0); MMA(0, 0, At, B0); BAR; SCHED;
;       LDB(B1, 1, 1); STAGE(SB(1, 0), Bt, ldb, bcol, t + 3);
;       BAR; WAIT_L(0); MMA(0, 1, At, B1); BAR;
;       LDA(At, 1, 1); STAGE(SA(1, 0), Ab, lda, brow, t + 3);
	v_add_u32_e32 v165, s76, v154
	v_lshl_add_u64 v[166:167], v[240:241], 0, s[40:41]
	v_readfirstlane_b32 s63, v165
	s_mov_b32 m0, s63
	v_lshl_add_u64 v[172:173], v[242:243], 0, s[40:41]
	global_load_lds_dwordx4 v[166:167], off
	v_add_u32_e32 v166, 0x2000, v165
	s_nop 0
	v_readfirstlane_b32 s63, v166
	s_mov_b32 m0, s63
	s_nop 0
	global_load_lds_dwordx4 v[172:173], off
	s_waitcnt vmcnt(6)
	s_barrier
	v_mfma_f32_16x16x32_bf16 v[28:31], v[188:191], v[216:219], v[28:31]
	v_mfma_f32_16x16x32_bf16 v[24:27], v[188:191], v[224:227], v[24:27]
	v_mfma_f32_16x16x32_bf16 v[20:23], v[196:199], v[216:219], v[20:23]
	v_mfma_f32_16x16x32_bf16 v[16:19], v[196:199], v[224:227], v[16:19]
	v_mfma_f32_16x16x32_bf16 v[12:15], v[204:207], v[216:219], v[12:15]
	v_mfma_f32_16x16x32_bf16 v[8:11], v[204:207], v[224:227], v[8:11]
	v_mfma_f32_16x16x32_bf16 v[4:7], v[212:215], v[216:219], v[4:7]
	v_mfma_f32_16x16x32_bf16 v[0:3], v[212:215], v[224:227], v[0:3]
	v_mfma_f32_16x16x32_bf16 v[28:31], v[192:195], v[220:223], v[28:31]
	v_mfma_f32_16x16x32_bf16 v[24:27], v[192:195], v[228:231], v[24:27]
	v_mfma_f32_16x16x32_bf16 v[20:23], v[200:203], v[220:223], v[20:23]
	v_mfma_f32_16x16x32_bf16 v[16:19], v[200:203], v[228:231], v[16:19]
	v_mfma_f32_16x16x32_bf16 v[12:15], v[208:211], v[220:223], v[12:15]
	v_mfma_f32_16x16x32_bf16 v[8:11], v[208:211], v[228:231], v[8:11]
	v_mfma_f32_16x16x32_bf16 v[4:7], v[232:235], v[220:223], v[4:7]
	v_mfma_f32_16x16x32_bf16 v[0:3], v[232:235], v[228:231], v[0:3]
	s_barrier
	ds_read_b128 v[172:175], v155
	ds_read_b128 v[176:179], v155 offset:1024
	ds_read_b128 v[180:183], v155 offset:2048
	ds_read_b128 v[184:187], v155 offset:3072
	v_add_u32_e32 v167, 0x4000, v148
	v_add_u32_e32 v168, 0x6000, v148
	v_readfirstlane_b32 s63, v167
	v_lshl_add_u64 v[220:221], v[236:237], 0, s[42:43]
	s_mov_b32 m0, s63
	v_readfirstlane_b32 s63, v168
	ds_read_b128 v[188:191], v152 offset:32768
	ds_read_b128 v[192:195], v152 offset:33792
	ds_read_b128 v[196:199], v151 offset:32768
	ds_read_b128 v[200:203], v151 offset:33792
	ds_read_b128 v[204:207], v150 offset:32768
	ds_read_b128 v[208:211], v150 offset:33792
	ds_read_b128 v[212:215], v149 offset:32768
	ds_read_b128 v[216:219], v149 offset:33792
	global_load_lds_dwordx4 v[220:221], off
	v_lshl_add_u64 v[220:221], v[238:239], 0, s[42:43]
	s_mov_b32 m0, s63
	s_nop 0
	global_load_lds_dwordx4 v[220:221], off
	s_waitcnt lgkmcnt(8)
	s_barrier
	s_waitcnt lgkmcnt(0)
	s_waitcnt lgkmcnt(0)
	v_mfma_f32_16x16x32_bf16 v[124:127], v[188:191], v[172:175], v[124:127]
	v_mfma_f32_16x16x32_bf16 v[120:123], v[188:191], v[180:183], v[120:123]
	v_mfma_f32_16x16x32_bf16 v[116:119], v[196:199], v[172:175], v[116:119]
	v_mfma_f32_16x16x32_bf16 v[112:115], v[196:199], v[180:183], v[112:115]
	v_mfma_f32_16x16x32_bf16 v[108:111], v[204:207], v[172:175], v[108:111]
	v_mfma_f32_16x16x32_bf16 v[104:107], v[204:207], v[180:183], v[104:107]
	v_mfma_f32_16x16x32_bf16 v[100:103], v[212:215], v[172:175], v[100:103]
	v_mfma_f32_16x16x32_bf16 v[96:99], v[212:215], v[180:183], v[96:99]
	v_mfma_f32_16x16x32_bf16 v[124:127], v[192:195], v[176:179], v[124:127]
	v_mfma_f32_16x16x32_bf16 v[120:123], v[192:195], v[184:187], v[120:123]
	v_mfma_f32_16x16x32_bf16 v[116:119], v[200:203], v[176:179], v[116:119]
	v_mfma_f32_16x16x32_bf16 v[112:115], v[200:203], v[184:187], v[112:115]
	v_mfma_f32_16x16x32_bf16 v[108:111], v[208:211], v[176:179], v[108:111]
	v_mfma_f32_16x16x32_bf16 v[104:107], v[208:211], v[184:187], v[104:107]
	v_mfma_f32_16x16x32_bf16 v[100:103], v[216:219], v[176:179], v[100:103]
	v_mfma_f32_16x16x32_bf16 v[96:99], v[216:219], v[184:187], v[96:99]
	s_barrier
	v_readfirstlane_b32 s63, v156
	v_add_u32_e32 v171, 0x2000, v156
	v_lshl_add_u64 v[244:245], v[240:241], 0, s[44:45]
	s_mov_b32 m0, s63
	v_readfirstlane_b32 s63, v171
	ds_read_b128 v[220:223], v153
	ds_read_b128 v[224:227], v153 offset:1024
	ds_read_b128 v[228:231], v153 offset:2048
	ds_read_b128 v[232:235], v153 offset:3072
	global_load_lds_dwordx4 v[244:245], off
	v_lshl_add_u64 v[244:245], v[242:243], 0, s[44:45]
	s_mov_b32 m0, s63
	s_nop 0
	global_load_lds_dwordx4 v[244:245], off
	s_barrier
	s_waitcnt lgkmcnt(0)
	s_waitcnt lgkmcnt(0)
	v_mfma_f32_16x16x32_bf16 v[92:95], v[188:191], v[220:223], v[92:95]
	v_mfma_f32_16x16x32_bf16 v[88:91], v[188:191], v[228:231], v[88:91]
	v_mfma_f32_16x16x32_bf16 v[84:87], v[196:199], v[220:223], v[84:87]
	v_mfma_f32_16x16x32_bf16 v[80:83], v[196:199], v[228:231], v[80:83]
	v_mfma_f32_16x16x32_bf16 v[76:79], v[204:207], v[220:223], v[76:79]
	v_mfma_f32_16x16x32_bf16 v[72:75], v[204:207], v[228:231], v[72:75]
	v_mfma_f32_16x16x32_bf16 v[68:71], v[212:215], v[220:223], v[68:71]
	v_mfma_f32_16x16x32_bf16 v[64:67], v[212:215], v[228:231], v[64:67]
	v_mfma_f32_16x16x32_bf16 v[92:95], v[192:195], v[224:227], v[92:95]
	v_mfma_f32_16x16x32_bf16 v[88:91], v[192:195], v[232:235], v[88:91]
	v_mfma_f32_16x16x32_bf16 v[84:87], v[200:203], v[224:227], v[84:87]
	v_mfma_f32_16x16x32_bf16 v[80:83], v[200:203], v[232:235], v[80:83]
	v_mfma_f32_16x16x32_bf16 v[76:79], v[208:211], v[224:227], v[76:79]
	v_mfma_f32_16x16x32_bf16 v[72:75], v[208:211], v[232:235], v[72:75]
	v_mfma_f32_16x16x32_bf16 v[68:71], v[216:219], v[224:227], v[68:71]
	v_mfma_f32_16x16x32_bf16 v[64:67], v[216:219], v[232:235], v[64:67]
	s_barrier
	v_readfirstlane_b32 s63, v157
	v_lshl_add_u64 v[236:237], v[236:237], 0, s[46:47]
	s_mov_b32 m0, s63
	v_readfirstlane_b32 s63, v158
	ds_read_b128 v[188:191], v152 offset:49152
	ds_read_b128 v[192:195], v152 offset:50176
	ds_read_b128 v[196:199], v151 offset:49152
	ds_read_b128 v[200:203], v151 offset:50176
	ds_read_b128 v[204:207], v150 offset:49152
	ds_read_b128 v[208:211], v150 offset:50176
	ds_read_b128 v[212:215], v149 offset:49152
	ds_read_b128 v[216:219], v149 offset:50176
	global_load_lds_dwordx4 v[236:237], off
	v_lshl_add_u64 v[236:237], v[238:239], 0, s[46:47]
	s_mov_b32 m0, s63
	s_nop 0
	global_load_lds_dwordx4 v[236:237], off
	s_barrier
; #define STAGE(P, BASE, LD, br, kt) do { const char* _g = (const char*)((BASE) + (size_t)(br) * (LD) + (size_t)(kt) * 64); \
;     for (int _i = 0; _i < 2; ++_i) { int _b = tidx * 16 + _i * 8192; int _r, _c; stage_rc(_b, _r, _c); \
;       __builtin_amdgcn_global_load_lds((const unsigned*)(_g + (unsigned)((_r * (LD) + _c) * 2)), (unsigned*)((char*)(P) + _b), 16, 0, 0); } } while (0)
; #define LDA(dst, b, h) for (int m = 0; m < 4; ++m) for (int k = 0; k < 2; ++k) \
;     dst[m][k] = *reinterpret_cast<const bf16x8*>((char*)SA(b, h) + lds_byte(wr * 64 + m * 16 + fr, k * 32 + fq * 8))
; #define LDB(dst, b, h) for (int n = 0; n < 2; ++n) for (int k = 0; k < 2; ++k) \
;     dst[n][k] = *reinterpret_cast<const bf16x8*>((char*)SB(b, h) + lds_byte(wc * 32 + n * 16 + fr, k * 32 + fq * 8))
; #define MMA(ai, bj, At_, Bt_) do { __builtin_amdgcn_s_setprio(1); \
;     for (int k = 0; k < 2; ++k) for (int m = 0; m < 4; ++m) for (int n = 0; n < 2; ++n) \
;       acc[ai][bj][m][n] = __builtin_amdgcn_mfma_f32_16x16x32_bf16(At_[m][k], Bt_[n][k], acc[ai][bj][m][n], 0, 0, 0); \
;     __builtin_amdgcn_s_setprio(0); } while (0)
; #define WAIT_V(n) asm volatile("s_waitcnt vmcnt(" #n ")" ::: "memory")
; #define WAIT_L(n) asm volatile("s_waitcnt lgkmcnt(" #n ")" ::: "memory")
; #define BAR __builtin_amdgcn_s_barrier()
; #define SCHED __builtin_amdgcn_sched_barrier(0)
; template <int EPI, int lda, int ldb, int N, int K>
; __device__ __forceinline__ void gemm_phase(const u16* __restrict__ A, const u16* __restrict__ Bt, const GemmEpi ep, int wv) {
;     ...
;       BAR; WAIT_L(0); MMA(1, 0, At, B0); BAR; SCHED;
;       STAGE(SB(1, 1), Bt, ldb, bcol + HALF, t + 3);
;       WAIT_V(6); BAR; MMA(1, 1, At, B1); BAR;
;     }
;     { LDB(B0, 0, 0); LDA(At, 0, 0); STAGE(SA(1, 1), Ab, lda, brow + HALF, nt - 1);
;       BAR; WAIT_L(0); MMA(0, 0, At, B0); BAR;
;       LDB(B1, 0, 1); BAR; WAIT_L(0); MMA(0, 1, At, B1); BAR;
	s_waitcnt lgkmcnt(0)
	s_waitcnt lgkmcnt(0)
	v_mfma_f32_16x16x32_bf16 v[60:63], v[188:191], v[172:175], v[60:63]
	v_mfma_f32_16x16x32_bf16 v[56:59], v[188:191], v[180:183], v[56:59]
	v_mfma_f32_16x16x32_bf16 v[52:55], v[196:199], v[172:175], v[52:55]
	v_mfma_f32_16x16x32_bf16 v[48:51], v[196:199], v[180:183], v[48:51]
	v_mfma_f32_16x16x32_bf16 v[44:47], v[204:207], v[172:175], v[44:47]
	v_mfma_f32_16x16x32_bf16 v[40:43], v[204:207], v[180:183], v[40:43]
	v_mfma_f32_16x16x32_bf16 v[36:39], v[212:215], v[172:175], v[36:39]
	v_mfma_f32_16x16x32_bf16 v[32:35], v[212:215], v[180:183], v[32:35]
	v_mfma_f32_16x16x32_bf16 v[60:63], v[192:195], v[176:179], v[60:63]
	v_mfma_f32_16x16x32_bf16 v[56:59], v[192:195], v[184:187], v[56:59]
	v_mfma_f32_16x16x32_bf16 v[52:55], v[200:203], v[176:179], v[52:55]
	v_mfma_f32_16x16x32_bf16 v[48:51], v[200:203], v[184:187], v[48:51]
	v_mfma_f32_16x16x32_bf16 v[44:47], v[208:211], v[176:179], v[44:47]
	v_mfma_f32_16x16x32_bf16 v[40:43], v[208:211], v[184:187], v[40:43]
	v_mfma_f32_16x16x32_bf16 v[36:39], v[216:219], v[176:179], v[36:39]
	v_mfma_f32_16x16x32_bf16 v[32:35], v[216:219], v[184:187], v[32:35]
	s_barrier
	v_readfirstlane_b32 s63, v159
	v_add_u32_e32 v171, 0x2000, v159
	v_lshl_add_u64 v[172:173], v[240:241], 0, s[48:49]
	s_mov_b32 m0, s63
	v_readfirstlane_b32 s63, v171
	global_load_lds_dwordx4 v[172:173], off
	v_lshl_add_u64 v[172:173], v[242:243], 0, s[48:49]
	s_mov_b32 m0, s63
	s_nop 0
	global_load_lds_dwordx4 v[172:173], off
	s_add_i32 s62, s62, 2
	s_add_u32 s60, s60, 0x100
	s_addc_u32 s61, s61, 0
	s_cmp_gt_u32 s62, 27
	s_waitcnt vmcnt(6)
	s_barrier
	v_mfma_f32_16x16x32_bf16 v[28:31], v[188:191], v[220:223], v[28:31]
	v_mfma_f32_16x16x32_bf16 v[24:27], v[188:191], v[228:231], v[24:27]
	v_mfma_f32_16x16x32_bf16 v[20:23], v[196:199], v[220:223], v[20:23]
	v_mfma_f32_16x16x32_bf16 v[16:19], v[196:199], v[228:231], v[16:19]
	v_mfma_f32_16x16x32_bf16 v[12:15], v[204:207], v[220:223], v[12:15]
	v_mfma_f32_16x16x32_bf16 v[8:11], v[204:207], v[228:231], v[8:11]
	v_mfma_f32_16x16x32_bf16 v[4:7], v[212:215], v[220:223], v[4:7]
	v_mfma_f32_16x16x32_bf16 v[0:3], v[212:215], v[228:231], v[0:3]
	v_mfma_f32_16x16x32_bf16 v[28:31], v[192:195], v[224:227], v[28:31]
	v_mfma_f32_16x16x32_bf16 v[24:27], v[192:195], v[232:235], v[24:27]
	v_mfma_f32_16x16x32_bf16 v[20:23], v[200:203], v[224:227], v[20:23]
	v_mfma_f32_16x16x32_bf16 v[16:19], v[200:203], v[232:235], v[16:19]
	v_mfma_f32_16x16x32_bf16 v[12:15], v[208:211], v[224:227], v[12:15]
	v_mfma_f32_16x16x32_bf16 v[8:11], v[208:211], v[232:235], v[8:11]
	v_mfma_f32_16x16x32_bf16 v[4:7], v[216:219], v[224:227], v[4:7]
	v_mfma_f32_16x16x32_bf16 v[0:3], v[216:219], v[232:235], v[0:3]
	s_barrier
	s_cbranch_scc0 .LBB0_1147
	s_add_i32 s60, s58, 0x80
	s_mul_hi_i32 s61, s60, 0x1080
	s_mulk_i32 s60, 0x1080
	s_add_u32 s60, s69, s60
	s_addc_u32 s61, s70, s61
	v_lshl_add_u64 v[208:209], s[60:61], 0, v[128:129]
	v_readfirstlane_b32 s62, v169
	v_lshl_add_u64 v[208:209], v[208:209], 0, s[50:51]
	s_mov_b32 m0, s62
	ds_read_b128 v[134:137], v161
	ds_read_b128 v[138:141], v161 offset:1024
	ds_read_b128 v[156:159], v161 offset:2048
	ds_read_b128 v[172:175], v161 offset:3072
	ds_read_b128 v[176:179], v152
	ds_read_b128 v[180:183], v152 offset:1024
	ds_read_b128 v[184:187], v151
	ds_read_b128 v[188:191], v151 offset:1024
	ds_read_b128 v[192:195], v150
	ds_read_b128 v[196:199], v150 offset:1024
	ds_read_b128 v[200:203], v149
	ds_read_b128 v[204:207], v149 offset:1024
	global_load_lds_dwordx4 v[208:209], off
	v_lshl_add_u64 v[208:209], s[60:61], 0, v[132:133]
	v_readfirstlane_b32 s60, v170
	v_lshl_add_u64 v[208:209], v[208:209], 0, s[50:51]
	s_mov_b32 m0, s60
	s_nop 0
	global_load_lds_dwordx4 v[208:209], off
	s_barrier
	s_waitcnt lgkmcnt(0)
	s_waitcnt lgkmcnt(0)
	v_mfma_f32_16x16x32_bf16 v[124:127], v[176:179], v[134:137], v[124:127]
	v_mfma_f32_16x16x32_bf16 v[120:123], v[176:179], v[156:159], v[120:123]
	v_mfma_f32_16x16x32_bf16 v[116:119], v[184:187], v[134:137], v[116:119]
	v_mfma_f32_16x16x32_bf16 v[112:115], v[184:187], v[156:159], v[112:115]
	v_mfma_f32_16x16x32_bf16 v[108:111], v[192:195], v[134:137], v[108:111]
	v_mfma_f32_16x16x32_bf16 v[104:107], v[192:195], v[156:159], v[104:107]
	v_mfma_f32_16x16x32_bf16 v[100:103], v[200:203], v[134:137], v[100:103]
	v_mfma_f32_16x16x32_bf16 v[96:99], v[200:203], v[156:159], v[96:99]
	v_mfma_f32_16x16x32_bf16 v[124:127], v[180:183], v[138:141], v[124:127]
	v_mfma_f32_16x16x32_bf16 v[120:123], v[180:183], v[172:175], v[120:123]
	v_mfma_f32_16x16x32_bf16 v[116:119], v[188:191], v[138:141], v[116:119]
	v_mfma_f32_16x16x32_bf16 v[112:115], v[188:191], v[172:175], v[112:115]
	v_mfma_f32_16x16x32_bf16 v[108:111], v[196:199], v[138:141], v[108:111]
	v_mfma_f32_16x16x32_bf16 v[104:107], v[196:199], v[172:175], v[104:107]
	v_mfma_f32_16x16x32_bf16 v[100:103], v[204:207], v[138:141], v[100:103]
	v_mfma_f32_16x16x32_bf16 v[96:99], v[204:207], v[172:175], v[96:99]
	s_barrier
	ds_read_b128 v[208:211], v160
	ds_read_b128 v[212:215], v160 offset:1024
	ds_read_b128 v[216:219], v160 offset:2048
	ds_read_b128 v[220:223], v160 offset:3072
	s_barrier
; #define LDA(dst, b, h) for (int m = 0; m < 4; ++m) for (int k = 0; k < 2; ++k) \
;     dst[m][k] = *reinterpret_cast<const bf16x8*>((char*)SA(b, h) + lds_byte(wr * 64 + m * 16 + fr, k * 32 + fq * 8))
; #define LDB(dst, b, h) for (int n = 0; n < 2; ++n) for (int k = 0; k < 2; ++k) \
;     dst[n][k] = *reinterpret_cast<const bf16x8*>((char*)SB(b, h) + lds_byte(wc * 32 + n * 16 + fr, k * 32 + fq * 8))
; #define MMA(ai, bj, At_, Bt_) do { __builtin_amdgcn_s_setprio(1); \
;     for (int k = 0; k < 2; ++k) for (int m = 0; m < 4; ++m) for (int n = 0; n < 2; ++n) \
;       acc[ai][bj][m][n] = __builtin_amdgcn_mfma_f32_16x16x32_bf16(At_[m][k], Bt_[n][k], acc[ai][bj][m][n], 0, 0, 0); \
;     __builtin_amdgcn_s_setprio(0); } while (0)
; #define WAIT_V(n) asm volatile("s_waitcnt vmcnt(" #n ")" ::: "memory")
; #define WAIT_L(n) asm volatile("s_waitcnt lgkmcnt(" #n ")" ::: "memory")
; #define BAR __builtin_amdgcn_s_barrier()
; template <int EPI, int lda, int ldb, int N, int K>
; __device__ __forceinline__ void gemm_phase(const u16* __restrict__ A, const u16* __restrict__ Bt, const GemmEpi ep, int wv) {
;     ...
;       LDB(B1, 0, 1); BAR; WAIT_L(0); MMA(0, 1, At, B1); BAR;
;       LDA(At, 0, 1); WAIT_V(4); BAR; WAIT_L(0); MMA(1, 0, At, B0); MMA(1, 1, At, B1); BAR; }
;     { LDB(B0, 1, 0); LDA(At, 1, 0); WAIT_V(2); BAR; WAIT_L(0); MMA(0, 0, At, B0); BAR;
	s_waitcnt lgkmcnt(0)
	s_waitcnt lgkmcnt(0)
	v_mfma_f32_16x16x32_bf16 v[92:95], v[176:179], v[208:211], v[92:95]
	v_mfma_f32_16x16x32_bf16 v[88:91], v[176:179], v[216:219], v[88:91]
	v_mfma_f32_16x16x32_bf16 v[76:79], v[192:195], v[208:211], v[76:79]
	v_mfma_f32_16x16x32_bf16 v[72:75], v[192:195], v[216:219], v[72:75]
	v_mfma_f32_16x16x32_bf16 v[84:87], v[184:187], v[208:211], v[84:87]
	v_mfma_f32_16x16x32_bf16 v[80:83], v[184:187], v[216:219], v[80:83]
	v_mfma_f32_16x16x32_bf16 v[68:71], v[200:203], v[208:211], v[68:71]
	v_mfma_f32_16x16x32_bf16 v[64:67], v[200:203], v[216:219], v[64:67]
	v_mfma_f32_16x16x32_bf16 v[92:95], v[180:183], v[212:215], v[92:95]
	v_mfma_f32_16x16x32_bf16 v[88:91], v[180:183], v[220:223], v[88:91]
	v_mfma_f32_16x16x32_bf16 v[76:79], v[196:199], v[212:215], v[76:79]
	v_mfma_f32_16x16x32_bf16 v[72:75], v[196:199], v[220:223], v[72:75]
	v_mfma_f32_16x16x32_bf16 v[176:179], v[188:191], v[212:215], v[84:87]
	v_mfma_f32_16x16x32_bf16 v[180:183], v[188:191], v[220:223], v[80:83]
	v_mfma_f32_16x16x32_bf16 v[184:187], v[204:207], v[212:215], v[68:71]
	v_mfma_f32_16x16x32_bf16 v[188:191], v[204:207], v[220:223], v[64:67]
	s_barrier
	s_nop 0
	ds_read_b128 v[64:67], v152 offset:16384
	ds_read_b128 v[68:71], v152 offset:17408
	ds_read_b128 v[80:83], v151 offset:16384
	ds_read_b128 v[84:87], v151 offset:17408
	ds_read_b128 v[192:195], v150 offset:16384
	ds_read_b128 v[196:199], v150 offset:17408
	ds_read_b128 v[200:203], v149 offset:16384
	ds_read_b128 v[204:207], v149 offset:17408
	s_waitcnt vmcnt(4)
	s_barrier
	s_waitcnt lgkmcnt(0)
	s_waitcnt lgkmcnt(0)
	v_mfma_f32_16x16x32_bf16 v[60:63], v[64:67], v[134:137], v[60:63]
	v_mfma_f32_16x16x32_bf16 v[56:59], v[64:67], v[156:159], v[56:59]
	v_mfma_f32_16x16x32_bf16 v[52:55], v[80:83], v[134:137], v[52:55]
	v_mfma_f32_16x16x32_bf16 v[48:51], v[80:83], v[156:159], v[48:51]
	v_mfma_f32_16x16x32_bf16 v[44:47], v[192:195], v[134:137], v[44:47]
	v_mfma_f32_16x16x32_bf16 v[40:43], v[192:195], v[156:159], v[40:43]
	v_mfma_f32_16x16x32_bf16 v[36:39], v[200:203], v[134:137], v[36:39]
	v_mfma_f32_16x16x32_bf16 v[32:35], v[200:203], v[156:159], v[32:35]
	v_mfma_f32_16x16x32_bf16 v[60:63], v[68:71], v[138:141], v[60:63]
	v_mfma_f32_16x16x32_bf16 v[56:59], v[68:71], v[172:175], v[56:59]
	v_mfma_f32_16x16x32_bf16 v[52:55], v[84:87], v[138:141], v[52:55]
	v_mfma_f32_16x16x32_bf16 v[48:51], v[84:87], v[172:175], v[48:51]
	v_mfma_f32_16x16x32_bf16 v[44:47], v[196:199], v[138:141], v[44:47]
	v_mfma_f32_16x16x32_bf16 v[40:43], v[196:199], v[172:175], v[40:43]
	v_mfma_f32_16x16x32_bf16 v[36:39], v[204:207], v[138:141], v[36:39]
	v_mfma_f32_16x16x32_bf16 v[32:35], v[204:207], v[172:175], v[32:35]
	v_mfma_f32_16x16x32_bf16 v[28:31], v[64:67], v[208:211], v[28:31]
	v_mfma_f32_16x16x32_bf16 v[24:27], v[64:67], v[216:219], v[24:27]
	v_mfma_f32_16x16x32_bf16 v[12:15], v[192:195], v[208:211], v[12:15]
	v_mfma_f32_16x16x32_bf16 v[8:11], v[192:195], v[216:219], v[8:11]
	v_mfma_f32_16x16x32_bf16 v[20:23], v[80:83], v[208:211], v[20:23]
	v_mfma_f32_16x16x32_bf16 v[16:19], v[80:83], v[216:219], v[16:19]
	v_mfma_f32_16x16x32_bf16 v[4:7], v[200:203], v[208:211], v[4:7]
	v_mfma_f32_16x16x32_bf16 v[0:3], v[200:203], v[216:219], v[0:3]
	v_mfma_f32_16x16x32_bf16 v[28:31], v[68:71], v[212:215], v[28:31]
	v_mfma_f32_16x16x32_bf16 v[24:27], v[68:71], v[220:223], v[24:27]
	v_mfma_f32_16x16x32_bf16 v[12:15], v[196:199], v[212:215], v[12:15]
	v_mfma_f32_16x16x32_bf16 v[8:11], v[196:199], v[220:223], v[8:11]
	v_mfma_f32_16x16x32_bf16 v[134:137], v[84:87], v[212:215], v[20:23]
	v_mfma_f32_16x16x32_bf16 v[138:141], v[84:87], v[220:223], v[16:19]
	v_mfma_f32_16x16x32_bf16 v[156:159], v[204:207], v[212:215], v[4:7]
	v_mfma_f32_16x16x32_bf16 v[170:173], v[204:207], v[220:223], v[0:3]
	s_barrier
	s_nop 0
	ds_read_b128 v[0:3], v155
	ds_read_b128 v[4:7], v155 offset:1024
	ds_read_b128 v[16:19], v155 offset:2048
	ds_read_b128 v[192:195], v155 offset:3072
	ds_read_b128 v[20:23], v152 offset:32768
	ds_read_b128 v[196:199], v152 offset:33792
	ds_read_b128 v[200:203], v151 offset:32768
	ds_read_b128 v[204:207], v151 offset:33792
	ds_read_b128 v[208:211], v150 offset:32768
	ds_read_b128 v[212:215], v150 offset:33792
	ds_read_b128 v[216:219], v149 offset:32768
	ds_read_b128 v[220:223], v149 offset:33792
	s_waitcnt vmcnt(2)
	s_barrier
; #define LDA(dst, b, h) for (int m = 0; m < 4; ++m) for (int k = 0; k < 2; ++k) \
;     dst[m][k] = *reinterpret_cast<const bf16x8*>((char*)SA(b, h) + lds_byte(wr * 64 + m * 16 + fr, k * 32 + fq * 8))
; #define LDB(dst, b, h) for (int n = 0; n < 2; ++n) for (int k = 0; k < 2; ++k) \
;     dst[n][k] = *reinterpret_cast<const bf16x8*>((char*)SB(b, h) + lds_byte(wc * 32 + n * 16 + fr, k * 32 + fq * 8))
; #define MMA(ai, bj, At_, Bt_) do { __builtin_amdgcn_s_setprio(1); \
;     for (int k = 0; k < 2; ++k) for (int m = 0; m < 4; ++m) for (int n = 0; n < 2; ++n) \
;       acc[ai][bj][m][n] = __builtin_amdgcn_mfma_f32_16x16x32_bf16(At_[m][k], Bt_[n][k], acc[ai][bj][m][n], 0, 0, 0); \
;     __builtin_amdgcn_s_setprio(0); } while (0)
; #define WAIT_V(n) asm volatile("s_waitcnt vmcnt(" #n ")" ::: "memory")
; #define WAIT_L(n) asm volatile("s_waitcnt lgkmcnt(" #n ")" ::: "memory")
; #define BAR __builtin_amdgcn_s_barrier()
; template <int EPI, int lda, int ldb, int N, int K>
; __device__ __forceinline__ void gemm_phase(const u16* __restrict__ A, const u16* __restrict__ Bt, const GemmEpi ep, int wv) {
;     ...
;     { LDB(B0, 1, 0); LDA(At, 1, 0); WAIT_V(2); BAR; WAIT_L(0); MMA(0, 0, At, B0); BAR;
;       LDB(B1, 1, 1); WAIT_V(0); BAR; WAIT_L(0); MMA(0, 1, At, B1); BAR;
;       LDA(At, 1, 1); BAR; WAIT_L(0); MMA(1, 0, At, B0); MMA(1, 1, At, B1); BAR; }
;     if (wr == 0) BAR;
	s_waitcnt lgkmcnt(0)
	s_waitcnt lgkmcnt(0)
	v_mfma_f32_16x16x32_bf16 v[64:67], v[20:23], v[0:3], v[124:127]
	v_mfma_f32_16x16x32_bf16 v[68:71], v[20:23], v[16:19], v[120:123]
	v_mfma_f32_16x16x32_bf16 v[80:83], v[200:203], v[0:3], v[116:119]
	v_mfma_f32_16x16x32_bf16 v[84:87], v[200:203], v[16:19], v[112:115]
	v_mfma_f32_16x16x32_bf16 v[108:111], v[208:211], v[0:3], v[108:111]
	v_mfma_f32_16x16x32_bf16 v[104:107], v[208:211], v[16:19], v[104:107]
	v_mfma_f32_16x16x32_bf16 v[120:123], v[216:219], v[0:3], v[100:103]
	v_mfma_f32_16x16x32_bf16 v[124:127], v[216:219], v[16:19], v[96:99]
	v_mfma_f32_16x16x32_bf16 v[116:119], v[196:199], v[4:7], v[64:67]
	v_mfma_f32_16x16x32_bf16 v[112:115], v[196:199], v[192:195], v[68:71]
	v_mfma_f32_16x16x32_bf16 v[100:103], v[204:207], v[4:7], v[80:83]
	v_mfma_f32_16x16x32_bf16 v[96:99], v[204:207], v[192:195], v[84:87]
	v_mfma_f32_16x16x32_bf16 v[84:87], v[212:215], v[4:7], v[108:111]
	v_mfma_f32_16x16x32_bf16 v[80:83], v[212:215], v[192:195], v[104:107]
	v_mfma_f32_16x16x32_bf16 v[68:71], v[220:223], v[4:7], v[120:123]
	v_mfma_f32_16x16x32_bf16 v[64:67], v[220:223], v[192:195], v[124:127]
	s_barrier
	ds_read_b128 v[224:227], v153
	ds_read_b128 v[228:231], v153 offset:1024
	ds_read_b128 v[232:235], v153 offset:2048
	ds_read_b128 v[236:239], v153 offset:3072
	s_waitcnt vmcnt(0)
	s_barrier
	s_waitcnt lgkmcnt(0)
	s_waitcnt lgkmcnt(0)
	v_mfma_f32_16x16x32_bf16 v[92:95], v[20:23], v[224:227], v[92:95]
	v_mfma_f32_16x16x32_bf16 v[20:23], v[20:23], v[232:235], v[88:91]
	v_mfma_f32_16x16x32_bf16 v[88:91], v[200:203], v[224:227], v[176:179]
	v_mfma_f32_16x16x32_bf16 v[104:107], v[200:203], v[232:235], v[180:183]
	v_mfma_f32_16x16x32_bf16 v[76:79], v[208:211], v[224:227], v[76:79]
	v_mfma_f32_16x16x32_bf16 v[72:75], v[208:211], v[232:235], v[72:75]
	v_mfma_f32_16x16x32_bf16 v[174:177], v[216:219], v[224:227], v[184:187]
	v_mfma_f32_16x16x32_bf16 v[178:181], v[216:219], v[232:235], v[188:191]
	v_mfma_f32_16x16x32_bf16 v[124:127], v[196:199], v[228:231], v[92:95]
	v_mfma_f32_16x16x32_bf16 v[120:123], v[196:199], v[236:239], v[20:23]
	v_mfma_f32_16x16x32_bf16 v[108:111], v[204:207], v[228:231], v[88:91]
	v_mfma_f32_16x16x32_bf16 v[104:107], v[204:207], v[236:239], v[104:107]
	v_mfma_f32_16x16x32_bf16 v[92:95], v[212:215], v[228:231], v[76:79]
	v_mfma_f32_16x16x32_bf16 v[88:91], v[212:215], v[236:239], v[72:75]
	v_mfma_f32_16x16x32_bf16 v[76:79], v[220:223], v[228:231], v[174:177]
	v_mfma_f32_16x16x32_bf16 v[72:75], v[220:223], v[236:239], v[178:181]
	s_barrier
	ds_read_b128 v[174:177], v152 offset:49152
	ds_read_b128 v[152:155], v152 offset:50176
	ds_read_b128 v[178:181], v151 offset:49152
	ds_read_b128 v[182:185], v151 offset:50176
	ds_read_b128 v[186:189], v150 offset:49152
	ds_read_b128 v[196:199], v150 offset:50176
	ds_read_b128 v[200:203], v149 offset:49152
	ds_read_b128 v[204:207], v149 offset:50176
	s_barrier
	s_waitcnt lgkmcnt(0)
	s_waitcnt lgkmcnt(0)
	v_mfma_f32_16x16x32_bf16 v[20:23], v[174:177], v[0:3], v[60:63]
	v_mfma_f32_16x16x32_bf16 v[56:59], v[174:177], v[16:19], v[56:59]
	v_mfma_f32_16x16x32_bf16 v[60:63], v[178:181], v[0:3], v[52:55]
	v_mfma_f32_16x16x32_bf16 v[208:211], v[178:181], v[16:19], v[48:51]
	v_mfma_f32_16x16x32_bf16 v[44:47], v[186:189], v[0:3], v[44:47]
	v_mfma_f32_16x16x32_bf16 v[40:43], v[186:189], v[16:19], v[40:43]
	v_mfma_f32_16x16x32_bf16 v[0:3], v[200:203], v[0:3], v[36:39]
	v_mfma_f32_16x16x32_bf16 v[212:215], v[200:203], v[16:19], v[32:35]
	v_mfma_f32_16x16x32_bf16 v[52:55], v[152:155], v[4:7], v[20:23]
	v_mfma_f32_16x16x32_bf16 v[48:51], v[152:155], v[192:195], v[56:59]
	v_mfma_f32_16x16x32_bf16 v[36:39], v[182:185], v[4:7], v[60:63]
	v_mfma_f32_16x16x32_bf16 v[32:35], v[182:185], v[192:195], v[208:211]
	v_mfma_f32_16x16x32_bf16 v[20:23], v[196:199], v[4:7], v[44:47]
	v_mfma_f32_16x16x32_bf16 v[16:19], v[196:199], v[192:195], v[40:43]
	v_mfma_f32_16x16x32_bf16 v[4:7], v[204:207], v[4:7], v[0:3]
	v_mfma_f32_16x16x32_bf16 v[0:3], v[204:207], v[192:195], v[212:215]
	v_mfma_f32_16x16x32_bf16 v[28:31], v[174:177], v[224:227], v[28:31]
	v_mfma_f32_16x16x32_bf16 v[24:27], v[174:177], v[232:235], v[24:27]
	v_mfma_f32_16x16x32_bf16 v[40:43], v[178:181], v[224:227], v[134:137]
	v_mfma_f32_16x16x32_bf16 v[134:137], v[178:181], v[232:235], v[138:141]
	v_mfma_f32_16x16x32_bf16 v[12:15], v[186:189], v[224:227], v[12:15]
	v_mfma_f32_16x16x32_bf16 v[8:11], v[186:189], v[232:235], v[8:11]
	v_mfma_f32_16x16x32_bf16 v[138:141], v[200:203], v[224:227], v[156:159]
	v_mfma_f32_16x16x32_bf16 v[156:159], v[200:203], v[232:235], v[170:173]
	v_mfma_f32_16x16x32_bf16 v[60:63], v[152:155], v[228:231], v[28:31]
	v_mfma_f32_16x16x32_bf16 v[56:59], v[152:155], v[236:239], v[24:27]
	v_mfma_f32_16x16x32_bf16 v[44:47], v[182:185], v[228:231], v[40:43]
	v_mfma_f32_16x16x32_bf16 v[40:43], v[182:185], v[236:239], v[134:137]
	v_mfma_f32_16x16x32_bf16 v[28:31], v[196:199], v[228:231], v[12:15]
	v_mfma_f32_16x16x32_bf16 v[24:27], v[196:199], v[236:239], v[8:11]
	v_mfma_f32_16x16x32_bf16 v[12:15], v[204:207], v[228:231], v[138:141]
	v_mfma_f32_16x16x32_bf16 v[8:11], v[204:207], v[236:239], v[156:159]
	v_cmp_gt_u32_e32 vcc, s80, v130
	s_barrier
	s_and_saveexec_b64 s[60:61], vcc
	s_cbranch_execz .LBB0_1150
	s_barrier

; #define STAGE(P, BASE, LD, br, kt) do { const char* _g = (const char*)((BASE) + (size_t)(br) * (LD) + (size_t)(kt) * 64); \
;     for (int _i = 0; _i < 2; ++_i) { int _b = tidx * 16 + _i * 8192; int _r, _c; stage_rc(_b, _r, _c); \
;       __builtin_amdgcn_global_load_lds((const unsigned*)(_g + (unsigned)((_r * (LD) + _c) * 2)), (unsigned*)((char*)(P) + _b), 16, 0, 0); } } while (0)
; #define LDA(dst, b, h) for (int m = 0; m < 4; ++m) for (int k = 0; k < 2; ++k) \
;     dst[m][k] = *reinterpret_cast<const bf16x8*>((char*)SA(b, h) + lds_byte(wr * 64 + m * 16 + fr, k * 32 + fq * 8))
; #define LDB(dst, b, h) for (int n = 0; n < 2; ++n) for (int k = 0; k < 2; ++k) \
;     dst[n][k] = *reinterpret_cast<const bf16x8*>((char*)SB(b, h) + lds_byte(wc * 32 + n * 16 + fr, k * 32 + fq * 8))
; #define MMA(ai, bj, At_, Bt_) do { __builtin_amdgcn_s_setprio(1); \
;     for (int k = 0; k < 2; ++k) for (int m = 0; m < 4; ++m) for (int n = 0; n < 2; ++n) \
;       acc[ai][bj][m][n] = __builtin_amdgcn_mfma_f32_16x16x32_bf16(At_[m][k], Bt_[n][k], acc[ai][bj][m][n], 0, 0, 0); \
;     __builtin_amdgcn_s_setprio(0); } while (0)
; #define WAIT_L(n) asm volatile("s_waitcnt lgkmcnt(" #n ")" ::: "memory")
; #define BAR __builtin_amdgcn_s_barrier()
; #define SCHED __builtin_amdgcn_sched_barrier(0)
; template <int EPI, int lda, int ldb, int N, int K>
; __device__ __forceinline__ void gemm_phase(const u16* __restrict__ A, const u16* __restrict__ Bt, const GemmEpi ep, int wv) {
;     ...
;     for (int t = 0; t < nt - 2; t += 2) {
;       LDB(B0, 0, 0); SCHED; LDA(At, 0, 0); STAGE(SA(1, 1), Ab, lda, brow + HALF, t + 1);
;       WAIT_L(8); BAR; WAIT_L(0); MMA(0, 0, At, B0); BAR; SCHED;
;       LDB(B1, 0, 1); STAGE(SB(0, 0), Bt, ldb, bcol, t + 2);
;       BAR; WAIT_L(0); MMA(0, 1, At, B1); BAR;
;       LDA(At, 0, 1); STAGE(SA(0, 0), Ab, lda, brow, t + 2);
;       BAR; WAIT_L(0); MMA(1, 0, At, B0); BAR; SCHED;
.LBB0_1448:
	ds_read_b128 v[164:167], v160
	ds_read_b128 v[170:173], v160 offset:1024
	ds_read_b128 v[174:177], v160 offset:2048
	ds_read_b128 v[178:181], v160 offset:3072
	v_add_u32_e32 v168, 0xc000, v143
	v_lshl_add_u64 v[234:235], v[138:139], 0, s[44:45]
	v_readfirstlane_b32 s47, v168
	v_add_u32_e32 v169, 0xe000, v143
	v_lshl_add_u64 v[162:163], v[234:235], 0, s[20:21]
	s_mov_b32 m0, s47
	v_lshl_add_u64 v[236:237], v[140:141], 0, s[44:45]
	v_readfirstlane_b32 s47, v169
	ds_read_b128 v[182:185], v151
	ds_read_b128 v[186:189], v151 offset:1024
	ds_read_b128 v[190:193], v150
	ds_read_b128 v[194:197], v150 offset:1024
	ds_read_b128 v[198:201], v149
	ds_read_b128 v[202:205], v149 offset:1024
	ds_read_b128 v[206:209], v148
	ds_read_b128 v[210:213], v148 offset:1024
	global_load_lds_dwordx4 v[162:163], off
	v_lshl_add_u64 v[162:163], v[236:237], 0, s[20:21]
	s_mov_b32 m0, s47
	s_nop 0
	global_load_lds_dwordx4 v[162:163], off
	s_waitcnt lgkmcnt(8)
	s_barrier
	s_waitcnt lgkmcnt(0)
	s_waitcnt lgkmcnt(0)
	v_mfma_f32_16x16x32_bf16 v[124:127], v[164:167], v[182:185], v[124:127]
	v_mfma_f32_16x16x32_bf16 v[120:123], v[174:177], v[182:185], v[120:123]
	v_mfma_f32_16x16x32_bf16 v[116:119], v[164:167], v[190:193], v[116:119]
	v_mfma_f32_16x16x32_bf16 v[112:115], v[174:177], v[190:193], v[112:115]
	v_mfma_f32_16x16x32_bf16 v[108:111], v[164:167], v[198:201], v[108:111]
	v_mfma_f32_16x16x32_bf16 v[104:107], v[174:177], v[198:201], v[104:107]
	v_mfma_f32_16x16x32_bf16 v[100:103], v[164:167], v[206:209], v[100:103]
	v_mfma_f32_16x16x32_bf16 v[96:99], v[174:177], v[206:209], v[96:99]
	v_mfma_f32_16x16x32_bf16 v[124:127], v[170:173], v[186:189], v[124:127]
	v_mfma_f32_16x16x32_bf16 v[120:123], v[178:181], v[186:189], v[120:123]
	v_mfma_f32_16x16x32_bf16 v[116:119], v[170:173], v[194:197], v[116:119]
	v_mfma_f32_16x16x32_bf16 v[112:115], v[178:181], v[194:197], v[112:115]
	v_mfma_f32_16x16x32_bf16 v[108:111], v[170:173], v[202:205], v[108:111]
	v_mfma_f32_16x16x32_bf16 v[104:107], v[178:181], v[202:205], v[104:107]
	v_mfma_f32_16x16x32_bf16 v[100:103], v[170:173], v[210:213], v[100:103]
	v_mfma_f32_16x16x32_bf16 v[96:99], v[178:181], v[210:213], v[96:99]
	s_barrier
	v_add_u32_e32 v161, s55, v153
	v_lshl_add_u64 v[238:239], v[134:135], 0, s[44:45]
	v_readfirstlane_b32 s47, v161
	v_lshl_add_u64 v[162:163], v[238:239], 0, s[22:23]
	s_mov_b32 m0, s47
	ds_read_b128 v[214:217], v159
	ds_read_b128 v[218:221], v159 offset:1024
	ds_read_b128 v[222:225], v159 offset:2048
	ds_read_b128 v[226:229], v159 offset:3072
	global_load_lds_dwordx4 v[162:163], off
	v_add_u32_e32 v162, 0x2000, v161
	v_lshl_add_u64 v[240:241], v[136:137], 0, s[44:45]
	v_readfirstlane_b32 s47, v162
	v_lshl_add_u64 v[230:231], v[240:241], 0, s[22:23]
	s_mov_b32 m0, s47
	s_nop 0
	global_load_lds_dwordx4 v[230:231], off
	s_barrier
	s_waitcnt lgkmcnt(0)
	s_waitcnt lgkmcnt(0)
	v_mfma_f32_16x16x32_bf16 v[92:95], v[214:217], v[182:185], v[92:95]
	v_mfma_f32_16x16x32_bf16 v[88:91], v[222:225], v[182:185], v[88:91]
	v_mfma_f32_16x16x32_bf16 v[84:87], v[214:217], v[190:193], v[84:87]
	v_mfma_f32_16x16x32_bf16 v[80:83], v[222:225], v[190:193], v[80:83]
	v_mfma_f32_16x16x32_bf16 v[76:79], v[214:217], v[198:201], v[76:79]
	v_mfma_f32_16x16x32_bf16 v[72:75], v[222:225], v[198:201], v[72:75]
	v_mfma_f32_16x16x32_bf16 v[68:71], v[214:217], v[206:209], v[68:71]
	v_mfma_f32_16x16x32_bf16 v[64:67], v[222:225], v[206:209], v[64:67]
	v_mfma_f32_16x16x32_bf16 v[92:95], v[218:221], v[186:189], v[92:95]
	v_mfma_f32_16x16x32_bf16 v[88:91], v[226:229], v[186:189], v[88:91]
	v_mfma_f32_16x16x32_bf16 v[84:87], v[218:221], v[194:197], v[84:87]
	v_mfma_f32_16x16x32_bf16 v[80:83], v[226:229], v[194:197], v[80:83]
	v_mfma_f32_16x16x32_bf16 v[76:79], v[218:221], v[202:205], v[76:79]
	v_mfma_f32_16x16x32_bf16 v[72:75], v[226:229], v[202:205], v[72:75]
	v_mfma_f32_16x16x32_bf16 v[68:71], v[218:221], v[210:213], v[68:71]
	v_mfma_f32_16x16x32_bf16 v[64:67], v[226:229], v[210:213], v[64:67]
	s_barrier
	v_readfirstlane_b32 s47, v143
	v_add_u32_e32 v163, 0x2000, v143
	v_lshl_add_u64 v[230:231], v[234:235], 0, s[24:25]
	s_mov_b32 m0, s47
	v_readfirstlane_b32 s47, v163
	ds_read_b128 v[182:185], v151 offset:16384
	ds_read_b128 v[186:189], v151 offset:17408
	ds_read_b128 v[190:193], v150 offset:16384
	ds_read_b128 v[194:197], v150 offset:17408
	ds_read_b128 v[198:201], v149 offset:16384
	ds_read_b128 v[202:205], v149 offset:17408
	ds_read_b128 v[206:209], v148 offset:16384
	ds_read_b128 v[210:213], v148 offset:17408
	global_load_lds_dwordx4 v[230:231], off
	v_lshl_add_u64 v[230:231], v[236:237], 0, s[24:25]
	s_mov_b32 m0, s47
	s_nop 0
	global_load_lds_dwordx4 v[230:231], off
	s_barrier
	s_waitcnt lgkmcnt(0)
	s_waitcnt lgkmcnt(0)
	v_mfma_f32_16x16x32_bf16 v[60:63], v[164:167], v[182:185], v[60:63]
	v_mfma_f32_16x16x32_bf16 v[56:59], v[174:177], v[182:185], v[56:59]
	v_mfma_f32_16x16x32_bf16 v[52:55], v[164:167], v[190:193], v[52:55]
	v_mfma_f32_16x16x32_bf16 v[48:51], v[174:177], v[190:193], v[48:51]
	v_mfma_f32_16x16x32_bf16 v[44:47], v[164:167], v[198:201], v[44:47]
	v_mfma_f32_16x16x32_bf16 v[40:43], v[174:177], v[198:201], v[40:43]
	v_mfma_f32_16x16x32_bf16 v[36:39], v[164:167], v[206:209], v[36:39]
	v_mfma_f32_16x16x32_bf16 v[32:35], v[174:177], v[206:209], v[32:35]
	v_mfma_f32_16x16x32_bf16 v[60:63], v[170:173], v[186:189], v[60:63]
	v_mfma_f32_16x16x32_bf16 v[56:59], v[178:181], v[186:189], v[56:59]
	v_mfma_f32_16x16x32_bf16 v[52:55], v[170:173], v[194:197], v[52:55]
	v_mfma_f32_16x16x32_bf16 v[48:51], v[178:181], v[194:197], v[48:51]
	v_mfma_f32_16x16x32_bf16 v[44:47], v[170:173], v[202:205], v[44:47]
	v_mfma_f32_16x16x32_bf16 v[40:43], v[178:181], v[202:205], v[40:43]
	v_mfma_f32_16x16x32_bf16 v[36:39], v[170:173], v[210:213], v[36:39]
	v_mfma_f32_16x16x32_bf16 v[32:35], v[178:181], v[210:213], v[32:35]
	s_barrier
; #define STAGE(P, BASE, LD, br, kt) do { const char* _g = (const char*)((BASE) + (size_t)(br) * (LD) + (size_t)(kt) * 64); \
;     for (int _i = 0; _i < 2; ++_i) { int _b = tidx * 16 + _i * 8192; int _r, _c; stage_rc(_b, _r, _c); \
;       __builtin_amdgcn_global_load_lds((const unsigned*)(_g + (unsigned)((_r * (LD) + _c) * 2)), (unsigned*)((char*)(P) + _b), 16, 0, 0); } } while (0)
; #define LDA(dst, b, h) for (int m = 0; m < 4; ++m) for (int k = 0; k < 2; ++k) \
;     dst[m][k] = *reinterpret_cast<const bf16x8*>((char*)SA(b, h) + lds_byte(wr * 64 + m * 16 + fr, k * 32 + fq * 8))
; #define LDB(dst, b, h) for (int n = 0; n < 2; ++n) for (int k = 0; k < 2; ++k) \
;     dst[n][k] = *reinterpret_cast<const bf16x8*>((char*)SB(b, h) + lds_byte(wc * 32 + n * 16 + fr, k * 32 + fq * 8))
; #define MMA(ai, bj, At_, Bt_) do { __builtin_amdgcn_s_setprio(1); \
;     for (int k = 0; k < 2; ++k) for (int m = 0; m < 4; ++m) for (int n = 0; n < 2; ++n) \
;       acc[ai][bj][m][n] = __builtin_amdgcn_mfma_f32_16x16x32_bf16(At_[m][k], Bt_[n][k], acc[ai][bj][m][n], 0, 0, 0); \
;     __builtin_amdgcn_s_setprio(0); } while (0)
; #define WAIT_V(n) asm volatile("s_waitcnt vmcnt(" #n ")" ::: "memory")
; #define WAIT_L(n) asm volatile("s_waitcnt lgkmcnt(" #n ")" ::: "memory")
; #define BAR __builtin_amdgcn_s_barrier()
; #define SCHED __builtin_amdgcn_sched_barrier(0)
; template <int EPI, int lda, int ldb, int N, int K>
; __device__ __forceinline__ void gemm_phase(const u16* __restrict__ A, const u16* __restrict__ Bt, const GemmEpi ep, int wv) {
;     ...
;       STAGE(SB(0, 1), Bt, ldb, bcol + HALF, t + 2);
;       WAIT_V(6); BAR; MMA(1, 1, At, B1); BAR;
;       LDB(B0, 1, 0); SCHED; LDA(At, 1, 0); STAGE(SA(0, 1), Ab, lda, brow + HALF, t + 2);
;       WAIT_L(8); BAR; WAIT_L(0); MMA(0, 0, At, B0); BAR; SCHED;
;       LDB(B1, 1, 1); STAGE(SB(1, 0), Bt, ldb, bcol, t + 3);
;       BAR; WAIT_L(0); MMA(0, 1, At, B1); BAR;
;       LDA(At, 1, 1); STAGE(SA(1, 0), Ab, lda, brow, t + 3);
;       BAR; WAIT_L(0); MMA(1, 0, At, B0); BAR; SCHED;
	v_add_u32_e32 v164, s56, v153
	v_add_u32_e32 v165, 0x2000, v164
	v_readfirstlane_b32 s47, v164
	v_lshl_add_u64 v[166:167], v[238:239], 0, s[26:27]
	s_mov_b32 m0, s47
	v_readfirstlane_b32 s47, v165
	global_load_lds_dwordx4 v[166:167], off
	v_lshl_add_u64 v[166:167], v[240:241], 0, s[26:27]
	s_mov_b32 m0, s47
	s_nop 0
	global_load_lds_dwordx4 v[166:167], off
	s_waitcnt vmcnt(6)
	s_barrier
	v_mfma_f32_16x16x32_bf16 v[28:31], v[214:217], v[182:185], v[28:31]
	v_mfma_f32_16x16x32_bf16 v[24:27], v[222:225], v[182:185], v[24:27]
	v_mfma_f32_16x16x32_bf16 v[20:23], v[214:217], v[190:193], v[20:23]
	v_mfma_f32_16x16x32_bf16 v[16:19], v[222:225], v[190:193], v[16:19]
	v_mfma_f32_16x16x32_bf16 v[12:15], v[214:217], v[198:201], v[12:15]
	v_mfma_f32_16x16x32_bf16 v[8:11], v[222:225], v[198:201], v[8:11]
	v_mfma_f32_16x16x32_bf16 v[4:7], v[214:217], v[206:209], v[4:7]
	v_mfma_f32_16x16x32_bf16 v[0:3], v[222:225], v[206:209], v[0:3]
	v_mfma_f32_16x16x32_bf16 v[28:31], v[218:221], v[186:189], v[28:31]
	v_mfma_f32_16x16x32_bf16 v[24:27], v[226:229], v[186:189], v[24:27]
	v_mfma_f32_16x16x32_bf16 v[20:23], v[218:221], v[194:197], v[20:23]
	v_mfma_f32_16x16x32_bf16 v[16:19], v[226:229], v[194:197], v[16:19]
	v_mfma_f32_16x16x32_bf16 v[12:15], v[218:221], v[202:205], v[12:15]
	v_mfma_f32_16x16x32_bf16 v[8:11], v[226:229], v[202:205], v[8:11]
	v_mfma_f32_16x16x32_bf16 v[4:7], v[218:221], v[210:213], v[4:7]
	v_mfma_f32_16x16x32_bf16 v[0:3], v[226:229], v[210:213], v[0:3]
	s_barrier
	ds_read_b128 v[170:173], v154
	ds_read_b128 v[174:177], v154 offset:1024
	ds_read_b128 v[178:181], v154 offset:2048
	ds_read_b128 v[182:185], v154 offset:3072
	v_add_u32_e32 v166, 0x4000, v143
	v_add_u32_e32 v167, 0x6000, v143
	v_readfirstlane_b32 s47, v166
	v_lshl_add_u64 v[218:219], v[234:235], 0, s[34:35]
	s_mov_b32 m0, s47
	v_readfirstlane_b32 s47, v167
	ds_read_b128 v[186:189], v151 offset:32768
	ds_read_b128 v[190:193], v151 offset:33792
	ds_read_b128 v[194:197], v150 offset:32768
	ds_read_b128 v[198:201], v150 offset:33792
	ds_read_b128 v[202:205], v149 offset:32768
	ds_read_b128 v[206:209], v149 offset:33792
	ds_read_b128 v[210:213], v148 offset:32768
	ds_read_b128 v[214:217], v148 offset:33792
	global_load_lds_dwordx4 v[218:219], off
	v_lshl_add_u64 v[218:219], v[236:237], 0, s[34:35]
	s_mov_b32 m0, s47
	s_nop 0
	global_load_lds_dwordx4 v[218:219], off
	s_waitcnt lgkmcnt(8)
	s_barrier
	s_waitcnt lgkmcnt(0)
	s_waitcnt lgkmcnt(0)
	v_mfma_f32_16x16x32_bf16 v[124:127], v[170:173], v[186:189], v[124:127]
	v_mfma_f32_16x16x32_bf16 v[120:123], v[178:181], v[186:189], v[120:123]
	v_mfma_f32_16x16x32_bf16 v[116:119], v[170:173], v[194:197], v[116:119]
	v_mfma_f32_16x16x32_bf16 v[112:115], v[178:181], v[194:197], v[112:115]
	v_mfma_f32_16x16x32_bf16 v[108:111], v[170:173], v[202:205], v[108:111]
	v_mfma_f32_16x16x32_bf16 v[104:107], v[178:181], v[202:205], v[104:107]
	v_mfma_f32_16x16x32_bf16 v[100:103], v[170:173], v[210:213], v[100:103]
	v_mfma_f32_16x16x32_bf16 v[96:99], v[178:181], v[210:213], v[96:99]
	v_mfma_f32_16x16x32_bf16 v[124:127], v[174:177], v[190:193], v[124:127]
	v_mfma_f32_16x16x32_bf16 v[120:123], v[182:185], v[190:193], v[120:123]
	v_mfma_f32_16x16x32_bf16 v[116:119], v[174:177], v[198:201], v[116:119]
	v_mfma_f32_16x16x32_bf16 v[112:115], v[182:185], v[198:201], v[112:115]
	v_mfma_f32_16x16x32_bf16 v[108:111], v[174:177], v[206:209], v[108:111]
	v_mfma_f32_16x16x32_bf16 v[104:107], v[182:185], v[206:209], v[104:107]
	v_mfma_f32_16x16x32_bf16 v[100:103], v[174:177], v[214:217], v[100:103]
	v_mfma_f32_16x16x32_bf16 v[96:99], v[182:185], v[214:217], v[96:99]
	s_barrier
	v_readfirstlane_b32 s47, v155
	v_add_u32_e32 v244, 0x2000, v155
	v_lshl_add_u64 v[242:243], v[238:239], 0, s[36:37]
	s_mov_b32 m0, s47
	v_readfirstlane_b32 s47, v244
	ds_read_b128 v[218:221], v152
	ds_read_b128 v[222:225], v152 offset:1024
	ds_read_b128 v[226:229], v152 offset:2048
	ds_read_b128 v[230:233], v152 offset:3072
	global_load_lds_dwordx4 v[242:243], off
	v_lshl_add_u64 v[242:243], v[240:241], 0, s[36:37]
	s_mov_b32 m0, s47
	s_nop 0
	global_load_lds_dwordx4 v[242:243], off
	s_barrier
	s_waitcnt lgkmcnt(0)
	s_waitcnt lgkmcnt(0)
	v_mfma_f32_16x16x32_bf16 v[92:95], v[218:221], v[186:189], v[92:95]
	v_mfma_f32_16x16x32_bf16 v[88:91], v[226:229], v[186:189], v[88:91]
	v_mfma_f32_16x16x32_bf16 v[84:87], v[218:221], v[194:197], v[84:87]
	v_mfma_f32_16x16x32_bf16 v[80:83], v[226:229], v[194:197], v[80:83]
	v_mfma_f32_16x16x32_bf16 v[76:79], v[218:221], v[202:205], v[76:79]
	v_mfma_f32_16x16x32_bf16 v[72:75], v[226:229], v[202:205], v[72:75]
	v_mfma_f32_16x16x32_bf16 v[68:71], v[218:221], v[210:213], v[68:71]
	v_mfma_f32_16x16x32_bf16 v[64:67], v[226:229], v[210:213], v[64:67]
	v_mfma_f32_16x16x32_bf16 v[92:95], v[222:225], v[190:193], v[92:95]
	v_mfma_f32_16x16x32_bf16 v[88:91], v[230:233], v[190:193], v[88:91]
	v_mfma_f32_16x16x32_bf16 v[84:87], v[222:225], v[198:201], v[84:87]
	v_mfma_f32_16x16x32_bf16 v[80:83], v[230:233], v[198:201], v[80:83]
	v_mfma_f32_16x16x32_bf16 v[76:79], v[222:225], v[206:209], v[76:79]
	v_mfma_f32_16x16x32_bf16 v[72:75], v[230:233], v[206:209], v[72:75]
	v_mfma_f32_16x16x32_bf16 v[68:71], v[222:225], v[214:217], v[68:71]
	v_mfma_f32_16x16x32_bf16 v[64:67], v[230:233], v[214:217], v[64:67]
	s_barrier
	v_readfirstlane_b32 s47, v156
	v_lshl_add_u64 v[234:235], v[234:235], 0, s[38:39]
	s_mov_b32 m0, s47
	v_readfirstlane_b32 s47, v157
	ds_read_b128 v[186:189], v151 offset:49152
	ds_read_b128 v[190:193], v151 offset:50176
	ds_read_b128 v[194:197], v150 offset:49152
	ds_read_b128 v[198:201], v150 offset:50176
	ds_read_b128 v[202:205], v149 offset:49152
	ds_read_b128 v[206:209], v149 offset:50176
	ds_read_b128 v[210:213], v148 offset:49152
	ds_read_b128 v[214:217], v148 offset:50176
	global_load_lds_dwordx4 v[234:235], off
	v_lshl_add_u64 v[234:235], v[236:237], 0, s[38:39]
	s_mov_b32 m0, s47
	s_nop 0
	global_load_lds_dwordx4 v[234:235], off
	s_barrier
; #define STAGE(P, BASE, LD, br, kt) do { const char* _g = (const char*)((BASE) + (size_t)(br) * (LD) + (size_t)(kt) * 64); \
;     for (int _i = 0; _i < 2; ++_i) { int _b = tidx * 16 + _i * 8192; int _r, _c; stage_rc(_b, _r, _c); \
;       __builtin_amdgcn_global_load_lds((const unsigned*)(_g + (unsigned)((_r * (LD) + _c) * 2)), (unsigned*)((char*)(P) + _b), 16, 0, 0); } } while (0)
; #define LDA(dst, b, h) for (int m = 0; m < 4; ++m) for (int k = 0; k < 2; ++k) \
;     dst[m][k] = *reinterpret_cast<const bf16x8*>((char*)SA(b, h) + lds_byte(wr * 64 + m * 16 + fr, k * 32 + fq * 8))
; #define LDB(dst, b, h) for (int n = 0; n < 2; ++n) for (int k = 0; k < 2; ++k) \
;     dst[n][k] = *reinterpret_cast<const bf16x8*>((char*)SB(b, h) + lds_byte(wc * 32 + n * 16 + fr, k * 32 + fq * 8))
; #define MMA(ai, bj, At_, Bt_) do { __builtin_amdgcn_s_setprio(1); \
;     for (int k = 0; k < 2; ++k) for (int m = 0; m < 4; ++m) for (int n = 0; n < 2; ++n) \
;       acc[ai][bj][m][n] = __builtin_amdgcn_mfma_f32_16x16x32_bf16(At_[m][k], Bt_[n][k], acc[ai][bj][m][n], 0, 0, 0); \
;     __builtin_amdgcn_s_setprio(0); } while (0)
; #define WAIT_V(n) asm volatile("s_waitcnt vmcnt(" #n ")" ::: "memory")
; #define WAIT_L(n) asm volatile("s_waitcnt lgkmcnt(" #n ")" ::: "memory")
; #define BAR __builtin_amdgcn_s_barrier()
; #define SCHED __builtin_amdgcn_sched_barrier(0)
; template <int EPI, int lda, int ldb, int N, int K>
; __device__ __forceinline__ void gemm_phase(const u16* __restrict__ A, const u16* __restrict__ Bt, const GemmEpi ep, int wv) {
;     ...
;       BAR; WAIT_L(0); MMA(1, 0, At, B0); BAR; SCHED;
;       STAGE(SB(1, 1), Bt, ldb, bcol + HALF, t + 3);
;       WAIT_V(6); BAR; MMA(1, 1, At, B1); BAR;
;     }
;     { LDB(B0, 0, 0); LDA(At, 0, 0); STAGE(SA(1, 1), Ab, lda, brow + HALF, nt - 1);
;       BAR; WAIT_L(0); MMA(0, 0, At, B0); BAR;
;       LDB(B1, 0, 1); BAR; WAIT_L(0); MMA(0, 1, At, B1); BAR;
	s_waitcnt lgkmcnt(0)
	s_waitcnt lgkmcnt(0)
	v_mfma_f32_16x16x32_bf16 v[60:63], v[170:173], v[186:189], v[60:63]
	v_mfma_f32_16x16x32_bf16 v[56:59], v[178:181], v[186:189], v[56:59]
	v_mfma_f32_16x16x32_bf16 v[52:55], v[170:173], v[194:197], v[52:55]
	v_mfma_f32_16x16x32_bf16 v[48:51], v[178:181], v[194:197], v[48:51]
	v_mfma_f32_16x16x32_bf16 v[44:47], v[170:173], v[202:205], v[44:47]
	v_mfma_f32_16x16x32_bf16 v[40:43], v[178:181], v[202:205], v[40:43]
	v_mfma_f32_16x16x32_bf16 v[36:39], v[170:173], v[210:213], v[36:39]
	v_mfma_f32_16x16x32_bf16 v[32:35], v[178:181], v[210:213], v[32:35]
	v_mfma_f32_16x16x32_bf16 v[60:63], v[174:177], v[190:193], v[60:63]
	v_mfma_f32_16x16x32_bf16 v[56:59], v[182:185], v[190:193], v[56:59]
	v_mfma_f32_16x16x32_bf16 v[52:55], v[174:177], v[198:201], v[52:55]
	v_mfma_f32_16x16x32_bf16 v[48:51], v[182:185], v[198:201], v[48:51]
	v_mfma_f32_16x16x32_bf16 v[44:47], v[174:177], v[206:209], v[44:47]
	v_mfma_f32_16x16x32_bf16 v[40:43], v[182:185], v[206:209], v[40:43]
	v_mfma_f32_16x16x32_bf16 v[36:39], v[174:177], v[214:217], v[36:39]
	v_mfma_f32_16x16x32_bf16 v[32:35], v[182:185], v[214:217], v[32:35]
	s_barrier
	v_readfirstlane_b32 s47, v158
	v_add_u32_e32 v172, 0x2000, v158
	v_lshl_add_u64 v[170:171], v[238:239], 0, s[40:41]
	s_mov_b32 m0, s47
	v_readfirstlane_b32 s47, v172
	global_load_lds_dwordx4 v[170:171], off
	v_lshl_add_u64 v[170:171], v[240:241], 0, s[40:41]
	s_mov_b32 m0, s47
	s_nop 0
	global_load_lds_dwordx4 v[170:171], off
	s_add_i32 s46, s46, 2
	s_add_u32 s44, s44, 0x100
	s_addc_u32 s45, s45, 0
	s_cmp_gt_u32 s46, 27
	s_waitcnt vmcnt(6)
	s_barrier
	v_mfma_f32_16x16x32_bf16 v[28:31], v[218:221], v[186:189], v[28:31]
	v_mfma_f32_16x16x32_bf16 v[24:27], v[226:229], v[186:189], v[24:27]
	v_mfma_f32_16x16x32_bf16 v[20:23], v[218:221], v[194:197], v[20:23]
	v_mfma_f32_16x16x32_bf16 v[16:19], v[226:229], v[194:197], v[16:19]
	v_mfma_f32_16x16x32_bf16 v[12:15], v[218:221], v[202:205], v[12:15]
	v_mfma_f32_16x16x32_bf16 v[8:11], v[226:229], v[202:205], v[8:11]
	v_mfma_f32_16x16x32_bf16 v[4:7], v[218:221], v[210:213], v[4:7]
	v_mfma_f32_16x16x32_bf16 v[0:3], v[226:229], v[210:213], v[0:3]
	v_mfma_f32_16x16x32_bf16 v[28:31], v[222:225], v[190:193], v[28:31]
	v_mfma_f32_16x16x32_bf16 v[24:27], v[230:233], v[190:193], v[24:27]
	v_mfma_f32_16x16x32_bf16 v[20:23], v[222:225], v[198:201], v[20:23]
	v_mfma_f32_16x16x32_bf16 v[16:19], v[230:233], v[198:201], v[16:19]
	v_mfma_f32_16x16x32_bf16 v[12:15], v[222:225], v[206:209], v[12:15]
	v_mfma_f32_16x16x32_bf16 v[8:11], v[230:233], v[206:209], v[8:11]
	v_mfma_f32_16x16x32_bf16 v[4:7], v[222:225], v[214:217], v[4:7]
	v_mfma_f32_16x16x32_bf16 v[0:3], v[230:233], v[214:217], v[0:3]
	s_barrier
	s_cbranch_scc0 .LBB0_1448
	s_lshl_b64 s[44:45], s[16:17], 12
	s_add_u32 s44, s14, s44
	s_addc_u32 s45, s15, s45
	s_add_u32 s44, s44, 0x80000
	s_addc_u32 s45, s45, 0
	v_lshl_add_u64 v[156:157], s[44:45], 0, v[128:129]
	v_readfirstlane_b32 s46, v168
	v_lshl_add_u64 v[156:157], v[156:157], 0, s[42:43]
	s_mov_b32 m0, s46
	ds_read_b128 v[134:137], v160
	ds_read_b128 v[138:141], v160 offset:1024
	ds_read_b128 v[170:173], v160 offset:2048
	ds_read_b128 v[174:177], v160 offset:3072
	ds_read_b128 v[178:181], v151
	ds_read_b128 v[182:185], v151 offset:1024
	ds_read_b128 v[186:189], v150
	ds_read_b128 v[190:193], v150 offset:1024
	ds_read_b128 v[194:197], v149
	ds_read_b128 v[198:201], v149 offset:1024
	ds_read_b128 v[202:205], v148
	ds_read_b128 v[206:209], v148 offset:1024
	global_load_lds_dwordx4 v[156:157], off
	v_lshl_add_u64 v[156:157], s[44:45], 0, v[132:133]
	v_readfirstlane_b32 s44, v169
	v_lshl_add_u64 v[156:157], v[156:157], 0, s[42:43]
	s_mov_b32 m0, s44
	s_nop 0
	global_load_lds_dwordx4 v[156:157], off
	s_barrier
	s_waitcnt lgkmcnt(0)
	s_waitcnt lgkmcnt(0)
	v_mfma_f32_16x16x32_bf16 v[124:127], v[134:137], v[178:181], v[124:127]
	v_mfma_f32_16x16x32_bf16 v[120:123], v[170:173], v[178:181], v[120:123]
	v_mfma_f32_16x16x32_bf16 v[116:119], v[134:137], v[186:189], v[116:119]
	v_mfma_f32_16x16x32_bf16 v[112:115], v[170:173], v[186:189], v[112:115]
	v_mfma_f32_16x16x32_bf16 v[108:111], v[134:137], v[194:197], v[108:111]
	v_mfma_f32_16x16x32_bf16 v[104:107], v[170:173], v[194:197], v[104:107]
	v_mfma_f32_16x16x32_bf16 v[100:103], v[134:137], v[202:205], v[100:103]
	v_mfma_f32_16x16x32_bf16 v[96:99], v[170:173], v[202:205], v[96:99]
	v_mfma_f32_16x16x32_bf16 v[124:127], v[138:141], v[182:185], v[124:127]
	v_mfma_f32_16x16x32_bf16 v[120:123], v[174:177], v[182:185], v[120:123]
	v_mfma_f32_16x16x32_bf16 v[116:119], v[138:141], v[190:193], v[116:119]
	v_mfma_f32_16x16x32_bf16 v[112:115], v[174:177], v[190:193], v[112:115]
	v_mfma_f32_16x16x32_bf16 v[108:111], v[138:141], v[198:201], v[108:111]
	v_mfma_f32_16x16x32_bf16 v[104:107], v[174:177], v[198:201], v[104:107]
	v_mfma_f32_16x16x32_bf16 v[100:103], v[138:141], v[206:209], v[100:103]
	v_mfma_f32_16x16x32_bf16 v[96:99], v[174:177], v[206:209], v[96:99]
	s_barrier
	ds_read_b128 v[210:213], v159
	ds_read_b128 v[214:217], v159 offset:1024
	ds_read_b128 v[218:221], v159 offset:2048
	ds_read_b128 v[156:159], v159 offset:3072
	s_barrier
; #define LDA(dst, b, h) for (int m = 0; m < 4; ++m) for (int k = 0; k < 2; ++k) \
;     dst[m][k] = *reinterpret_cast<const bf16x8*>((char*)SA(b, h) + lds_byte(wr * 64 + m * 16 + fr, k * 32 + fq * 8))
; #define LDB(dst, b, h) for (int n = 0; n < 2; ++n) for (int k = 0; k < 2; ++k) \
;     dst[n][k] = *reinterpret_cast<const bf16x8*>((char*)SB(b, h) + lds_byte(wc * 32 + n * 16 + fr, k * 32 + fq * 8))
; #define MMA(ai, bj, At_, Bt_) do { __builtin_amdgcn_s_setprio(1); \
;     for (int k = 0; k < 2; ++k) for (int m = 0; m < 4; ++m) for (int n = 0; n < 2; ++n) \
;       acc[ai][bj][m][n] = __builtin_amdgcn_mfma_f32_16x16x32_bf16(At_[m][k], Bt_[n][k], acc[ai][bj][m][n], 0, 0, 0); \
;     __builtin_amdgcn_s_setprio(0); } while (0)
; #define WAIT_V(n) asm volatile("s_waitcnt vmcnt(" #n ")" ::: "memory")
; #define WAIT_L(n) asm volatile("s_waitcnt lgkmcnt(" #n ")" ::: "memory")
; #define BAR __builtin_amdgcn_s_barrier()
; template <int EPI, int lda, int ldb, int N, int K>
; __device__ __forceinline__ void gemm_phase(const u16* __restrict__ A, const u16* __restrict__ Bt, const GemmEpi ep, int wv) {
;     ...
;       LDB(B1, 0, 1); BAR; WAIT_L(0); MMA(0, 1, At, B1); BAR;
;       LDA(At, 0, 1); WAIT_V(4); BAR; WAIT_L(0); MMA(1, 0, At, B0); MMA(1, 1, At, B1); BAR; }
;     { LDB(B0, 1, 0); LDA(At, 1, 0); WAIT_V(2); BAR; WAIT_L(0); MMA(0, 0, At, B0); BAR;
	s_waitcnt lgkmcnt(0)
	s_waitcnt lgkmcnt(0)
	v_mfma_f32_16x16x32_bf16 v[92:95], v[210:213], v[178:181], v[92:95]
	v_mfma_f32_16x16x32_bf16 v[88:91], v[218:221], v[178:181], v[88:91]
	v_mfma_f32_16x16x32_bf16 v[76:79], v[210:213], v[194:197], v[76:79]
	v_mfma_f32_16x16x32_bf16 v[72:75], v[218:221], v[194:197], v[72:75]
	v_mfma_f32_16x16x32_bf16 v[84:87], v[210:213], v[186:189], v[84:87]
	v_mfma_f32_16x16x32_bf16 v[80:83], v[218:221], v[186:189], v[80:83]
	v_mfma_f32_16x16x32_bf16 v[68:71], v[210:213], v[202:205], v[68:71]
	v_mfma_f32_16x16x32_bf16 v[64:67], v[218:221], v[202:205], v[64:67]
	v_mfma_f32_16x16x32_bf16 v[92:95], v[214:217], v[182:185], v[92:95]
	v_mfma_f32_16x16x32_bf16 v[88:91], v[156:159], v[182:185], v[88:91]
	v_mfma_f32_16x16x32_bf16 v[76:79], v[214:217], v[198:201], v[76:79]
	v_mfma_f32_16x16x32_bf16 v[72:75], v[156:159], v[198:201], v[72:75]
	v_mfma_f32_16x16x32_bf16 v[178:181], v[214:217], v[190:193], v[84:87]
	v_mfma_f32_16x16x32_bf16 v[182:185], v[156:159], v[190:193], v[80:83]
	v_mfma_f32_16x16x32_bf16 v[186:189], v[214:217], v[206:209], v[68:71]
	v_mfma_f32_16x16x32_bf16 v[190:193], v[156:159], v[206:209], v[64:67]
	s_barrier
	s_nop 0
	ds_read_b128 v[64:67], v151 offset:16384
	ds_read_b128 v[68:71], v151 offset:17408
	ds_read_b128 v[80:83], v150 offset:16384
	ds_read_b128 v[84:87], v150 offset:17408
	ds_read_b128 v[194:197], v149 offset:16384
	ds_read_b128 v[198:201], v149 offset:17408
	ds_read_b128 v[202:205], v148 offset:16384
	ds_read_b128 v[206:209], v148 offset:17408
	s_waitcnt vmcnt(4)
	s_barrier
	s_waitcnt lgkmcnt(0)
	s_waitcnt lgkmcnt(0)
	v_mfma_f32_16x16x32_bf16 v[60:63], v[134:137], v[64:67], v[60:63]
	v_mfma_f32_16x16x32_bf16 v[56:59], v[170:173], v[64:67], v[56:59]
	v_mfma_f32_16x16x32_bf16 v[52:55], v[134:137], v[80:83], v[52:55]
	v_mfma_f32_16x16x32_bf16 v[48:51], v[170:173], v[80:83], v[48:51]
	v_mfma_f32_16x16x32_bf16 v[44:47], v[134:137], v[194:197], v[44:47]
	v_mfma_f32_16x16x32_bf16 v[40:43], v[170:173], v[194:197], v[40:43]
	v_mfma_f32_16x16x32_bf16 v[36:39], v[134:137], v[202:205], v[36:39]
	v_mfma_f32_16x16x32_bf16 v[32:35], v[170:173], v[202:205], v[32:35]
	v_mfma_f32_16x16x32_bf16 v[60:63], v[138:141], v[68:71], v[60:63]
	v_mfma_f32_16x16x32_bf16 v[56:59], v[174:177], v[68:71], v[56:59]
	v_mfma_f32_16x16x32_bf16 v[52:55], v[138:141], v[84:87], v[52:55]
	v_mfma_f32_16x16x32_bf16 v[48:51], v[174:177], v[84:87], v[48:51]
	v_mfma_f32_16x16x32_bf16 v[44:47], v[138:141], v[198:201], v[44:47]
	v_mfma_f32_16x16x32_bf16 v[40:43], v[174:177], v[198:201], v[40:43]
	v_mfma_f32_16x16x32_bf16 v[36:39], v[138:141], v[206:209], v[36:39]
	v_mfma_f32_16x16x32_bf16 v[32:35], v[174:177], v[206:209], v[32:35]
	v_mfma_f32_16x16x32_bf16 v[28:31], v[210:213], v[64:67], v[28:31]
	v_mfma_f32_16x16x32_bf16 v[20:23], v[210:213], v[80:83], v[20:23]
	v_mfma_f32_16x16x32_bf16 v[12:15], v[210:213], v[194:197], v[12:15]
	v_mfma_f32_16x16x32_bf16 v[4:7], v[210:213], v[202:205], v[4:7]
	v_mfma_f32_16x16x32_bf16 v[24:27], v[218:221], v[64:67], v[24:27]
	v_mfma_f32_16x16x32_bf16 v[16:19], v[218:221], v[80:83], v[16:19]
	v_mfma_f32_16x16x32_bf16 v[8:11], v[218:221], v[194:197], v[8:11]
	v_mfma_f32_16x16x32_bf16 v[0:3], v[218:221], v[202:205], v[0:3]
	v_mfma_f32_16x16x32_bf16 v[28:31], v[214:217], v[68:71], v[28:31]
	v_mfma_f32_16x16x32_bf16 v[20:23], v[214:217], v[84:87], v[20:23]
	v_mfma_f32_16x16x32_bf16 v[12:15], v[214:217], v[198:201], v[12:15]
	v_mfma_f32_16x16x32_bf16 v[4:7], v[214:217], v[206:209], v[4:7]
	v_mfma_f32_16x16x32_bf16 v[134:137], v[156:159], v[68:71], v[24:27]
	v_mfma_f32_16x16x32_bf16 v[138:141], v[156:159], v[84:87], v[16:19]
	v_mfma_f32_16x16x32_bf16 v[168:171], v[156:159], v[198:201], v[8:11]
	v_mfma_f32_16x16x32_bf16 v[156:159], v[156:159], v[206:209], v[0:3]
	s_barrier
	s_nop 0
	ds_read_b128 v[0:3], v154
	ds_read_b128 v[8:11], v154 offset:1024
	ds_read_b128 v[16:19], v154 offset:2048
	ds_read_b128 v[172:175], v154 offset:3072
	ds_read_b128 v[24:27], v151 offset:32768
	ds_read_b128 v[194:197], v151 offset:33792
	ds_read_b128 v[198:201], v150 offset:32768
	ds_read_b128 v[202:205], v150 offset:33792
	ds_read_b128 v[206:209], v149 offset:32768
	ds_read_b128 v[210:213], v149 offset:33792
	ds_read_b128 v[214:217], v148 offset:32768
	ds_read_b128 v[218:221], v148 offset:33792
	s_waitcnt vmcnt(2)
	s_barrier
; #define LDA(dst, b, h) for (int m = 0; m < 4; ++m) for (int k = 0; k < 2; ++k) \
;     dst[m][k] = *reinterpret_cast<const bf16x8*>((char*)SA(b, h) + lds_byte(wr * 64 + m * 16 + fr, k * 32 + fq * 8))
; #define LDB(dst, b, h) for (int n = 0; n < 2; ++n) for (int k = 0; k < 2; ++k) \
;     dst[n][k] = *reinterpret_cast<const bf16x8*>((char*)SB(b, h) + lds_byte(wc * 32 + n * 16 + fr, k * 32 + fq * 8))
; #define MMA(ai, bj, At_, Bt_) do { __builtin_amdgcn_s_setprio(1); \
;     for (int k = 0; k < 2; ++k) for (int m = 0; m < 4; ++m) for (int n = 0; n < 2; ++n) \
;       acc[ai][bj][m][n] = __builtin_amdgcn_mfma_f32_16x16x32_bf16(At_[m][k], Bt_[n][k], acc[ai][bj][m][n], 0, 0, 0); \
;     __builtin_amdgcn_s_setprio(0); } while (0)
; #define WAIT_V(n) asm volatile("s_waitcnt vmcnt(" #n ")" ::: "memory")
; #define WAIT_L(n) asm volatile("s_waitcnt lgkmcnt(" #n ")" ::: "memory")
; #define BAR __builtin_amdgcn_s_barrier()
; template <int EPI, int lda, int ldb, int N, int K>
; __device__ __forceinline__ void gemm_phase(const u16* __restrict__ A, const u16* __restrict__ Bt, const GemmEpi ep, int wv) {
;     ...
;     { LDB(B0, 1, 0); LDA(At, 1, 0); WAIT_V(2); BAR; WAIT_L(0); MMA(0, 0, At, B0); BAR;
;       LDB(B1, 1, 1); WAIT_V(0); BAR; WAIT_L(0); MMA(0, 1, At, B1); BAR;
;       LDA(At, 1, 1); BAR; WAIT_L(0); MMA(1, 0, At, B0); MMA(1, 1, At, B1); BAR; }
;     if (wr == 0) BAR;
	s_waitcnt lgkmcnt(0)
	s_waitcnt lgkmcnt(0)
	v_mfma_f32_16x16x32_bf16 v[64:67], v[0:3], v[24:27], v[124:127]
	v_mfma_f32_16x16x32_bf16 v[68:71], v[16:19], v[24:27], v[120:123]
	v_mfma_f32_16x16x32_bf16 v[80:83], v[0:3], v[198:201], v[116:119]
	v_mfma_f32_16x16x32_bf16 v[84:87], v[16:19], v[198:201], v[112:115]
	v_mfma_f32_16x16x32_bf16 v[108:111], v[0:3], v[206:209], v[108:111]
	v_mfma_f32_16x16x32_bf16 v[104:107], v[16:19], v[206:209], v[104:107]
	v_mfma_f32_16x16x32_bf16 v[120:123], v[0:3], v[214:217], v[100:103]
	v_mfma_f32_16x16x32_bf16 v[124:127], v[16:19], v[214:217], v[96:99]
	v_mfma_f32_16x16x32_bf16 v[116:119], v[8:11], v[194:197], v[64:67]
	v_mfma_f32_16x16x32_bf16 v[112:115], v[172:175], v[194:197], v[68:71]
	v_mfma_f32_16x16x32_bf16 v[100:103], v[8:11], v[202:205], v[80:83]
	v_mfma_f32_16x16x32_bf16 v[96:99], v[172:175], v[202:205], v[84:87]
	v_mfma_f32_16x16x32_bf16 v[84:87], v[8:11], v[210:213], v[108:111]
	v_mfma_f32_16x16x32_bf16 v[80:83], v[172:175], v[210:213], v[104:107]
	v_mfma_f32_16x16x32_bf16 v[68:71], v[8:11], v[218:221], v[120:123]
	v_mfma_f32_16x16x32_bf16 v[64:67], v[172:175], v[218:221], v[124:127]
	s_barrier
	ds_read_b128 v[222:225], v152
	ds_read_b128 v[226:229], v152 offset:1024
	ds_read_b128 v[230:233], v152 offset:2048
	ds_read_b128 v[152:155], v152 offset:3072
	s_waitcnt vmcnt(0)
	s_barrier
	s_waitcnt lgkmcnt(0)
	s_waitcnt lgkmcnt(0)
	v_mfma_f32_16x16x32_bf16 v[92:95], v[222:225], v[24:27], v[92:95]
	v_mfma_f32_16x16x32_bf16 v[24:27], v[230:233], v[24:27], v[88:91]
	v_mfma_f32_16x16x32_bf16 v[88:91], v[222:225], v[198:201], v[178:181]
	v_mfma_f32_16x16x32_bf16 v[104:107], v[230:233], v[198:201], v[182:185]
	v_mfma_f32_16x16x32_bf16 v[76:79], v[222:225], v[206:209], v[76:79]
	v_mfma_f32_16x16x32_bf16 v[72:75], v[230:233], v[206:209], v[72:75]
	v_mfma_f32_16x16x32_bf16 v[176:179], v[222:225], v[214:217], v[186:189]
	v_mfma_f32_16x16x32_bf16 v[180:183], v[230:233], v[214:217], v[190:193]
	v_mfma_f32_16x16x32_bf16 v[124:127], v[226:229], v[194:197], v[92:95]
	v_mfma_f32_16x16x32_bf16 v[120:123], v[152:155], v[194:197], v[24:27]
	v_mfma_f32_16x16x32_bf16 v[108:111], v[226:229], v[202:205], v[88:91]
	v_mfma_f32_16x16x32_bf16 v[104:107], v[152:155], v[202:205], v[104:107]
	v_mfma_f32_16x16x32_bf16 v[92:95], v[226:229], v[210:213], v[76:79]
	v_mfma_f32_16x16x32_bf16 v[88:91], v[152:155], v[210:213], v[72:75]
	v_mfma_f32_16x16x32_bf16 v[76:79], v[226:229], v[218:221], v[176:179]
	v_mfma_f32_16x16x32_bf16 v[72:75], v[152:155], v[218:221], v[180:183]
	s_barrier
	ds_read_b128 v[176:179], v151 offset:49152
	ds_read_b128 v[180:183], v151 offset:50176
	ds_read_b128 v[184:187], v150 offset:49152
	ds_read_b128 v[188:191], v150 offset:50176
	ds_read_b128 v[192:195], v149 offset:49152
	ds_read_b128 v[196:199], v149 offset:50176
	ds_read_b128 v[200:203], v148 offset:49152
	ds_read_b128 v[148:151], v148 offset:50176
	s_barrier
	s_waitcnt lgkmcnt(0)
	s_waitcnt lgkmcnt(0)
	v_mfma_f32_16x16x32_bf16 v[24:27], v[0:3], v[176:179], v[60:63]
	v_mfma_f32_16x16x32_bf16 v[60:63], v[16:19], v[176:179], v[56:59]
	v_mfma_f32_16x16x32_bf16 v[52:55], v[0:3], v[184:187], v[52:55]
	v_mfma_f32_16x16x32_bf16 v[204:207], v[16:19], v[184:187], v[48:51]
	v_mfma_f32_16x16x32_bf16 v[44:47], v[0:3], v[192:195], v[44:47]
	v_mfma_f32_16x16x32_bf16 v[208:211], v[16:19], v[192:195], v[40:43]
	v_mfma_f32_16x16x32_bf16 v[0:3], v[0:3], v[200:203], v[36:39]
	v_mfma_f32_16x16x32_bf16 v[36:39], v[16:19], v[200:203], v[32:35]
	v_mfma_f32_16x16x32_bf16 v[56:59], v[8:11], v[180:183], v[24:27]
	v_mfma_f32_16x16x32_bf16 v[48:51], v[172:175], v[180:183], v[60:63]
	v_mfma_f32_16x16x32_bf16 v[40:43], v[8:11], v[188:191], v[52:55]
	v_mfma_f32_16x16x32_bf16 v[32:35], v[172:175], v[188:191], v[204:207]
	v_mfma_f32_16x16x32_bf16 v[24:27], v[8:11], v[196:199], v[44:47]
	v_mfma_f32_16x16x32_bf16 v[16:19], v[172:175], v[196:199], v[208:211]
	v_mfma_f32_16x16x32_bf16 v[8:11], v[8:11], v[148:151], v[0:3]
	v_mfma_f32_16x16x32_bf16 v[0:3], v[172:175], v[148:151], v[36:39]
	v_mfma_f32_16x16x32_bf16 v[28:31], v[222:225], v[176:179], v[28:31]
	v_mfma_f32_16x16x32_bf16 v[36:39], v[230:233], v[176:179], v[134:137]
	v_mfma_f32_16x16x32_bf16 v[20:23], v[222:225], v[184:187], v[20:23]
	v_mfma_f32_16x16x32_bf16 v[134:137], v[230:233], v[184:187], v[138:141]
	v_mfma_f32_16x16x32_bf16 v[12:15], v[222:225], v[192:195], v[12:15]
	v_mfma_f32_16x16x32_bf16 v[138:141], v[230:233], v[192:195], v[168:171]
	v_mfma_f32_16x16x32_bf16 v[4:7], v[222:225], v[200:203], v[4:7]
	v_mfma_f32_16x16x32_bf16 v[156:159], v[230:233], v[200:203], v[156:159]
	v_mfma_f32_16x16x32_bf16 v[60:63], v[226:229], v[180:183], v[28:31]
	v_mfma_f32_16x16x32_bf16 v[52:55], v[152:155], v[180:183], v[36:39]
	v_mfma_f32_16x16x32_bf16 v[44:47], v[226:229], v[188:191], v[20:23]
	v_mfma_f32_16x16x32_bf16 v[36:39], v[152:155], v[188:191], v[134:137]
	v_mfma_f32_16x16x32_bf16 v[28:31], v[226:229], v[196:199], v[12:15]
	v_mfma_f32_16x16x32_bf16 v[20:23], v[152:155], v[196:199], v[138:141]
	v_mfma_f32_16x16x32_bf16 v[12:15], v[226:229], v[148:151], v[4:7]
	v_mfma_f32_16x16x32_bf16 v[4:7], v[152:155], v[148:151], v[156:159]
	v_cmp_gt_u32_e32 vcc, s60, v130
	s_barrier
	s_and_saveexec_b64 s[44:45], vcc
	s_cbranch_execz .LBB0_1451
	s_barrier

; #define STAGE(P, BASE, LD, br, kt) do { const char* _g = (const char*)((BASE) + (size_t)(br) * (LD) + (size_t)(kt) * 64); \
;     for (int _i = 0; _i < 2; ++_i) { int _b = tidx * 16 + _i * 8192; int _r, _c; stage_rc(_b, _r, _c); \
;       __builtin_amdgcn_global_load_lds((const unsigned*)(_g + (unsigned)((_r * (LD) + _c) * 2)), (unsigned*)((char*)(P) + _b), 16, 0, 0); } } while (0)
; #define LDA(dst, b, h) for (int m = 0; m < 4; ++m) for (int k = 0; k < 2; ++k) \
;     dst[m][k] = *reinterpret_cast<const bf16x8*>((char*)SA(b, h) + lds_byte(wr * 64 + m * 16 + fr, k * 32 + fq * 8))
; #define LDB(dst, b, h) for (int n = 0; n < 2; ++n) for (int k = 0; k < 2; ++k) \
;     dst[n][k] = *reinterpret_cast<const bf16x8*>((char*)SB(b, h) + lds_byte(wc * 32 + n * 16 + fr, k * 32 + fq * 8))
; #define MMA(ai, bj, At_, Bt_) do { __builtin_amdgcn_s_setprio(1); \
;     for (int k = 0; k < 2; ++k) for (int m = 0; m < 4; ++m) for (int n = 0; n < 2; ++n) \
;       acc[ai][bj][m][n] = __builtin_amdgcn_mfma_f32_16x16x32_bf16(At_[m][k], Bt_[n][k], acc[ai][bj][m][n], 0, 0, 0); \
;     __builtin_amdgcn_s_setprio(0); } while (0)
; #define WAIT_L(n) asm volatile("s_waitcnt lgkmcnt(" #n ")" ::: "memory")
; #define BAR __builtin_amdgcn_s_barrier()
; #define SCHED __builtin_amdgcn_sched_barrier(0)
; template <int EPI, int lda, int ldb, int N, int K>
; __device__ __forceinline__ void gemm_phase(const u16* __restrict__ A, const u16* __restrict__ Bt, const GemmEpi ep, int wv) {
;     ...
;       LDB(B0, 0, 0); SCHED; LDA(At, 0, 0); STAGE(SA(1, 1), Ab, lda, brow + HALF, t + 1);
;       WAIT_L(8); BAR; WAIT_L(0); MMA(0, 0, At, B0); BAR; SCHED;
;       LDB(B1, 0, 1); STAGE(SB(0, 0), Bt, ldb, bcol, t + 2);
;       BAR; WAIT_L(0); MMA(0, 1, At, B1); BAR;
;       LDA(At, 0, 1); STAGE(SA(0, 0), Ab, lda, brow, t + 2);
;       BAR; WAIT_L(0); MMA(1, 0, At, B0); BAR; SCHED;
.LBB0_1564:
	ds_read_b128 v[172:175], v161
	ds_read_b128 v[176:179], v161 offset:1024
	ds_read_b128 v[180:183], v161 offset:2048
	ds_read_b128 v[184:187], v161 offset:3072
	v_add_u32_e32 v169, 0xc000, v148
	v_lshl_add_u64 v[236:237], v[136:137], 0, s[40:41]
	v_readfirstlane_b32 s43, v169
	v_add_u32_e32 v170, 0xe000, v148
	v_lshl_add_u64 v[162:163], v[236:237], 0, s[14:15]
	s_mov_b32 m0, s43
	v_lshl_add_u64 v[238:239], v[134:135], 0, s[40:41]
	v_readfirstlane_b32 s43, v170
	ds_read_b128 v[164:167], v152
	ds_read_b128 v[188:191], v152 offset:1024
	ds_read_b128 v[192:195], v151
	ds_read_b128 v[196:199], v151 offset:1024
	ds_read_b128 v[200:203], v150
	ds_read_b128 v[204:207], v150 offset:1024
	ds_read_b128 v[208:211], v149
	ds_read_b128 v[212:215], v149 offset:1024
	global_load_lds_dwordx4 v[162:163], off
	v_lshl_add_u64 v[162:163], v[238:239], 0, s[14:15]
	s_mov_b32 m0, s43
	s_nop 0
	global_load_lds_dwordx4 v[162:163], off
	s_waitcnt lgkmcnt(8)
	s_barrier
	s_waitcnt lgkmcnt(0)
	s_waitcnt lgkmcnt(0)
	v_mfma_f32_16x16x32_bf16 v[124:127], v[172:175], v[164:167], v[124:127]
	v_mfma_f32_16x16x32_bf16 v[120:123], v[180:183], v[164:167], v[120:123]
	v_mfma_f32_16x16x32_bf16 v[116:119], v[172:175], v[192:195], v[116:119]
	v_mfma_f32_16x16x32_bf16 v[112:115], v[180:183], v[192:195], v[112:115]
	v_mfma_f32_16x16x32_bf16 v[108:111], v[172:175], v[200:203], v[108:111]
	v_mfma_f32_16x16x32_bf16 v[104:107], v[180:183], v[200:203], v[104:107]
	v_mfma_f32_16x16x32_bf16 v[100:103], v[172:175], v[208:211], v[100:103]
	v_mfma_f32_16x16x32_bf16 v[96:99], v[180:183], v[208:211], v[96:99]
	v_mfma_f32_16x16x32_bf16 v[124:127], v[176:179], v[188:191], v[124:127]
	v_mfma_f32_16x16x32_bf16 v[120:123], v[184:187], v[188:191], v[120:123]
	v_mfma_f32_16x16x32_bf16 v[116:119], v[176:179], v[196:199], v[116:119]
	v_mfma_f32_16x16x32_bf16 v[112:115], v[184:187], v[196:199], v[112:115]
	v_mfma_f32_16x16x32_bf16 v[108:111], v[176:179], v[204:207], v[108:111]
	v_mfma_f32_16x16x32_bf16 v[104:107], v[184:187], v[204:207], v[104:107]
	v_mfma_f32_16x16x32_bf16 v[100:103], v[176:179], v[212:215], v[100:103]
	v_mfma_f32_16x16x32_bf16 v[96:99], v[184:187], v[212:215], v[96:99]
	s_barrier
	v_add_u32_e32 v162, s52, v153
	v_lshl_add_u64 v[240:241], v[140:141], 0, s[40:41]
	v_readfirstlane_b32 s43, v162
	v_add_u32_e32 v163, 0x2000, v162
	v_lshl_add_u64 v[232:233], v[240:241], 0, s[16:17]
	s_mov_b32 m0, s43
	v_lshl_add_u64 v[242:243], v[138:139], 0, s[40:41]
	v_readfirstlane_b32 s43, v163
	ds_read_b128 v[216:219], v160
	ds_read_b128 v[220:223], v160 offset:1024
	ds_read_b128 v[224:227], v160 offset:2048
	ds_read_b128 v[228:231], v160 offset:3072
	global_load_lds_dwordx4 v[232:233], off
	v_lshl_add_u64 v[232:233], v[242:243], 0, s[16:17]
	s_mov_b32 m0, s43
	s_nop 0
	global_load_lds_dwordx4 v[232:233], off
	s_barrier
	s_waitcnt lgkmcnt(0)
	s_waitcnt lgkmcnt(0)
	v_mfma_f32_16x16x32_bf16 v[92:95], v[216:219], v[164:167], v[92:95]
	v_mfma_f32_16x16x32_bf16 v[88:91], v[224:227], v[164:167], v[88:91]
	v_mfma_f32_16x16x32_bf16 v[84:87], v[216:219], v[192:195], v[84:87]
	v_mfma_f32_16x16x32_bf16 v[80:83], v[224:227], v[192:195], v[80:83]
	v_mfma_f32_16x16x32_bf16 v[76:79], v[216:219], v[200:203], v[76:79]
	v_mfma_f32_16x16x32_bf16 v[72:75], v[224:227], v[200:203], v[72:75]
	v_mfma_f32_16x16x32_bf16 v[68:71], v[216:219], v[208:211], v[68:71]
	v_mfma_f32_16x16x32_bf16 v[64:67], v[224:227], v[208:211], v[64:67]
	v_mfma_f32_16x16x32_bf16 v[92:95], v[220:223], v[188:191], v[92:95]
	v_mfma_f32_16x16x32_bf16 v[88:91], v[228:231], v[188:191], v[88:91]
	v_mfma_f32_16x16x32_bf16 v[84:87], v[220:223], v[196:199], v[84:87]
	v_mfma_f32_16x16x32_bf16 v[80:83], v[228:231], v[196:199], v[80:83]
	v_mfma_f32_16x16x32_bf16 v[76:79], v[220:223], v[204:207], v[76:79]
	v_mfma_f32_16x16x32_bf16 v[72:75], v[228:231], v[204:207], v[72:75]
	v_mfma_f32_16x16x32_bf16 v[68:71], v[220:223], v[212:215], v[68:71]
	v_mfma_f32_16x16x32_bf16 v[64:67], v[228:231], v[212:215], v[64:67]
	s_barrier
	v_readfirstlane_b32 s43, v148
	v_lshl_add_u64 v[164:165], v[236:237], 0, s[18:19]
	s_mov_b32 m0, s43
	ds_read_b128 v[188:191], v152 offset:16384
	ds_read_b128 v[192:195], v152 offset:17408
	ds_read_b128 v[196:199], v151 offset:16384
	ds_read_b128 v[200:203], v151 offset:17408
	ds_read_b128 v[204:207], v150 offset:16384
	ds_read_b128 v[208:211], v150 offset:17408
	ds_read_b128 v[212:215], v149 offset:16384
	ds_read_b128 v[232:235], v149 offset:17408
	global_load_lds_dwordx4 v[164:165], off
	v_add_u32_e32 v164, 0x2000, v148
	v_lshl_add_u64 v[166:167], v[238:239], 0, s[18:19]
	v_readfirstlane_b32 s43, v164
	s_mov_b32 m0, s43
	s_nop 0
	global_load_lds_dwordx4 v[166:167], off
	s_barrier
	s_waitcnt lgkmcnt(0)
	s_waitcnt lgkmcnt(0)
	v_mfma_f32_16x16x32_bf16 v[60:63], v[172:175], v[188:191], v[60:63]
	v_mfma_f32_16x16x32_bf16 v[56:59], v[180:183], v[188:191], v[56:59]
	v_mfma_f32_16x16x32_bf16 v[52:55], v[172:175], v[196:199], v[52:55]
	v_mfma_f32_16x16x32_bf16 v[48:51], v[180:183], v[196:199], v[48:51]
	v_mfma_f32_16x16x32_bf16 v[44:47], v[172:175], v[204:207], v[44:47]
	v_mfma_f32_16x16x32_bf16 v[40:43], v[180:183], v[204:207], v[40:43]
	v_mfma_f32_16x16x32_bf16 v[36:39], v[172:175], v[212:215], v[36:39]
	v_mfma_f32_16x16x32_bf16 v[32:35], v[180:183], v[212:215], v[32:35]
	v_mfma_f32_16x16x32_bf16 v[60:63], v[176:179], v[192:195], v[60:63]
	v_mfma_f32_16x16x32_bf16 v[56:59], v[184:187], v[192:195], v[56:59]
	v_mfma_f32_16x16x32_bf16 v[52:55], v[176:179], v[200:203], v[52:55]
	v_mfma_f32_16x16x32_bf16 v[48:51], v[184:187], v[200:203], v[48:51]
	v_mfma_f32_16x16x32_bf16 v[44:47], v[176:179], v[208:211], v[44:47]
	v_mfma_f32_16x16x32_bf16 v[40:43], v[184:187], v[208:211], v[40:43]
	v_mfma_f32_16x16x32_bf16 v[36:39], v[176:179], v[232:235], v[36:39]
	v_mfma_f32_16x16x32_bf16 v[32:35], v[184:187], v[232:235], v[32:35]
	s_barrier
; #define STAGE(P, BASE, LD, br, kt) do { const char* _g = (const char*)((BASE) + (size_t)(br) * (LD) + (size_t)(kt) * 64); \
;     for (int _i = 0; _i < 2; ++_i) { int _b = tidx * 16 + _i * 8192; int _r, _c; stage_rc(_b, _r, _c); \
;       __builtin_amdgcn_global_load_lds((const unsigned*)(_g + (unsigned)((_r * (LD) + _c) * 2)), (unsigned*)((char*)(P) + _b), 16, 0, 0); } } while (0)
; #define LDA(dst, b, h) for (int m = 0; m < 4; ++m) for (int k = 0; k < 2; ++k) \
;     dst[m][k] = *reinterpret_cast<const bf16x8*>((char*)SA(b, h) + lds_byte(wr * 64 + m * 16 + fr, k * 32 + fq * 8))
; #define LDB(dst, b, h) for (int n = 0; n < 2; ++n) for (int k = 0; k < 2; ++k) \
;     dst[n][k] = *reinterpret_cast<const bf16x8*>((char*)SB(b, h) + lds_byte(wc * 32 + n * 16 + fr, k * 32 + fq * 8))
; #define MMA(ai, bj, At_, Bt_) do { __builtin_amdgcn_s_setprio(1); \
;     for (int k = 0; k < 2; ++k) for (int m = 0; m < 4; ++m) for (int n = 0; n < 2; ++n) \
;       acc[ai][bj][m][n] = __builtin_amdgcn_mfma_f32_16x16x32_bf16(At_[m][k], Bt_[n][k], acc[ai][bj][m][n], 0, 0, 0); \
;     __builtin_amdgcn_s_setprio(0); } while (0)
; #define WAIT_V(n) asm volatile("s_waitcnt vmcnt(" #n ")" ::: "memory")
; #define WAIT_L(n) asm volatile("s_waitcnt lgkmcnt(" #n ")" ::: "memory")
; #define BAR __builtin_amdgcn_s_barrier()
; #define SCHED __builtin_amdgcn_sched_barrier(0)
; template <int EPI, int lda, int ldb, int N, int K>
; __device__ __forceinline__ void gemm_phase(const u16* __restrict__ A, const u16* __restrict__ Bt, const GemmEpi ep, int wv) {
;     ...
;       STAGE(SB(0, 1), Bt, ldb, bcol + HALF, t + 2);
;       WAIT_V(6); BAR; MMA(1, 1, At, B1); BAR;
;       LDB(B0, 1, 0); SCHED; LDA(At, 1, 0); STAGE(SA(0, 1), Ab, lda, brow + HALF, t + 2);
;       WAIT_L(8); BAR; WAIT_L(0); MMA(0, 0, At, B0); BAR; SCHED;
;       LDB(B1, 1, 1); STAGE(SB(1, 0), Bt, ldb, bcol, t + 3);
;       BAR; WAIT_L(0); MMA(0, 1, At, B1); BAR;
	v_add_u32_e32 v165, s53, v153
	v_lshl_add_u64 v[166:167], v[240:241], 0, s[20:21]
	v_readfirstlane_b32 s43, v165
	s_mov_b32 m0, s43
	v_lshl_add_u64 v[172:173], v[242:243], 0, s[20:21]
	global_load_lds_dwordx4 v[166:167], off
	v_add_u32_e32 v166, 0x2000, v165
	s_nop 0
	v_readfirstlane_b32 s43, v166
	s_mov_b32 m0, s43
	s_nop 0
	global_load_lds_dwordx4 v[172:173], off
	s_waitcnt vmcnt(6)
	s_barrier
	v_mfma_f32_16x16x32_bf16 v[28:31], v[216:219], v[188:191], v[28:31]
	v_mfma_f32_16x16x32_bf16 v[24:27], v[224:227], v[188:191], v[24:27]
	v_mfma_f32_16x16x32_bf16 v[20:23], v[216:219], v[196:199], v[20:23]
	v_mfma_f32_16x16x32_bf16 v[16:19], v[224:227], v[196:199], v[16:19]
	v_mfma_f32_16x16x32_bf16 v[12:15], v[216:219], v[204:207], v[12:15]
	v_mfma_f32_16x16x32_bf16 v[8:11], v[224:227], v[204:207], v[8:11]
	v_mfma_f32_16x16x32_bf16 v[4:7], v[216:219], v[212:215], v[4:7]
	v_mfma_f32_16x16x32_bf16 v[0:3], v[224:227], v[212:215], v[0:3]
	v_mfma_f32_16x16x32_bf16 v[28:31], v[220:223], v[192:195], v[28:31]
	v_mfma_f32_16x16x32_bf16 v[24:27], v[228:231], v[192:195], v[24:27]
	v_mfma_f32_16x16x32_bf16 v[20:23], v[220:223], v[200:203], v[20:23]
	v_mfma_f32_16x16x32_bf16 v[16:19], v[228:231], v[200:203], v[16:19]
	v_mfma_f32_16x16x32_bf16 v[12:15], v[220:223], v[208:211], v[12:15]
	v_mfma_f32_16x16x32_bf16 v[8:11], v[228:231], v[208:211], v[8:11]
	v_mfma_f32_16x16x32_bf16 v[4:7], v[220:223], v[232:235], v[4:7]
	v_mfma_f32_16x16x32_bf16 v[0:3], v[228:231], v[232:235], v[0:3]
	s_barrier
	ds_read_b128 v[172:175], v156
	ds_read_b128 v[176:179], v156 offset:1024
	ds_read_b128 v[180:183], v156 offset:2048
	ds_read_b128 v[184:187], v156 offset:3072
	v_add_u32_e32 v167, 0x4000, v148
	v_add_u32_e32 v168, 0x6000, v148
	v_readfirstlane_b32 s43, v167
	v_lshl_add_u64 v[220:221], v[236:237], 0, s[22:23]
	s_mov_b32 m0, s43
	v_readfirstlane_b32 s43, v168
	ds_read_b128 v[188:191], v152 offset:32768
	ds_read_b128 v[192:195], v152 offset:33792
	ds_read_b128 v[196:199], v151 offset:32768
	ds_read_b128 v[200:203], v151 offset:33792
	ds_read_b128 v[204:207], v150 offset:32768
	ds_read_b128 v[208:211], v150 offset:33792
	ds_read_b128 v[212:215], v149 offset:32768
	ds_read_b128 v[216:219], v149 offset:33792
	global_load_lds_dwordx4 v[220:221], off
	v_lshl_add_u64 v[220:221], v[238:239], 0, s[22:23]
	s_mov_b32 m0, s43
	s_nop 0
	global_load_lds_dwordx4 v[220:221], off
	s_waitcnt lgkmcnt(8)
	s_barrier
	s_waitcnt lgkmcnt(0)
	s_waitcnt lgkmcnt(0)
	v_mfma_f32_16x16x32_bf16 v[124:127], v[172:175], v[188:191], v[124:127]
	v_mfma_f32_16x16x32_bf16 v[120:123], v[180:183], v[188:191], v[120:123]
	v_mfma_f32_16x16x32_bf16 v[116:119], v[172:175], v[196:199], v[116:119]
	v_mfma_f32_16x16x32_bf16 v[112:115], v[180:183], v[196:199], v[112:115]
	v_mfma_f32_16x16x32_bf16 v[108:111], v[172:175], v[204:207], v[108:111]
	v_mfma_f32_16x16x32_bf16 v[104:107], v[180:183], v[204:207], v[104:107]
	v_mfma_f32_16x16x32_bf16 v[100:103], v[172:175], v[212:215], v[100:103]
	v_mfma_f32_16x16x32_bf16 v[96:99], v[180:183], v[212:215], v[96:99]
	v_mfma_f32_16x16x32_bf16 v[124:127], v[176:179], v[192:195], v[124:127]
	v_mfma_f32_16x16x32_bf16 v[120:123], v[184:187], v[192:195], v[120:123]
	v_mfma_f32_16x16x32_bf16 v[116:119], v[176:179], v[200:203], v[116:119]
	v_mfma_f32_16x16x32_bf16 v[112:115], v[184:187], v[200:203], v[112:115]
	v_mfma_f32_16x16x32_bf16 v[108:111], v[176:179], v[208:211], v[108:111]
	v_mfma_f32_16x16x32_bf16 v[104:107], v[184:187], v[208:211], v[104:107]
	v_mfma_f32_16x16x32_bf16 v[100:103], v[176:179], v[216:219], v[100:103]
	v_mfma_f32_16x16x32_bf16 v[96:99], v[184:187], v[216:219], v[96:99]
	s_barrier
	v_readfirstlane_b32 s43, v155
	v_add_u32_e32 v171, 0x2000, v155
	v_lshl_add_u64 v[244:245], v[240:241], 0, s[24:25]
	s_mov_b32 m0, s43
	v_readfirstlane_b32 s43, v171
	ds_read_b128 v[220:223], v154
	ds_read_b128 v[224:227], v154 offset:1024
	ds_read_b128 v[228:231], v154 offset:2048
	ds_read_b128 v[232:235], v154 offset:3072
	global_load_lds_dwordx4 v[244:245], off
	v_lshl_add_u64 v[244:245], v[242:243], 0, s[24:25]
	s_mov_b32 m0, s43
	s_nop 0
	global_load_lds_dwordx4 v[244:245], off
	s_barrier
	s_waitcnt lgkmcnt(0)
	s_waitcnt lgkmcnt(0)
	v_mfma_f32_16x16x32_bf16 v[92:95], v[220:223], v[188:191], v[92:95]
	v_mfma_f32_16x16x32_bf16 v[88:91], v[228:231], v[188:191], v[88:91]
	v_mfma_f32_16x16x32_bf16 v[84:87], v[220:223], v[196:199], v[84:87]
	v_mfma_f32_16x16x32_bf16 v[80:83], v[228:231], v[196:199], v[80:83]
	v_mfma_f32_16x16x32_bf16 v[76:79], v[220:223], v[204:207], v[76:79]
	v_mfma_f32_16x16x32_bf16 v[72:75], v[228:231], v[204:207], v[72:75]
	v_mfma_f32_16x16x32_bf16 v[68:71], v[220:223], v[212:215], v[68:71]
	v_mfma_f32_16x16x32_bf16 v[64:67], v[228:231], v[212:215], v[64:67]
	v_mfma_f32_16x16x32_bf16 v[92:95], v[224:227], v[192:195], v[92:95]
	v_mfma_f32_16x16x32_bf16 v[88:91], v[232:235], v[192:195], v[88:91]
	v_mfma_f32_16x16x32_bf16 v[84:87], v[224:227], v[200:203], v[84:87]
	v_mfma_f32_16x16x32_bf16 v[80:83], v[232:235], v[200:203], v[80:83]
	v_mfma_f32_16x16x32_bf16 v[76:79], v[224:227], v[208:211], v[76:79]
	v_mfma_f32_16x16x32_bf16 v[72:75], v[232:235], v[208:211], v[72:75]
	v_mfma_f32_16x16x32_bf16 v[68:71], v[224:227], v[216:219], v[68:71]
	v_mfma_f32_16x16x32_bf16 v[64:67], v[232:235], v[216:219], v[64:67]
	s_barrier
	v_readfirstlane_b32 s43, v157
	v_lshl_add_u64 v[236:237], v[236:237], 0, s[26:27]
	s_mov_b32 m0, s43
	v_readfirstlane_b32 s43, v158
	ds_read_b128 v[188:191], v152 offset:49152
	ds_read_b128 v[192:195], v152 offset:50176
	ds_read_b128 v[196:199], v151 offset:49152
	ds_read_b128 v[200:203], v151 offset:50176
	ds_read_b128 v[204:207], v150 offset:49152
	ds_read_b128 v[208:211], v150 offset:50176
	ds_read_b128 v[212:215], v149 offset:49152
	ds_read_b128 v[216:219], v149 offset:50176
	global_load_lds_dwordx4 v[236:237], off
	v_lshl_add_u64 v[236:237], v[238:239], 0, s[26:27]
	s_mov_b32 m0, s43
	s_nop 0
	global_load_lds_dwordx4 v[236:237], off
	s_barrier
; #define STAGE(P, BASE, LD, br, kt) do { const char* _g = (const char*)((BASE) + (size_t)(br) * (LD) + (size_t)(kt) * 64); \
;     for (int _i = 0; _i < 2; ++_i) { int _b = tidx * 16 + _i * 8192; int _r, _c; stage_rc(_b, _r, _c); \
;       __builtin_amdgcn_global_load_lds((const unsigned*)(_g + (unsigned)((_r * (LD) + _c) * 2)), (unsigned*)((char*)(P) + _b), 16, 0, 0); } } while (0)
; #define LDA(dst, b, h) for (int m = 0; m < 4; ++m) for (int k = 0; k < 2; ++k) \
;     dst[m][k] = *reinterpret_cast<const bf16x8*>((char*)SA(b, h) + lds_byte(wr * 64 + m * 16 + fr, k * 32 + fq * 8))
; #define LDB(dst, b, h) for (int n = 0; n < 2; ++n) for (int k = 0; k < 2; ++k) \
;     dst[n][k] = *reinterpret_cast<const bf16x8*>((char*)SB(b, h) + lds_byte(wc * 32 + n * 16 + fr, k * 32 + fq * 8))
; #define MMA(ai, bj, At_, Bt_) do { __builtin_amdgcn_s_setprio(1); \
;     for (int k = 0; k < 2; ++k) for (int m = 0; m < 4; ++m) for (int n = 0; n < 2; ++n) \
;       acc[ai][bj][m][n] = __builtin_amdgcn_mfma_f32_16x16x32_bf16(At_[m][k], Bt_[n][k], acc[ai][bj][m][n], 0, 0, 0); \
;     __builtin_amdgcn_s_setprio(0); } while (0)
; #define WAIT_V(n) asm volatile("s_waitcnt vmcnt(" #n ")" ::: "memory")
; #define WAIT_L(n) asm volatile("s_waitcnt lgkmcnt(" #n ")" ::: "memory")
; #define BAR __builtin_amdgcn_s_barrier()
; #define SCHED __builtin_amdgcn_sched_barrier(0)
; template <int EPI, int lda, int ldb, int N, int K>
; __device__ __forceinline__ void gemm_phase(const u16* __restrict__ A, const u16* __restrict__ Bt, const GemmEpi ep, int wv) {
;     ...
;       BAR; WAIT_L(0); MMA(1, 0, At, B0); BAR; SCHED;
;       STAGE(SB(1, 1), Bt, ldb, bcol + HALF, t + 3);
;       WAIT_V(6); BAR; MMA(1, 1, At, B1); BAR;
;     }
;     { LDB(B0, 0, 0); LDA(At, 0, 0); STAGE(SA(1, 1), Ab, lda, brow + HALF, nt - 1);
;       BAR; WAIT_L(0); MMA(0, 0, At, B0); BAR;
;       LDB(B1, 0, 1); BAR; WAIT_L(0); MMA(0, 1, At, B1); BAR;
	s_waitcnt lgkmcnt(0)
	s_waitcnt lgkmcnt(0)
	v_mfma_f32_16x16x32_bf16 v[60:63], v[172:175], v[188:191], v[60:63]
	v_mfma_f32_16x16x32_bf16 v[56:59], v[180:183], v[188:191], v[56:59]
	v_mfma_f32_16x16x32_bf16 v[52:55], v[172:175], v[196:199], v[52:55]
	v_mfma_f32_16x16x32_bf16 v[48:51], v[180:183], v[196:199], v[48:51]
	v_mfma_f32_16x16x32_bf16 v[44:47], v[172:175], v[204:207], v[44:47]
	v_mfma_f32_16x16x32_bf16 v[40:43], v[180:183], v[204:207], v[40:43]
	v_mfma_f32_16x16x32_bf16 v[36:39], v[172:175], v[212:215], v[36:39]
	v_mfma_f32_16x16x32_bf16 v[32:35], v[180:183], v[212:215], v[32:35]
	v_mfma_f32_16x16x32_bf16 v[60:63], v[176:179], v[192:195], v[60:63]
	v_mfma_f32_16x16x32_bf16 v[56:59], v[184:187], v[192:195], v[56:59]
	v_mfma_f32_16x16x32_bf16 v[52:55], v[176:179], v[200:203], v[52:55]
	v_mfma_f32_16x16x32_bf16 v[48:51], v[184:187], v[200:203], v[48:51]
	v_mfma_f32_16x16x32_bf16 v[44:47], v[176:179], v[208:211], v[44:47]
	v_mfma_f32_16x16x32_bf16 v[40:43], v[184:187], v[208:211], v[40:43]
	v_mfma_f32_16x16x32_bf16 v[36:39], v[176:179], v[216:219], v[36:39]
	v_mfma_f32_16x16x32_bf16 v[32:35], v[184:187], v[216:219], v[32:35]
	s_barrier
	v_readfirstlane_b32 s43, v159
	v_add_u32_e32 v171, 0x2000, v159
	v_lshl_add_u64 v[172:173], v[240:241], 0, s[34:35]
	s_mov_b32 m0, s43
	v_readfirstlane_b32 s43, v171
	global_load_lds_dwordx4 v[172:173], off
	v_lshl_add_u64 v[172:173], v[242:243], 0, s[34:35]
	s_mov_b32 m0, s43
	s_nop 0
	global_load_lds_dwordx4 v[172:173], off
	s_add_i32 s42, s42, 2
	s_add_u32 s40, s40, 0x100
	s_addc_u32 s41, s41, 0
	s_cmp_gt_u32 s42, 27
	s_waitcnt vmcnt(6)
	s_barrier
	v_mfma_f32_16x16x32_bf16 v[28:31], v[220:223], v[188:191], v[28:31]
	v_mfma_f32_16x16x32_bf16 v[24:27], v[228:231], v[188:191], v[24:27]
	v_mfma_f32_16x16x32_bf16 v[20:23], v[220:223], v[196:199], v[20:23]
	v_mfma_f32_16x16x32_bf16 v[16:19], v[228:231], v[196:199], v[16:19]
	v_mfma_f32_16x16x32_bf16 v[12:15], v[220:223], v[204:207], v[12:15]
	v_mfma_f32_16x16x32_bf16 v[8:11], v[228:231], v[204:207], v[8:11]
	v_mfma_f32_16x16x32_bf16 v[4:7], v[220:223], v[212:215], v[4:7]
	v_mfma_f32_16x16x32_bf16 v[0:3], v[228:231], v[212:215], v[0:3]
	v_mfma_f32_16x16x32_bf16 v[28:31], v[224:227], v[192:195], v[28:31]
	v_mfma_f32_16x16x32_bf16 v[24:27], v[232:235], v[192:195], v[24:27]
	v_mfma_f32_16x16x32_bf16 v[20:23], v[224:227], v[200:203], v[20:23]
	v_mfma_f32_16x16x32_bf16 v[16:19], v[232:235], v[200:203], v[16:19]
	v_mfma_f32_16x16x32_bf16 v[12:15], v[224:227], v[208:211], v[12:15]
	v_mfma_f32_16x16x32_bf16 v[8:11], v[232:235], v[208:211], v[8:11]
	v_mfma_f32_16x16x32_bf16 v[4:7], v[224:227], v[216:219], v[4:7]
	v_mfma_f32_16x16x32_bf16 v[0:3], v[232:235], v[216:219], v[0:3]
	s_barrier
	s_cbranch_scc0 .LBB0_1564
	s_add_i32 s40, s38, 0x80
	s_mul_hi_i32 s41, s40, 0x1080
	s_mulk_i32 s40, 0x1080
	s_add_u32 s40, s49, s40
	s_addc_u32 s41, s50, s41
	v_lshl_add_u64 v[158:159], s[40:41], 0, v[128:129]
	v_readfirstlane_b32 s42, v169
	v_lshl_add_u64 v[158:159], v[158:159], 0, s[36:37]
	s_mov_b32 m0, s42
	ds_read_b128 v[134:137], v161
	ds_read_b128 v[138:141], v161 offset:1024
	ds_read_b128 v[172:175], v161 offset:2048
	ds_read_b128 v[176:179], v161 offset:3072
	ds_read_b128 v[180:183], v152
	ds_read_b128 v[184:187], v152 offset:1024
	ds_read_b128 v[188:191], v151
	ds_read_b128 v[192:195], v151 offset:1024
	ds_read_b128 v[196:199], v150
	ds_read_b128 v[200:203], v150 offset:1024
	ds_read_b128 v[204:207], v149
	ds_read_b128 v[208:211], v149 offset:1024
	global_load_lds_dwordx4 v[158:159], off
	v_lshl_add_u64 v[158:159], s[40:41], 0, v[132:133]
	v_readfirstlane_b32 s40, v170
	v_lshl_add_u64 v[158:159], v[158:159], 0, s[36:37]
	s_mov_b32 m0, s40
	s_nop 0
	global_load_lds_dwordx4 v[158:159], off
	s_barrier
	s_waitcnt lgkmcnt(0)
	s_waitcnt lgkmcnt(0)
	v_mfma_f32_16x16x32_bf16 v[124:127], v[134:137], v[180:183], v[124:127]
	v_mfma_f32_16x16x32_bf16 v[120:123], v[172:175], v[180:183], v[120:123]
	v_mfma_f32_16x16x32_bf16 v[116:119], v[134:137], v[188:191], v[116:119]
	v_mfma_f32_16x16x32_bf16 v[112:115], v[172:175], v[188:191], v[112:115]
	v_mfma_f32_16x16x32_bf16 v[108:111], v[134:137], v[196:199], v[108:111]
	v_mfma_f32_16x16x32_bf16 v[104:107], v[172:175], v[196:199], v[104:107]
	v_mfma_f32_16x16x32_bf16 v[100:103], v[134:137], v[204:207], v[100:103]
	v_mfma_f32_16x16x32_bf16 v[96:99], v[172:175], v[204:207], v[96:99]
	v_mfma_f32_16x16x32_bf16 v[124:127], v[138:141], v[184:187], v[124:127]
	v_mfma_f32_16x16x32_bf16 v[120:123], v[176:179], v[184:187], v[120:123]
	v_mfma_f32_16x16x32_bf16 v[116:119], v[138:141], v[192:195], v[116:119]
	v_mfma_f32_16x16x32_bf16 v[112:115], v[176:179], v[192:195], v[112:115]
	v_mfma_f32_16x16x32_bf16 v[108:111], v[138:141], v[200:203], v[108:111]
	v_mfma_f32_16x16x32_bf16 v[104:107], v[176:179], v[200:203], v[104:107]
	v_mfma_f32_16x16x32_bf16 v[100:103], v[138:141], v[208:211], v[100:103]
	v_mfma_f32_16x16x32_bf16 v[96:99], v[176:179], v[208:211], v[96:99]
	s_barrier
	ds_read_b128 v[212:215], v160
	ds_read_b128 v[216:219], v160 offset:1024
	ds_read_b128 v[220:223], v160 offset:2048
	ds_read_b128 v[158:161], v160 offset:3072
	s_barrier
; #define LDA(dst, b, h) for (int m = 0; m < 4; ++m) for (int k = 0; k < 2; ++k) \
;     dst[m][k] = *reinterpret_cast<const bf16x8*>((char*)SA(b, h) + lds_byte(wr * 64 + m * 16 + fr, k * 32 + fq * 8))
; #define LDB(dst, b, h) for (int n = 0; n < 2; ++n) for (int k = 0; k < 2; ++k) \
;     dst[n][k] = *reinterpret_cast<const bf16x8*>((char*)SB(b, h) + lds_byte(wc * 32 + n * 16 + fr, k * 32 + fq * 8))
; #define MMA(ai, bj, At_, Bt_) do { __builtin_amdgcn_s_setprio(1); \
;     for (int k = 0; k < 2; ++k) for (int m = 0; m < 4; ++m) for (int n = 0; n < 2; ++n) \
;       acc[ai][bj][m][n] = __builtin_amdgcn_mfma_f32_16x16x32_bf16(At_[m][k], Bt_[n][k], acc[ai][bj][m][n], 0, 0, 0); \
;     __builtin_amdgcn_s_setprio(0); } while (0)
; #define WAIT_V(n) asm volatile("s_waitcnt vmcnt(" #n ")" ::: "memory")
; #define WAIT_L(n) asm volatile("s_waitcnt lgkmcnt(" #n ")" ::: "memory")
; #define BAR __builtin_amdgcn_s_barrier()
; template <int EPI, int lda, int ldb, int N, int K>
; __device__ __forceinline__ void gemm_phase(const u16* __restrict__ A, const u16* __restrict__ Bt, const GemmEpi ep, int wv) {
;     ...
;       LDB(B1, 0, 1); BAR; WAIT_L(0); MMA(0, 1, At, B1); BAR;
;       LDA(At, 0, 1); WAIT_V(4); BAR; WAIT_L(0); MMA(1, 0, At, B0); MMA(1, 1, At, B1); BAR; }
;     { LDB(B0, 1, 0); LDA(At, 1, 0); WAIT_V(2); BAR; WAIT_L(0); MMA(0, 0, At, B0); BAR;
	s_waitcnt lgkmcnt(0)
	s_waitcnt lgkmcnt(0)
	v_mfma_f32_16x16x32_bf16 v[92:95], v[212:215], v[180:183], v[92:95]
	v_mfma_f32_16x16x32_bf16 v[88:91], v[220:223], v[180:183], v[88:91]
	v_mfma_f32_16x16x32_bf16 v[76:79], v[212:215], v[196:199], v[76:79]
	v_mfma_f32_16x16x32_bf16 v[72:75], v[220:223], v[196:199], v[72:75]
	v_mfma_f32_16x16x32_bf16 v[84:87], v[212:215], v[188:191], v[84:87]
	v_mfma_f32_16x16x32_bf16 v[80:83], v[220:223], v[188:191], v[80:83]
	v_mfma_f32_16x16x32_bf16 v[68:71], v[212:215], v[204:207], v[68:71]
	v_mfma_f32_16x16x32_bf16 v[64:67], v[220:223], v[204:207], v[64:67]
	v_mfma_f32_16x16x32_bf16 v[92:95], v[216:219], v[184:187], v[92:95]
	v_mfma_f32_16x16x32_bf16 v[88:91], v[158:161], v[184:187], v[88:91]
	v_mfma_f32_16x16x32_bf16 v[76:79], v[216:219], v[200:203], v[76:79]
	v_mfma_f32_16x16x32_bf16 v[72:75], v[158:161], v[200:203], v[72:75]
	v_mfma_f32_16x16x32_bf16 v[180:183], v[216:219], v[192:195], v[84:87]
	v_mfma_f32_16x16x32_bf16 v[184:187], v[158:161], v[192:195], v[80:83]
	v_mfma_f32_16x16x32_bf16 v[188:191], v[216:219], v[208:211], v[68:71]
	v_mfma_f32_16x16x32_bf16 v[192:195], v[158:161], v[208:211], v[64:67]
	s_barrier
	s_nop 0
	ds_read_b128 v[64:67], v152 offset:16384
	ds_read_b128 v[68:71], v152 offset:17408
	ds_read_b128 v[80:83], v151 offset:16384
	ds_read_b128 v[84:87], v151 offset:17408
	ds_read_b128 v[196:199], v150 offset:16384
	ds_read_b128 v[200:203], v150 offset:17408
	ds_read_b128 v[204:207], v149 offset:16384
	ds_read_b128 v[208:211], v149 offset:17408
	s_waitcnt vmcnt(4)
	s_barrier
	s_waitcnt lgkmcnt(0)
	s_waitcnt lgkmcnt(0)
	v_mfma_f32_16x16x32_bf16 v[60:63], v[134:137], v[64:67], v[60:63]
	v_mfma_f32_16x16x32_bf16 v[56:59], v[172:175], v[64:67], v[56:59]
	v_mfma_f32_16x16x32_bf16 v[52:55], v[134:137], v[80:83], v[52:55]
	v_mfma_f32_16x16x32_bf16 v[48:51], v[172:175], v[80:83], v[48:51]
	v_mfma_f32_16x16x32_bf16 v[44:47], v[134:137], v[196:199], v[44:47]
	v_mfma_f32_16x16x32_bf16 v[40:43], v[172:175], v[196:199], v[40:43]
	v_mfma_f32_16x16x32_bf16 v[36:39], v[134:137], v[204:207], v[36:39]
	v_mfma_f32_16x16x32_bf16 v[32:35], v[172:175], v[204:207], v[32:35]
	v_mfma_f32_16x16x32_bf16 v[60:63], v[138:141], v[68:71], v[60:63]
	v_mfma_f32_16x16x32_bf16 v[56:59], v[176:179], v[68:71], v[56:59]
	v_mfma_f32_16x16x32_bf16 v[52:55], v[138:141], v[84:87], v[52:55]
	v_mfma_f32_16x16x32_bf16 v[48:51], v[176:179], v[84:87], v[48:51]
	v_mfma_f32_16x16x32_bf16 v[44:47], v[138:141], v[200:203], v[44:47]
	v_mfma_f32_16x16x32_bf16 v[40:43], v[176:179], v[200:203], v[40:43]
	v_mfma_f32_16x16x32_bf16 v[36:39], v[138:141], v[208:211], v[36:39]
	v_mfma_f32_16x16x32_bf16 v[32:35], v[176:179], v[208:211], v[32:35]
	v_mfma_f32_16x16x32_bf16 v[28:31], v[212:215], v[64:67], v[28:31]
	v_mfma_f32_16x16x32_bf16 v[24:27], v[220:223], v[64:67], v[24:27]
	v_mfma_f32_16x16x32_bf16 v[12:15], v[212:215], v[196:199], v[12:15]
	v_mfma_f32_16x16x32_bf16 v[8:11], v[220:223], v[196:199], v[8:11]
	v_mfma_f32_16x16x32_bf16 v[20:23], v[212:215], v[80:83], v[20:23]
	v_mfma_f32_16x16x32_bf16 v[16:19], v[220:223], v[80:83], v[16:19]
	v_mfma_f32_16x16x32_bf16 v[4:7], v[212:215], v[204:207], v[4:7]
	v_mfma_f32_16x16x32_bf16 v[0:3], v[220:223], v[204:207], v[0:3]
	v_mfma_f32_16x16x32_bf16 v[28:31], v[216:219], v[68:71], v[28:31]
	v_mfma_f32_16x16x32_bf16 v[24:27], v[158:161], v[68:71], v[24:27]
	v_mfma_f32_16x16x32_bf16 v[12:15], v[216:219], v[200:203], v[12:15]
	v_mfma_f32_16x16x32_bf16 v[8:11], v[158:161], v[200:203], v[8:11]
	v_mfma_f32_16x16x32_bf16 v[134:137], v[216:219], v[84:87], v[20:23]
	v_mfma_f32_16x16x32_bf16 v[138:141], v[158:161], v[84:87], v[16:19]
	v_mfma_f32_16x16x32_bf16 v[170:173], v[216:219], v[208:211], v[4:7]
	v_mfma_f32_16x16x32_bf16 v[158:161], v[158:161], v[208:211], v[0:3]
	s_barrier
	s_nop 0
	ds_read_b128 v[0:3], v156
	ds_read_b128 v[4:7], v156 offset:1024
	ds_read_b128 v[16:19], v156 offset:2048
	ds_read_b128 v[174:177], v156 offset:3072
	ds_read_b128 v[20:23], v152 offset:32768
	ds_read_b128 v[196:199], v152 offset:33792
	ds_read_b128 v[200:203], v151 offset:32768
	ds_read_b128 v[204:207], v151 offset:33792
	ds_read_b128 v[208:211], v150 offset:32768
	ds_read_b128 v[212:215], v150 offset:33792
	ds_read_b128 v[216:219], v149 offset:32768
	ds_read_b128 v[220:223], v149 offset:33792
	s_waitcnt vmcnt(2)
	s_barrier
; #define LDA(dst, b, h) for (int m = 0; m < 4; ++m) for (int k = 0; k < 2; ++k) \
;     dst[m][k] = *reinterpret_cast<const bf16x8*>((char*)SA(b, h) + lds_byte(wr * 64 + m * 16 + fr, k * 32 + fq * 8))
; #define LDB(dst, b, h) for (int n = 0; n < 2; ++n) for (int k = 0; k < 2; ++k) \
;     dst[n][k] = *reinterpret_cast<const bf16x8*>((char*)SB(b, h) + lds_byte(wc * 32 + n * 16 + fr, k * 32 + fq * 8))
; #define MMA(ai, bj, At_, Bt_) do { __builtin_amdgcn_s_setprio(1); \
;     for (int k = 0; k < 2; ++k) for (int m = 0; m < 4; ++m) for (int n = 0; n < 2; ++n) \
;       acc[ai][bj][m][n] = __builtin_amdgcn_mfma_f32_16x16x32_bf16(At_[m][k], Bt_[n][k], acc[ai][bj][m][n], 0, 0, 0); \
;     __builtin_amdgcn_s_setprio(0); } while (0)
; #define WAIT_V(n) asm volatile("s_waitcnt vmcnt(" #n ")" ::: "memory")
; #define WAIT_L(n) asm volatile("s_waitcnt lgkmcnt(" #n ")" ::: "memory")
; #define BAR __builtin_amdgcn_s_barrier()
; template <int EPI, int lda, int ldb, int N, int K>
; __device__ __forceinline__ void gemm_phase(const u16* __restrict__ A, const u16* __restrict__ Bt, const GemmEpi ep, int wv) {
;     ...
;     { LDB(B0, 1, 0); LDA(At, 1, 0); WAIT_V(2); BAR; WAIT_L(0); MMA(0, 0, At, B0); BAR;
;       LDB(B1, 1, 1); WAIT_V(0); BAR; WAIT_L(0); MMA(0, 1, At, B1); BAR;
;       LDA(At, 1, 1); BAR; WAIT_L(0); MMA(1, 0, At, B0); MMA(1, 1, At, B1); BAR; }
;     if (wr == 0) BAR;
	s_waitcnt lgkmcnt(0)
	s_waitcnt lgkmcnt(0)
	v_mfma_f32_16x16x32_bf16 v[64:67], v[0:3], v[20:23], v[124:127]
	v_mfma_f32_16x16x32_bf16 v[68:71], v[16:19], v[20:23], v[120:123]
	v_mfma_f32_16x16x32_bf16 v[80:83], v[0:3], v[200:203], v[116:119]
	v_mfma_f32_16x16x32_bf16 v[84:87], v[16:19], v[200:203], v[112:115]
	v_mfma_f32_16x16x32_bf16 v[108:111], v[0:3], v[208:211], v[108:111]
	v_mfma_f32_16x16x32_bf16 v[104:107], v[16:19], v[208:211], v[104:107]
	v_mfma_f32_16x16x32_bf16 v[120:123], v[0:3], v[216:219], v[100:103]
	v_mfma_f32_16x16x32_bf16 v[124:127], v[16:19], v[216:219], v[96:99]
	v_mfma_f32_16x16x32_bf16 v[116:119], v[4:7], v[196:199], v[64:67]
	v_mfma_f32_16x16x32_bf16 v[112:115], v[174:177], v[196:199], v[68:71]
	v_mfma_f32_16x16x32_bf16 v[100:103], v[4:7], v[204:207], v[80:83]
	v_mfma_f32_16x16x32_bf16 v[96:99], v[174:177], v[204:207], v[84:87]
	v_mfma_f32_16x16x32_bf16 v[84:87], v[4:7], v[212:215], v[108:111]
	v_mfma_f32_16x16x32_bf16 v[80:83], v[174:177], v[212:215], v[104:107]
	v_mfma_f32_16x16x32_bf16 v[68:71], v[4:7], v[220:223], v[120:123]
	v_mfma_f32_16x16x32_bf16 v[64:67], v[174:177], v[220:223], v[124:127]
	s_barrier
	ds_read_b128 v[224:227], v154
	ds_read_b128 v[228:231], v154 offset:1024
	ds_read_b128 v[232:235], v154 offset:2048
	ds_read_b128 v[154:157], v154 offset:3072
	s_waitcnt vmcnt(0)
	s_barrier
	s_waitcnt lgkmcnt(0)
	s_waitcnt lgkmcnt(0)
	v_mfma_f32_16x16x32_bf16 v[92:95], v[224:227], v[20:23], v[92:95]
	v_mfma_f32_16x16x32_bf16 v[20:23], v[232:235], v[20:23], v[88:91]
	v_mfma_f32_16x16x32_bf16 v[88:91], v[224:227], v[200:203], v[180:183]
	v_mfma_f32_16x16x32_bf16 v[104:107], v[232:235], v[200:203], v[184:187]
	v_mfma_f32_16x16x32_bf16 v[76:79], v[224:227], v[208:211], v[76:79]
	v_mfma_f32_16x16x32_bf16 v[72:75], v[232:235], v[208:211], v[72:75]
	v_mfma_f32_16x16x32_bf16 v[178:181], v[224:227], v[216:219], v[188:191]
	v_mfma_f32_16x16x32_bf16 v[182:185], v[232:235], v[216:219], v[192:195]
	v_mfma_f32_16x16x32_bf16 v[124:127], v[228:231], v[196:199], v[92:95]
	v_mfma_f32_16x16x32_bf16 v[120:123], v[154:157], v[196:199], v[20:23]
	v_mfma_f32_16x16x32_bf16 v[108:111], v[228:231], v[204:207], v[88:91]
	v_mfma_f32_16x16x32_bf16 v[104:107], v[154:157], v[204:207], v[104:107]
	v_mfma_f32_16x16x32_bf16 v[92:95], v[228:231], v[212:215], v[76:79]
	v_mfma_f32_16x16x32_bf16 v[88:91], v[154:157], v[212:215], v[72:75]
	v_mfma_f32_16x16x32_bf16 v[76:79], v[228:231], v[220:223], v[178:181]
	v_mfma_f32_16x16x32_bf16 v[72:75], v[154:157], v[220:223], v[182:185]
	s_barrier
	ds_read_b128 v[178:181], v152 offset:49152
	ds_read_b128 v[182:185], v152 offset:50176
	ds_read_b128 v[186:189], v151 offset:49152
	ds_read_b128 v[190:193], v151 offset:50176
	ds_read_b128 v[194:197], v150 offset:49152
	ds_read_b128 v[150:153], v150 offset:50176
	ds_read_b128 v[198:201], v149 offset:49152
	ds_read_b128 v[202:205], v149 offset:50176
	s_barrier
	s_waitcnt lgkmcnt(0)
	s_waitcnt lgkmcnt(0)
	v_mfma_f32_16x16x32_bf16 v[20:23], v[0:3], v[178:181], v[60:63]
	v_mfma_f32_16x16x32_bf16 v[56:59], v[16:19], v[178:181], v[56:59]
	v_mfma_f32_16x16x32_bf16 v[60:63], v[0:3], v[186:189], v[52:55]
	v_mfma_f32_16x16x32_bf16 v[206:209], v[16:19], v[186:189], v[48:51]
	v_mfma_f32_16x16x32_bf16 v[44:47], v[0:3], v[194:197], v[44:47]
	v_mfma_f32_16x16x32_bf16 v[40:43], v[16:19], v[194:197], v[40:43]
	v_mfma_f32_16x16x32_bf16 v[0:3], v[0:3], v[198:201], v[36:39]
	v_mfma_f32_16x16x32_bf16 v[210:213], v[16:19], v[198:201], v[32:35]
	v_mfma_f32_16x16x32_bf16 v[52:55], v[4:7], v[182:185], v[20:23]
	v_mfma_f32_16x16x32_bf16 v[48:51], v[174:177], v[182:185], v[56:59]
	v_mfma_f32_16x16x32_bf16 v[36:39], v[4:7], v[190:193], v[60:63]
	v_mfma_f32_16x16x32_bf16 v[32:35], v[174:177], v[190:193], v[206:209]
	v_mfma_f32_16x16x32_bf16 v[20:23], v[4:7], v[150:153], v[44:47]
	v_mfma_f32_16x16x32_bf16 v[16:19], v[174:177], v[150:153], v[40:43]
	v_mfma_f32_16x16x32_bf16 v[4:7], v[4:7], v[202:205], v[0:3]
	v_mfma_f32_16x16x32_bf16 v[0:3], v[174:177], v[202:205], v[210:213]
	v_mfma_f32_16x16x32_bf16 v[28:31], v[224:227], v[178:181], v[28:31]
	v_mfma_f32_16x16x32_bf16 v[24:27], v[232:235], v[178:181], v[24:27]
	v_mfma_f32_16x16x32_bf16 v[40:43], v[224:227], v[186:189], v[134:137]
	v_mfma_f32_16x16x32_bf16 v[134:137], v[232:235], v[186:189], v[138:141]
	v_mfma_f32_16x16x32_bf16 v[12:15], v[224:227], v[194:197], v[12:15]
	v_mfma_f32_16x16x32_bf16 v[8:11], v[232:235], v[194:197], v[8:11]
	v_mfma_f32_16x16x32_bf16 v[138:141], v[224:227], v[198:201], v[170:173]
	v_mfma_f32_16x16x32_bf16 v[158:161], v[232:235], v[198:201], v[158:161]
	v_mfma_f32_16x16x32_bf16 v[60:63], v[228:231], v[182:185], v[28:31]
	v_mfma_f32_16x16x32_bf16 v[56:59], v[154:157], v[182:185], v[24:27]
	v_mfma_f32_16x16x32_bf16 v[44:47], v[228:231], v[190:193], v[40:43]
	v_mfma_f32_16x16x32_bf16 v[40:43], v[154:157], v[190:193], v[134:137]
	v_mfma_f32_16x16x32_bf16 v[28:31], v[228:231], v[150:153], v[12:15]
	v_mfma_f32_16x16x32_bf16 v[24:27], v[154:157], v[150:153], v[8:11]
	v_mfma_f32_16x16x32_bf16 v[12:15], v[228:231], v[202:205], v[138:141]
	v_mfma_f32_16x16x32_bf16 v[8:11], v[154:157], v[202:205], v[158:161]
	v_cmp_gt_u32_e32 vcc, s54, v130
	s_barrier
	s_and_saveexec_b64 s[40:41], vcc
	s_cbranch_execz .LBB0_1567
	s_barrier

; #define STAGE(P, BASE, LD, br, kt) do { const char* _g = (const char*)((BASE) + (size_t)(br) * (LD) + (size_t)(kt) * 64); \
;     for (int _i = 0; _i < 2; ++_i) { int _b = tidx * 16 + _i * 8192; int _r, _c; stage_rc(_b, _r, _c); \
;       __builtin_amdgcn_global_load_lds((const unsigned*)(_g + (unsigned)((_r * (LD) + _c) * 2)), (unsigned*)((char*)(P) + _b), 16, 0, 0); } } while (0)
; #define LDA(dst, b, h) for (int m = 0; m < 4; ++m) for (int k = 0; k < 2; ++k) \
;     dst[m][k] = *reinterpret_cast<const bf16x8*>((char*)SA(b, h) + lds_byte(wr * 64 + m * 16 + fr, k * 32 + fq * 8))
; #define LDB(dst, b, h) for (int n = 0; n < 2; ++n) for (int k = 0; k < 2; ++k) \
;     dst[n][k] = *reinterpret_cast<const bf16x8*>((char*)SB(b, h) + lds_byte(wc * 32 + n * 16 + fr, k * 32 + fq * 8))
; #define MMA(ai, bj, At_, Bt_) do { __builtin_amdgcn_s_setprio(1); \
;     for (int k = 0; k < 2; ++k) for (int m = 0; m < 4; ++m) for (int n = 0; n < 2; ++n) \
;       acc[ai][bj][m][n] = __builtin_amdgcn_mfma_f32_16x16x32_bf16(At_[m][k], Bt_[n][k], acc[ai][bj][m][n], 0, 0, 0); \
;     __builtin_amdgcn_s_setprio(0); } while (0)
; #define WAIT_L(n) asm volatile("s_waitcnt lgkmcnt(" #n ")" ::: "memory")
; #define BAR __builtin_amdgcn_s_barrier()
; #define SCHED __builtin_amdgcn_sched_barrier(0)
; template <int EPI, int lda, int ldb, int N, int K>
; __device__ __forceinline__ void gemm_phase(const u16* __restrict__ A, const u16* __restrict__ Bt, const GemmEpi ep, int wv) {
;     ...
;       LDB(B0, 0, 0); SCHED; LDA(At, 0, 0); STAGE(SA(1, 1), Ab, lda, brow + HALF, t + 1);
;       WAIT_L(8); BAR; WAIT_L(0); MMA(0, 0, At, B0); BAR; SCHED;
;       LDB(B1, 0, 1); STAGE(SB(0, 0), Bt, ldb, bcol, t + 2);
;       BAR; WAIT_L(0); MMA(0, 1, At, B1); BAR;
;       LDA(At, 0, 1); STAGE(SA(0, 0), Ab, lda, brow, t + 2);
;       BAR; WAIT_L(0); MMA(1, 0, At, B0); BAR; SCHED;
.LBB0_1624:
	ds_read_b128 v[174:177], v163
	ds_read_b128 v[178:181], v163 offset:1024
	ds_read_b128 v[182:185], v163 offset:2048
	ds_read_b128 v[186:189], v163 offset:3072
	v_add_u32_e32 v171, 0xc000, v149
	v_lshl_add_u64 v[238:239], v[134:135], 0, s[28:29]
	v_readfirstlane_b32 s50, v171
	v_add_u32_e32 v172, 0xe000, v149
	v_lshl_add_u64 v[164:165], v[238:239], 0, s[10:11]
	s_mov_b32 m0, s50
	v_lshl_add_u64 v[240:241], v[132:133], 0, s[28:29]
	v_readfirstlane_b32 s50, v172
	ds_read_b128 v[166:169], v154
	ds_read_b128 v[190:193], v154 offset:1024
	ds_read_b128 v[194:197], v153
	ds_read_b128 v[198:201], v153 offset:1024
	ds_read_b128 v[202:205], v151
	ds_read_b128 v[206:209], v151 offset:1024
	ds_read_b128 v[210:213], v150
	ds_read_b128 v[214:217], v150 offset:1024
	global_load_lds_dwordx4 v[164:165], off
	v_lshl_add_u64 v[164:165], v[240:241], 0, s[10:11]
	s_mov_b32 m0, s50
	s_nop 0
	global_load_lds_dwordx4 v[164:165], off
	s_waitcnt lgkmcnt(8)
	s_barrier
	s_waitcnt lgkmcnt(0)
	s_waitcnt lgkmcnt(0)
	v_mfma_f32_16x16x32_bf16 v[124:127], v[166:169], v[174:177], v[124:127]
	v_mfma_f32_16x16x32_bf16 v[120:123], v[166:169], v[182:185], v[120:123]
	v_mfma_f32_16x16x32_bf16 v[116:119], v[194:197], v[174:177], v[116:119]
	v_mfma_f32_16x16x32_bf16 v[112:115], v[194:197], v[182:185], v[112:115]
	v_mfma_f32_16x16x32_bf16 v[108:111], v[202:205], v[174:177], v[108:111]
	v_mfma_f32_16x16x32_bf16 v[104:107], v[202:205], v[182:185], v[104:107]
	v_mfma_f32_16x16x32_bf16 v[100:103], v[210:213], v[174:177], v[100:103]
	v_mfma_f32_16x16x32_bf16 v[96:99], v[210:213], v[182:185], v[96:99]
	v_mfma_f32_16x16x32_bf16 v[124:127], v[190:193], v[178:181], v[124:127]
	v_mfma_f32_16x16x32_bf16 v[120:123], v[190:193], v[186:189], v[120:123]
	v_mfma_f32_16x16x32_bf16 v[116:119], v[198:201], v[178:181], v[116:119]
	v_mfma_f32_16x16x32_bf16 v[112:115], v[198:201], v[186:189], v[112:115]
	v_mfma_f32_16x16x32_bf16 v[108:111], v[206:209], v[178:181], v[108:111]
	v_mfma_f32_16x16x32_bf16 v[104:107], v[206:209], v[186:189], v[104:107]
	v_mfma_f32_16x16x32_bf16 v[100:103], v[214:217], v[178:181], v[100:103]
	v_mfma_f32_16x16x32_bf16 v[96:99], v[214:217], v[186:189], v[96:99]
	s_barrier
	v_add_u32_e32 v164, s40, v155
	v_lshl_add_u64 v[242:243], v[142:143], 0, s[28:29]
	v_readfirstlane_b32 s50, v164
	v_add_u32_e32 v165, 0x2000, v164
	v_lshl_add_u64 v[234:235], v[242:243], 0, s[12:13]
	s_mov_b32 m0, s50
	v_lshl_add_u64 v[244:245], v[140:141], 0, s[28:29]
	v_readfirstlane_b32 s50, v165
	ds_read_b128 v[218:221], v162
	ds_read_b128 v[222:225], v162 offset:1024
	ds_read_b128 v[226:229], v162 offset:2048
	ds_read_b128 v[230:233], v162 offset:3072
	global_load_lds_dwordx4 v[234:235], off
	v_lshl_add_u64 v[234:235], v[244:245], 0, s[12:13]
	s_mov_b32 m0, s50
	s_nop 0
	global_load_lds_dwordx4 v[234:235], off
	s_barrier
	s_waitcnt lgkmcnt(0)
	s_waitcnt lgkmcnt(0)
	v_mfma_f32_16x16x32_bf16 v[92:95], v[166:169], v[218:221], v[92:95]
	v_mfma_f32_16x16x32_bf16 v[88:91], v[166:169], v[226:229], v[88:91]
	v_mfma_f32_16x16x32_bf16 v[84:87], v[194:197], v[218:221], v[84:87]
	v_mfma_f32_16x16x32_bf16 v[80:83], v[194:197], v[226:229], v[80:83]
	v_mfma_f32_16x16x32_bf16 v[76:79], v[202:205], v[218:221], v[76:79]
	v_mfma_f32_16x16x32_bf16 v[72:75], v[202:205], v[226:229], v[72:75]
	v_mfma_f32_16x16x32_bf16 v[68:71], v[210:213], v[218:221], v[68:71]
	v_mfma_f32_16x16x32_bf16 v[64:67], v[210:213], v[226:229], v[64:67]
	v_mfma_f32_16x16x32_bf16 v[92:95], v[190:193], v[222:225], v[92:95]
	v_mfma_f32_16x16x32_bf16 v[88:91], v[190:193], v[230:233], v[88:91]
	v_mfma_f32_16x16x32_bf16 v[84:87], v[198:201], v[222:225], v[84:87]
	v_mfma_f32_16x16x32_bf16 v[80:83], v[198:201], v[230:233], v[80:83]
	v_mfma_f32_16x16x32_bf16 v[76:79], v[206:209], v[222:225], v[76:79]
	v_mfma_f32_16x16x32_bf16 v[72:75], v[206:209], v[230:233], v[72:75]
	v_mfma_f32_16x16x32_bf16 v[68:71], v[214:217], v[222:225], v[68:71]
	v_mfma_f32_16x16x32_bf16 v[64:67], v[214:217], v[230:233], v[64:67]
	s_barrier
	v_readfirstlane_b32 s50, v149
	v_lshl_add_u64 v[166:167], v[238:239], 0, s[14:15]
	s_mov_b32 m0, s50
	ds_read_b128 v[190:193], v154 offset:16384
	ds_read_b128 v[194:197], v154 offset:17408
	ds_read_b128 v[198:201], v153 offset:16384
	ds_read_b128 v[202:205], v153 offset:17408
	ds_read_b128 v[206:209], v151 offset:16384
	ds_read_b128 v[210:213], v151 offset:17408
	ds_read_b128 v[214:217], v150 offset:16384
	ds_read_b128 v[234:237], v150 offset:17408
	global_load_lds_dwordx4 v[166:167], off
	v_add_u32_e32 v166, 0x2000, v149
	v_lshl_add_u64 v[168:169], v[240:241], 0, s[14:15]
	v_readfirstlane_b32 s50, v166
	s_mov_b32 m0, s50
	s_nop 0
	global_load_lds_dwordx4 v[168:169], off
	s_barrier
	s_waitcnt lgkmcnt(0)
	s_waitcnt lgkmcnt(0)
	v_mfma_f32_16x16x32_bf16 v[60:63], v[190:193], v[174:177], v[60:63]
	v_mfma_f32_16x16x32_bf16 v[56:59], v[190:193], v[182:185], v[56:59]
	v_mfma_f32_16x16x32_bf16 v[52:55], v[198:201], v[174:177], v[52:55]
	v_mfma_f32_16x16x32_bf16 v[48:51], v[198:201], v[182:185], v[48:51]
	v_mfma_f32_16x16x32_bf16 v[44:47], v[206:209], v[174:177], v[44:47]
	v_mfma_f32_16x16x32_bf16 v[40:43], v[206:209], v[182:185], v[40:43]
	v_mfma_f32_16x16x32_bf16 v[36:39], v[214:217], v[174:177], v[36:39]
	v_mfma_f32_16x16x32_bf16 v[32:35], v[214:217], v[182:185], v[32:35]
	v_mfma_f32_16x16x32_bf16 v[60:63], v[194:197], v[178:181], v[60:63]
	v_mfma_f32_16x16x32_bf16 v[56:59], v[194:197], v[186:189], v[56:59]
	v_mfma_f32_16x16x32_bf16 v[52:55], v[202:205], v[178:181], v[52:55]
	v_mfma_f32_16x16x32_bf16 v[48:51], v[202:205], v[186:189], v[48:51]
	v_mfma_f32_16x16x32_bf16 v[44:47], v[210:213], v[178:181], v[44:47]
	v_mfma_f32_16x16x32_bf16 v[40:43], v[210:213], v[186:189], v[40:43]
	v_mfma_f32_16x16x32_bf16 v[36:39], v[234:237], v[178:181], v[36:39]
	v_mfma_f32_16x16x32_bf16 v[32:35], v[234:237], v[186:189], v[32:35]
	s_barrier
; #define STAGE(P, BASE, LD, br, kt) do { const char* _g = (const char*)((BASE) + (size_t)(br) * (LD) + (size_t)(kt) * 64); \
;     for (int _i = 0; _i < 2; ++_i) { int _b = tidx * 16 + _i * 8192; int _r, _c; stage_rc(_b, _r, _c); \
;       __builtin_amdgcn_global_load_lds((const unsigned*)(_g + (unsigned)((_r * (LD) + _c) * 2)), (unsigned*)((char*)(P) + _b), 16, 0, 0); } } while (0)
; #define LDA(dst, b, h) for (int m = 0; m < 4; ++m) for (int k = 0; k < 2; ++k) \
;     dst[m][k] = *reinterpret_cast<const bf16x8*>((char*)SA(b, h) + lds_byte(wr * 64 + m * 16 + fr, k * 32 + fq * 8))
; #define LDB(dst, b, h) for (int n = 0; n < 2; ++n) for (int k = 0; k < 2; ++k) \
;     dst[n][k] = *reinterpret_cast<const bf16x8*>((char*)SB(b, h) + lds_byte(wc * 32 + n * 16 + fr, k * 32 + fq * 8))
; #define MMA(ai, bj, At_, Bt_) do { __builtin_amdgcn_s_setprio(1); \
;     for (int k = 0; k < 2; ++k) for (int m = 0; m < 4; ++m) for (int n = 0; n < 2; ++n) \
;       acc[ai][bj][m][n] = __builtin_amdgcn_mfma_f32_16x16x32_bf16(At_[m][k], Bt_[n][k], acc[ai][bj][m][n], 0, 0, 0); \
;     __builtin_amdgcn_s_setprio(0); } while (0)
; #define WAIT_V(n) asm volatile("s_waitcnt vmcnt(" #n ")" ::: "memory")
; #define WAIT_L(n) asm volatile("s_waitcnt lgkmcnt(" #n ")" ::: "memory")
; #define BAR __builtin_amdgcn_s_barrier()
; #define SCHED __builtin_amdgcn_sched_barrier(0)
; template <int EPI, int lda, int ldb, int N, int K>
; __device__ __forceinline__ void gemm_phase(const u16* __restrict__ A, const u16* __restrict__ Bt, const GemmEpi ep, int wv) {
;     ...
;       STAGE(SB(0, 1), Bt, ldb, bcol + HALF, t + 2);
;       WAIT_V(6); BAR; MMA(1, 1, At, B1); BAR;
;       LDB(B0, 1, 0); SCHED; LDA(At, 1, 0); STAGE(SA(0, 1), Ab, lda, brow + HALF, t + 2);
;       WAIT_L(8); BAR; WAIT_L(0); MMA(0, 0, At, B0); BAR; SCHED;
;       LDB(B1, 1, 1); STAGE(SB(1, 0), Bt, ldb, bcol, t + 3);
;       BAR; WAIT_L(0); MMA(0, 1, At, B1); BAR;
	v_add_u32_e32 v167, s41, v155
	v_lshl_add_u64 v[246:247], v[138:139], 0, s[28:29]
	v_readfirstlane_b32 s50, v167
	v_lshl_add_u64 v[168:169], v[246:247], 0, s[16:17]
	s_mov_b32 m0, s50
	v_lshl_add_u64 v[248:249], v[136:137], 0, s[28:29]
	global_load_lds_dwordx4 v[168:169], off
	v_add_u32_e32 v168, 0x2000, v167
	v_lshl_add_u64 v[174:175], v[248:249], 0, s[16:17]
	v_readfirstlane_b32 s50, v168
	s_mov_b32 m0, s50
	s_nop 0
	global_load_lds_dwordx4 v[174:175], off
	s_waitcnt vmcnt(6)
	s_barrier
	v_mfma_f32_16x16x32_bf16 v[28:31], v[190:193], v[218:221], v[28:31]
	v_mfma_f32_16x16x32_bf16 v[24:27], v[190:193], v[226:229], v[24:27]
	v_mfma_f32_16x16x32_bf16 v[20:23], v[198:201], v[218:221], v[20:23]
	v_mfma_f32_16x16x32_bf16 v[16:19], v[198:201], v[226:229], v[16:19]
	v_mfma_f32_16x16x32_bf16 v[12:15], v[206:209], v[218:221], v[12:15]
	v_mfma_f32_16x16x32_bf16 v[8:11], v[206:209], v[226:229], v[8:11]
	v_mfma_f32_16x16x32_bf16 v[4:7], v[214:217], v[218:221], v[4:7]
	v_mfma_f32_16x16x32_bf16 v[0:3], v[214:217], v[226:229], v[0:3]
	v_mfma_f32_16x16x32_bf16 v[28:31], v[194:197], v[222:225], v[28:31]
	v_mfma_f32_16x16x32_bf16 v[24:27], v[194:197], v[230:233], v[24:27]
	v_mfma_f32_16x16x32_bf16 v[20:23], v[202:205], v[222:225], v[20:23]
	v_mfma_f32_16x16x32_bf16 v[16:19], v[202:205], v[230:233], v[16:19]
	v_mfma_f32_16x16x32_bf16 v[12:15], v[210:213], v[222:225], v[12:15]
	v_mfma_f32_16x16x32_bf16 v[8:11], v[210:213], v[230:233], v[8:11]
	v_mfma_f32_16x16x32_bf16 v[4:7], v[234:237], v[222:225], v[4:7]
	v_mfma_f32_16x16x32_bf16 v[0:3], v[234:237], v[230:233], v[0:3]
	s_barrier
	ds_read_b128 v[174:177], v158
	ds_read_b128 v[178:181], v158 offset:1024
	ds_read_b128 v[182:185], v158 offset:2048
	ds_read_b128 v[186:189], v158 offset:3072
	v_add_u32_e32 v169, 0x4000, v149
	v_add_u32_e32 v170, 0x6000, v149
	v_readfirstlane_b32 s50, v169
	v_lshl_add_u64 v[222:223], v[238:239], 0, s[18:19]
	s_mov_b32 m0, s50
	v_readfirstlane_b32 s50, v170
	ds_read_b128 v[190:193], v154 offset:32768
	ds_read_b128 v[194:197], v154 offset:33792
	ds_read_b128 v[198:201], v153 offset:32768
	ds_read_b128 v[202:205], v153 offset:33792
	ds_read_b128 v[206:209], v151 offset:32768
	ds_read_b128 v[210:213], v151 offset:33792
	ds_read_b128 v[214:217], v150 offset:32768
	ds_read_b128 v[218:221], v150 offset:33792
	global_load_lds_dwordx4 v[222:223], off
	v_lshl_add_u64 v[222:223], v[240:241], 0, s[18:19]
	s_mov_b32 m0, s50
	s_nop 0
	global_load_lds_dwordx4 v[222:223], off
	s_waitcnt lgkmcnt(8)
	s_barrier
	s_waitcnt lgkmcnt(0)
	s_waitcnt lgkmcnt(0)
	v_mfma_f32_16x16x32_bf16 v[124:127], v[190:193], v[174:177], v[124:127]
	v_mfma_f32_16x16x32_bf16 v[120:123], v[190:193], v[182:185], v[120:123]
	v_mfma_f32_16x16x32_bf16 v[116:119], v[198:201], v[174:177], v[116:119]
	v_mfma_f32_16x16x32_bf16 v[112:115], v[198:201], v[182:185], v[112:115]
	v_mfma_f32_16x16x32_bf16 v[108:111], v[206:209], v[174:177], v[108:111]
	v_mfma_f32_16x16x32_bf16 v[104:107], v[206:209], v[182:185], v[104:107]
	v_mfma_f32_16x16x32_bf16 v[100:103], v[214:217], v[174:177], v[100:103]
	v_mfma_f32_16x16x32_bf16 v[96:99], v[214:217], v[182:185], v[96:99]
	v_mfma_f32_16x16x32_bf16 v[124:127], v[194:197], v[178:181], v[124:127]
	v_mfma_f32_16x16x32_bf16 v[120:123], v[194:197], v[186:189], v[120:123]
	v_mfma_f32_16x16x32_bf16 v[116:119], v[202:205], v[178:181], v[116:119]
	v_mfma_f32_16x16x32_bf16 v[112:115], v[202:205], v[186:189], v[112:115]
	v_mfma_f32_16x16x32_bf16 v[108:111], v[210:213], v[178:181], v[108:111]
	v_mfma_f32_16x16x32_bf16 v[104:107], v[210:213], v[186:189], v[104:107]
	v_mfma_f32_16x16x32_bf16 v[100:103], v[218:221], v[178:181], v[100:103]
	v_mfma_f32_16x16x32_bf16 v[96:99], v[218:221], v[186:189], v[96:99]
	s_barrier
	v_readfirstlane_b32 s50, v157
	v_add_u32_e32 v173, 0x2000, v157
	v_lshl_add_u64 v[242:243], v[242:243], 0, s[20:21]
	s_mov_b32 m0, s50
	v_readfirstlane_b32 s50, v173
	ds_read_b128 v[222:225], v156
	ds_read_b128 v[226:229], v156 offset:1024
	ds_read_b128 v[230:233], v156 offset:2048
	ds_read_b128 v[234:237], v156 offset:3072
	global_load_lds_dwordx4 v[242:243], off
	v_lshl_add_u64 v[242:243], v[244:245], 0, s[20:21]
	s_mov_b32 m0, s50
	s_nop 0
	global_load_lds_dwordx4 v[242:243], off
	s_barrier
	s_waitcnt lgkmcnt(0)
	s_waitcnt lgkmcnt(0)
	v_mfma_f32_16x16x32_bf16 v[92:95], v[190:193], v[222:225], v[92:95]
	v_mfma_f32_16x16x32_bf16 v[88:91], v[190:193], v[230:233], v[88:91]
	v_mfma_f32_16x16x32_bf16 v[84:87], v[198:201], v[222:225], v[84:87]
	v_mfma_f32_16x16x32_bf16 v[80:83], v[198:201], v[230:233], v[80:83]
	v_mfma_f32_16x16x32_bf16 v[76:79], v[206:209], v[222:225], v[76:79]
	v_mfma_f32_16x16x32_bf16 v[72:75], v[206:209], v[230:233], v[72:75]
	v_mfma_f32_16x16x32_bf16 v[68:71], v[214:217], v[222:225], v[68:71]
	v_mfma_f32_16x16x32_bf16 v[64:67], v[214:217], v[230:233], v[64:67]
	v_mfma_f32_16x16x32_bf16 v[92:95], v[194:197], v[226:229], v[92:95]
	v_mfma_f32_16x16x32_bf16 v[88:91], v[194:197], v[234:237], v[88:91]
	v_mfma_f32_16x16x32_bf16 v[84:87], v[202:205], v[226:229], v[84:87]
	v_mfma_f32_16x16x32_bf16 v[80:83], v[202:205], v[234:237], v[80:83]
	v_mfma_f32_16x16x32_bf16 v[76:79], v[210:213], v[226:229], v[76:79]
	v_mfma_f32_16x16x32_bf16 v[72:75], v[210:213], v[234:237], v[72:75]
	v_mfma_f32_16x16x32_bf16 v[68:71], v[218:221], v[226:229], v[68:71]
	v_mfma_f32_16x16x32_bf16 v[64:67], v[218:221], v[234:237], v[64:67]
	s_barrier
; #define STAGE(P, BASE, LD, br, kt) do { const char* _g = (const char*)((BASE) + (size_t)(br) * (LD) + (size_t)(kt) * 64); \
;     for (int _i = 0; _i < 2; ++_i) { int _b = tidx * 16 + _i * 8192; int _r, _c; stage_rc(_b, _r, _c); \
;       __builtin_amdgcn_global_load_lds((const unsigned*)(_g + (unsigned)((_r * (LD) + _c) * 2)), (unsigned*)((char*)(P) + _b), 16, 0, 0); } } while (0)
; #define LDA(dst, b, h) for (int m = 0; m < 4; ++m) for (int k = 0; k < 2; ++k) \
;     dst[m][k] = *reinterpret_cast<const bf16x8*>((char*)SA(b, h) + lds_byte(wr * 64 + m * 16 + fr, k * 32 + fq * 8))
; #define LDB(dst, b, h) for (int n = 0; n < 2; ++n) for (int k = 0; k < 2; ++k) \
;     dst[n][k] = *reinterpret_cast<const bf16x8*>((char*)SB(b, h) + lds_byte(wc * 32 + n * 16 + fr, k * 32 + fq * 8))
; #define MMA(ai, bj, At_, Bt_) do { __builtin_amdgcn_s_setprio(1); \
;     for (int k = 0; k < 2; ++k) for (int m = 0; m < 4; ++m) for (int n = 0; n < 2; ++n) \
;       acc[ai][bj][m][n] = __builtin_amdgcn_mfma_f32_16x16x32_bf16(At_[m][k], Bt_[n][k], acc[ai][bj][m][n], 0, 0, 0); \
;     __builtin_amdgcn_s_setprio(0); } while (0)
; #define WAIT_V(n) asm volatile("s_waitcnt vmcnt(" #n ")" ::: "memory")
; #define WAIT_L(n) asm volatile("s_waitcnt lgkmcnt(" #n ")" ::: "memory")
; #define BAR __builtin_amdgcn_s_barrier()
; #define SCHED __builtin_amdgcn_sched_barrier(0)
; template <int EPI, int lda, int ldb, int N, int K>
; __device__ __forceinline__ void gemm_phase(const u16* __restrict__ A, const u16* __restrict__ Bt, const GemmEpi ep, int wv) {
;     ...
;       LDA(At, 1, 1); STAGE(SA(1, 0), Ab, lda, brow, t + 3);
;       BAR; WAIT_L(0); MMA(1, 0, At, B0); BAR; SCHED;
;       STAGE(SB(1, 1), Bt, ldb, bcol + HALF, t + 3);
;       WAIT_V(6); BAR; MMA(1, 1, At, B1); BAR;
;     }
;     { LDB(B0, 0, 0); LDA(At, 0, 0); STAGE(SA(1, 1), Ab, lda, brow + HALF, nt - 1);
;       BAR; WAIT_L(0); MMA(0, 0, At, B0); BAR;
;       LDB(B1, 0, 1); BAR; WAIT_L(0); MMA(0, 1, At, B1); BAR;
	v_readfirstlane_b32 s50, v159
	v_lshl_add_u64 v[238:239], v[238:239], 0, s[22:23]
	s_mov_b32 m0, s50
	v_readfirstlane_b32 s50, v160
	ds_read_b128 v[190:193], v154 offset:49152
	ds_read_b128 v[194:197], v154 offset:50176
	ds_read_b128 v[198:201], v153 offset:49152
	ds_read_b128 v[202:205], v153 offset:50176
	ds_read_b128 v[206:209], v151 offset:49152
	ds_read_b128 v[210:213], v151 offset:50176
	ds_read_b128 v[214:217], v150 offset:49152
	ds_read_b128 v[218:221], v150 offset:50176
	global_load_lds_dwordx4 v[238:239], off
	v_lshl_add_u64 v[238:239], v[240:241], 0, s[22:23]
	s_mov_b32 m0, s50
	s_nop 0
	global_load_lds_dwordx4 v[238:239], off
	s_barrier
	s_waitcnt lgkmcnt(0)
	s_waitcnt lgkmcnt(0)
	v_mfma_f32_16x16x32_bf16 v[60:63], v[190:193], v[174:177], v[60:63]
	v_mfma_f32_16x16x32_bf16 v[56:59], v[190:193], v[182:185], v[56:59]
	v_mfma_f32_16x16x32_bf16 v[52:55], v[198:201], v[174:177], v[52:55]
	v_mfma_f32_16x16x32_bf16 v[48:51], v[198:201], v[182:185], v[48:51]
	v_mfma_f32_16x16x32_bf16 v[44:47], v[206:209], v[174:177], v[44:47]
	v_mfma_f32_16x16x32_bf16 v[40:43], v[206:209], v[182:185], v[40:43]
	v_mfma_f32_16x16x32_bf16 v[36:39], v[214:217], v[174:177], v[36:39]
	v_mfma_f32_16x16x32_bf16 v[32:35], v[214:217], v[182:185], v[32:35]
	v_mfma_f32_16x16x32_bf16 v[60:63], v[194:197], v[178:181], v[60:63]
	v_mfma_f32_16x16x32_bf16 v[56:59], v[194:197], v[186:189], v[56:59]
	v_mfma_f32_16x16x32_bf16 v[52:55], v[202:205], v[178:181], v[52:55]
	v_mfma_f32_16x16x32_bf16 v[48:51], v[202:205], v[186:189], v[48:51]
	v_mfma_f32_16x16x32_bf16 v[44:47], v[210:213], v[178:181], v[44:47]
	v_mfma_f32_16x16x32_bf16 v[40:43], v[210:213], v[186:189], v[40:43]
	v_mfma_f32_16x16x32_bf16 v[36:39], v[218:221], v[178:181], v[36:39]
	v_mfma_f32_16x16x32_bf16 v[32:35], v[218:221], v[186:189], v[32:35]
	s_barrier
	v_readfirstlane_b32 s50, v161
	v_add_u32_e32 v173, 0x2000, v161
	v_lshl_add_u64 v[174:175], v[246:247], 0, s[24:25]
	s_mov_b32 m0, s50
	v_readfirstlane_b32 s50, v173
	global_load_lds_dwordx4 v[174:175], off
	v_lshl_add_u64 v[174:175], v[248:249], 0, s[24:25]
	s_mov_b32 m0, s50
	s_nop 0
	global_load_lds_dwordx4 v[174:175], off
	s_add_i32 s49, s49, 2
	s_add_u32 s28, s28, 0x100
	s_addc_u32 s29, s29, 0
	s_cmpk_gt_u32 s49, 0x51
	s_waitcnt vmcnt(6)
	s_barrier
	v_mfma_f32_16x16x32_bf16 v[28:31], v[190:193], v[222:225], v[28:31]
	v_mfma_f32_16x16x32_bf16 v[24:27], v[190:193], v[230:233], v[24:27]
	v_mfma_f32_16x16x32_bf16 v[20:23], v[198:201], v[222:225], v[20:23]
	v_mfma_f32_16x16x32_bf16 v[16:19], v[198:201], v[230:233], v[16:19]
	v_mfma_f32_16x16x32_bf16 v[12:15], v[206:209], v[222:225], v[12:15]
	v_mfma_f32_16x16x32_bf16 v[8:11], v[206:209], v[230:233], v[8:11]
	v_mfma_f32_16x16x32_bf16 v[4:7], v[214:217], v[222:225], v[4:7]
	v_mfma_f32_16x16x32_bf16 v[0:3], v[214:217], v[230:233], v[0:3]
	v_mfma_f32_16x16x32_bf16 v[28:31], v[194:197], v[226:229], v[28:31]
	v_mfma_f32_16x16x32_bf16 v[24:27], v[194:197], v[234:237], v[24:27]
	v_mfma_f32_16x16x32_bf16 v[20:23], v[202:205], v[226:229], v[20:23]
	v_mfma_f32_16x16x32_bf16 v[16:19], v[202:205], v[234:237], v[16:19]
	v_mfma_f32_16x16x32_bf16 v[12:15], v[210:213], v[226:229], v[12:15]
	v_mfma_f32_16x16x32_bf16 v[8:11], v[210:213], v[234:237], v[8:11]
	v_mfma_f32_16x16x32_bf16 v[4:7], v[218:221], v[226:229], v[4:7]
	v_mfma_f32_16x16x32_bf16 v[0:3], v[218:221], v[234:237], v[0:3]
	s_barrier
	s_cbranch_scc0 .LBB0_1624
	s_add_i32 s28, s48, 0x80
	s_mul_hi_i32 s29, s28, 0x2b00
	s_mulk_i32 s28, 0x2b00
	s_add_u32 s28, s34, s28
	s_addc_u32 s29, s35, s29
	s_add_u32 s28, s28, 0x2a80
	s_addc_u32 s29, s29, 0
	v_readfirstlane_b32 s49, v171
	v_lshl_add_u64 v[160:161], s[28:29], 0, v[128:129]
	s_mov_b32 m0, s49
	ds_read_b128 v[132:135], v163
	ds_read_b128 v[136:139], v163 offset:1024
	ds_read_b128 v[140:143], v163 offset:2048
	ds_read_b128 v[174:177], v163 offset:3072
	ds_read_b128 v[178:181], v154
	ds_read_b128 v[182:185], v154 offset:1024
	ds_read_b128 v[186:189], v153
	ds_read_b128 v[190:193], v153 offset:1024
	ds_read_b128 v[194:197], v151
	ds_read_b128 v[198:201], v151 offset:1024
	ds_read_b128 v[202:205], v150
	ds_read_b128 v[206:209], v150 offset:1024
	global_load_lds_dwordx4 v[160:161], off
	v_lshl_add_u64 v[160:161], s[28:29], 0, v[130:131]
	v_readfirstlane_b32 s28, v172
	s_mov_b32 m0, s28
	s_nop 0
	global_load_lds_dwordx4 v[160:161], off
	s_barrier
	s_waitcnt lgkmcnt(0)
	s_waitcnt lgkmcnt(0)
	v_mfma_f32_16x16x32_bf16 v[124:127], v[178:181], v[132:135], v[124:127]
	v_mfma_f32_16x16x32_bf16 v[120:123], v[178:181], v[140:143], v[120:123]
	v_mfma_f32_16x16x32_bf16 v[116:119], v[186:189], v[132:135], v[116:119]
	v_mfma_f32_16x16x32_bf16 v[112:115], v[186:189], v[140:143], v[112:115]
	v_mfma_f32_16x16x32_bf16 v[108:111], v[194:197], v[132:135], v[108:111]
	v_mfma_f32_16x16x32_bf16 v[104:107], v[194:197], v[140:143], v[104:107]
	v_mfma_f32_16x16x32_bf16 v[100:103], v[202:205], v[132:135], v[100:103]
	v_mfma_f32_16x16x32_bf16 v[96:99], v[202:205], v[140:143], v[96:99]
	v_mfma_f32_16x16x32_bf16 v[124:127], v[182:185], v[136:139], v[124:127]
	v_mfma_f32_16x16x32_bf16 v[120:123], v[182:185], v[174:177], v[120:123]
	v_mfma_f32_16x16x32_bf16 v[116:119], v[190:193], v[136:139], v[116:119]
	v_mfma_f32_16x16x32_bf16 v[112:115], v[190:193], v[174:177], v[112:115]
	v_mfma_f32_16x16x32_bf16 v[108:111], v[198:201], v[136:139], v[108:111]
	v_mfma_f32_16x16x32_bf16 v[104:107], v[198:201], v[174:177], v[104:107]
	v_mfma_f32_16x16x32_bf16 v[100:103], v[206:209], v[136:139], v[100:103]
	v_mfma_f32_16x16x32_bf16 v[96:99], v[206:209], v[174:177], v[96:99]
	s_barrier
; #define LDA(dst, b, h) for (int m = 0; m < 4; ++m) for (int k = 0; k < 2; ++k) \
;     dst[m][k] = *reinterpret_cast<const bf16x8*>((char*)SA(b, h) + lds_byte(wr * 64 + m * 16 + fr, k * 32 + fq * 8))
; #define LDB(dst, b, h) for (int n = 0; n < 2; ++n) for (int k = 0; k < 2; ++k) \
;     dst[n][k] = *reinterpret_cast<const bf16x8*>((char*)SB(b, h) + lds_byte(wc * 32 + n * 16 + fr, k * 32 + fq * 8))
; #define MMA(ai, bj, At_, Bt_) do { __builtin_amdgcn_s_setprio(1); \
;     for (int k = 0; k < 2; ++k) for (int m = 0; m < 4; ++m) for (int n = 0; n < 2; ++n) \
;       acc[ai][bj][m][n] = __builtin_amdgcn_mfma_f32_16x16x32_bf16(At_[m][k], Bt_[n][k], acc[ai][bj][m][n], 0, 0, 0); \
;     __builtin_amdgcn_s_setprio(0); } while (0)
; #define WAIT_V(n) asm volatile("s_waitcnt vmcnt(" #n ")" ::: "memory")
; #define WAIT_L(n) asm volatile("s_waitcnt lgkmcnt(" #n ")" ::: "memory")
; #define BAR __builtin_amdgcn_s_barrier()
; template <int EPI, int lda, int ldb, int N, int K>
; __device__ __forceinline__ void gemm_phase(const u16* __restrict__ A, const u16* __restrict__ Bt, const GemmEpi ep, int wv) {
;     ...
;       LDB(B1, 0, 1); BAR; WAIT_L(0); MMA(0, 1, At, B1); BAR;
;       LDA(At, 0, 1); WAIT_V(4); BAR; WAIT_L(0); MMA(1, 0, At, B0); MMA(1, 1, At, B1); BAR; }
;     { LDB(B0, 1, 0); LDA(At, 1, 0); WAIT_V(2); BAR; WAIT_L(0); MMA(0, 0, At, B0); BAR;
	ds_read_b128 v[210:213], v162
	ds_read_b128 v[214:217], v162 offset:1024
	ds_read_b128 v[218:221], v162 offset:2048
	ds_read_b128 v[160:163], v162 offset:3072
	s_barrier
	s_waitcnt lgkmcnt(0)
	s_waitcnt lgkmcnt(0)
	v_mfma_f32_16x16x32_bf16 v[92:95], v[178:181], v[210:213], v[92:95]
	v_mfma_f32_16x16x32_bf16 v[88:91], v[178:181], v[218:221], v[88:91]
	v_mfma_f32_16x16x32_bf16 v[72:75], v[194:197], v[218:221], v[72:75]
	v_mfma_f32_16x16x32_bf16 v[68:71], v[202:205], v[210:213], v[68:71]
	v_mfma_f32_16x16x32_bf16 v[84:87], v[186:189], v[210:213], v[84:87]
	v_mfma_f32_16x16x32_bf16 v[80:83], v[186:189], v[218:221], v[80:83]
	v_mfma_f32_16x16x32_bf16 v[76:79], v[194:197], v[210:213], v[76:79]
	v_mfma_f32_16x16x32_bf16 v[64:67], v[202:205], v[218:221], v[64:67]
	v_mfma_f32_16x16x32_bf16 v[92:95], v[182:185], v[214:217], v[92:95]
	v_mfma_f32_16x16x32_bf16 v[88:91], v[182:185], v[160:163], v[88:91]
	v_mfma_f32_16x16x32_bf16 v[72:75], v[198:201], v[160:163], v[72:75]
	v_mfma_f32_16x16x32_bf16 v[68:71], v[206:209], v[214:217], v[68:71]
	v_mfma_f32_16x16x32_bf16 v[178:181], v[190:193], v[214:217], v[84:87]
	v_mfma_f32_16x16x32_bf16 v[182:185], v[190:193], v[160:163], v[80:83]
	v_mfma_f32_16x16x32_bf16 v[186:189], v[198:201], v[214:217], v[76:79]
	v_mfma_f32_16x16x32_bf16 v[190:193], v[206:209], v[160:163], v[64:67]
	s_barrier
	s_nop 0
	ds_read_b128 v[64:67], v154 offset:16384
	ds_read_b128 v[76:79], v154 offset:17408
	ds_read_b128 v[80:83], v153 offset:16384
	ds_read_b128 v[84:87], v153 offset:17408
	ds_read_b128 v[194:197], v151 offset:16384
	ds_read_b128 v[198:201], v151 offset:17408
	ds_read_b128 v[202:205], v150 offset:16384
	ds_read_b128 v[206:209], v150 offset:17408
	s_waitcnt vmcnt(4)
	s_barrier
	s_waitcnt lgkmcnt(0)
	s_waitcnt lgkmcnt(0)
	v_mfma_f32_16x16x32_bf16 v[60:63], v[64:67], v[132:135], v[60:63]
	v_mfma_f32_16x16x32_bf16 v[56:59], v[64:67], v[140:143], v[56:59]
	v_mfma_f32_16x16x32_bf16 v[52:55], v[80:83], v[132:135], v[52:55]
	v_mfma_f32_16x16x32_bf16 v[48:51], v[80:83], v[140:143], v[48:51]
	v_mfma_f32_16x16x32_bf16 v[44:47], v[194:197], v[132:135], v[44:47]
	v_mfma_f32_16x16x32_bf16 v[40:43], v[194:197], v[140:143], v[40:43]
	v_mfma_f32_16x16x32_bf16 v[36:39], v[202:205], v[132:135], v[36:39]
	v_mfma_f32_16x16x32_bf16 v[32:35], v[202:205], v[140:143], v[32:35]
	v_mfma_f32_16x16x32_bf16 v[60:63], v[76:79], v[136:139], v[60:63]
	v_mfma_f32_16x16x32_bf16 v[56:59], v[76:79], v[174:177], v[56:59]
	v_mfma_f32_16x16x32_bf16 v[52:55], v[84:87], v[136:139], v[52:55]
	v_mfma_f32_16x16x32_bf16 v[48:51], v[84:87], v[174:177], v[48:51]
	v_mfma_f32_16x16x32_bf16 v[44:47], v[198:201], v[136:139], v[44:47]
	v_mfma_f32_16x16x32_bf16 v[40:43], v[198:201], v[174:177], v[40:43]
	v_mfma_f32_16x16x32_bf16 v[36:39], v[206:209], v[136:139], v[36:39]
	v_mfma_f32_16x16x32_bf16 v[32:35], v[206:209], v[174:177], v[32:35]
	v_mfma_f32_16x16x32_bf16 v[28:31], v[64:67], v[210:213], v[28:31]
	v_mfma_f32_16x16x32_bf16 v[24:27], v[64:67], v[218:221], v[24:27]
	v_mfma_f32_16x16x32_bf16 v[12:15], v[194:197], v[210:213], v[12:15]
	v_mfma_f32_16x16x32_bf16 v[8:11], v[194:197], v[218:221], v[8:11]
	v_mfma_f32_16x16x32_bf16 v[20:23], v[80:83], v[210:213], v[20:23]
	v_mfma_f32_16x16x32_bf16 v[16:19], v[80:83], v[218:221], v[16:19]
	v_mfma_f32_16x16x32_bf16 v[4:7], v[202:205], v[210:213], v[4:7]
	v_mfma_f32_16x16x32_bf16 v[0:3], v[202:205], v[218:221], v[0:3]
	v_mfma_f32_16x16x32_bf16 v[28:31], v[76:79], v[214:217], v[28:31]
	v_mfma_f32_16x16x32_bf16 v[24:27], v[76:79], v[160:163], v[24:27]
	v_mfma_f32_16x16x32_bf16 v[12:15], v[198:201], v[214:217], v[12:15]
	v_mfma_f32_16x16x32_bf16 v[8:11], v[198:201], v[160:163], v[8:11]
	v_mfma_f32_16x16x32_bf16 v[132:135], v[84:87], v[214:217], v[20:23]
	v_mfma_f32_16x16x32_bf16 v[136:139], v[84:87], v[160:163], v[16:19]
	v_mfma_f32_16x16x32_bf16 v[140:143], v[206:209], v[214:217], v[4:7]
	v_mfma_f32_16x16x32_bf16 v[160:163], v[206:209], v[160:163], v[0:3]
	s_barrier
	s_nop 0
	ds_read_b128 v[0:3], v158
	ds_read_b128 v[4:7], v158 offset:1024
	ds_read_b128 v[16:19], v158 offset:2048
	ds_read_b128 v[172:175], v158 offset:3072
	ds_read_b128 v[20:23], v154 offset:32768
	ds_read_b128 v[194:197], v154 offset:33792
	ds_read_b128 v[198:201], v153 offset:32768
	ds_read_b128 v[202:205], v153 offset:33792
	ds_read_b128 v[206:209], v151 offset:32768
	ds_read_b128 v[210:213], v151 offset:33792
	ds_read_b128 v[214:217], v150 offset:32768
	ds_read_b128 v[218:221], v150 offset:33792
	s_waitcnt vmcnt(2)
	s_barrier
; #define LDA(dst, b, h) for (int m = 0; m < 4; ++m) for (int k = 0; k < 2; ++k) \
;     dst[m][k] = *reinterpret_cast<const bf16x8*>((char*)SA(b, h) + lds_byte(wr * 64 + m * 16 + fr, k * 32 + fq * 8))
; #define LDB(dst, b, h) for (int n = 0; n < 2; ++n) for (int k = 0; k < 2; ++k) \
;     dst[n][k] = *reinterpret_cast<const bf16x8*>((char*)SB(b, h) + lds_byte(wc * 32 + n * 16 + fr, k * 32 + fq * 8))
; #define MMA(ai, bj, At_, Bt_) do { __builtin_amdgcn_s_setprio(1); \
;     for (int k = 0; k < 2; ++k) for (int m = 0; m < 4; ++m) for (int n = 0; n < 2; ++n) \
;       acc[ai][bj][m][n] = __builtin_amdgcn_mfma_f32_16x16x32_bf16(At_[m][k], Bt_[n][k], acc[ai][bj][m][n], 0, 0, 0); \
;     __builtin_amdgcn_s_setprio(0); } while (0)
; #define WAIT_V(n) asm volatile("s_waitcnt vmcnt(" #n ")" ::: "memory")
; #define WAIT_L(n) asm volatile("s_waitcnt lgkmcnt(" #n ")" ::: "memory")
; #define BAR __builtin_amdgcn_s_barrier()
; template <int EPI, int lda, int ldb, int N, int K>
; __device__ __forceinline__ void gemm_phase(const u16* __restrict__ A, const u16* __restrict__ Bt, const GemmEpi ep, int wv) {
;     ...
;     { LDB(B0, 1, 0); LDA(At, 1, 0); WAIT_V(2); BAR; WAIT_L(0); MMA(0, 0, At, B0); BAR;
;       LDB(B1, 1, 1); WAIT_V(0); BAR; WAIT_L(0); MMA(0, 1, At, B1); BAR;
;       LDA(At, 1, 1); BAR; WAIT_L(0); MMA(1, 0, At, B0); MMA(1, 1, At, B1); BAR; }
;     if (wr == 0) BAR;
	s_waitcnt lgkmcnt(0)
	s_waitcnt lgkmcnt(0)
	v_mfma_f32_16x16x32_bf16 v[64:67], v[20:23], v[0:3], v[124:127]
	v_mfma_f32_16x16x32_bf16 v[76:79], v[20:23], v[16:19], v[120:123]
	v_mfma_f32_16x16x32_bf16 v[80:83], v[198:201], v[0:3], v[116:119]
	v_mfma_f32_16x16x32_bf16 v[84:87], v[198:201], v[16:19], v[112:115]
	v_mfma_f32_16x16x32_bf16 v[108:111], v[206:209], v[0:3], v[108:111]
	v_mfma_f32_16x16x32_bf16 v[104:107], v[206:209], v[16:19], v[104:107]
	v_mfma_f32_16x16x32_bf16 v[120:123], v[214:217], v[0:3], v[100:103]
	v_mfma_f32_16x16x32_bf16 v[124:127], v[214:217], v[16:19], v[96:99]
	v_mfma_f32_16x16x32_bf16 v[116:119], v[194:197], v[4:7], v[64:67]
	v_mfma_f32_16x16x32_bf16 v[112:115], v[194:197], v[172:175], v[76:79]
	v_mfma_f32_16x16x32_bf16 v[100:103], v[202:205], v[4:7], v[80:83]
	v_mfma_f32_16x16x32_bf16 v[96:99], v[202:205], v[172:175], v[84:87]
	v_mfma_f32_16x16x32_bf16 v[84:87], v[210:213], v[4:7], v[108:111]
	v_mfma_f32_16x16x32_bf16 v[80:83], v[210:213], v[172:175], v[104:107]
	v_mfma_f32_16x16x32_bf16 v[76:79], v[218:221], v[4:7], v[120:123]
	v_mfma_f32_16x16x32_bf16 v[64:67], v[218:221], v[172:175], v[124:127]
	s_barrier
	ds_read_b128 v[222:225], v156
	ds_read_b128 v[226:229], v156 offset:1024
	ds_read_b128 v[230:233], v156 offset:2048
	ds_read_b128 v[156:159], v156 offset:3072
	s_waitcnt vmcnt(0)
	s_barrier
	s_waitcnt lgkmcnt(0)
	s_waitcnt lgkmcnt(0)
	v_mfma_f32_16x16x32_bf16 v[92:95], v[20:23], v[222:225], v[92:95]
	v_mfma_f32_16x16x32_bf16 v[20:23], v[20:23], v[230:233], v[88:91]
	v_mfma_f32_16x16x32_bf16 v[88:91], v[198:201], v[222:225], v[178:181]
	v_mfma_f32_16x16x32_bf16 v[104:107], v[198:201], v[230:233], v[182:185]
	v_mfma_f32_16x16x32_bf16 v[176:179], v[206:209], v[222:225], v[186:189]
	v_mfma_f32_16x16x32_bf16 v[72:75], v[206:209], v[230:233], v[72:75]
	v_mfma_f32_16x16x32_bf16 v[68:71], v[214:217], v[222:225], v[68:71]
	v_mfma_f32_16x16x32_bf16 v[180:183], v[214:217], v[230:233], v[190:193]
	v_mfma_f32_16x16x32_bf16 v[124:127], v[194:197], v[226:229], v[92:95]
	v_mfma_f32_16x16x32_bf16 v[120:123], v[194:197], v[156:159], v[20:23]
	v_mfma_f32_16x16x32_bf16 v[108:111], v[202:205], v[226:229], v[88:91]
	v_mfma_f32_16x16x32_bf16 v[104:107], v[202:205], v[156:159], v[104:107]
	v_mfma_f32_16x16x32_bf16 v[92:95], v[210:213], v[226:229], v[176:179]
	v_mfma_f32_16x16x32_bf16 v[88:91], v[210:213], v[156:159], v[72:75]
	v_mfma_f32_16x16x32_bf16 v[72:75], v[218:221], v[226:229], v[68:71]
	v_mfma_f32_16x16x32_bf16 v[68:71], v[218:221], v[156:159], v[180:183]
	s_barrier
	ds_read_b128 v[176:179], v154 offset:49152
	ds_read_b128 v[180:183], v154 offset:50176
	ds_read_b128 v[184:187], v153 offset:49152
	ds_read_b128 v[188:191], v153 offset:50176
	ds_read_b128 v[192:195], v151 offset:49152
	ds_read_b128 v[196:199], v151 offset:50176
	ds_read_b128 v[200:203], v150 offset:49152
	ds_read_b128 v[204:207], v150 offset:50176
	s_barrier
	s_waitcnt lgkmcnt(0)
	s_waitcnt lgkmcnt(0)
	v_mfma_f32_16x16x32_bf16 v[20:23], v[176:179], v[0:3], v[60:63]
	v_mfma_f32_16x16x32_bf16 v[56:59], v[176:179], v[16:19], v[56:59]
	v_mfma_f32_16x16x32_bf16 v[60:63], v[184:187], v[0:3], v[52:55]
	v_mfma_f32_16x16x32_bf16 v[208:211], v[184:187], v[16:19], v[48:51]
	v_mfma_f32_16x16x32_bf16 v[44:47], v[192:195], v[0:3], v[44:47]
	v_mfma_f32_16x16x32_bf16 v[40:43], v[192:195], v[16:19], v[40:43]
	v_mfma_f32_16x16x32_bf16 v[0:3], v[200:203], v[0:3], v[36:39]
	v_mfma_f32_16x16x32_bf16 v[212:215], v[200:203], v[16:19], v[32:35]
	v_mfma_f32_16x16x32_bf16 v[52:55], v[180:183], v[4:7], v[20:23]
	v_mfma_f32_16x16x32_bf16 v[48:51], v[180:183], v[172:175], v[56:59]
	v_mfma_f32_16x16x32_bf16 v[36:39], v[188:191], v[4:7], v[60:63]
	v_mfma_f32_16x16x32_bf16 v[32:35], v[188:191], v[172:175], v[208:211]
	v_mfma_f32_16x16x32_bf16 v[20:23], v[196:199], v[4:7], v[44:47]
	v_mfma_f32_16x16x32_bf16 v[16:19], v[196:199], v[172:175], v[40:43]
	v_mfma_f32_16x16x32_bf16 v[4:7], v[204:207], v[4:7], v[0:3]
	v_mfma_f32_16x16x32_bf16 v[0:3], v[204:207], v[172:175], v[212:215]
	v_mfma_f32_16x16x32_bf16 v[28:31], v[176:179], v[222:225], v[28:31]
	v_mfma_f32_16x16x32_bf16 v[24:27], v[176:179], v[230:233], v[24:27]
	v_mfma_f32_16x16x32_bf16 v[40:43], v[184:187], v[222:225], v[132:135]
	v_mfma_f32_16x16x32_bf16 v[132:135], v[184:187], v[230:233], v[136:139]
	v_mfma_f32_16x16x32_bf16 v[12:15], v[192:195], v[222:225], v[12:15]
	v_mfma_f32_16x16x32_bf16 v[8:11], v[192:195], v[230:233], v[8:11]
	v_mfma_f32_16x16x32_bf16 v[136:139], v[200:203], v[222:225], v[140:143]
	v_mfma_f32_16x16x32_bf16 v[140:143], v[200:203], v[230:233], v[160:163]
	v_mfma_f32_16x16x32_bf16 v[60:63], v[180:183], v[226:229], v[28:31]
	v_mfma_f32_16x16x32_bf16 v[56:59], v[180:183], v[156:159], v[24:27]
	v_mfma_f32_16x16x32_bf16 v[44:47], v[188:191], v[226:229], v[40:43]
	v_mfma_f32_16x16x32_bf16 v[40:43], v[188:191], v[156:159], v[132:135]
	v_mfma_f32_16x16x32_bf16 v[28:31], v[196:199], v[226:229], v[12:15]
	v_mfma_f32_16x16x32_bf16 v[24:27], v[196:199], v[156:159], v[8:11]
	v_mfma_f32_16x16x32_bf16 v[12:15], v[204:207], v[226:229], v[136:139]
	v_mfma_f32_16x16x32_bf16 v[8:11], v[204:207], v[156:159], v[140:143]
	v_cmp_gt_u32_e32 vcc, s46, v147
	s_barrier
	s_and_saveexec_b64 s[28:29], vcc
	s_cbranch_execz .LBB0_1627
	s_barrier
